# v47 (unit-boundary vmcnt(0) removed in EpiUpGlu prefetch) + nt hint on P0's f32 weight loads (read once)
# baseline (speedup 1.0000x reference)
; #define P0_SEG(COUNT, IPM, CALL) if (r < (COUNT) * (IPM)) { const int mi = r / (IPM), item = r % (IPM); (void)mi; CALL; continue; } r -= (COUNT) * (IPM);
; #define P0_UP(mat) p0_transpose_item<1>(A->in[I_FWUP] + (size_t)(mat) * DM * FF2, DM, FF2, WUP + (size_t)(mat) * DM * FF2, scr, item, F.lane, A->in[I_NFFN] + (size_t)(mat) * DM)
; #define P0_DN(mat) p0_transpose_item(A->in[I_FWDN] + (size_t)(mat) * DM * FF, FF, DM, WDN + (size_t)(mat) * DM * FF, scr, item, F.lane)
; #define P0_QKV(mat) p0_transpose_item(A->in[I_AWQKV] + (size_t)(mat) * DM * NQKV, DM, NQKV, WQKV + (size_t)(mat) * DM * NQKV, scr, item, F.lane, A->in[I_NMIX] + (size_t)(2 * (mat) + 1) * DM)
; #define P0_IN(mat) p0_transpose_item(A->in[I_LWIN] + (size_t)(mat) * DM * 4096, DM, 4096, WIN + (size_t)(mat) * DM * 4096, scr, item, F.lane, A->in[I_NMIX] + (size_t)(2 * (mat)) * DM)
; #define P0_OUT(mat) p0_transpose_item(A->in[I_LWOUT] + (size_t)(mat) * DM * DM, DM, DM, WOUT + (size_t)(mat) * DM * DM, scr, item, F.lane)
;     const int nblk = N / 32, kb = item / nblk, nb = item % nblk, k0 = 128 * kb, n0 = 32 * nb;
;     const int nd0 = GLU ? (n0 < 6144 ? 256 * (n0 >> 7) + (n0 & 127) : 256 * ((n0 - 6144) >> 7) + 128 + ((n0 - 6144) & 127)) : n0;
; #pragma unroll 32
;     for (int i = 0; i < 64; ++i) { const int kk = 2 * i + (lane >> 5); scr[kk * 33 + (lane & 31)] = W[(size_t)(k0 + kk) * N + n0 + (lane & 31)]; }
; __device__ __forceinline__ void p0_prologue(const Frame& F, CArgs* A, unsigned char* ws) {
;     ...
;     for (int it = F.gw; it < NITEMS; it += F.ngw) {
;         int r = it;
;         P0_SEG(3, IP_DN, P0_DN(3 - mi)) P0_SEG(3, IP_UP, P0_UP(3 - mi))
;         P0_SEG(1, IP_QKV, P0_QKV(1)) P0_SEG(1, IP_WO, P0_WO(1)) P0_SEG(1, IP_IN, P0_IN(1)) P0_SEG(1, IP_OUT, P0_OUT(1))
;         P0_SEG(1, IP_QKV, P0_QKV(0)) P0_SEG(1, IP_WO, P0_WO(0))
;         P0_SEG(1, IP_DN, P0_DN(0)) P0_SEG(1, IP_UP, P0_UP(0))
;         if (r < 32 * IP_G) { const int gate = r / (16 * IP_G); const int rr = r % (16 * IP_G); const int mat = rr / IP_G;
;           p0_transpose_item(A->in[gate ? I_LWI : I_LWA] + (size_t)mat * 65536, 256, 256, GT + (size_t)(mat >> 3) * (4096 * 256) + (size_t)gate * (2048 * 256) + (size_t)(mat & 7) * 65536, scr, rr % IP_G, F.lane); continue; } r -= 32 * IP_G;
;         P0_SEG(1, IP_OUT, P0_OUT(0)) P0_SEG(1, IP_IN, P0_IN(0))
.LBB0_11:
	s_cmpk_gt_i32 s56, 0x23ff
	s_mov_b64 s[2:3], -1
	s_cbranch_scc0 .LBB0_74
	s_cmpk_gt_u32 s56, 0x6bff
	s_cbranch_scc0 .LBB0_64
	s_cmpk_gt_u32 s56, 0x7dff
	s_cbranch_scc0 .LBB0_61
	s_cmpk_gt_u32 s56, 0x7fff
	s_cbranch_scc0 .LBB0_58
	s_cmpk_gt_u32 s56, 0x87ff
	s_cbranch_scc0 .LBB0_55
	s_cmpk_gt_u32 s56, 0x8bff
	s_cbranch_scc0 .LBB0_52
	s_cmpk_gt_u32 s56, 0x9dff
	s_cbranch_scc0 .LBB0_49
	s_cmpk_gt_u32 s56, 0x9fff
	s_cbranch_scc0 .LBB0_46
	s_cmpk_gt_u32 s56, 0xabff
	s_cbranch_scc0 .LBB0_43
	s_cmpk_gt_u32 s56, 0xc3ff
	s_cbranch_scc0 .LBB0_33
	s_cmpk_gt_u32 s56, 0xc5ff
	s_cbranch_scc0 .LBB0_30
	s_cmpk_gt_u32 s56, 0xc9ff
	s_cbranch_scc0 .LBB0_27
	s_load_dwordx2 s[2:3], s[6:7], 0x58
	s_and_b32 s24, s41, 0xfe0
	s_lshl_b32 s10, s24, 2
	v_lshlrev_b32_e32 v14, 2, v12
	s_waitcnt lgkmcnt(0)
	s_add_u32 s2, s2, s10
	s_addc_u32 s3, s3, 0
	s_add_i32 s10, s56, 0x600
	s_and_b32 s10, s10, 0x780
	v_add_u32_e32 v4, s10, v10
	v_add_u32_e32 v2, s10, v9
	v_ashrrev_i32_e32 v5, 31, v4
	v_add_u32_e32 v6, s10, v11
	v_add_u32_e32 v172, s10, v38
	v_add_u32_e32 v174, s10, v13
	v_add_u32_e32 v176, s10, v40
	v_add_u32_e32 v178, s10, v17
	v_add_u32_e32 v180, s10, v42
	v_lshl_add_u64 v[0:1], s[2:3], 0, v[14:15]
	v_ashrrev_i32_e32 v3, 31, v2
	v_lshlrev_b64 v[4:5], 14, v[4:5]
	v_ashrrev_i32_e32 v173, 31, v172
	v_ashrrev_i32_e32 v7, 31, v6
	v_ashrrev_i32_e32 v177, 31, v176
	v_ashrrev_i32_e32 v175, 31, v174
	v_ashrrev_i32_e32 v181, 31, v180
	v_ashrrev_i32_e32 v179, 31, v178
	v_lshlrev_b64 v[2:3], 14, v[2:3]
	v_lshl_add_u64 v[4:5], v[0:1], 0, v[4:5]
	v_lshlrev_b64 v[6:7], 14, v[6:7]
	v_lshlrev_b64 v[172:173], 14, v[172:173]
	v_lshlrev_b64 v[174:175], 14, v[174:175]
	v_lshlrev_b64 v[176:177], 14, v[176:177]
	v_lshlrev_b64 v[178:179], 14, v[178:179]
	v_lshlrev_b64 v[180:181], 14, v[180:181]
	v_lshl_add_u64 v[2:3], v[0:1], 0, v[2:3]
	v_lshl_add_u64 v[172:173], v[0:1], 0, v[172:173]
	v_lshl_add_u64 v[6:7], v[0:1], 0, v[6:7]
	v_lshl_add_u64 v[176:177], v[0:1], 0, v[176:177]
	v_lshl_add_u64 v[174:175], v[0:1], 0, v[174:175]
	v_lshl_add_u64 v[180:181], v[0:1], 0, v[180:181]
	v_lshl_add_u64 v[178:179], v[0:1], 0, v[178:179]
	global_load_dword v14, v[4:5], off nt
	global_load_dword v182, v[2:3], off nt
	global_load_dword v183, v[172:173], off nt
	global_load_dword v184, v[6:7], off nt
	global_load_dword v185, v[176:177], off nt
	global_load_dword v186, v[174:175], off nt
	global_load_dword v187, v[180:181], off nt
	global_load_dword v188, v[178:179], off nt
	v_add_u32_e32 v4, s10, v44
	v_add_u32_e32 v6, s10, v41
	v_add_u32_e32 v172, s10, v46
	v_add_u32_e32 v178, s10, v45
	v_add_u32_e32 v180, s10, v50
	v_add_u32_e32 v2, s10, v39
	v_ashrrev_i32_e32 v5, 31, v4
	v_ashrrev_i32_e32 v173, 31, v172
	v_ashrrev_i32_e32 v7, 31, v6
	v_add_u32_e32 v174, s10, v43
	v_add_u32_e32 v176, s10, v48
	v_ashrrev_i32_e32 v181, 31, v180
	v_ashrrev_i32_e32 v179, 31, v178
	v_ashrrev_i32_e32 v3, 31, v2
	v_lshlrev_b64 v[4:5], 14, v[4:5]
	v_lshlrev_b64 v[6:7], 14, v[6:7]
	v_lshlrev_b64 v[172:173], 14, v[172:173]
	v_ashrrev_i32_e32 v177, 31, v176
	v_ashrrev_i32_e32 v175, 31, v174
	v_lshlrev_b64 v[178:179], 14, v[178:179]
	v_lshlrev_b64 v[180:181], 14, v[180:181]
	v_lshlrev_b64 v[2:3], 14, v[2:3]
	v_lshl_add_u64 v[4:5], v[0:1], 0, v[4:5]
	v_lshl_add_u64 v[172:173], v[0:1], 0, v[172:173]
	v_lshl_add_u64 v[6:7], v[0:1], 0, v[6:7]
	v_lshlrev_b64 v[174:175], 14, v[174:175]
	v_lshlrev_b64 v[176:177], 14, v[176:177]
	v_lshl_add_u64 v[180:181], v[0:1], 0, v[180:181]
	v_lshl_add_u64 v[178:179], v[0:1], 0, v[178:179]
	v_lshl_add_u64 v[2:3], v[0:1], 0, v[2:3]
	v_lshl_add_u64 v[176:177], v[0:1], 0, v[176:177]
	v_lshl_add_u64 v[174:175], v[0:1], 0, v[174:175]
	global_load_dword v189, v[4:5], off nt
	global_load_dword v190, v[2:3], off nt
	global_load_dword v191, v[172:173], off nt
	global_load_dword v192, v[6:7], off nt
	global_load_dword v193, v[176:177], off nt
	global_load_dword v194, v[174:175], off nt
	s_nop 0
	global_load_dword v180, v[180:181], off nt
	s_nop 0
	global_load_dword v178, v[178:179], off nt
	v_add_u32_e32 v4, s10, v52
	v_add_u32_e32 v6, s10, v49
	v_add_u32_e32 v172, s10, v54
	v_add_u32_e32 v2, s10, v47
	v_ashrrev_i32_e32 v5, 31, v4
	v_ashrrev_i32_e32 v173, 31, v172
	v_ashrrev_i32_e32 v7, 31, v6
	v_add_u32_e32 v174, s10, v51
	v_add_u32_e32 v176, s10, v56
	v_ashrrev_i32_e32 v3, 31, v2
	v_lshlrev_b64 v[4:5], 14, v[4:5]
	v_lshlrev_b64 v[6:7], 14, v[6:7]
	v_lshlrev_b64 v[172:173], 14, v[172:173]
	v_ashrrev_i32_e32 v177, 31, v176
	v_ashrrev_i32_e32 v175, 31, v174
	v_lshlrev_b64 v[2:3], 14, v[2:3]
	v_lshl_add_u64 v[4:5], v[0:1], 0, v[4:5]
	v_lshl_add_u64 v[172:173], v[0:1], 0, v[172:173]
	v_lshl_add_u64 v[6:7], v[0:1], 0, v[6:7]
	v_lshlrev_b64 v[174:175], 14, v[174:175]
	v_lshlrev_b64 v[176:177], 14, v[176:177]
	v_lshl_add_u64 v[2:3], v[0:1], 0, v[2:3]
	v_lshl_add_u64 v[176:177], v[0:1], 0, v[176:177]
	v_lshl_add_u64 v[174:175], v[0:1], 0, v[174:175]
	global_load_dword v179, v[4:5], off nt
	global_load_dword v181, v[2:3], off nt
	s_nop 0
	global_load_dword v172, v[172:173], off nt
	s_nop 0
	global_load_dword v6, v[6:7], off nt
	s_nop 0
	global_load_dword v7, v[176:177], off nt
	global_load_dword v173, v[174:175], off nt
	v_add_u32_e32 v4, s10, v58
	v_add_u32_e32 v2, s10, v53
	v_ashrrev_i32_e32 v5, 31, v4
	v_ashrrev_i32_e32 v3, 31, v2
	v_lshlrev_b64 v[4:5], 14, v[4:5]
	v_lshlrev_b64 v[2:3], 14, v[2:3]
	v_lshl_add_u64 v[4:5], v[0:1], 0, v[4:5]
	global_load_dword v4, v[4:5], off nt
	v_lshl_add_u64 v[2:3], v[0:1], 0, v[2:3]
	global_load_dword v2, v[2:3], off nt
	v_add_u32_e32 v3, v97, v108
	v_add_u32_e32 v174, s10, v59
	v_add_u32_e32 v176, s10, v64
	v_ashrrev_i32_e32 v177, 31, v176
	s_waitcnt vmcnt(23)
; #define LDS_WAIT() asm volatile("s_waitcnt lgkmcnt(0)" ::: "memory")
;     ...
; #pragma unroll 32
;     for (int i = 0; i < 64; ++i) { const int kk = 2 * i + (lane >> 5); scr[kk * 33 + (lane & 31)] = W[(size_t)(k0 + kk) * N + n0 + (lane & 31)]; }
;     LDS_WAIT(); asm volatile("" ::: "memory");
;     const int c = lane & 15;
;     float gk[8];
;     if (gain) load8f(gain + k0 + 8 * c, gk); else {
	ds_write_b32 v3, v14
	v_add_u32_e32 v3, v97, v109
	s_waitcnt vmcnt(22)
	ds_write_b32 v3, v182
	v_add_u32_e32 v3, v97, v110
	s_waitcnt vmcnt(21)
	ds_write_b32 v3, v183
	v_add_u32_e32 v3, v97, v111
	s_waitcnt vmcnt(20)
	ds_write_b32 v3, v184
	v_add_u32_e32 v3, v97, v112
	s_waitcnt vmcnt(19)
	ds_write_b32 v3, v185
	v_add_u32_e32 v3, v97, v113
	s_waitcnt vmcnt(18)
	ds_write_b32 v3, v186
	v_add_u32_e32 v3, v97, v114
	s_waitcnt vmcnt(17)
	ds_write_b32 v3, v187
	v_add_u32_e32 v3, v97, v115
	s_waitcnt vmcnt(16)
	ds_write_b32 v3, v188
	v_add_u32_e32 v3, v97, v116
	v_ashrrev_i32_e32 v175, 31, v174
	v_lshlrev_b64 v[174:175], 14, v[174:175]
	v_lshlrev_b64 v[176:177], 14, v[176:177]
	s_load_dwordx2 s[2:3], s[6:7], 0x40
	v_lshl_add_u64 v[176:177], v[0:1], 0, v[176:177]
	v_lshl_add_u64 v[174:175], v[0:1], 0, v[174:175]
	s_waitcnt lgkmcnt(0)
	s_cmp_eq_u64 s[2:3], 0
	s_waitcnt vmcnt(15)
	ds_write_b32 v3, v189
	v_add_u32_e32 v3, v97, v117
	s_waitcnt vmcnt(14)
	ds_write_b32 v3, v190
	v_add_u32_e32 v3, v97, v118
	s_waitcnt vmcnt(13)
	ds_write_b32 v3, v191
	v_add_u32_e32 v3, v97, v119
	s_waitcnt vmcnt(12)
	ds_write_b32 v3, v192
	v_add_u32_e32 v3, v97, v120
	s_waitcnt vmcnt(11)
	ds_write_b32 v3, v193
	v_add_u32_e32 v3, v97, v121
	s_waitcnt vmcnt(10)
	ds_write_b32 v3, v194
	v_add_u32_e32 v3, v97, v122
	s_waitcnt vmcnt(9)
	ds_write_b32 v3, v180
	v_add_u32_e32 v3, v97, v123
	s_waitcnt vmcnt(8)
	ds_write_b32 v3, v178
	v_add_u32_e32 v3, v97, v124
	v_add_u32_e32 v178, s10, v61
	v_add_u32_e32 v180, s10, v66
	s_waitcnt vmcnt(7)
	ds_write_b32 v3, v179
	v_add_u32_e32 v3, v97, v125
	s_waitcnt vmcnt(6)
	ds_write_b32 v3, v181
	v_add_u32_e32 v3, v97, v126
	s_waitcnt vmcnt(5)
	ds_write_b32 v3, v172
	v_add_u32_e32 v3, v97, v127
	s_waitcnt vmcnt(4)
	ds_write_b32 v3, v6
	v_add_u32_e32 v3, v97, v128
	s_waitcnt vmcnt(3)
	ds_write_b32 v3, v7
	v_add_u32_e32 v3, v97, v129
	s_waitcnt vmcnt(2)
	ds_write_b32 v3, v173
	v_add_u32_e32 v3, v97, v130
	v_add_u32_e32 v6, s10, v57
	s_waitcnt vmcnt(1)
	ds_write_b32 v3, v4
	v_add_u32_e32 v3, v97, v131
	v_add_u32_e32 v4, s10, v60
	s_waitcnt vmcnt(0)
	ds_write_b32 v3, v2
	v_add_u32_e32 v2, s10, v55
	v_ashrrev_i32_e32 v5, 31, v4
	v_add_u32_e32 v172, s10, v62
	v_ashrrev_i32_e32 v3, 31, v2
	v_lshlrev_b64 v[4:5], 14, v[4:5]
	v_ashrrev_i32_e32 v173, 31, v172
	v_ashrrev_i32_e32 v7, 31, v6
	v_ashrrev_i32_e32 v181, 31, v180
	v_ashrrev_i32_e32 v179, 31, v178
	v_lshlrev_b64 v[2:3], 14, v[2:3]
	v_lshl_add_u64 v[4:5], v[0:1], 0, v[4:5]
	v_lshlrev_b64 v[6:7], 14, v[6:7]
	v_lshlrev_b64 v[172:173], 14, v[172:173]
	v_lshlrev_b64 v[178:179], 14, v[178:179]
	v_lshlrev_b64 v[180:181], 14, v[180:181]
	v_lshl_add_u64 v[2:3], v[0:1], 0, v[2:3]
	v_lshl_add_u64 v[172:173], v[0:1], 0, v[172:173]
	v_lshl_add_u64 v[6:7], v[0:1], 0, v[6:7]
	v_lshl_add_u64 v[180:181], v[0:1], 0, v[180:181]
	v_lshl_add_u64 v[178:179], v[0:1], 0, v[178:179]
	global_load_dword v14, v[4:5], off nt
	global_load_dword v182, v[2:3], off nt
	global_load_dword v183, v[172:173], off nt
	global_load_dword v184, v[6:7], off nt
	global_load_dword v185, v[176:177], off nt
	global_load_dword v186, v[174:175], off nt
	global_load_dword v187, v[180:181], off nt
	global_load_dword v188, v[178:179], off nt
	v_add_u32_e32 v4, s10, v68
	v_add_u32_e32 v2, s10, v63
	v_ashrrev_i32_e32 v5, 31, v4
	v_add_u32_e32 v6, s10, v65
	v_add_u32_e32 v172, s10, v70
	v_add_u32_e32 v174, s10, v67
	v_add_u32_e32 v176, s10, v72
	v_add_u32_e32 v178, s10, v69
	v_add_u32_e32 v180, s10, v74
	v_ashrrev_i32_e32 v3, 31, v2
	v_lshlrev_b64 v[4:5], 14, v[4:5]
	v_ashrrev_i32_e32 v173, 31, v172
	v_ashrrev_i32_e32 v7, 31, v6
	v_ashrrev_i32_e32 v177, 31, v176
	v_ashrrev_i32_e32 v175, 31, v174
	v_ashrrev_i32_e32 v181, 31, v180
	v_ashrrev_i32_e32 v179, 31, v178
	v_lshlrev_b64 v[2:3], 14, v[2:3]
	v_lshl_add_u64 v[4:5], v[0:1], 0, v[4:5]
	v_lshlrev_b64 v[6:7], 14, v[6:7]
	v_lshlrev_b64 v[172:173], 14, v[172:173]
	v_lshlrev_b64 v[174:175], 14, v[174:175]
	v_lshlrev_b64 v[176:177], 14, v[176:177]
	v_lshlrev_b64 v[178:179], 14, v[178:179]
	v_lshlrev_b64 v[180:181], 14, v[180:181]
	v_lshl_add_u64 v[2:3], v[0:1], 0, v[2:3]
	v_lshl_add_u64 v[172:173], v[0:1], 0, v[172:173]
	v_lshl_add_u64 v[6:7], v[0:1], 0, v[6:7]
	v_lshl_add_u64 v[176:177], v[0:1], 0, v[176:177]
	v_lshl_add_u64 v[174:175], v[0:1], 0, v[174:175]
	v_lshl_add_u64 v[180:181], v[0:1], 0, v[180:181]
	v_lshl_add_u64 v[178:179], v[0:1], 0, v[178:179]
	global_load_dword v189, v[4:5], off nt
	global_load_dword v190, v[2:3], off nt
	global_load_dword v191, v[172:173], off nt
	global_load_dword v192, v[6:7], off nt
	global_load_dword v193, v[176:177], off nt
	global_load_dword v194, v[174:175], off nt
	global_load_dword v195, v[180:181], off nt
	global_load_dword v196, v[178:179], off nt
	v_add_u32_e32 v4, s10, v76
	v_add_u32_e32 v2, s10, v71
	v_ashrrev_i32_e32 v5, 31, v4
	v_add_u32_e32 v6, s10, v73
	v_add_u32_e32 v172, s10, v78
	v_add_u32_e32 v174, s10, v75
	v_add_u32_e32 v176, s10, v80
	v_add_u32_e32 v178, s10, v77
	v_add_u32_e32 v180, s10, v82
	v_ashrrev_i32_e32 v3, 31, v2
	v_lshlrev_b64 v[4:5], 14, v[4:5]
	v_ashrrev_i32_e32 v173, 31, v172
	v_ashrrev_i32_e32 v7, 31, v6
	v_ashrrev_i32_e32 v177, 31, v176
	v_ashrrev_i32_e32 v175, 31, v174
	v_ashrrev_i32_e32 v181, 31, v180
	v_ashrrev_i32_e32 v179, 31, v178
	v_lshlrev_b64 v[2:3], 14, v[2:3]
	v_lshl_add_u64 v[4:5], v[0:1], 0, v[4:5]
	v_lshlrev_b64 v[6:7], 14, v[6:7]
	v_lshlrev_b64 v[172:173], 14, v[172:173]
	v_lshlrev_b64 v[174:175], 14, v[174:175]
	v_lshlrev_b64 v[176:177], 14, v[176:177]
	v_lshlrev_b64 v[178:179], 14, v[178:179]
	v_lshlrev_b64 v[180:181], 14, v[180:181]
	v_lshl_add_u64 v[2:3], v[0:1], 0, v[2:3]
	v_lshl_add_u64 v[172:173], v[0:1], 0, v[172:173]
; #define LDS_WAIT() asm volatile("s_waitcnt lgkmcnt(0)" ::: "memory")
;     ...
; #pragma unroll 32
;     for (int i = 0; i < 64; ++i) { const int kk = 2 * i + (lane >> 5); scr[kk * 33 + (lane & 31)] = W[(size_t)(k0 + kk) * N + n0 + (lane & 31)]; }
;     LDS_WAIT(); asm volatile("" ::: "memory");
;     const int c = lane & 15;
;     float gk[8];
;     if (gain) load8f(gain + k0 + 8 * c, gk); else {
	v_lshl_add_u64 v[6:7], v[0:1], 0, v[6:7]
	v_lshl_add_u64 v[176:177], v[0:1], 0, v[176:177]
	v_lshl_add_u64 v[174:175], v[0:1], 0, v[174:175]
	v_lshl_add_u64 v[180:181], v[0:1], 0, v[180:181]
	v_lshl_add_u64 v[178:179], v[0:1], 0, v[178:179]
	global_load_dword v197, v[4:5], off nt
	global_load_dword v198, v[2:3], off nt
	global_load_dword v199, v[172:173], off nt
	global_load_dword v200, v[6:7], off nt
	global_load_dword v201, v[176:177], off nt
	global_load_dword v202, v[174:175], off nt
	global_load_dword v203, v[180:181], off nt
	global_load_dword v204, v[178:179], off nt
	v_add_u32_e32 v4, s10, v84
	v_add_u32_e32 v6, s10, v81
	v_add_u32_e32 v172, s10, v86
	v_add_u32_e32 v178, s10, v85
	v_add_u32_e32 v180, s10, v90
	v_add_u32_e32 v2, s10, v79
	v_ashrrev_i32_e32 v5, 31, v4
	v_ashrrev_i32_e32 v173, 31, v172
	v_ashrrev_i32_e32 v7, 31, v6
	v_add_u32_e32 v174, s10, v83
	v_add_u32_e32 v176, s10, v88
	v_ashrrev_i32_e32 v181, 31, v180
	v_ashrrev_i32_e32 v179, 31, v178
	v_ashrrev_i32_e32 v3, 31, v2
	v_lshlrev_b64 v[4:5], 14, v[4:5]
	v_lshlrev_b64 v[6:7], 14, v[6:7]
	v_lshlrev_b64 v[172:173], 14, v[172:173]
	v_ashrrev_i32_e32 v177, 31, v176
	v_ashrrev_i32_e32 v175, 31, v174
	v_lshlrev_b64 v[178:179], 14, v[178:179]
	v_lshlrev_b64 v[180:181], 14, v[180:181]
	v_lshlrev_b64 v[2:3], 14, v[2:3]
	v_lshl_add_u64 v[4:5], v[0:1], 0, v[4:5]
	v_lshl_add_u64 v[172:173], v[0:1], 0, v[172:173]
	v_lshl_add_u64 v[6:7], v[0:1], 0, v[6:7]
	v_lshlrev_b64 v[174:175], 14, v[174:175]
	v_lshlrev_b64 v[176:177], 14, v[176:177]
	v_lshl_add_u64 v[180:181], v[0:1], 0, v[180:181]
	v_lshl_add_u64 v[178:179], v[0:1], 0, v[178:179]
	v_lshl_add_u64 v[2:3], v[0:1], 0, v[2:3]
	v_lshl_add_u64 v[176:177], v[0:1], 0, v[176:177]
	v_lshl_add_u64 v[174:175], v[0:1], 0, v[174:175]
	global_load_dword v205, v[4:5], off nt
	global_load_dword v206, v[2:3], off nt
	global_load_dword v207, v[172:173], off nt
	global_load_dword v208, v[6:7], off nt
	global_load_dword v209, v[176:177], off nt
	global_load_dword v210, v[174:175], off nt
	s_nop 0
	global_load_dword v180, v[180:181], off nt
	s_nop 0
	global_load_dword v178, v[178:179], off nt
	v_add_u32_e32 v4, s10, v92
	v_add_u32_e32 v6, s10, v89
	v_add_u32_e32 v172, s10, v94
	v_add_u32_e32 v2, s10, v87
	v_ashrrev_i32_e32 v5, 31, v4
	v_ashrrev_i32_e32 v173, 31, v172
	v_ashrrev_i32_e32 v7, 31, v6
	v_add_u32_e32 v174, s10, v91
	v_add_u32_e32 v176, s10, v96
	v_ashrrev_i32_e32 v3, 31, v2
	v_lshlrev_b64 v[4:5], 14, v[4:5]
	v_lshlrev_b64 v[6:7], 14, v[6:7]
	v_lshlrev_b64 v[172:173], 14, v[172:173]
	v_ashrrev_i32_e32 v177, 31, v176
	v_ashrrev_i32_e32 v175, 31, v174
	v_lshlrev_b64 v[2:3], 14, v[2:3]
	v_lshl_add_u64 v[4:5], v[0:1], 0, v[4:5]
	v_lshl_add_u64 v[172:173], v[0:1], 0, v[172:173]
	v_lshl_add_u64 v[6:7], v[0:1], 0, v[6:7]
	v_lshlrev_b64 v[174:175], 14, v[174:175]
	v_lshlrev_b64 v[176:177], 14, v[176:177]
	v_lshl_add_u64 v[2:3], v[0:1], 0, v[2:3]
	v_lshl_add_u64 v[176:177], v[0:1], 0, v[176:177]
	v_lshl_add_u64 v[174:175], v[0:1], 0, v[174:175]
	global_load_dword v179, v[4:5], off nt
	global_load_dword v181, v[2:3], off nt
	s_nop 0
	global_load_dword v172, v[172:173], off nt
	s_nop 0
	global_load_dword v6, v[6:7], off nt
	s_nop 0
	global_load_dword v7, v[176:177], off nt
	global_load_dword v173, v[174:175], off nt
	v_add_u32_e32 v4, s10, v98
	v_add_u32_e32 v2, s10, v93
	v_ashrrev_i32_e32 v5, 31, v4
	v_ashrrev_i32_e32 v3, 31, v2
	v_lshlrev_b64 v[4:5], 14, v[4:5]
	v_lshlrev_b64 v[2:3], 14, v[2:3]
	v_lshl_add_u64 v[4:5], v[0:1], 0, v[4:5]
	global_load_dword v4, v[4:5], off nt
	v_lshl_add_u64 v[0:1], v[0:1], 0, v[2:3]
	global_load_dword v0, v[0:1], off nt
	v_add_u32_e32 v1, v97, v132
	s_waitcnt vmcnt(39)
	ds_write_b32 v1, v14
	v_add_u32_e32 v1, v97, v133
	s_waitcnt vmcnt(38)
	ds_write_b32 v1, v182
	v_add_u32_e32 v1, v97, v134
	s_waitcnt vmcnt(37)
	ds_write_b32 v1, v183
	v_add_u32_e32 v1, v97, v135
	s_waitcnt vmcnt(36)
	ds_write_b32 v1, v184
	v_add_u32_e32 v1, v97, v136
	s_waitcnt vmcnt(35)
	ds_write_b32 v1, v185
	v_add_u32_e32 v1, v97, v137
	s_waitcnt vmcnt(34)
	ds_write_b32 v1, v186
	v_add_u32_e32 v1, v97, v138
	s_waitcnt vmcnt(33)
	ds_write_b32 v1, v187
	v_add_u32_e32 v1, v97, v139
	s_waitcnt vmcnt(32)
	ds_write_b32 v1, v188
	v_add_u32_e32 v1, v97, v140
	s_waitcnt vmcnt(31)
	ds_write_b32 v1, v189
	v_add_u32_e32 v1, v97, v141
	s_waitcnt vmcnt(30)
	ds_write_b32 v1, v190
	v_add_u32_e32 v1, v97, v142
	s_waitcnt vmcnt(29)
	ds_write_b32 v1, v191
	v_add_u32_e32 v1, v97, v143
	s_waitcnt vmcnt(28)
	ds_write_b32 v1, v192
	v_add_u32_e32 v1, v97, v144
	s_waitcnt vmcnt(27)
	ds_write_b32 v1, v193
	v_add_u32_e32 v1, v97, v145
	s_waitcnt vmcnt(26)
	ds_write_b32 v1, v194
	v_add_u32_e32 v1, v97, v146
	s_waitcnt vmcnt(25)
	ds_write_b32 v1, v195
	v_add_u32_e32 v1, v97, v147
	s_waitcnt vmcnt(24)
	ds_write_b32 v1, v196
	v_add_u32_e32 v1, v97, v148
	s_waitcnt vmcnt(23)
	ds_write_b32 v1, v197
	v_add_u32_e32 v1, v97, v149
	s_waitcnt vmcnt(22)
	ds_write_b32 v1, v198
	v_add_u32_e32 v1, v97, v150
	s_waitcnt vmcnt(21)
	ds_write_b32 v1, v199
	v_add_u32_e32 v1, v97, v151
	s_waitcnt vmcnt(20)
	ds_write_b32 v1, v200
	v_add_u32_e32 v1, v97, v152
	s_waitcnt vmcnt(19)
	ds_write_b32 v1, v201
	v_add_u32_e32 v1, v97, v153
	s_waitcnt vmcnt(18)
	ds_write_b32 v1, v202
	v_add_u32_e32 v1, v97, v154
	s_waitcnt vmcnt(17)
	ds_write_b32 v1, v203
	v_add_u32_e32 v1, v97, v155
	s_waitcnt vmcnt(16)
	ds_write_b32 v1, v204
	v_add_u32_e32 v1, v97, v156
	s_waitcnt vmcnt(15)
	ds_write_b32 v1, v205
	v_add_u32_e32 v1, v97, v157
	s_waitcnt vmcnt(14)
	ds_write_b32 v1, v206
	v_add_u32_e32 v1, v97, v158
	s_waitcnt vmcnt(13)
	ds_write_b32 v1, v207
	v_add_u32_e32 v1, v97, v159
	s_waitcnt vmcnt(12)
	ds_write_b32 v1, v208
	v_add_u32_e32 v1, v97, v160
	s_waitcnt vmcnt(11)
	ds_write_b32 v1, v209
	v_add_u32_e32 v1, v97, v161
	s_waitcnt vmcnt(10)
	ds_write_b32 v1, v210
	v_add_u32_e32 v1, v97, v162
	s_waitcnt vmcnt(9)
	ds_write_b32 v1, v180
	v_add_u32_e32 v1, v97, v163
	s_waitcnt vmcnt(8)
	ds_write_b32 v1, v178
	v_add_u32_e32 v1, v97, v164
	s_waitcnt vmcnt(7)
	ds_write_b32 v1, v179
	v_add_u32_e32 v1, v97, v165
	s_waitcnt vmcnt(6)
	ds_write_b32 v1, v181
	v_add_u32_e32 v1, v97, v166
	s_waitcnt vmcnt(5)
	ds_write_b32 v1, v172
	v_add_u32_e32 v1, v97, v167
	s_waitcnt vmcnt(4)
	ds_write_b32 v1, v6
	v_add_u32_e32 v1, v97, v168
	s_waitcnt vmcnt(3)
	ds_write_b32 v1, v7
	v_add_u32_e32 v1, v97, v169
	s_waitcnt vmcnt(2)
	ds_write_b32 v1, v173
	v_add_u32_e32 v1, v97, v170
	s_waitcnt vmcnt(1)
	ds_write_b32 v1, v4
	v_add_u32_e32 v1, v97, v171
	s_waitcnt vmcnt(0)
	ds_write_b32 v1, v0
	s_waitcnt lgkmcnt(0)
	s_cbranch_scc1 .LBB0_25
	s_lshl_b32 s25, s10, 2
	s_add_u32 s2, s2, s25
	s_addc_u32 s3, s3, 0
	v_lshlrev_b32_e32 v0, 2, v16
	global_load_dwordx4 v[4:7], v0, s[2:3]
	s_nop 0
	global_load_dwordx4 v[0:3], v0, s[2:3] offset:16
	s_branch .LBB0_26

;     const int nblk = N / 32, kb = item / nblk, nb = item % nblk, k0 = 128 * kb, n0 = 32 * nb;
;     const int nd0 = GLU ? (n0 < 6144 ? 256 * (n0 >> 7) + (n0 & 127) : 256 * ((n0 - 6144) >> 7) + 128 + ((n0 - 6144) & 127)) : n0;
; #pragma unroll 32
;     for (int i = 0; i < 64; ++i) { const int kk = 2 * i + (lane >> 5); scr[kk * 33 + (lane & 31)] = W[(size_t)(k0 + kk) * N + n0 + (lane & 31)]; }
.LBB0_27:
	s_and_b64 vcc, exec, s[2:3]
	s_cbranch_vccz .LBB0_29
	s_load_dwordx2 s[24:25], s[6:7], 0xa0
	s_and_b32 s2, s41, 0x7e0
	s_lshl_b32 s3, s2, 2
	v_lshlrev_b32_e32 v14, 2, v12
	s_waitcnt lgkmcnt(0)
	s_add_u32 s24, s24, s3
	s_addc_u32 s25, s25, 0
	s_and_b32 s3, s43, 0x780
	s_xor_b32 s3, s3, 0x400
	v_add_u32_e32 v4, s3, v10
	v_add_u32_e32 v2, s3, v9
	v_ashrrev_i32_e32 v5, 31, v4
	v_add_u32_e32 v6, s3, v11
	v_add_u32_e32 v172, s3, v38
	v_add_u32_e32 v174, s3, v13
	v_add_u32_e32 v176, s3, v40
	v_add_u32_e32 v178, s3, v17
	v_add_u32_e32 v180, s3, v42
	v_lshl_add_u64 v[0:1], s[24:25], 0, v[14:15]
	v_ashrrev_i32_e32 v3, 31, v2
	v_lshlrev_b64 v[4:5], 13, v[4:5]
	v_ashrrev_i32_e32 v173, 31, v172
	v_ashrrev_i32_e32 v7, 31, v6
	v_ashrrev_i32_e32 v177, 31, v176
	v_ashrrev_i32_e32 v175, 31, v174
	v_ashrrev_i32_e32 v181, 31, v180
	v_ashrrev_i32_e32 v179, 31, v178
	v_lshlrev_b64 v[2:3], 13, v[2:3]
	v_lshl_add_u64 v[4:5], v[0:1], 0, v[4:5]
	v_lshlrev_b64 v[6:7], 13, v[6:7]
	v_lshlrev_b64 v[172:173], 13, v[172:173]
	v_lshlrev_b64 v[174:175], 13, v[174:175]
	v_lshlrev_b64 v[176:177], 13, v[176:177]
	v_lshlrev_b64 v[178:179], 13, v[178:179]
	v_lshlrev_b64 v[180:181], 13, v[180:181]
	v_lshl_add_u64 v[2:3], v[0:1], 0, v[2:3]
	v_lshl_add_u64 v[172:173], v[0:1], 0, v[172:173]
	v_lshl_add_u64 v[6:7], v[0:1], 0, v[6:7]
	v_lshl_add_u64 v[176:177], v[0:1], 0, v[176:177]
	v_lshl_add_u64 v[174:175], v[0:1], 0, v[174:175]
	v_lshl_add_u64 v[180:181], v[0:1], 0, v[180:181]
	v_lshl_add_u64 v[178:179], v[0:1], 0, v[178:179]
	global_load_dword v14, v[4:5], off nt
	global_load_dword v182, v[2:3], off nt
	global_load_dword v183, v[172:173], off nt
	global_load_dword v184, v[6:7], off nt
	global_load_dword v185, v[176:177], off nt
	global_load_dword v186, v[174:175], off nt
	global_load_dword v187, v[180:181], off nt
	global_load_dword v188, v[178:179], off nt
	v_add_u32_e32 v4, s3, v44
	v_add_u32_e32 v6, s3, v41
	v_add_u32_e32 v172, s3, v46
	v_add_u32_e32 v178, s3, v45
	v_add_u32_e32 v180, s3, v50
	v_add_u32_e32 v2, s3, v39
	v_ashrrev_i32_e32 v5, 31, v4
	v_ashrrev_i32_e32 v173, 31, v172
	v_ashrrev_i32_e32 v7, 31, v6
	v_add_u32_e32 v174, s3, v43
	v_add_u32_e32 v176, s3, v48
	v_ashrrev_i32_e32 v181, 31, v180
	v_ashrrev_i32_e32 v179, 31, v178
	v_ashrrev_i32_e32 v3, 31, v2
	v_lshlrev_b64 v[4:5], 13, v[4:5]
	v_lshlrev_b64 v[6:7], 13, v[6:7]
	v_lshlrev_b64 v[172:173], 13, v[172:173]
	v_ashrrev_i32_e32 v177, 31, v176
	v_ashrrev_i32_e32 v175, 31, v174
	v_lshlrev_b64 v[178:179], 13, v[178:179]
	v_lshlrev_b64 v[180:181], 13, v[180:181]
	v_lshlrev_b64 v[2:3], 13, v[2:3]
	v_lshl_add_u64 v[4:5], v[0:1], 0, v[4:5]
	v_lshl_add_u64 v[172:173], v[0:1], 0, v[172:173]
	v_lshl_add_u64 v[6:7], v[0:1], 0, v[6:7]
	v_lshlrev_b64 v[174:175], 13, v[174:175]
	v_lshlrev_b64 v[176:177], 13, v[176:177]
	v_lshl_add_u64 v[180:181], v[0:1], 0, v[180:181]
	v_lshl_add_u64 v[178:179], v[0:1], 0, v[178:179]
	v_lshl_add_u64 v[2:3], v[0:1], 0, v[2:3]
	v_lshl_add_u64 v[176:177], v[0:1], 0, v[176:177]
	v_lshl_add_u64 v[174:175], v[0:1], 0, v[174:175]
	global_load_dword v189, v[4:5], off nt
	global_load_dword v190, v[2:3], off nt
	global_load_dword v191, v[172:173], off nt
	global_load_dword v192, v[6:7], off nt
	global_load_dword v193, v[176:177], off nt
	global_load_dword v194, v[174:175], off nt
	s_nop 0
	global_load_dword v180, v[180:181], off nt
	s_nop 0
	global_load_dword v178, v[178:179], off nt
	v_add_u32_e32 v4, s3, v52
	v_add_u32_e32 v6, s3, v49
	v_add_u32_e32 v172, s3, v54
	v_add_u32_e32 v2, s3, v47
	v_ashrrev_i32_e32 v5, 31, v4
	v_ashrrev_i32_e32 v173, 31, v172
	v_ashrrev_i32_e32 v7, 31, v6
	v_add_u32_e32 v174, s3, v51
	v_add_u32_e32 v176, s3, v56
	v_ashrrev_i32_e32 v3, 31, v2
	v_lshlrev_b64 v[4:5], 13, v[4:5]
	v_lshlrev_b64 v[6:7], 13, v[6:7]
	v_lshlrev_b64 v[172:173], 13, v[172:173]
	v_ashrrev_i32_e32 v177, 31, v176
	v_ashrrev_i32_e32 v175, 31, v174
	v_lshlrev_b64 v[2:3], 13, v[2:3]
	v_lshl_add_u64 v[4:5], v[0:1], 0, v[4:5]
	v_lshl_add_u64 v[172:173], v[0:1], 0, v[172:173]
	v_lshl_add_u64 v[6:7], v[0:1], 0, v[6:7]
	v_lshlrev_b64 v[174:175], 13, v[174:175]
	v_lshlrev_b64 v[176:177], 13, v[176:177]
	v_lshl_add_u64 v[2:3], v[0:1], 0, v[2:3]
	v_lshl_add_u64 v[176:177], v[0:1], 0, v[176:177]
	v_lshl_add_u64 v[174:175], v[0:1], 0, v[174:175]
	global_load_dword v179, v[4:5], off nt
	global_load_dword v181, v[2:3], off nt
	s_nop 0
	global_load_dword v172, v[172:173], off nt
	s_nop 0
	global_load_dword v6, v[6:7], off nt
	s_nop 0
	global_load_dword v7, v[176:177], off nt
	global_load_dword v173, v[174:175], off nt
	v_add_u32_e32 v4, s3, v58
	v_add_u32_e32 v2, s3, v53
	v_ashrrev_i32_e32 v5, 31, v4
	v_ashrrev_i32_e32 v3, 31, v2
	v_lshlrev_b64 v[4:5], 13, v[4:5]
	v_lshlrev_b64 v[2:3], 13, v[2:3]
	v_lshl_add_u64 v[4:5], v[0:1], 0, v[4:5]
	global_load_dword v4, v[4:5], off nt
	v_lshl_add_u64 v[2:3], v[0:1], 0, v[2:3]
	global_load_dword v2, v[2:3], off nt
	v_add_u32_e32 v3, v97, v108
	v_add_u32_e32 v174, s3, v59
	v_add_u32_e32 v176, s3, v64
	v_ashrrev_i32_e32 v177, 31, v176
	s_waitcnt vmcnt(23)
	ds_write_b32 v3, v14
	v_add_u32_e32 v3, v97, v109
	s_waitcnt vmcnt(22)
	ds_write_b32 v3, v182
	v_add_u32_e32 v3, v97, v110
	s_waitcnt vmcnt(21)
	ds_write_b32 v3, v183
	v_add_u32_e32 v3, v97, v111
	s_waitcnt vmcnt(20)
	ds_write_b32 v3, v184
	v_add_u32_e32 v3, v97, v112
	s_waitcnt vmcnt(19)
	ds_write_b32 v3, v185
	v_add_u32_e32 v3, v97, v113
	s_waitcnt vmcnt(18)
	ds_write_b32 v3, v186
	v_add_u32_e32 v3, v97, v114
	s_waitcnt vmcnt(17)
	ds_write_b32 v3, v187
	v_add_u32_e32 v3, v97, v115
	s_waitcnt vmcnt(16)
;     ...
; #pragma unroll 32
;     for (int i = 0; i < 64; ++i) { const int kk = 2 * i + (lane >> 5); scr[kk * 33 + (lane & 31)] = W[(size_t)(k0 + kk) * N + n0 + (lane & 31)]; }
	ds_write_b32 v3, v188
	v_add_u32_e32 v3, v97, v116
	v_ashrrev_i32_e32 v175, 31, v174
	v_lshlrev_b64 v[174:175], 13, v[174:175]
	v_lshlrev_b64 v[176:177], 13, v[176:177]
	v_lshl_add_u64 v[176:177], v[0:1], 0, v[176:177]
	v_lshl_add_u64 v[174:175], v[0:1], 0, v[174:175]
	s_lshl_b32 s10, s3, 1
	s_waitcnt vmcnt(15)
	ds_write_b32 v3, v189
	v_add_u32_e32 v3, v97, v117
	s_waitcnt vmcnt(14)
	ds_write_b32 v3, v190
	v_add_u32_e32 v3, v97, v118
	s_waitcnt vmcnt(13)
	ds_write_b32 v3, v191
	v_add_u32_e32 v3, v97, v119
	s_waitcnt vmcnt(12)
	ds_write_b32 v3, v192
	v_add_u32_e32 v3, v97, v120
	s_waitcnt vmcnt(11)
	ds_write_b32 v3, v193
	v_add_u32_e32 v3, v97, v121
	s_waitcnt vmcnt(10)
	ds_write_b32 v3, v194
	v_add_u32_e32 v3, v97, v122
	s_waitcnt vmcnt(9)
	ds_write_b32 v3, v180
	v_add_u32_e32 v3, v97, v123
	s_waitcnt vmcnt(8)
	ds_write_b32 v3, v178
	v_add_u32_e32 v3, v97, v124
	v_add_u32_e32 v178, s3, v61
	v_add_u32_e32 v180, s3, v66
	s_waitcnt vmcnt(7)
	ds_write_b32 v3, v179
	v_add_u32_e32 v3, v97, v125
	s_waitcnt vmcnt(6)
	ds_write_b32 v3, v181
	v_add_u32_e32 v3, v97, v126
	s_waitcnt vmcnt(5)
	ds_write_b32 v3, v172
	v_add_u32_e32 v3, v97, v127
	s_waitcnt vmcnt(4)
	ds_write_b32 v3, v6
	v_add_u32_e32 v3, v97, v128
	s_waitcnt vmcnt(3)
	ds_write_b32 v3, v7
	v_add_u32_e32 v3, v97, v129
	s_waitcnt vmcnt(2)
	ds_write_b32 v3, v173
	v_add_u32_e32 v3, v97, v130
	v_add_u32_e32 v6, s3, v57
	s_waitcnt vmcnt(1)
	ds_write_b32 v3, v4
	v_add_u32_e32 v3, v97, v131
	v_add_u32_e32 v4, s3, v60
	s_waitcnt vmcnt(0)
	ds_write_b32 v3, v2
	v_add_u32_e32 v2, s3, v55
	v_ashrrev_i32_e32 v5, 31, v4
	v_add_u32_e32 v172, s3, v62
	v_ashrrev_i32_e32 v3, 31, v2
	v_lshlrev_b64 v[4:5], 13, v[4:5]
	v_ashrrev_i32_e32 v173, 31, v172
	v_ashrrev_i32_e32 v7, 31, v6
	v_ashrrev_i32_e32 v181, 31, v180
	v_ashrrev_i32_e32 v179, 31, v178
	v_lshlrev_b64 v[2:3], 13, v[2:3]
	v_lshl_add_u64 v[4:5], v[0:1], 0, v[4:5]
	v_lshlrev_b64 v[6:7], 13, v[6:7]
	v_lshlrev_b64 v[172:173], 13, v[172:173]
	v_lshlrev_b64 v[178:179], 13, v[178:179]
	v_lshlrev_b64 v[180:181], 13, v[180:181]
	v_lshl_add_u64 v[2:3], v[0:1], 0, v[2:3]
	v_lshl_add_u64 v[172:173], v[0:1], 0, v[172:173]
	v_lshl_add_u64 v[6:7], v[0:1], 0, v[6:7]
	v_lshl_add_u64 v[180:181], v[0:1], 0, v[180:181]
	v_lshl_add_u64 v[178:179], v[0:1], 0, v[178:179]
	global_load_dword v14, v[4:5], off nt
	global_load_dword v182, v[2:3], off nt
	global_load_dword v183, v[172:173], off nt
	global_load_dword v184, v[6:7], off nt
	global_load_dword v185, v[176:177], off nt
	global_load_dword v186, v[174:175], off nt
	global_load_dword v187, v[180:181], off nt
	global_load_dword v188, v[178:179], off nt
	v_add_u32_e32 v4, s3, v68
	v_add_u32_e32 v2, s3, v63
	v_ashrrev_i32_e32 v5, 31, v4
	v_add_u32_e32 v6, s3, v65
	v_add_u32_e32 v172, s3, v70
	v_add_u32_e32 v174, s3, v67
	v_add_u32_e32 v176, s3, v72
	v_add_u32_e32 v178, s3, v69
	v_add_u32_e32 v180, s3, v74
	v_ashrrev_i32_e32 v3, 31, v2
	v_lshlrev_b64 v[4:5], 13, v[4:5]
	v_ashrrev_i32_e32 v173, 31, v172
	v_ashrrev_i32_e32 v7, 31, v6
	v_ashrrev_i32_e32 v177, 31, v176
	v_ashrrev_i32_e32 v175, 31, v174
	v_ashrrev_i32_e32 v181, 31, v180
	v_ashrrev_i32_e32 v179, 31, v178
	v_lshlrev_b64 v[2:3], 13, v[2:3]
	v_lshl_add_u64 v[4:5], v[0:1], 0, v[4:5]
	v_lshlrev_b64 v[6:7], 13, v[6:7]
	v_lshlrev_b64 v[172:173], 13, v[172:173]
	v_lshlrev_b64 v[174:175], 13, v[174:175]
	v_lshlrev_b64 v[176:177], 13, v[176:177]
	v_lshlrev_b64 v[178:179], 13, v[178:179]
	v_lshlrev_b64 v[180:181], 13, v[180:181]
	v_lshl_add_u64 v[2:3], v[0:1], 0, v[2:3]
	v_lshl_add_u64 v[172:173], v[0:1], 0, v[172:173]
	v_lshl_add_u64 v[6:7], v[0:1], 0, v[6:7]
	v_lshl_add_u64 v[176:177], v[0:1], 0, v[176:177]
	v_lshl_add_u64 v[174:175], v[0:1], 0, v[174:175]
	v_lshl_add_u64 v[180:181], v[0:1], 0, v[180:181]
	v_lshl_add_u64 v[178:179], v[0:1], 0, v[178:179]
	global_load_dword v189, v[4:5], off nt
	global_load_dword v190, v[2:3], off nt
	global_load_dword v191, v[172:173], off nt
	global_load_dword v192, v[6:7], off nt
	global_load_dword v193, v[176:177], off nt
	global_load_dword v194, v[174:175], off nt
	global_load_dword v195, v[180:181], off nt
	global_load_dword v196, v[178:179], off nt
	v_add_u32_e32 v4, s3, v76
	v_add_u32_e32 v174, s3, v75
	v_add_u32_e32 v176, s3, v80
	v_add_u32_e32 v2, s3, v71
	v_ashrrev_i32_e32 v5, 31, v4
	v_add_u32_e32 v6, s3, v73
	v_add_u32_e32 v172, s3, v78
	v_ashrrev_i32_e32 v177, 31, v176
	v_ashrrev_i32_e32 v175, 31, v174
	v_add_u32_e32 v178, s3, v77
	v_add_u32_e32 v180, s3, v82
	v_ashrrev_i32_e32 v3, 31, v2
	v_lshlrev_b64 v[4:5], 13, v[4:5]
	v_ashrrev_i32_e32 v173, 31, v172
	v_ashrrev_i32_e32 v7, 31, v6
	v_lshlrev_b64 v[174:175], 13, v[174:175]
	v_lshlrev_b64 v[176:177], 13, v[176:177]
	v_ashrrev_i32_e32 v181, 31, v180
	v_ashrrev_i32_e32 v179, 31, v178
	v_lshlrev_b64 v[2:3], 13, v[2:3]
	v_lshl_add_u64 v[4:5], v[0:1], 0, v[4:5]
	v_lshlrev_b64 v[6:7], 13, v[6:7]
	v_lshlrev_b64 v[172:173], 13, v[172:173]
	v_lshl_add_u64 v[176:177], v[0:1], 0, v[176:177]
	v_lshl_add_u64 v[174:175], v[0:1], 0, v[174:175]
	v_lshlrev_b64 v[178:179], 13, v[178:179]
	v_lshlrev_b64 v[180:181], 13, v[180:181]
	v_lshl_add_u64 v[2:3], v[0:1], 0, v[2:3]
	v_lshl_add_u64 v[172:173], v[0:1], 0, v[172:173]
	v_lshl_add_u64 v[6:7], v[0:1], 0, v[6:7]
	v_lshl_add_u64 v[180:181], v[0:1], 0, v[180:181]
	v_lshl_add_u64 v[178:179], v[0:1], 0, v[178:179]
	global_load_dword v197, v[4:5], off nt
	global_load_dword v198, v[2:3], off nt
	global_load_dword v199, v[172:173], off nt
	global_load_dword v200, v[6:7], off nt
	global_load_dword v201, v[176:177], off nt
	global_load_dword v202, v[174:175], off nt
	global_load_dword v203, v[180:181], off nt
	global_load_dword v204, v[178:179], off nt
;     ...
; #pragma unroll 32
;     for (int i = 0; i < 64; ++i) { const int kk = 2 * i + (lane >> 5); scr[kk * 33 + (lane & 31)] = W[(size_t)(k0 + kk) * N + n0 + (lane & 31)]; }
	v_add_u32_e32 v4, s3, v84
	v_add_u32_e32 v174, s3, v83
	v_add_u32_e32 v176, s3, v88
	v_add_u32_e32 v2, s3, v79
	v_ashrrev_i32_e32 v5, 31, v4
	v_add_u32_e32 v6, s3, v81
	v_add_u32_e32 v172, s3, v86
	v_ashrrev_i32_e32 v177, 31, v176
	v_ashrrev_i32_e32 v175, 31, v174
	v_add_u32_e32 v178, s3, v85
	v_add_u32_e32 v180, s3, v90
	v_ashrrev_i32_e32 v3, 31, v2
	v_lshlrev_b64 v[4:5], 13, v[4:5]
	v_ashrrev_i32_e32 v173, 31, v172
	v_ashrrev_i32_e32 v7, 31, v6
	v_lshlrev_b64 v[174:175], 13, v[174:175]
	v_lshlrev_b64 v[176:177], 13, v[176:177]
	v_ashrrev_i32_e32 v181, 31, v180
	v_ashrrev_i32_e32 v179, 31, v178
	v_lshlrev_b64 v[2:3], 13, v[2:3]
	v_lshl_add_u64 v[4:5], v[0:1], 0, v[4:5]
	v_lshlrev_b64 v[6:7], 13, v[6:7]
	v_lshlrev_b64 v[172:173], 13, v[172:173]
	v_lshl_add_u64 v[176:177], v[0:1], 0, v[176:177]
	v_lshl_add_u64 v[174:175], v[0:1], 0, v[174:175]
	v_lshlrev_b64 v[178:179], 13, v[178:179]
	v_lshlrev_b64 v[180:181], 13, v[180:181]
	v_lshl_add_u64 v[2:3], v[0:1], 0, v[2:3]
	v_lshl_add_u64 v[172:173], v[0:1], 0, v[172:173]
	v_lshl_add_u64 v[6:7], v[0:1], 0, v[6:7]
	v_lshl_add_u64 v[180:181], v[0:1], 0, v[180:181]
	v_lshl_add_u64 v[178:179], v[0:1], 0, v[178:179]
	global_load_dword v205, v[4:5], off nt
	global_load_dword v206, v[2:3], off nt
	global_load_dword v207, v[172:173], off nt
	global_load_dword v208, v[6:7], off nt
	s_nop 0
	global_load_dword v176, v[176:177], off nt
	s_nop 0
	global_load_dword v174, v[174:175], off nt
	s_nop 0
	global_load_dword v175, v[180:181], off nt
	global_load_dword v177, v[178:179], off nt
	v_add_u32_e32 v4, s3, v92
	v_add_u32_e32 v2, s3, v87
	v_ashrrev_i32_e32 v5, 31, v4
	v_ashrrev_i32_e32 v3, 31, v2
	v_lshlrev_b64 v[4:5], 13, v[4:5]
	v_lshlrev_b64 v[2:3], 13, v[2:3]
	v_lshl_add_u64 v[4:5], v[0:1], 0, v[4:5]
	v_lshl_add_u64 v[2:3], v[0:1], 0, v[2:3]
	global_load_dword v178, v[4:5], off nt
	global_load_dword v179, v[2:3], off nt
	v_add_u32_e32 v4, s3, v94
	v_add_u32_e32 v6, s3, v91
	v_add_u32_e32 v172, s3, v96
	v_add_u32_e32 v2, s3, v89
	v_ashrrev_i32_e32 v5, 31, v4
	v_ashrrev_i32_e32 v173, 31, v172
	v_ashrrev_i32_e32 v7, 31, v6
	v_ashrrev_i32_e32 v3, 31, v2
	v_lshlrev_b64 v[4:5], 13, v[4:5]
	v_lshlrev_b64 v[6:7], 13, v[6:7]
	v_lshlrev_b64 v[172:173], 13, v[172:173]
	v_lshlrev_b64 v[2:3], 13, v[2:3]
	v_lshl_add_u64 v[4:5], v[0:1], 0, v[4:5]
	v_lshl_add_u64 v[172:173], v[0:1], 0, v[172:173]
	v_lshl_add_u64 v[6:7], v[0:1], 0, v[6:7]
	v_lshl_add_u64 v[2:3], v[0:1], 0, v[2:3]
	global_load_dword v180, v[4:5], off nt
	global_load_dword v181, v[2:3], off nt
	s_nop 0
	global_load_dword v172, v[172:173], off nt
	s_nop 0
	global_load_dword v6, v[6:7], off nt
	v_add_u32_e32 v4, s3, v98
	v_add_u32_e32 v2, s3, v93
	v_ashrrev_i32_e32 v5, 31, v4
	v_ashrrev_i32_e32 v3, 31, v2
	v_lshlrev_b64 v[4:5], 13, v[4:5]
	v_lshlrev_b64 v[2:3], 13, v[2:3]
	v_lshl_add_u64 v[4:5], v[0:1], 0, v[4:5]
	global_load_dword v4, v[4:5], off nt
	v_lshl_add_u64 v[0:1], v[0:1], 0, v[2:3]
	global_load_dword v0, v[0:1], off nt
	v_add_u32_e32 v1, v97, v132
	s_waitcnt vmcnt(39)
	ds_write_b32 v1, v14
	v_add_u32_e32 v1, v97, v133
	s_waitcnt vmcnt(38)
	ds_write_b32 v1, v182
	v_add_u32_e32 v1, v97, v134
	s_waitcnt vmcnt(37)
	ds_write_b32 v1, v183
	v_add_u32_e32 v1, v97, v135
	s_waitcnt vmcnt(36)
	ds_write_b32 v1, v184
	v_add_u32_e32 v1, v97, v136
	s_waitcnt vmcnt(35)
	ds_write_b32 v1, v185
	v_add_u32_e32 v1, v97, v137
	s_waitcnt vmcnt(34)
	ds_write_b32 v1, v186
	v_add_u32_e32 v1, v97, v138
	s_waitcnt vmcnt(33)
	ds_write_b32 v1, v187
	v_add_u32_e32 v1, v97, v139
	s_waitcnt vmcnt(32)
	ds_write_b32 v1, v188
	v_add_u32_e32 v1, v97, v140
	s_waitcnt vmcnt(31)
	ds_write_b32 v1, v189
	v_add_u32_e32 v1, v97, v141
	s_waitcnt vmcnt(30)
	ds_write_b32 v1, v190
	v_add_u32_e32 v1, v97, v142
	s_waitcnt vmcnt(29)
	ds_write_b32 v1, v191
	v_add_u32_e32 v1, v97, v143
	s_waitcnt vmcnt(28)
	ds_write_b32 v1, v192
	v_add_u32_e32 v1, v97, v144
	s_waitcnt vmcnt(27)
	ds_write_b32 v1, v193
	v_add_u32_e32 v1, v97, v145
	s_waitcnt vmcnt(26)
	ds_write_b32 v1, v194
	v_add_u32_e32 v1, v97, v146
	s_waitcnt vmcnt(25)
	ds_write_b32 v1, v195
	v_add_u32_e32 v1, v97, v147
	s_waitcnt vmcnt(24)
	ds_write_b32 v1, v196
	v_add_u32_e32 v1, v97, v148
	s_waitcnt vmcnt(23)
	ds_write_b32 v1, v197
	v_add_u32_e32 v1, v97, v149
	s_waitcnt vmcnt(22)
	ds_write_b32 v1, v198
	v_add_u32_e32 v1, v97, v150
	s_waitcnt vmcnt(21)
	ds_write_b32 v1, v199
	v_add_u32_e32 v1, v97, v151
	s_waitcnt vmcnt(20)
	ds_write_b32 v1, v200
	v_add_u32_e32 v1, v97, v152
	s_waitcnt vmcnt(19)
	ds_write_b32 v1, v201
	v_add_u32_e32 v1, v97, v153
	s_waitcnt vmcnt(18)
	ds_write_b32 v1, v202
	v_add_u32_e32 v1, v97, v154
	s_waitcnt vmcnt(17)
	ds_write_b32 v1, v203
	v_add_u32_e32 v1, v97, v155
	s_waitcnt vmcnt(16)
	ds_write_b32 v1, v204
	v_add_u32_e32 v1, v97, v156
	s_waitcnt vmcnt(15)
	ds_write_b32 v1, v205
	v_add_u32_e32 v1, v97, v157
	s_waitcnt vmcnt(14)
	ds_write_b32 v1, v206
	v_add_u32_e32 v1, v97, v158
	s_waitcnt vmcnt(13)
	ds_write_b32 v1, v207
	v_add_u32_e32 v1, v97, v159
	s_waitcnt vmcnt(12)
	ds_write_b32 v1, v208
	v_add_u32_e32 v1, v97, v160
	s_waitcnt vmcnt(11)
	ds_write_b32 v1, v176
	v_add_u32_e32 v1, v97, v161
	s_waitcnt vmcnt(10)
	ds_write_b32 v1, v174
	v_add_u32_e32 v1, v97, v162
	s_waitcnt vmcnt(9)
	ds_write_b32 v1, v175
	v_add_u32_e32 v1, v97, v163
	s_waitcnt vmcnt(8)
	ds_write_b32 v1, v177
	v_add_u32_e32 v1, v97, v164
	s_waitcnt vmcnt(7)
	ds_write_b32 v1, v178
	v_add_u32_e32 v1, v97, v165
	s_waitcnt vmcnt(6)
; __device__ __forceinline__ unsigned cvt_pk_bf16(float lo, float hi) { unsigned r; asm volatile("v_cvt_pk_bf16_f32 %0, %1, %2" : "=v"(r) : "v"(lo), "v"(hi)); return r; }
; #define GAS __attribute__((address_space(1)))
; #define LAS __attribute__((address_space(3)))
; #define LDS_WAIT() asm volatile("s_waitcnt lgkmcnt(0)" ::: "memory")
;     ...
;     for (int i = 0; i < 64; ++i) { const int kk = 2 * i + (lane >> 5); scr[kk * 33 + (lane & 31)] = W[(size_t)(k0 + kk) * N + n0 + (lane & 31)]; }
;     LDS_WAIT(); asm volatile("" ::: "memory");
;     const int c = lane & 15;
;     float gk[8];
;     if (gain) load8f(gain + k0 + 8 * c, gk); else {
; #pragma unroll
;         for (int e = 0; e < 8; ++e) gk[e] = 1.0f; }
; #pragma unroll
;     for (int j = 0; j < 8; ++j) { const int n = (lane >> 4) + 4 * j; const LAS float* s = scr + (8 * c) * 33 + n;
;         v4u o; o.x = cvt_pk_bf16(s[0 * 33] * gk[0], s[1 * 33] * gk[1]); o.y = cvt_pk_bf16(s[2 * 33] * gk[2], s[3 * 33] * gk[3]); o.z = cvt_pk_bf16(s[4 * 33] * gk[4], s[5 * 33] * gk[5]); o.w = cvt_pk_bf16(s[6 * 33] * gk[6], s[7 * 33] * gk[7]);
;         *(GAS v4u*)(WT + (size_t)(nd0 + n) * K + k0 + 8 * c) = o; }
;     LDS_WAIT(); asm volatile("" ::: "memory");
	ds_write_b32 v1, v179
	v_add_u32_e32 v1, v97, v166
	s_waitcnt vmcnt(5)
	ds_write_b32 v1, v180
	v_add_u32_e32 v1, v97, v167
	s_waitcnt vmcnt(4)
	ds_write_b32 v1, v181
	v_add_u32_e32 v1, v97, v168
	s_waitcnt vmcnt(3)
	ds_write_b32 v1, v172
	v_add_u32_e32 v1, v97, v169
	s_waitcnt vmcnt(2)
	ds_write_b32 v1, v6
	v_add_u32_e32 v1, v97, v170
	s_waitcnt vmcnt(1)
	ds_write_b32 v1, v4
	v_add_u32_e32 v1, v97, v171
	s_waitcnt vmcnt(0)
	ds_write_b32 v1, v0
	s_waitcnt lgkmcnt(0)
	ds_read2_b32 v[0:1], v100 offset1:33
	s_waitcnt lgkmcnt(0)
	v_cvt_pk_bf16_f32 v0, v0, v1
	ds_read2_b32 v[2:3], v100 offset0:66 offset1:99
	s_waitcnt lgkmcnt(0)
	v_cvt_pk_bf16_f32 v1, v2, v3
	ds_read2_b32 v[2:3], v100 offset0:132 offset1:165
	s_waitcnt lgkmcnt(0)
	v_cvt_pk_bf16_f32 v2, v2, v3
	ds_read2_b32 v[4:5], v100 offset0:198 offset1:231
	s_waitcnt lgkmcnt(0)
	v_cvt_pk_bf16_f32 v3, v4, v5
	v_add_u32_e32 v4, s2, v99
	v_ashrrev_i32_e32 v5, 31, v4
	v_lshl_add_u64 v[6:7], v[18:19], 0, s[10:11]
	v_lshlrev_b64 v[4:5], 12, v[4:5]
	v_lshl_add_u64 v[4:5], v[6:7], 0, v[4:5]
	ds_read2_b32 v[172:173], v100 offset0:4 offset1:37
	global_store_dwordx4 v[4:5], v[0:3], off
	s_waitcnt lgkmcnt(0)
	s_nop 0
	v_cvt_pk_bf16_f32 v0, v172, v173
	ds_read2_b32 v[2:3], v100 offset0:70 offset1:103
	s_waitcnt lgkmcnt(0)
	v_cvt_pk_bf16_f32 v1, v2, v3
	ds_read2_b32 v[2:3], v100 offset0:136 offset1:169
	s_waitcnt lgkmcnt(0)
	v_cvt_pk_bf16_f32 v2, v2, v3
	ds_read2_b32 v[4:5], v100 offset0:202 offset1:235
	s_waitcnt lgkmcnt(0)
	v_cvt_pk_bf16_f32 v3, v4, v5
	v_add_u32_e32 v4, s2, v101
	v_ashrrev_i32_e32 v5, 31, v4
	v_lshlrev_b64 v[4:5], 12, v[4:5]
	v_lshl_add_u64 v[4:5], v[6:7], 0, v[4:5]
	ds_read2_b32 v[172:173], v100 offset0:8 offset1:41
	global_store_dwordx4 v[4:5], v[0:3], off
	s_waitcnt lgkmcnt(0)
	s_nop 0
	v_cvt_pk_bf16_f32 v0, v172, v173
	ds_read2_b32 v[2:3], v100 offset0:74 offset1:107
	s_waitcnt lgkmcnt(0)
	v_cvt_pk_bf16_f32 v1, v2, v3
	ds_read2_b32 v[2:3], v100 offset0:140 offset1:173
	s_waitcnt lgkmcnt(0)
	v_cvt_pk_bf16_f32 v2, v2, v3
	ds_read2_b32 v[4:5], v100 offset0:206 offset1:239
	s_waitcnt lgkmcnt(0)
	v_cvt_pk_bf16_f32 v3, v4, v5
	v_add_u32_e32 v4, s2, v102
	v_ashrrev_i32_e32 v5, 31, v4
	v_lshlrev_b64 v[4:5], 12, v[4:5]
	v_lshl_add_u64 v[4:5], v[6:7], 0, v[4:5]
	ds_read2_b32 v[172:173], v100 offset0:12 offset1:45
	global_store_dwordx4 v[4:5], v[0:3], off
	s_waitcnt lgkmcnt(0)
	s_nop 0
	v_cvt_pk_bf16_f32 v0, v172, v173
	ds_read2_b32 v[2:3], v100 offset0:78 offset1:111
	s_waitcnt lgkmcnt(0)
	v_cvt_pk_bf16_f32 v1, v2, v3
	ds_read2_b32 v[2:3], v100 offset0:144 offset1:177
	s_waitcnt lgkmcnt(0)
	v_cvt_pk_bf16_f32 v2, v2, v3
	ds_read2_b32 v[4:5], v100 offset0:210 offset1:243
	s_waitcnt lgkmcnt(0)
	v_cvt_pk_bf16_f32 v3, v4, v5
	v_add_u32_e32 v4, s2, v103
	v_ashrrev_i32_e32 v5, 31, v4
	v_lshlrev_b64 v[4:5], 12, v[4:5]
	v_lshl_add_u64 v[4:5], v[6:7], 0, v[4:5]
	ds_read2_b32 v[172:173], v100 offset0:16 offset1:49
	global_store_dwordx4 v[4:5], v[0:3], off
	s_waitcnt lgkmcnt(0)
	s_nop 0
	v_cvt_pk_bf16_f32 v0, v172, v173
	ds_read2_b32 v[2:3], v100 offset0:82 offset1:115
	s_waitcnt lgkmcnt(0)
	v_cvt_pk_bf16_f32 v1, v2, v3
	ds_read2_b32 v[2:3], v100 offset0:148 offset1:181
	s_waitcnt lgkmcnt(0)
	v_cvt_pk_bf16_f32 v2, v2, v3
	ds_read2_b32 v[4:5], v100 offset0:214 offset1:247
	s_waitcnt lgkmcnt(0)
	v_cvt_pk_bf16_f32 v3, v4, v5
	v_add_u32_e32 v4, s2, v104
	v_ashrrev_i32_e32 v5, 31, v4
	v_lshlrev_b64 v[4:5], 12, v[4:5]
	v_lshl_add_u64 v[4:5], v[6:7], 0, v[4:5]
	ds_read2_b32 v[172:173], v100 offset0:20 offset1:53
	global_store_dwordx4 v[4:5], v[0:3], off
	s_waitcnt lgkmcnt(0)
	s_nop 0
	v_cvt_pk_bf16_f32 v0, v172, v173
	ds_read2_b32 v[2:3], v100 offset0:86 offset1:119
	s_waitcnt lgkmcnt(0)
	v_cvt_pk_bf16_f32 v1, v2, v3
	ds_read2_b32 v[2:3], v100 offset0:152 offset1:185
	s_waitcnt lgkmcnt(0)
	v_cvt_pk_bf16_f32 v2, v2, v3
	ds_read2_b32 v[4:5], v100 offset0:218 offset1:251
	s_waitcnt lgkmcnt(0)
	v_cvt_pk_bf16_f32 v3, v4, v5
	v_add_u32_e32 v4, s2, v105
	v_ashrrev_i32_e32 v5, 31, v4
	v_lshlrev_b64 v[4:5], 12, v[4:5]
	v_lshl_add_u64 v[4:5], v[6:7], 0, v[4:5]
	ds_read2_b32 v[172:173], v100 offset0:24 offset1:57
	global_store_dwordx4 v[4:5], v[0:3], off
	s_waitcnt lgkmcnt(0)
	s_nop 0
	v_cvt_pk_bf16_f32 v0, v172, v173
	ds_read2_b32 v[2:3], v100 offset0:90 offset1:123
	s_waitcnt lgkmcnt(0)
	v_cvt_pk_bf16_f32 v1, v2, v3
	ds_read2_b32 v[2:3], v100 offset0:156 offset1:189
	s_waitcnt lgkmcnt(0)
	v_cvt_pk_bf16_f32 v2, v2, v3
	ds_read2_b32 v[4:5], v100 offset0:222 offset1:255
	s_waitcnt lgkmcnt(0)
	v_cvt_pk_bf16_f32 v3, v4, v5
	v_add_u32_e32 v4, s2, v106
	v_ashrrev_i32_e32 v5, 31, v4
	v_lshlrev_b64 v[4:5], 12, v[4:5]
	v_lshl_add_u64 v[4:5], v[6:7], 0, v[4:5]
	ds_read2_b32 v[172:173], v100 offset0:28 offset1:61
	global_store_dwordx4 v[4:5], v[0:3], off
	s_waitcnt lgkmcnt(0)
	s_nop 0
	v_cvt_pk_bf16_f32 v0, v172, v173
	ds_read2_b32 v[2:3], v100 offset0:94 offset1:127
	s_waitcnt lgkmcnt(0)
	v_cvt_pk_bf16_f32 v1, v2, v3
	ds_read2_b32 v[2:3], v100 offset0:160 offset1:193
	s_waitcnt lgkmcnt(0)
	v_cvt_pk_bf16_f32 v2, v2, v3
	v_add_u32_e32 v3, 0x200, v100
	ds_read2_b32 v[4:5], v3 offset0:98 offset1:131
	s_waitcnt lgkmcnt(0)
	v_cvt_pk_bf16_f32 v3, v4, v5
	v_add_u32_e32 v4, s2, v107
	v_ashrrev_i32_e32 v5, 31, v4
	v_lshlrev_b64 v[4:5], 12, v[4:5]
	v_lshl_add_u64 v[4:5], v[6:7], 0, v[4:5]
	global_store_dwordx4 v[4:5], v[0:3], off
	s_waitcnt lgkmcnt(0)

;     const int nblk = N / 32, kb = item / nblk, nb = item % nblk, k0 = 128 * kb, n0 = 32 * nb;
;     const int nd0 = GLU ? (n0 < 6144 ? 256 * (n0 >> 7) + (n0 & 127) : 256 * ((n0 - 6144) >> 7) + 128 + ((n0 - 6144) & 127)) : n0;
; #pragma unroll 32
;     for (int i = 0; i < 64; ++i) { const int kk = 2 * i + (lane >> 5); scr[kk * 33 + (lane & 31)] = W[(size_t)(k0 + kk) * N + n0 + (lane & 31)]; }
; __device__ __forceinline__ void p0_prologue(const Frame& F, CArgs* A, unsigned char* ws) {
;     ...
;         if (r < 32 * IP_G) { const int gate = r / (16 * IP_G); const int rr = r % (16 * IP_G); const int mat = rr / IP_G;
;           p0_transpose_item(A->in[gate ? I_LWI : I_LWA] + (size_t)mat * 65536, 256, 256, GT + (size_t)(mat >> 3) * (4096 * 256) + (size_t)gate * (2048 * 256) + (size_t)(mat & 7) * 65536, scr, rr % IP_G, F.lane); continue; } r -= 32 * IP_G;
.LBB0_30:
	s_andn2_b64 vcc, exec, s[2:3]
	s_cbranch_vccnz .LBB0_32
	s_add_i32 s3, s56, 0xffff3c00
	s_cmpk_lt_u32 s3, 0x100
	s_cselect_b32 s2, 0x78, s49
	s_add_u32 s24, s6, s2
	s_addc_u32 s25, s7, 0
	s_load_dwordx2 s[24:25], s[24:25], 0x0
	s_and_b32 s2, s45, 0xf0000
	s_lshl_b32 s2, s2, 2
	v_lshlrev_b32_e32 v14, 2, v12
	s_waitcnt lgkmcnt(0)
	s_add_u32 s10, s24, s2
	s_addc_u32 s25, s25, 0
	s_and_b32 s38, s56, 15
	s_add_i32 s2, s38, 0xfff8
	s_and_b32 s2, s2, 0xffff
	s_min_u32 s24, s38, s2
	s_lshl_b32 s2, s24, 5
	s_lshl_b32 s24, s24, 7
	s_add_u32 s24, s10, s24
	s_addc_u32 s25, s25, 0
	s_cmp_gt_u32 s38, 7
	v_lshl_add_u64 v[0:1], s[24:25], 0, v[14:15]
	s_cselect_b32 s24, 0x80, 0
	v_add_u32_e32 v4, s24, v10
	v_add_u32_e32 v2, s24, v9
	v_ashrrev_i32_e32 v5, 31, v4
	v_add_u32_e32 v6, s24, v11
	v_add_u32_e32 v172, s24, v38
	v_add_u32_e32 v174, s24, v13
	v_add_u32_e32 v176, s24, v40
	v_add_u32_e32 v178, s24, v17
	v_add_u32_e32 v180, s24, v42
	v_ashrrev_i32_e32 v3, 31, v2
	v_lshlrev_b64 v[4:5], 10, v[4:5]
	v_ashrrev_i32_e32 v173, 31, v172
	v_ashrrev_i32_e32 v7, 31, v6
	v_ashrrev_i32_e32 v177, 31, v176
	v_ashrrev_i32_e32 v175, 31, v174
	v_ashrrev_i32_e32 v181, 31, v180
	v_ashrrev_i32_e32 v179, 31, v178
	v_lshlrev_b64 v[2:3], 10, v[2:3]
	v_lshl_add_u64 v[4:5], v[0:1], 0, v[4:5]
	v_lshlrev_b64 v[6:7], 10, v[6:7]
	v_lshlrev_b64 v[172:173], 10, v[172:173]
	v_lshlrev_b64 v[174:175], 10, v[174:175]
	v_lshlrev_b64 v[176:177], 10, v[176:177]
	v_lshlrev_b64 v[178:179], 10, v[178:179]
	v_lshlrev_b64 v[180:181], 10, v[180:181]
	v_lshl_add_u64 v[2:3], v[0:1], 0, v[2:3]
	v_lshl_add_u64 v[172:173], v[0:1], 0, v[172:173]
	v_lshl_add_u64 v[6:7], v[0:1], 0, v[6:7]
	v_lshl_add_u64 v[176:177], v[0:1], 0, v[176:177]
	v_lshl_add_u64 v[174:175], v[0:1], 0, v[174:175]
	v_lshl_add_u64 v[180:181], v[0:1], 0, v[180:181]
	v_lshl_add_u64 v[178:179], v[0:1], 0, v[178:179]
	global_load_dword v14, v[4:5], off nt
	global_load_dword v182, v[2:3], off nt
	global_load_dword v183, v[172:173], off nt
	global_load_dword v184, v[6:7], off nt
	global_load_dword v185, v[176:177], off nt
	global_load_dword v186, v[174:175], off nt
	global_load_dword v187, v[180:181], off nt
	global_load_dword v188, v[178:179], off nt
	v_add_u32_e32 v4, s24, v44
	v_add_u32_e32 v6, s24, v41
	v_add_u32_e32 v172, s24, v46
	v_add_u32_e32 v178, s24, v45
	v_add_u32_e32 v180, s24, v50
	v_add_u32_e32 v2, s24, v39
	v_ashrrev_i32_e32 v5, 31, v4
	v_ashrrev_i32_e32 v173, 31, v172
	v_ashrrev_i32_e32 v7, 31, v6
	v_add_u32_e32 v174, s24, v43
	v_add_u32_e32 v176, s24, v48
	v_ashrrev_i32_e32 v181, 31, v180
	v_ashrrev_i32_e32 v179, 31, v178
	v_ashrrev_i32_e32 v3, 31, v2
	v_lshlrev_b64 v[4:5], 10, v[4:5]
	v_lshlrev_b64 v[6:7], 10, v[6:7]
	v_lshlrev_b64 v[172:173], 10, v[172:173]
	v_ashrrev_i32_e32 v177, 31, v176
	v_ashrrev_i32_e32 v175, 31, v174
	v_lshlrev_b64 v[178:179], 10, v[178:179]
	v_lshlrev_b64 v[180:181], 10, v[180:181]
	v_lshlrev_b64 v[2:3], 10, v[2:3]
	v_lshl_add_u64 v[4:5], v[0:1], 0, v[4:5]
	v_lshl_add_u64 v[172:173], v[0:1], 0, v[172:173]
	v_lshl_add_u64 v[6:7], v[0:1], 0, v[6:7]
	v_lshlrev_b64 v[174:175], 10, v[174:175]
	v_lshlrev_b64 v[176:177], 10, v[176:177]
	v_lshl_add_u64 v[180:181], v[0:1], 0, v[180:181]
	v_lshl_add_u64 v[178:179], v[0:1], 0, v[178:179]
	v_lshl_add_u64 v[2:3], v[0:1], 0, v[2:3]
	v_lshl_add_u64 v[176:177], v[0:1], 0, v[176:177]
	v_lshl_add_u64 v[174:175], v[0:1], 0, v[174:175]
	global_load_dword v189, v[4:5], off nt
	global_load_dword v190, v[2:3], off nt
	global_load_dword v191, v[172:173], off nt
	global_load_dword v192, v[6:7], off nt
	global_load_dword v193, v[176:177], off nt
	global_load_dword v194, v[174:175], off nt
	s_nop 0
	global_load_dword v180, v[180:181], off nt
	s_nop 0
	global_load_dword v178, v[178:179], off nt
	v_add_u32_e32 v4, s24, v52
	v_add_u32_e32 v6, s24, v49
	v_add_u32_e32 v172, s24, v54
	v_add_u32_e32 v2, s24, v47
	v_ashrrev_i32_e32 v5, 31, v4
	v_ashrrev_i32_e32 v173, 31, v172
	v_ashrrev_i32_e32 v7, 31, v6
	v_add_u32_e32 v174, s24, v51
	v_add_u32_e32 v176, s24, v56
	v_ashrrev_i32_e32 v3, 31, v2
	v_lshlrev_b64 v[4:5], 10, v[4:5]
	v_lshlrev_b64 v[6:7], 10, v[6:7]
	v_lshlrev_b64 v[172:173], 10, v[172:173]
	v_ashrrev_i32_e32 v177, 31, v176
	v_ashrrev_i32_e32 v175, 31, v174
	v_lshlrev_b64 v[2:3], 10, v[2:3]
	v_lshl_add_u64 v[4:5], v[0:1], 0, v[4:5]
	v_lshl_add_u64 v[172:173], v[0:1], 0, v[172:173]
	v_lshl_add_u64 v[6:7], v[0:1], 0, v[6:7]
	v_lshlrev_b64 v[174:175], 10, v[174:175]
	v_lshlrev_b64 v[176:177], 10, v[176:177]
	v_lshl_add_u64 v[2:3], v[0:1], 0, v[2:3]
	v_lshl_add_u64 v[176:177], v[0:1], 0, v[176:177]
	v_lshl_add_u64 v[174:175], v[0:1], 0, v[174:175]
	global_load_dword v179, v[4:5], off nt
	global_load_dword v181, v[2:3], off nt
	s_nop 0
	global_load_dword v172, v[172:173], off nt
	s_nop 0
	global_load_dword v6, v[6:7], off nt
	s_nop 0
	global_load_dword v7, v[176:177], off nt
	global_load_dword v173, v[174:175], off nt
	v_add_u32_e32 v4, s24, v58
	v_add_u32_e32 v2, s24, v53
	v_ashrrev_i32_e32 v5, 31, v4
	v_ashrrev_i32_e32 v3, 31, v2
	v_lshlrev_b64 v[4:5], 10, v[4:5]
	v_lshlrev_b64 v[2:3], 10, v[2:3]
	v_lshl_add_u64 v[4:5], v[0:1], 0, v[4:5]
	global_load_dword v4, v[4:5], off nt
	v_lshl_add_u64 v[2:3], v[0:1], 0, v[2:3]
	global_load_dword v2, v[2:3], off nt
	v_add_u32_e32 v3, v97, v108
	v_add_u32_e32 v174, s24, v59
	v_add_u32_e32 v176, s24, v64
	v_ashrrev_i32_e32 v177, 31, v176
	s_waitcnt vmcnt(23)
	ds_write_b32 v3, v14
	v_add_u32_e32 v3, v97, v109
	s_waitcnt vmcnt(22)
	ds_write_b32 v3, v182
	v_add_u32_e32 v3, v97, v110
	s_waitcnt vmcnt(21)
	ds_write_b32 v3, v183
	v_add_u32_e32 v3, v97, v111
	s_waitcnt vmcnt(20)
	ds_write_b32 v3, v184
	v_add_u32_e32 v3, v97, v112
	s_waitcnt vmcnt(19)
;     ...
; #pragma unroll 32
;     for (int i = 0; i < 64; ++i) { const int kk = 2 * i + (lane >> 5); scr[kk * 33 + (lane & 31)] = W[(size_t)(k0 + kk) * N + n0 + (lane & 31)]; }
	ds_write_b32 v3, v185
	v_add_u32_e32 v3, v97, v113
	s_waitcnt vmcnt(18)
	ds_write_b32 v3, v186
	v_add_u32_e32 v3, v97, v114
	s_waitcnt vmcnt(17)
	ds_write_b32 v3, v187
	v_add_u32_e32 v3, v97, v115
	s_waitcnt vmcnt(16)
	ds_write_b32 v3, v188
	v_add_u32_e32 v3, v97, v116
	v_ashrrev_i32_e32 v175, 31, v174
	v_lshlrev_b64 v[174:175], 10, v[174:175]
	v_lshlrev_b64 v[176:177], 10, v[176:177]
	v_lshl_add_u64 v[176:177], v[0:1], 0, v[176:177]
	v_lshl_add_u64 v[174:175], v[0:1], 0, v[174:175]
	s_lshr_b32 s10, s3, 8
	s_and_b32 s3, s47, 0x100000
	s_and_b32 s25, s45, 0x70000
	s_lshl_b64 s[38:39], s[10:11], 20
	s_lshl_b32 s3, s3, 1
	s_add_u32 s3, s21, s3
	s_addc_u32 s10, s40, 0
	s_add_u32 s3, s3, s38
	s_addc_u32 s10, s10, s39
	s_lshl_b32 s25, s25, 1
	s_add_u32 s3, s3, s25
	s_addc_u32 s10, s10, 0
	s_waitcnt vmcnt(15)
	ds_write_b32 v3, v189
	v_add_u32_e32 v3, v97, v117
	s_waitcnt vmcnt(14)
	ds_write_b32 v3, v190
	v_add_u32_e32 v3, v97, v118
	s_waitcnt vmcnt(13)
	ds_write_b32 v3, v191
	v_add_u32_e32 v3, v97, v119
	s_waitcnt vmcnt(12)
	ds_write_b32 v3, v192
	v_add_u32_e32 v3, v97, v120
	s_waitcnt vmcnt(11)
	ds_write_b32 v3, v193
	v_add_u32_e32 v3, v97, v121
	s_waitcnt vmcnt(10)
	ds_write_b32 v3, v194
	v_add_u32_e32 v3, v97, v122
	s_waitcnt vmcnt(9)
	ds_write_b32 v3, v180
	v_add_u32_e32 v3, v97, v123
	s_waitcnt vmcnt(8)
	ds_write_b32 v3, v178
	v_add_u32_e32 v3, v97, v124
	v_add_u32_e32 v178, s24, v61
	v_add_u32_e32 v180, s24, v66
	s_waitcnt vmcnt(7)
	ds_write_b32 v3, v179
	v_add_u32_e32 v3, v97, v125
	s_waitcnt vmcnt(6)
	ds_write_b32 v3, v181
	v_add_u32_e32 v3, v97, v126
	s_waitcnt vmcnt(5)
	ds_write_b32 v3, v172
	v_add_u32_e32 v3, v97, v127
	s_waitcnt vmcnt(4)
	ds_write_b32 v3, v6
	v_add_u32_e32 v3, v97, v128
	s_waitcnt vmcnt(3)
	ds_write_b32 v3, v7
	v_add_u32_e32 v3, v97, v129
	s_waitcnt vmcnt(2)
	ds_write_b32 v3, v173
	v_add_u32_e32 v3, v97, v130
	v_add_u32_e32 v6, s24, v57
	s_waitcnt vmcnt(1)
	ds_write_b32 v3, v4
	v_add_u32_e32 v3, v97, v131
	v_add_u32_e32 v4, s24, v60
	s_waitcnt vmcnt(0)
	ds_write_b32 v3, v2
	v_add_u32_e32 v2, s24, v55
	v_ashrrev_i32_e32 v5, 31, v4
	v_add_u32_e32 v172, s24, v62
	v_ashrrev_i32_e32 v3, 31, v2
	v_lshlrev_b64 v[4:5], 10, v[4:5]
	v_ashrrev_i32_e32 v173, 31, v172
	v_ashrrev_i32_e32 v7, 31, v6
	v_ashrrev_i32_e32 v181, 31, v180
	v_ashrrev_i32_e32 v179, 31, v178
	v_lshlrev_b64 v[2:3], 10, v[2:3]
	v_lshl_add_u64 v[4:5], v[0:1], 0, v[4:5]
	v_lshlrev_b64 v[6:7], 10, v[6:7]
	v_lshlrev_b64 v[172:173], 10, v[172:173]
	v_lshlrev_b64 v[178:179], 10, v[178:179]
	v_lshlrev_b64 v[180:181], 10, v[180:181]
	v_lshl_add_u64 v[2:3], v[0:1], 0, v[2:3]
	v_lshl_add_u64 v[172:173], v[0:1], 0, v[172:173]
	v_lshl_add_u64 v[6:7], v[0:1], 0, v[6:7]
	v_lshl_add_u64 v[180:181], v[0:1], 0, v[180:181]
	v_lshl_add_u64 v[178:179], v[0:1], 0, v[178:179]
	global_load_dword v14, v[4:5], off nt
	global_load_dword v182, v[2:3], off nt
	global_load_dword v183, v[172:173], off nt
	global_load_dword v184, v[6:7], off nt
	global_load_dword v185, v[176:177], off nt
	global_load_dword v186, v[174:175], off nt
	global_load_dword v187, v[180:181], off nt
	global_load_dword v188, v[178:179], off nt
	v_add_u32_e32 v4, s24, v68
	v_add_u32_e32 v2, s24, v63
	v_ashrrev_i32_e32 v5, 31, v4
	v_add_u32_e32 v6, s24, v65
	v_add_u32_e32 v172, s24, v70
	v_add_u32_e32 v174, s24, v67
	v_add_u32_e32 v176, s24, v72
	v_add_u32_e32 v178, s24, v69
	v_add_u32_e32 v180, s24, v74
	v_ashrrev_i32_e32 v3, 31, v2
	v_lshlrev_b64 v[4:5], 10, v[4:5]
	v_ashrrev_i32_e32 v173, 31, v172
	v_ashrrev_i32_e32 v7, 31, v6
	v_ashrrev_i32_e32 v177, 31, v176
	v_ashrrev_i32_e32 v175, 31, v174
	v_ashrrev_i32_e32 v181, 31, v180
	v_ashrrev_i32_e32 v179, 31, v178
	v_lshlrev_b64 v[2:3], 10, v[2:3]
	v_lshl_add_u64 v[4:5], v[0:1], 0, v[4:5]
	v_lshlrev_b64 v[6:7], 10, v[6:7]
	v_lshlrev_b64 v[172:173], 10, v[172:173]
	v_lshlrev_b64 v[174:175], 10, v[174:175]
	v_lshlrev_b64 v[176:177], 10, v[176:177]
	v_lshlrev_b64 v[178:179], 10, v[178:179]
	v_lshlrev_b64 v[180:181], 10, v[180:181]
	v_lshl_add_u64 v[2:3], v[0:1], 0, v[2:3]
	v_lshl_add_u64 v[172:173], v[0:1], 0, v[172:173]
	v_lshl_add_u64 v[6:7], v[0:1], 0, v[6:7]
	v_lshl_add_u64 v[176:177], v[0:1], 0, v[176:177]
	v_lshl_add_u64 v[174:175], v[0:1], 0, v[174:175]
	v_lshl_add_u64 v[180:181], v[0:1], 0, v[180:181]
	v_lshl_add_u64 v[178:179], v[0:1], 0, v[178:179]
	global_load_dword v189, v[4:5], off nt
	global_load_dword v190, v[2:3], off nt
	global_load_dword v191, v[172:173], off nt
	global_load_dword v192, v[6:7], off nt
	global_load_dword v193, v[176:177], off nt
	global_load_dword v194, v[174:175], off nt
	global_load_dword v195, v[180:181], off nt
	global_load_dword v196, v[178:179], off nt
	v_add_u32_e32 v4, s24, v76
	v_add_u32_e32 v174, s24, v75
	v_add_u32_e32 v176, s24, v80
	v_add_u32_e32 v2, s24, v71
	v_ashrrev_i32_e32 v5, 31, v4
	v_add_u32_e32 v6, s24, v73
	v_add_u32_e32 v172, s24, v78
	v_ashrrev_i32_e32 v177, 31, v176
	v_ashrrev_i32_e32 v175, 31, v174
	v_add_u32_e32 v178, s24, v77
	v_add_u32_e32 v180, s24, v82
	v_ashrrev_i32_e32 v3, 31, v2
	v_lshlrev_b64 v[4:5], 10, v[4:5]
	v_ashrrev_i32_e32 v173, 31, v172
	v_ashrrev_i32_e32 v7, 31, v6
	v_lshlrev_b64 v[174:175], 10, v[174:175]
	v_lshlrev_b64 v[176:177], 10, v[176:177]
	v_ashrrev_i32_e32 v181, 31, v180
	v_ashrrev_i32_e32 v179, 31, v178
	v_lshlrev_b64 v[2:3], 10, v[2:3]
	v_lshl_add_u64 v[4:5], v[0:1], 0, v[4:5]
	v_lshlrev_b64 v[6:7], 10, v[6:7]
	v_lshlrev_b64 v[172:173], 10, v[172:173]
	v_lshl_add_u64 v[176:177], v[0:1], 0, v[176:177]
	v_lshl_add_u64 v[174:175], v[0:1], 0, v[174:175]
	v_lshlrev_b64 v[178:179], 10, v[178:179]
	v_lshlrev_b64 v[180:181], 10, v[180:181]
	v_lshl_add_u64 v[2:3], v[0:1], 0, v[2:3]
;     ...
; #pragma unroll 32
;     for (int i = 0; i < 64; ++i) { const int kk = 2 * i + (lane >> 5); scr[kk * 33 + (lane & 31)] = W[(size_t)(k0 + kk) * N + n0 + (lane & 31)]; }
	v_lshl_add_u64 v[172:173], v[0:1], 0, v[172:173]
	v_lshl_add_u64 v[6:7], v[0:1], 0, v[6:7]
	v_lshl_add_u64 v[180:181], v[0:1], 0, v[180:181]
	v_lshl_add_u64 v[178:179], v[0:1], 0, v[178:179]
	global_load_dword v197, v[4:5], off nt
	global_load_dword v198, v[2:3], off nt
	global_load_dword v199, v[172:173], off nt
	global_load_dword v200, v[6:7], off nt
	global_load_dword v201, v[176:177], off nt
	global_load_dword v202, v[174:175], off nt
	global_load_dword v203, v[180:181], off nt
	global_load_dword v204, v[178:179], off nt
	v_add_u32_e32 v4, s24, v84
	v_add_u32_e32 v174, s24, v83
	v_add_u32_e32 v176, s24, v88
	v_add_u32_e32 v2, s24, v79
	v_ashrrev_i32_e32 v5, 31, v4
	v_add_u32_e32 v6, s24, v81
	v_add_u32_e32 v172, s24, v86
	v_ashrrev_i32_e32 v177, 31, v176
	v_ashrrev_i32_e32 v175, 31, v174
	v_add_u32_e32 v178, s24, v85
	v_add_u32_e32 v180, s24, v90
	v_ashrrev_i32_e32 v3, 31, v2
	v_lshlrev_b64 v[4:5], 10, v[4:5]
	v_ashrrev_i32_e32 v173, 31, v172
	v_ashrrev_i32_e32 v7, 31, v6
	v_lshlrev_b64 v[174:175], 10, v[174:175]
	v_lshlrev_b64 v[176:177], 10, v[176:177]
	v_ashrrev_i32_e32 v181, 31, v180
	v_ashrrev_i32_e32 v179, 31, v178
	v_lshlrev_b64 v[2:3], 10, v[2:3]
	v_lshl_add_u64 v[4:5], v[0:1], 0, v[4:5]
	v_lshlrev_b64 v[6:7], 10, v[6:7]
	v_lshlrev_b64 v[172:173], 10, v[172:173]
	v_lshl_add_u64 v[176:177], v[0:1], 0, v[176:177]
	v_lshl_add_u64 v[174:175], v[0:1], 0, v[174:175]
	v_lshlrev_b64 v[178:179], 10, v[178:179]
	v_lshlrev_b64 v[180:181], 10, v[180:181]
	v_lshl_add_u64 v[2:3], v[0:1], 0, v[2:3]
	v_lshl_add_u64 v[172:173], v[0:1], 0, v[172:173]
	v_lshl_add_u64 v[6:7], v[0:1], 0, v[6:7]
	v_lshl_add_u64 v[180:181], v[0:1], 0, v[180:181]
	v_lshl_add_u64 v[178:179], v[0:1], 0, v[178:179]
	global_load_dword v205, v[4:5], off nt
	global_load_dword v206, v[2:3], off nt
	global_load_dword v207, v[172:173], off nt
	global_load_dword v208, v[6:7], off nt
	s_nop 0
	global_load_dword v176, v[176:177], off nt
	s_nop 0
	global_load_dword v174, v[174:175], off nt
	s_nop 0
	global_load_dword v175, v[180:181], off nt
	global_load_dword v177, v[178:179], off nt
	v_add_u32_e32 v4, s24, v92
	v_add_u32_e32 v2, s24, v87
	v_ashrrev_i32_e32 v5, 31, v4
	v_ashrrev_i32_e32 v3, 31, v2
	v_lshlrev_b64 v[4:5], 10, v[4:5]
	v_lshlrev_b64 v[2:3], 10, v[2:3]
	v_lshl_add_u64 v[4:5], v[0:1], 0, v[4:5]
	v_lshl_add_u64 v[2:3], v[0:1], 0, v[2:3]
	global_load_dword v178, v[4:5], off nt
	global_load_dword v179, v[2:3], off nt
	v_add_u32_e32 v4, s24, v94
	v_add_u32_e32 v6, s24, v91
	v_add_u32_e32 v172, s24, v96
	v_add_u32_e32 v2, s24, v89
	v_ashrrev_i32_e32 v5, 31, v4
	v_ashrrev_i32_e32 v173, 31, v172
	v_ashrrev_i32_e32 v7, 31, v6
	v_ashrrev_i32_e32 v3, 31, v2
	v_lshlrev_b64 v[4:5], 10, v[4:5]
	v_lshlrev_b64 v[6:7], 10, v[6:7]
	v_lshlrev_b64 v[172:173], 10, v[172:173]
	v_lshlrev_b64 v[2:3], 10, v[2:3]
	v_lshl_add_u64 v[4:5], v[0:1], 0, v[4:5]
	v_lshl_add_u64 v[172:173], v[0:1], 0, v[172:173]
	v_lshl_add_u64 v[6:7], v[0:1], 0, v[6:7]
	v_lshl_add_u64 v[2:3], v[0:1], 0, v[2:3]
	global_load_dword v180, v[4:5], off nt
	global_load_dword v181, v[2:3], off nt
	s_nop 0
	global_load_dword v172, v[172:173], off nt
	s_nop 0
	global_load_dword v6, v[6:7], off nt
	v_add_u32_e32 v4, s24, v98
	v_add_u32_e32 v2, s24, v93
	v_ashrrev_i32_e32 v5, 31, v4
	v_ashrrev_i32_e32 v3, 31, v2
	v_lshlrev_b64 v[4:5], 10, v[4:5]
	v_lshlrev_b64 v[2:3], 10, v[2:3]
	v_lshl_add_u64 v[4:5], v[0:1], 0, v[4:5]
	global_load_dword v4, v[4:5], off nt
	v_lshl_add_u64 v[0:1], v[0:1], 0, v[2:3]
	global_load_dword v0, v[0:1], off nt
	v_add_u32_e32 v1, v97, v132
	s_waitcnt vmcnt(39)
	ds_write_b32 v1, v14
	v_add_u32_e32 v1, v97, v133
	s_waitcnt vmcnt(38)
	ds_write_b32 v1, v182
	v_add_u32_e32 v1, v97, v134
	s_waitcnt vmcnt(37)
	ds_write_b32 v1, v183
	v_add_u32_e32 v1, v97, v135
	s_waitcnt vmcnt(36)
	ds_write_b32 v1, v184
	v_add_u32_e32 v1, v97, v136
	s_waitcnt vmcnt(35)
	ds_write_b32 v1, v185
	v_add_u32_e32 v1, v97, v137
	s_waitcnt vmcnt(34)
	ds_write_b32 v1, v186
	v_add_u32_e32 v1, v97, v138
	s_waitcnt vmcnt(33)
	ds_write_b32 v1, v187
	v_add_u32_e32 v1, v97, v139
	s_waitcnt vmcnt(32)
	ds_write_b32 v1, v188
	v_add_u32_e32 v1, v97, v140
	s_waitcnt vmcnt(31)
	ds_write_b32 v1, v189
	v_add_u32_e32 v1, v97, v141
	s_waitcnt vmcnt(30)
	ds_write_b32 v1, v190
	v_add_u32_e32 v1, v97, v142
	s_waitcnt vmcnt(29)
	ds_write_b32 v1, v191
	v_add_u32_e32 v1, v97, v143
	s_waitcnt vmcnt(28)
	ds_write_b32 v1, v192
	v_add_u32_e32 v1, v97, v144
	s_waitcnt vmcnt(27)
	ds_write_b32 v1, v193
	v_add_u32_e32 v1, v97, v145
	s_waitcnt vmcnt(26)
	ds_write_b32 v1, v194
	v_add_u32_e32 v1, v97, v146
	s_waitcnt vmcnt(25)
	ds_write_b32 v1, v195
	v_add_u32_e32 v1, v97, v147
	s_waitcnt vmcnt(24)
	ds_write_b32 v1, v196
	v_add_u32_e32 v1, v97, v148
	s_waitcnt vmcnt(23)
	ds_write_b32 v1, v197
	v_add_u32_e32 v1, v97, v149
	s_waitcnt vmcnt(22)
	ds_write_b32 v1, v198
	v_add_u32_e32 v1, v97, v150
	s_waitcnt vmcnt(21)
	ds_write_b32 v1, v199
	v_add_u32_e32 v1, v97, v151
	s_waitcnt vmcnt(20)
	ds_write_b32 v1, v200
	v_add_u32_e32 v1, v97, v152
	s_waitcnt vmcnt(19)
	ds_write_b32 v1, v201
	v_add_u32_e32 v1, v97, v153
	s_waitcnt vmcnt(18)
	ds_write_b32 v1, v202
	v_add_u32_e32 v1, v97, v154
	s_waitcnt vmcnt(17)
	ds_write_b32 v1, v203
	v_add_u32_e32 v1, v97, v155
	s_waitcnt vmcnt(16)
	ds_write_b32 v1, v204
	v_add_u32_e32 v1, v97, v156
	s_waitcnt vmcnt(15)
	ds_write_b32 v1, v205
	v_add_u32_e32 v1, v97, v157
	s_waitcnt vmcnt(14)
	ds_write_b32 v1, v206
	v_add_u32_e32 v1, v97, v158
	s_waitcnt vmcnt(13)
	ds_write_b32 v1, v207
	v_add_u32_e32 v1, v97, v159
	s_waitcnt vmcnt(12)
	ds_write_b32 v1, v208
	v_add_u32_e32 v1, v97, v160
	s_waitcnt vmcnt(11)
; __device__ __forceinline__ unsigned cvt_pk_bf16(float lo, float hi) { unsigned r; asm volatile("v_cvt_pk_bf16_f32 %0, %1, %2" : "=v"(r) : "v"(lo), "v"(hi)); return r; }
; #define GAS __attribute__((address_space(1)))
; #define LAS __attribute__((address_space(3)))
; #define LDS_WAIT() asm volatile("s_waitcnt lgkmcnt(0)" ::: "memory")
;     ...
;     for (int i = 0; i < 64; ++i) { const int kk = 2 * i + (lane >> 5); scr[kk * 33 + (lane & 31)] = W[(size_t)(k0 + kk) * N + n0 + (lane & 31)]; }
;     LDS_WAIT(); asm volatile("" ::: "memory");
;     const int c = lane & 15;
;     float gk[8];
;     if (gain) load8f(gain + k0 + 8 * c, gk); else {
; #pragma unroll
;         for (int e = 0; e < 8; ++e) gk[e] = 1.0f; }
; #pragma unroll
;     for (int j = 0; j < 8; ++j) { const int n = (lane >> 4) + 4 * j; const LAS float* s = scr + (8 * c) * 33 + n;
;         v4u o; o.x = cvt_pk_bf16(s[0 * 33] * gk[0], s[1 * 33] * gk[1]); o.y = cvt_pk_bf16(s[2 * 33] * gk[2], s[3 * 33] * gk[3]); o.z = cvt_pk_bf16(s[4 * 33] * gk[4], s[5 * 33] * gk[5]); o.w = cvt_pk_bf16(s[6 * 33] * gk[6], s[7 * 33] * gk[7]);
;         *(GAS v4u*)(WT + (size_t)(nd0 + n) * K + k0 + 8 * c) = o; }
;     LDS_WAIT(); asm volatile("" ::: "memory");
	ds_write_b32 v1, v176
	v_add_u32_e32 v1, v97, v161
	s_waitcnt vmcnt(10)
	ds_write_b32 v1, v174
	v_add_u32_e32 v1, v97, v162
	s_waitcnt vmcnt(9)
	ds_write_b32 v1, v175
	v_add_u32_e32 v1, v97, v163
	s_waitcnt vmcnt(8)
	ds_write_b32 v1, v177
	v_add_u32_e32 v1, v97, v164
	s_waitcnt vmcnt(7)
	ds_write_b32 v1, v178
	v_add_u32_e32 v1, v97, v165
	s_waitcnt vmcnt(6)
	ds_write_b32 v1, v179
	v_add_u32_e32 v1, v97, v166
	s_waitcnt vmcnt(5)
	ds_write_b32 v1, v180
	v_add_u32_e32 v1, v97, v167
	s_waitcnt vmcnt(4)
	ds_write_b32 v1, v181
	v_add_u32_e32 v1, v97, v168
	s_waitcnt vmcnt(3)
	ds_write_b32 v1, v172
	v_add_u32_e32 v1, v97, v169
	s_waitcnt vmcnt(2)
	ds_write_b32 v1, v6
	v_add_u32_e32 v1, v97, v170
	s_waitcnt vmcnt(1)
	ds_write_b32 v1, v4
	v_add_u32_e32 v1, v97, v171
	s_waitcnt vmcnt(0)
	ds_write_b32 v1, v0
	s_waitcnt lgkmcnt(0)
	ds_read2_b32 v[0:1], v100 offset1:33
	s_waitcnt lgkmcnt(0)
	v_cvt_pk_bf16_f32 v0, v0, v1
	ds_read2_b32 v[2:3], v100 offset0:66 offset1:99
	s_waitcnt lgkmcnt(0)
	v_cvt_pk_bf16_f32 v1, v2, v3
	ds_read2_b32 v[2:3], v100 offset0:132 offset1:165
	s_lshl_b32 s24, s24, 1
	s_waitcnt lgkmcnt(0)
	v_cvt_pk_bf16_f32 v2, v2, v3
	ds_read2_b32 v[4:5], v100 offset0:198 offset1:231
	s_add_u32 s24, s3, s24
	s_waitcnt lgkmcnt(0)
	v_cvt_pk_bf16_f32 v3, v4, v5
	v_add_u32_e32 v4, s2, v99
	s_addc_u32 s25, s10, 0
	v_lshlrev_b32_e32 v14, 1, v16
	v_ashrrev_i32_e32 v5, 31, v4
	v_lshl_add_u64 v[6:7], s[24:25], 0, v[14:15]
	v_lshlrev_b64 v[4:5], 9, v[4:5]
	v_lshl_add_u64 v[4:5], v[6:7], 0, v[4:5]
	ds_read2_b32 v[172:173], v100 offset0:4 offset1:37
	global_store_dwordx4 v[4:5], v[0:3], off
	s_waitcnt lgkmcnt(0)
	s_nop 0
	v_cvt_pk_bf16_f32 v0, v172, v173
	ds_read2_b32 v[2:3], v100 offset0:70 offset1:103
	s_waitcnt lgkmcnt(0)
	v_cvt_pk_bf16_f32 v1, v2, v3
	ds_read2_b32 v[2:3], v100 offset0:136 offset1:169
	s_waitcnt lgkmcnt(0)
	v_cvt_pk_bf16_f32 v2, v2, v3
	ds_read2_b32 v[4:5], v100 offset0:202 offset1:235
	s_waitcnt lgkmcnt(0)
	v_cvt_pk_bf16_f32 v3, v4, v5
	v_add_u32_e32 v4, s2, v101
	v_ashrrev_i32_e32 v5, 31, v4
	v_lshlrev_b64 v[4:5], 9, v[4:5]
	v_lshl_add_u64 v[4:5], v[6:7], 0, v[4:5]
	ds_read2_b32 v[172:173], v100 offset0:8 offset1:41
	global_store_dwordx4 v[4:5], v[0:3], off
	s_waitcnt lgkmcnt(0)
	s_nop 0
	v_cvt_pk_bf16_f32 v0, v172, v173
	ds_read2_b32 v[2:3], v100 offset0:74 offset1:107
	s_waitcnt lgkmcnt(0)
	v_cvt_pk_bf16_f32 v1, v2, v3
	ds_read2_b32 v[2:3], v100 offset0:140 offset1:173
	s_waitcnt lgkmcnt(0)
	v_cvt_pk_bf16_f32 v2, v2, v3
	ds_read2_b32 v[4:5], v100 offset0:206 offset1:239
	s_waitcnt lgkmcnt(0)
	v_cvt_pk_bf16_f32 v3, v4, v5
	v_add_u32_e32 v4, s2, v102
	v_ashrrev_i32_e32 v5, 31, v4
	v_lshlrev_b64 v[4:5], 9, v[4:5]
	v_lshl_add_u64 v[4:5], v[6:7], 0, v[4:5]
	ds_read2_b32 v[172:173], v100 offset0:12 offset1:45
	global_store_dwordx4 v[4:5], v[0:3], off
	s_waitcnt lgkmcnt(0)
	s_nop 0
	v_cvt_pk_bf16_f32 v0, v172, v173
	ds_read2_b32 v[2:3], v100 offset0:78 offset1:111
	s_waitcnt lgkmcnt(0)
	v_cvt_pk_bf16_f32 v1, v2, v3
	ds_read2_b32 v[2:3], v100 offset0:144 offset1:177
	s_waitcnt lgkmcnt(0)
	v_cvt_pk_bf16_f32 v2, v2, v3
	ds_read2_b32 v[4:5], v100 offset0:210 offset1:243
	s_waitcnt lgkmcnt(0)
	v_cvt_pk_bf16_f32 v3, v4, v5
	v_add_u32_e32 v4, s2, v103
	v_ashrrev_i32_e32 v5, 31, v4
	v_lshlrev_b64 v[4:5], 9, v[4:5]
	v_lshl_add_u64 v[4:5], v[6:7], 0, v[4:5]
	ds_read2_b32 v[172:173], v100 offset0:16 offset1:49
	global_store_dwordx4 v[4:5], v[0:3], off
	s_waitcnt lgkmcnt(0)
	s_nop 0
	v_cvt_pk_bf16_f32 v0, v172, v173
	ds_read2_b32 v[2:3], v100 offset0:82 offset1:115
	s_waitcnt lgkmcnt(0)
	v_cvt_pk_bf16_f32 v1, v2, v3
	ds_read2_b32 v[2:3], v100 offset0:148 offset1:181
	s_waitcnt lgkmcnt(0)
	v_cvt_pk_bf16_f32 v2, v2, v3
	ds_read2_b32 v[4:5], v100 offset0:214 offset1:247
	s_waitcnt lgkmcnt(0)
	v_cvt_pk_bf16_f32 v3, v4, v5
	v_add_u32_e32 v4, s2, v104
	v_ashrrev_i32_e32 v5, 31, v4
	v_lshlrev_b64 v[4:5], 9, v[4:5]
	v_lshl_add_u64 v[4:5], v[6:7], 0, v[4:5]
	ds_read2_b32 v[172:173], v100 offset0:20 offset1:53
	global_store_dwordx4 v[4:5], v[0:3], off
	s_waitcnt lgkmcnt(0)
	s_nop 0
	v_cvt_pk_bf16_f32 v0, v172, v173
	ds_read2_b32 v[2:3], v100 offset0:86 offset1:119
	s_waitcnt lgkmcnt(0)
	v_cvt_pk_bf16_f32 v1, v2, v3
	ds_read2_b32 v[2:3], v100 offset0:152 offset1:185
	s_waitcnt lgkmcnt(0)
	v_cvt_pk_bf16_f32 v2, v2, v3
	ds_read2_b32 v[4:5], v100 offset0:218 offset1:251
	s_waitcnt lgkmcnt(0)
	v_cvt_pk_bf16_f32 v3, v4, v5
	v_add_u32_e32 v4, s2, v105
	v_ashrrev_i32_e32 v5, 31, v4
	v_lshlrev_b64 v[4:5], 9, v[4:5]
	v_lshl_add_u64 v[4:5], v[6:7], 0, v[4:5]
	ds_read2_b32 v[172:173], v100 offset0:24 offset1:57
	global_store_dwordx4 v[4:5], v[0:3], off
	s_waitcnt lgkmcnt(0)
	s_nop 0
	v_cvt_pk_bf16_f32 v0, v172, v173
	ds_read2_b32 v[2:3], v100 offset0:90 offset1:123
	s_waitcnt lgkmcnt(0)
	v_cvt_pk_bf16_f32 v1, v2, v3
	ds_read2_b32 v[2:3], v100 offset0:156 offset1:189
	s_waitcnt lgkmcnt(0)
	v_cvt_pk_bf16_f32 v2, v2, v3
	ds_read2_b32 v[4:5], v100 offset0:222 offset1:255
	s_waitcnt lgkmcnt(0)
	v_cvt_pk_bf16_f32 v3, v4, v5
	v_add_u32_e32 v4, s2, v106
	v_ashrrev_i32_e32 v5, 31, v4
	v_lshlrev_b64 v[4:5], 9, v[4:5]
	v_lshl_add_u64 v[4:5], v[6:7], 0, v[4:5]
	ds_read2_b32 v[172:173], v100 offset0:28 offset1:61
	global_store_dwordx4 v[4:5], v[0:3], off
	s_waitcnt lgkmcnt(0)
	s_nop 0
	v_cvt_pk_bf16_f32 v0, v172, v173
	ds_read2_b32 v[2:3], v100 offset0:94 offset1:127
	s_waitcnt lgkmcnt(0)
	v_cvt_pk_bf16_f32 v1, v2, v3
	ds_read2_b32 v[2:3], v100 offset0:160 offset1:193
	s_waitcnt lgkmcnt(0)
	v_cvt_pk_bf16_f32 v2, v2, v3
	v_add_u32_e32 v3, 0x200, v100
	ds_read2_b32 v[4:5], v3 offset0:98 offset1:131
	s_waitcnt lgkmcnt(0)
	v_cvt_pk_bf16_f32 v3, v4, v5
	v_add_u32_e32 v4, s2, v107
	v_ashrrev_i32_e32 v5, 31, v4
	v_lshlrev_b64 v[4:5], 9, v[4:5]
	v_lshl_add_u64 v[4:5], v[6:7], 0, v[4:5]
	global_store_dwordx4 v[4:5], v[0:3], off
	s_waitcnt lgkmcnt(0)

;     const int nblk = N / 32, kb = item / nblk, nb = item % nblk, k0 = 128 * kb, n0 = 32 * nb;
;     const int nd0 = GLU ? (n0 < 6144 ? 256 * (n0 >> 7) + (n0 & 127) : 256 * ((n0 - 6144) >> 7) + 128 + ((n0 - 6144) & 127)) : n0;
; #pragma unroll 32
;     for (int i = 0; i < 64; ++i) { const int kk = 2 * i + (lane >> 5); scr[kk * 33 + (lane & 31)] = W[(size_t)(k0 + kk) * N + n0 + (lane & 31)]; }
.LBB0_38:
	s_lshl_b32 s10, s10, 7
	s_lshl_b32 s24, s39, 2
	s_waitcnt lgkmcnt(0)
	s_add_u32 s2, s2, s24
	s_addc_u32 s3, s3, 0
	v_lshlrev_b32_e32 v14, 2, v12
	s_and_b32 s10, s10, 0x7f80
	v_lshl_add_u64 v[0:1], s[2:3], 0, v[14:15]
	v_add_u32_e32 v14, s10, v11
	v_add_u32_e32 v2, s10, v10
	v_mad_i64_i32 v[172:173], s[2:3], v14, s50, v[0:1]
	v_add_u32_e32 v14, s10, v13
	v_add_u32_e32 v4, s10, v9
	v_mad_i64_i32 v[2:3], s[2:3], v2, s50, v[0:1]
	v_add_u32_e32 v6, s10, v38
	v_add_u32_e32 v174, s10, v40
	v_mad_i64_i32 v[176:177], s[2:3], v14, s50, v[0:1]
	v_add_u32_e32 v14, s10, v17
	v_add_u32_e32 v178, s10, v42
	v_mad_i64_i32 v[4:5], s[2:3], v4, s50, v[0:1]
	v_mad_i64_i32 v[6:7], s[2:3], v6, s50, v[0:1]
	v_mad_i64_i32 v[174:175], s[2:3], v174, s50, v[0:1]
	v_mad_i64_i32 v[178:179], s[2:3], v178, s50, v[0:1]
	v_mad_i64_i32 v[180:181], s[2:3], v14, s50, v[0:1]
	global_load_dword v14, v[2:3], off nt
	global_load_dword v182, v[4:5], off nt
	global_load_dword v183, v[6:7], off nt
	global_load_dword v184, v[172:173], off nt
	global_load_dword v185, v[174:175], off nt
	global_load_dword v186, v[176:177], off nt
	global_load_dword v187, v[178:179], off nt
	global_load_dword v188, v[180:181], off nt
	v_add_u32_e32 v2, s10, v44
	v_add_u32_e32 v176, s10, v43
	v_add_u32_e32 v178, s10, v50
	v_add_u32_e32 v4, s10, v39
	v_mad_i64_i32 v[2:3], s[2:3], v2, s50, v[0:1]
	v_add_u32_e32 v172, s10, v41
	v_add_u32_e32 v6, s10, v46
	v_add_u32_e32 v174, s10, v48
	v_mad_i64_i32 v[176:177], s[2:3], v176, s50, v[0:1]
	v_add_u32_e32 v180, s10, v45
	v_mad_i64_i32 v[178:179], s[2:3], v178, s50, v[0:1]
	v_mad_i64_i32 v[4:5], s[2:3], v4, s50, v[0:1]
	v_mad_i64_i32 v[6:7], s[2:3], v6, s50, v[0:1]
	v_mad_i64_i32 v[172:173], s[2:3], v172, s50, v[0:1]
	v_mad_i64_i32 v[174:175], s[2:3], v174, s50, v[0:1]
	v_mad_i64_i32 v[180:181], s[2:3], v180, s50, v[0:1]
	global_load_dword v189, v[2:3], off nt
	global_load_dword v190, v[4:5], off nt
	global_load_dword v191, v[6:7], off nt
	global_load_dword v192, v[172:173], off nt
	global_load_dword v193, v[174:175], off nt
	s_nop 0
	global_load_dword v176, v[176:177], off nt
	s_nop 0
	global_load_dword v177, v[178:179], off nt
	s_nop 0
	global_load_dword v178, v[180:181], off nt
	v_add_u32_e32 v2, s10, v52
	v_mad_i64_i32 v[2:3], s[2:3], v2, s50, v[0:1]
	global_load_dword v179, v[2:3], off nt
	v_add_u32_e32 v4, s10, v47
	v_add_u32_e32 v6, s10, v49
	v_add_u32_e32 v2, s10, v54
	v_mad_i64_i32 v[4:5], s[2:3], v4, s50, v[0:1]
	v_mad_i64_i32 v[2:3], s[2:3], v2, s50, v[0:1]
	v_mad_i64_i32 v[6:7], s[2:3], v6, s50, v[0:1]
	v_add_u32_e32 v172, s10, v56
	v_add_u32_e32 v174, s10, v51
	v_mad_i64_i32 v[172:173], s[2:3], v172, s50, v[0:1]
	global_load_dword v4, v[4:5], off nt
	s_nop 0
	global_load_dword v5, v[2:3], off nt
	s_nop 0
	global_load_dword v6, v[6:7], off nt
	s_nop 0
	global_load_dword v7, v[172:173], off nt
	v_add_u32_e32 v2, s10, v58
	v_mad_i64_i32 v[174:175], s[2:3], v174, s50, v[0:1]
	v_add_u32_e32 v172, s10, v53
	v_mad_i64_i32 v[2:3], s[2:3], v2, s50, v[0:1]
	global_load_dword v173, v[174:175], off nt
	s_nop 0
	global_load_dword v174, v[2:3], off nt
	v_mad_i64_i32 v[2:3], s[2:3], v172, s50, v[0:1]
	global_load_dword v2, v[2:3], off nt
	v_add_u32_e32 v3, v97, v108
	s_load_dwordx2 s[2:3], s[6:7], 0x48
	s_waitcnt lgkmcnt(0)
	s_cmp_eq_u64 s[2:3], 0
	s_waitcnt vmcnt(23)
	ds_write_b32 v3, v14
	v_add_u32_e32 v3, v97, v109
	s_waitcnt vmcnt(22)
	ds_write_b32 v3, v182
	v_add_u32_e32 v3, v97, v110
	s_waitcnt vmcnt(21)
	ds_write_b32 v3, v183
	v_add_u32_e32 v3, v97, v111
	s_waitcnt vmcnt(20)
	ds_write_b32 v3, v184
	v_add_u32_e32 v3, v97, v112
	s_waitcnt vmcnt(19)
	ds_write_b32 v3, v185
	v_add_u32_e32 v3, v97, v113
	s_waitcnt vmcnt(18)
	ds_write_b32 v3, v186
	v_add_u32_e32 v3, v97, v114
	s_waitcnt vmcnt(17)
	ds_write_b32 v3, v187
	v_add_u32_e32 v3, v97, v115
	s_waitcnt vmcnt(16)
	ds_write_b32 v3, v188
	v_add_u32_e32 v3, v97, v116
	v_add_u32_e32 v14, s10, v57
	s_waitcnt vmcnt(15)
	ds_write_b32 v3, v189
	v_add_u32_e32 v3, v97, v117
	s_waitcnt vmcnt(14)
	ds_write_b32 v3, v190
	v_add_u32_e32 v3, v97, v118
	s_waitcnt vmcnt(13)
	ds_write_b32 v3, v191
	v_add_u32_e32 v3, v97, v119
	s_waitcnt vmcnt(12)
	ds_write_b32 v3, v192
	v_add_u32_e32 v3, v97, v120
	s_waitcnt vmcnt(11)
	ds_write_b32 v3, v193
	v_add_u32_e32 v3, v97, v121
	s_waitcnt vmcnt(10)
	ds_write_b32 v3, v176
	v_add_u32_e32 v3, v97, v122
	s_waitcnt vmcnt(9)
	ds_write_b32 v3, v177
	v_add_u32_e32 v3, v97, v123
	s_waitcnt vmcnt(8)
	ds_write_b32 v3, v178
	v_add_u32_e32 v3, v97, v124
	s_waitcnt vmcnt(7)
	ds_write_b32 v3, v179
	v_add_u32_e32 v3, v97, v125
	v_add_u32_e32 v178, s10, v66
	v_mad_i64_i32 v[178:179], s[24:25], v178, s50, v[0:1]
	s_waitcnt vmcnt(6)
	ds_write_b32 v3, v4
	v_add_u32_e32 v3, v97, v126
	s_waitcnt vmcnt(5)
	ds_write_b32 v3, v5
	v_add_u32_e32 v3, v97, v127
	s_waitcnt vmcnt(4)
	ds_write_b32 v3, v6
	v_add_u32_e32 v3, v97, v128
	s_waitcnt vmcnt(3)
	ds_write_b32 v3, v7
	v_add_u32_e32 v3, v97, v129
	v_add_u32_e32 v4, s10, v55
	s_waitcnt vmcnt(2)
	ds_write_b32 v3, v173
	v_add_u32_e32 v3, v97, v130
	s_waitcnt vmcnt(1)
	ds_write_b32 v3, v174
	v_add_u32_e32 v3, v97, v131
	s_waitcnt vmcnt(0)
;     ...
; #pragma unroll 32
;     for (int i = 0; i < 64; ++i) { const int kk = 2 * i + (lane >> 5); scr[kk * 33 + (lane & 31)] = W[(size_t)(k0 + kk) * N + n0 + (lane & 31)]; }
	ds_write_b32 v3, v2
	v_add_u32_e32 v2, s10, v60
	v_mad_i64_i32 v[172:173], s[24:25], v14, s50, v[0:1]
	v_add_u32_e32 v14, s10, v59
	v_mad_i64_i32 v[2:3], s[24:25], v2, s50, v[0:1]
	v_add_u32_e32 v6, s10, v62
	v_add_u32_e32 v174, s10, v64
	v_mad_i64_i32 v[176:177], s[24:25], v14, s50, v[0:1]
	v_add_u32_e32 v14, s10, v61
	v_mad_i64_i32 v[4:5], s[24:25], v4, s50, v[0:1]
	v_mad_i64_i32 v[6:7], s[24:25], v6, s50, v[0:1]
	v_mad_i64_i32 v[174:175], s[24:25], v174, s50, v[0:1]
	v_mad_i64_i32 v[180:181], s[24:25], v14, s50, v[0:1]
	global_load_dword v14, v[2:3], off nt
	global_load_dword v182, v[4:5], off nt
	global_load_dword v183, v[6:7], off nt
	global_load_dword v184, v[172:173], off nt
	global_load_dword v185, v[174:175], off nt
	global_load_dword v186, v[176:177], off nt
	global_load_dword v187, v[178:179], off nt
	global_load_dword v188, v[180:181], off nt
	v_add_u32_e32 v2, s10, v68
	v_add_u32_e32 v4, s10, v63
	v_mad_i64_i32 v[2:3], s[24:25], v2, s50, v[0:1]
	v_add_u32_e32 v172, s10, v65
	v_add_u32_e32 v6, s10, v70
	v_add_u32_e32 v176, s10, v67
	v_add_u32_e32 v174, s10, v72
	v_add_u32_e32 v180, s10, v69
	v_add_u32_e32 v178, s10, v74
	v_mad_i64_i32 v[4:5], s[24:25], v4, s50, v[0:1]
	v_mad_i64_i32 v[6:7], s[24:25], v6, s50, v[0:1]
	v_mad_i64_i32 v[172:173], s[24:25], v172, s50, v[0:1]
	v_mad_i64_i32 v[174:175], s[24:25], v174, s50, v[0:1]
	v_mad_i64_i32 v[176:177], s[24:25], v176, s50, v[0:1]
	v_mad_i64_i32 v[178:179], s[24:25], v178, s50, v[0:1]
	v_mad_i64_i32 v[180:181], s[24:25], v180, s50, v[0:1]
	global_load_dword v189, v[2:3], off nt
	global_load_dword v190, v[4:5], off nt
	global_load_dword v191, v[6:7], off nt
	global_load_dword v192, v[172:173], off nt
	global_load_dword v193, v[174:175], off nt
	global_load_dword v194, v[176:177], off nt
	global_load_dword v195, v[178:179], off nt
	global_load_dword v196, v[180:181], off nt
	v_add_u32_e32 v2, s10, v76
	v_add_u32_e32 v4, s10, v71
	v_mad_i64_i32 v[2:3], s[24:25], v2, s50, v[0:1]
	v_add_u32_e32 v172, s10, v73
	v_add_u32_e32 v6, s10, v78
	v_add_u32_e32 v176, s10, v75
	v_add_u32_e32 v174, s10, v80
	v_add_u32_e32 v180, s10, v77
	v_add_u32_e32 v178, s10, v82
	v_mad_i64_i32 v[4:5], s[24:25], v4, s50, v[0:1]
	v_mad_i64_i32 v[6:7], s[24:25], v6, s50, v[0:1]
	v_mad_i64_i32 v[172:173], s[24:25], v172, s50, v[0:1]
	v_mad_i64_i32 v[174:175], s[24:25], v174, s50, v[0:1]
	v_mad_i64_i32 v[176:177], s[24:25], v176, s50, v[0:1]
	v_mad_i64_i32 v[178:179], s[24:25], v178, s50, v[0:1]
	v_mad_i64_i32 v[180:181], s[24:25], v180, s50, v[0:1]
	global_load_dword v197, v[2:3], off nt
	global_load_dword v198, v[4:5], off nt
	global_load_dword v199, v[6:7], off nt
	global_load_dword v200, v[172:173], off nt
	global_load_dword v201, v[174:175], off nt
	global_load_dword v202, v[176:177], off nt
	global_load_dword v203, v[178:179], off nt
	global_load_dword v204, v[180:181], off nt
	v_add_u32_e32 v2, s10, v84
	v_add_u32_e32 v176, s10, v83
	v_add_u32_e32 v178, s10, v90
	v_add_u32_e32 v4, s10, v79
	v_mad_i64_i32 v[2:3], s[24:25], v2, s50, v[0:1]
	v_add_u32_e32 v172, s10, v81
	v_add_u32_e32 v6, s10, v86
	v_add_u32_e32 v174, s10, v88
	v_mad_i64_i32 v[176:177], s[24:25], v176, s50, v[0:1]
	v_add_u32_e32 v180, s10, v85
	v_mad_i64_i32 v[178:179], s[24:25], v178, s50, v[0:1]
	v_mad_i64_i32 v[4:5], s[24:25], v4, s50, v[0:1]
	v_mad_i64_i32 v[6:7], s[24:25], v6, s50, v[0:1]
	v_mad_i64_i32 v[172:173], s[24:25], v172, s50, v[0:1]
	v_mad_i64_i32 v[174:175], s[24:25], v174, s50, v[0:1]
	v_mad_i64_i32 v[180:181], s[24:25], v180, s50, v[0:1]
	global_load_dword v205, v[2:3], off nt
	global_load_dword v206, v[4:5], off nt
	global_load_dword v207, v[6:7], off nt
	global_load_dword v208, v[172:173], off nt
	global_load_dword v209, v[174:175], off nt
	s_nop 0
	global_load_dword v176, v[176:177], off nt
	s_nop 0
	global_load_dword v177, v[178:179], off nt
	s_nop 0
	global_load_dword v178, v[180:181], off nt
	v_add_u32_e32 v2, s10, v92
	v_mad_i64_i32 v[2:3], s[24:25], v2, s50, v[0:1]
	global_load_dword v179, v[2:3], off nt
	v_add_u32_e32 v4, s10, v87
	v_add_u32_e32 v6, s10, v89
	v_add_u32_e32 v2, s10, v94
	v_mad_i64_i32 v[4:5], s[24:25], v4, s50, v[0:1]
	v_mad_i64_i32 v[2:3], s[24:25], v2, s50, v[0:1]
	v_mad_i64_i32 v[6:7], s[24:25], v6, s50, v[0:1]
	v_add_u32_e32 v172, s10, v96
	v_add_u32_e32 v174, s10, v91
	v_mad_i64_i32 v[172:173], s[24:25], v172, s50, v[0:1]
	global_load_dword v4, v[4:5], off nt
	s_nop 0
	global_load_dword v5, v[2:3], off nt
	s_nop 0
	global_load_dword v6, v[6:7], off nt
	s_nop 0
	global_load_dword v7, v[172:173], off nt
	v_add_u32_e32 v2, s10, v98
	v_mad_i64_i32 v[174:175], s[24:25], v174, s50, v[0:1]
	v_add_u32_e32 v172, s10, v93
	v_mad_i64_i32 v[2:3], s[24:25], v2, s50, v[0:1]
	global_load_dword v173, v[174:175], off nt
	s_nop 0
	global_load_dword v2, v[2:3], off nt
	v_mad_i64_i32 v[0:1], s[24:25], v172, s50, v[0:1]
	global_load_dword v0, v[0:1], off nt
	v_add_u32_e32 v1, v97, v132
	s_waitcnt vmcnt(39)
; #define LDS_WAIT() asm volatile("s_waitcnt lgkmcnt(0)" ::: "memory")
;     ...
;     for (int i = 0; i < 64; ++i) { const int kk = 2 * i + (lane >> 5); scr[kk * 33 + (lane & 31)] = W[(size_t)(k0 + kk) * N + n0 + (lane & 31)]; }
;     LDS_WAIT(); asm volatile("" ::: "memory");
;     const int c = lane & 15;
;     float gk[8];
;     if (gain) load8f(gain + k0 + 8 * c, gk); else {
	ds_write_b32 v1, v14
	v_add_u32_e32 v1, v97, v133
	s_waitcnt vmcnt(38)
	ds_write_b32 v1, v182
	v_add_u32_e32 v1, v97, v134
	s_waitcnt vmcnt(37)
	ds_write_b32 v1, v183
	v_add_u32_e32 v1, v97, v135
	s_waitcnt vmcnt(36)
	ds_write_b32 v1, v184
	v_add_u32_e32 v1, v97, v136
	s_waitcnt vmcnt(35)
	ds_write_b32 v1, v185
	v_add_u32_e32 v1, v97, v137
	s_waitcnt vmcnt(34)
	ds_write_b32 v1, v186
	v_add_u32_e32 v1, v97, v138
	s_waitcnt vmcnt(33)
	ds_write_b32 v1, v187
	v_add_u32_e32 v1, v97, v139
	s_waitcnt vmcnt(32)
	ds_write_b32 v1, v188
	v_add_u32_e32 v1, v97, v140
	s_waitcnt vmcnt(31)
	ds_write_b32 v1, v189
	v_add_u32_e32 v1, v97, v141
	s_waitcnt vmcnt(30)
	ds_write_b32 v1, v190
	v_add_u32_e32 v1, v97, v142
	s_waitcnt vmcnt(29)
	ds_write_b32 v1, v191
	v_add_u32_e32 v1, v97, v143
	s_waitcnt vmcnt(28)
	ds_write_b32 v1, v192
	v_add_u32_e32 v1, v97, v144
	s_waitcnt vmcnt(27)
	ds_write_b32 v1, v193
	v_add_u32_e32 v1, v97, v145
	s_waitcnt vmcnt(26)
	ds_write_b32 v1, v194
	v_add_u32_e32 v1, v97, v146
	s_waitcnt vmcnt(25)
	ds_write_b32 v1, v195
	v_add_u32_e32 v1, v97, v147
	s_waitcnt vmcnt(24)
	ds_write_b32 v1, v196
	v_add_u32_e32 v1, v97, v148
	s_waitcnt vmcnt(23)
	ds_write_b32 v1, v197
	v_add_u32_e32 v1, v97, v149
	s_waitcnt vmcnt(22)
	ds_write_b32 v1, v198
	v_add_u32_e32 v1, v97, v150
	s_waitcnt vmcnt(21)
	ds_write_b32 v1, v199
	v_add_u32_e32 v1, v97, v151
	s_waitcnt vmcnt(20)
	ds_write_b32 v1, v200
	v_add_u32_e32 v1, v97, v152
	s_waitcnt vmcnt(19)
	ds_write_b32 v1, v201
	v_add_u32_e32 v1, v97, v153
	s_waitcnt vmcnt(18)
	ds_write_b32 v1, v202
	v_add_u32_e32 v1, v97, v154
	s_waitcnt vmcnt(17)
	ds_write_b32 v1, v203
	v_add_u32_e32 v1, v97, v155
	s_waitcnt vmcnt(16)
	ds_write_b32 v1, v204
	v_add_u32_e32 v1, v97, v156
	s_waitcnt vmcnt(15)
	ds_write_b32 v1, v205
	v_add_u32_e32 v1, v97, v157
	s_waitcnt vmcnt(14)
	ds_write_b32 v1, v206
	v_add_u32_e32 v1, v97, v158
	s_waitcnt vmcnt(13)
	ds_write_b32 v1, v207
	v_add_u32_e32 v1, v97, v159
	s_waitcnt vmcnt(12)
	ds_write_b32 v1, v208
	v_add_u32_e32 v1, v97, v160
	s_waitcnt vmcnt(11)
	ds_write_b32 v1, v209
	v_add_u32_e32 v1, v97, v161
	s_waitcnt vmcnt(10)
	ds_write_b32 v1, v176
	v_add_u32_e32 v1, v97, v162
	s_waitcnt vmcnt(9)
	ds_write_b32 v1, v177
	v_add_u32_e32 v1, v97, v163
	s_waitcnt vmcnt(8)
	ds_write_b32 v1, v178
	v_add_u32_e32 v1, v97, v164
	s_waitcnt vmcnt(7)
	ds_write_b32 v1, v179
	v_add_u32_e32 v1, v97, v165
	s_waitcnt vmcnt(6)
	ds_write_b32 v1, v4
	v_add_u32_e32 v1, v97, v166
	s_waitcnt vmcnt(5)
	ds_write_b32 v1, v5
	v_add_u32_e32 v1, v97, v167
	s_waitcnt vmcnt(4)
	ds_write_b32 v1, v6
	v_add_u32_e32 v1, v97, v168
	s_waitcnt vmcnt(3)
	ds_write_b32 v1, v7
	v_add_u32_e32 v1, v97, v169
	s_waitcnt vmcnt(2)
	ds_write_b32 v1, v173
	v_add_u32_e32 v1, v97, v170
	s_waitcnt vmcnt(1)
	ds_write_b32 v1, v2
	v_add_u32_e32 v1, v97, v171
	s_waitcnt vmcnt(0)
	ds_write_b32 v1, v0
	s_waitcnt lgkmcnt(0)
	s_cbranch_scc1 .LBB0_40
	s_lshl_b32 s24, s10, 2
	s_add_u32 s2, s2, s24
	s_addc_u32 s3, s3, 0
	v_lshlrev_b32_e32 v0, 2, v16
	global_load_dwordx4 v[4:7], v0, s[2:3]
	s_nop 0
	global_load_dwordx4 v[0:3], v0, s[2:3] offset:16
	s_branch .LBB0_41

;     const int nblk = N / 32, kb = item / nblk, nb = item % nblk, k0 = 128 * kb, n0 = 32 * nb;
;     const int nd0 = GLU ? (n0 < 6144 ? 256 * (n0 >> 7) + (n0 & 127) : 256 * ((n0 - 6144) >> 7) + 128 + ((n0 - 6144) & 127)) : n0;
; #pragma unroll 32
;     for (int i = 0; i < 64; ++i) { const int kk = 2 * i + (lane >> 5); scr[kk * 33 + (lane & 31)] = W[(size_t)(k0 + kk) * N + n0 + (lane & 31)]; }
.LBB0_43:
	s_andn2_b64 vcc, exec, s[2:3]
	s_cbranch_vccnz .LBB0_45
	s_load_dwordx2 s[24:25], s[6:7], 0xd8
	s_and_b32 s2, s41, 0x7e0
	s_lshl_b32 s3, s2, 2
	v_lshlrev_b32_e32 v14, 2, v12
	s_waitcnt lgkmcnt(0)
	s_add_u32 s24, s24, s3
	s_addc_u32 s25, s25, 0
	s_add_i32 s3, s43, 0xc000
	s_and_b32 s3, s3, 0x1ff80
	v_add_u32_e32 v4, s3, v10
	v_add_u32_e32 v2, s3, v9
	v_ashrrev_i32_e32 v5, 31, v4
	v_add_u32_e32 v6, s3, v11
	v_add_u32_e32 v172, s3, v38
	v_add_u32_e32 v174, s3, v13
	v_add_u32_e32 v176, s3, v40
	v_add_u32_e32 v178, s3, v17
	v_add_u32_e32 v180, s3, v42
	v_lshl_add_u64 v[0:1], s[24:25], 0, v[14:15]
	v_ashrrev_i32_e32 v3, 31, v2
	v_lshlrev_b64 v[4:5], 13, v[4:5]
	v_ashrrev_i32_e32 v173, 31, v172
	v_ashrrev_i32_e32 v7, 31, v6
	v_ashrrev_i32_e32 v177, 31, v176
	v_ashrrev_i32_e32 v175, 31, v174
	v_ashrrev_i32_e32 v181, 31, v180
	v_ashrrev_i32_e32 v179, 31, v178
	v_lshlrev_b64 v[2:3], 13, v[2:3]
	v_lshl_add_u64 v[4:5], v[0:1], 0, v[4:5]
	v_lshlrev_b64 v[6:7], 13, v[6:7]
	v_lshlrev_b64 v[172:173], 13, v[172:173]
	v_lshlrev_b64 v[174:175], 13, v[174:175]
	v_lshlrev_b64 v[176:177], 13, v[176:177]
	v_lshlrev_b64 v[178:179], 13, v[178:179]
	v_lshlrev_b64 v[180:181], 13, v[180:181]
	v_lshl_add_u64 v[2:3], v[0:1], 0, v[2:3]
	v_lshl_add_u64 v[172:173], v[0:1], 0, v[172:173]
	v_lshl_add_u64 v[6:7], v[0:1], 0, v[6:7]
	v_lshl_add_u64 v[176:177], v[0:1], 0, v[176:177]
	v_lshl_add_u64 v[174:175], v[0:1], 0, v[174:175]
	v_lshl_add_u64 v[180:181], v[0:1], 0, v[180:181]
	v_lshl_add_u64 v[178:179], v[0:1], 0, v[178:179]
	global_load_dword v14, v[4:5], off nt
	global_load_dword v182, v[2:3], off nt
	global_load_dword v183, v[172:173], off nt
	global_load_dword v184, v[6:7], off nt
	global_load_dword v185, v[176:177], off nt
	global_load_dword v186, v[174:175], off nt
	global_load_dword v187, v[180:181], off nt
	global_load_dword v188, v[178:179], off nt
	v_add_u32_e32 v4, s3, v44
	v_add_u32_e32 v6, s3, v41
	v_add_u32_e32 v172, s3, v46
	v_add_u32_e32 v178, s3, v45
	v_add_u32_e32 v180, s3, v50
	v_add_u32_e32 v2, s3, v39
	v_ashrrev_i32_e32 v5, 31, v4
	v_ashrrev_i32_e32 v173, 31, v172
	v_ashrrev_i32_e32 v7, 31, v6
	v_add_u32_e32 v174, s3, v43
	v_add_u32_e32 v176, s3, v48
	v_ashrrev_i32_e32 v181, 31, v180
	v_ashrrev_i32_e32 v179, 31, v178
	v_ashrrev_i32_e32 v3, 31, v2
	v_lshlrev_b64 v[4:5], 13, v[4:5]
	v_lshlrev_b64 v[6:7], 13, v[6:7]
	v_lshlrev_b64 v[172:173], 13, v[172:173]
	v_ashrrev_i32_e32 v177, 31, v176
	v_ashrrev_i32_e32 v175, 31, v174
	v_lshlrev_b64 v[178:179], 13, v[178:179]
	v_lshlrev_b64 v[180:181], 13, v[180:181]
	v_lshlrev_b64 v[2:3], 13, v[2:3]
	v_lshl_add_u64 v[4:5], v[0:1], 0, v[4:5]
	v_lshl_add_u64 v[172:173], v[0:1], 0, v[172:173]
	v_lshl_add_u64 v[6:7], v[0:1], 0, v[6:7]
	v_lshlrev_b64 v[174:175], 13, v[174:175]
	v_lshlrev_b64 v[176:177], 13, v[176:177]
	v_lshl_add_u64 v[180:181], v[0:1], 0, v[180:181]
	v_lshl_add_u64 v[178:179], v[0:1], 0, v[178:179]
	v_lshl_add_u64 v[2:3], v[0:1], 0, v[2:3]
	v_lshl_add_u64 v[176:177], v[0:1], 0, v[176:177]
	v_lshl_add_u64 v[174:175], v[0:1], 0, v[174:175]
	global_load_dword v189, v[4:5], off nt
	global_load_dword v190, v[2:3], off nt
	global_load_dword v191, v[172:173], off nt
	global_load_dword v192, v[6:7], off nt
	global_load_dword v193, v[176:177], off nt
	global_load_dword v194, v[174:175], off nt
	s_nop 0
	global_load_dword v180, v[180:181], off nt
	s_nop 0
	global_load_dword v178, v[178:179], off nt
	v_add_u32_e32 v4, s3, v52
	v_add_u32_e32 v6, s3, v49
	v_add_u32_e32 v172, s3, v54
	v_add_u32_e32 v2, s3, v47
	v_ashrrev_i32_e32 v5, 31, v4
	v_ashrrev_i32_e32 v173, 31, v172
	v_ashrrev_i32_e32 v7, 31, v6
	v_add_u32_e32 v174, s3, v51
	v_add_u32_e32 v176, s3, v56
	v_ashrrev_i32_e32 v3, 31, v2
	v_lshlrev_b64 v[4:5], 13, v[4:5]
	v_lshlrev_b64 v[6:7], 13, v[6:7]
	v_lshlrev_b64 v[172:173], 13, v[172:173]
	v_ashrrev_i32_e32 v177, 31, v176
	v_ashrrev_i32_e32 v175, 31, v174
	v_lshlrev_b64 v[2:3], 13, v[2:3]
	v_lshl_add_u64 v[4:5], v[0:1], 0, v[4:5]
	v_lshl_add_u64 v[172:173], v[0:1], 0, v[172:173]
	v_lshl_add_u64 v[6:7], v[0:1], 0, v[6:7]
	v_lshlrev_b64 v[174:175], 13, v[174:175]
	v_lshlrev_b64 v[176:177], 13, v[176:177]
	v_lshl_add_u64 v[2:3], v[0:1], 0, v[2:3]
	v_lshl_add_u64 v[176:177], v[0:1], 0, v[176:177]
	v_lshl_add_u64 v[174:175], v[0:1], 0, v[174:175]
	global_load_dword v179, v[4:5], off nt
	global_load_dword v181, v[2:3], off nt
	s_nop 0
	global_load_dword v172, v[172:173], off nt
	s_nop 0
	global_load_dword v6, v[6:7], off nt
	s_nop 0
	global_load_dword v7, v[176:177], off nt
	global_load_dword v173, v[174:175], off nt
	v_add_u32_e32 v4, s3, v58
	v_add_u32_e32 v2, s3, v53
	v_ashrrev_i32_e32 v5, 31, v4
	v_ashrrev_i32_e32 v3, 31, v2
	v_lshlrev_b64 v[4:5], 13, v[4:5]
	v_lshlrev_b64 v[2:3], 13, v[2:3]
	v_lshl_add_u64 v[4:5], v[0:1], 0, v[4:5]
	global_load_dword v4, v[4:5], off nt
	v_lshl_add_u64 v[2:3], v[0:1], 0, v[2:3]
	global_load_dword v2, v[2:3], off nt
	v_add_u32_e32 v3, v97, v108
	v_add_u32_e32 v174, s3, v59
	v_add_u32_e32 v176, s3, v64
	v_ashrrev_i32_e32 v177, 31, v176
	s_waitcnt vmcnt(23)
	ds_write_b32 v3, v14
	v_add_u32_e32 v3, v97, v109
	s_waitcnt vmcnt(22)
	ds_write_b32 v3, v182
	v_add_u32_e32 v3, v97, v110
	s_waitcnt vmcnt(21)
	ds_write_b32 v3, v183
	v_add_u32_e32 v3, v97, v111
	s_waitcnt vmcnt(20)
	ds_write_b32 v3, v184
	v_add_u32_e32 v3, v97, v112
	s_waitcnt vmcnt(19)
	ds_write_b32 v3, v185
	v_add_u32_e32 v3, v97, v113
	s_waitcnt vmcnt(18)
	ds_write_b32 v3, v186
	v_add_u32_e32 v3, v97, v114
	s_waitcnt vmcnt(17)
	ds_write_b32 v3, v187
	v_add_u32_e32 v3, v97, v115
	s_waitcnt vmcnt(16)
; #define LDS_WAIT() asm volatile("s_waitcnt lgkmcnt(0)" ::: "memory")
;     ...
; #pragma unroll 32
;     for (int i = 0; i < 64; ++i) { const int kk = 2 * i + (lane >> 5); scr[kk * 33 + (lane & 31)] = W[(size_t)(k0 + kk) * N + n0 + (lane & 31)]; }
;     LDS_WAIT(); asm volatile("" ::: "memory");
	ds_write_b32 v3, v188
	v_add_u32_e32 v3, v97, v116
	v_ashrrev_i32_e32 v175, 31, v174
	v_lshlrev_b64 v[174:175], 13, v[174:175]
	v_lshlrev_b64 v[176:177], 13, v[176:177]
	v_lshl_add_u64 v[176:177], v[0:1], 0, v[176:177]
	v_lshl_add_u64 v[174:175], v[0:1], 0, v[174:175]
	s_lshl_b32 s10, s3, 1
	s_waitcnt vmcnt(15)
	ds_write_b32 v3, v189
	v_add_u32_e32 v3, v97, v117
	s_waitcnt vmcnt(14)
	ds_write_b32 v3, v190
	v_add_u32_e32 v3, v97, v118
	s_waitcnt vmcnt(13)
	ds_write_b32 v3, v191
	v_add_u32_e32 v3, v97, v119
	s_waitcnt vmcnt(12)
	ds_write_b32 v3, v192
	v_add_u32_e32 v3, v97, v120
	s_waitcnt vmcnt(11)
	ds_write_b32 v3, v193
	v_add_u32_e32 v3, v97, v121
	s_waitcnt vmcnt(10)
	ds_write_b32 v3, v194
	v_add_u32_e32 v3, v97, v122
	s_waitcnt vmcnt(9)
	ds_write_b32 v3, v180
	v_add_u32_e32 v3, v97, v123
	s_waitcnt vmcnt(8)
	ds_write_b32 v3, v178
	v_add_u32_e32 v3, v97, v124
	v_add_u32_e32 v178, s3, v61
	v_add_u32_e32 v180, s3, v66
	s_waitcnt vmcnt(7)
	ds_write_b32 v3, v179
	v_add_u32_e32 v3, v97, v125
	s_waitcnt vmcnt(6)
	ds_write_b32 v3, v181
	v_add_u32_e32 v3, v97, v126
	s_waitcnt vmcnt(5)
	ds_write_b32 v3, v172
	v_add_u32_e32 v3, v97, v127
	s_waitcnt vmcnt(4)
	ds_write_b32 v3, v6
	v_add_u32_e32 v3, v97, v128
	s_waitcnt vmcnt(3)
	ds_write_b32 v3, v7
	v_add_u32_e32 v3, v97, v129
	s_waitcnt vmcnt(2)
	ds_write_b32 v3, v173
	v_add_u32_e32 v3, v97, v130
	v_add_u32_e32 v6, s3, v57
	s_waitcnt vmcnt(1)
	ds_write_b32 v3, v4
	v_add_u32_e32 v3, v97, v131
	v_add_u32_e32 v4, s3, v60
	s_waitcnt vmcnt(0)
	ds_write_b32 v3, v2
	v_add_u32_e32 v2, s3, v55
	v_ashrrev_i32_e32 v5, 31, v4
	v_add_u32_e32 v172, s3, v62
	v_ashrrev_i32_e32 v3, 31, v2
	v_lshlrev_b64 v[4:5], 13, v[4:5]
	v_ashrrev_i32_e32 v173, 31, v172
	v_ashrrev_i32_e32 v7, 31, v6
	v_ashrrev_i32_e32 v181, 31, v180
	v_ashrrev_i32_e32 v179, 31, v178
	v_lshlrev_b64 v[2:3], 13, v[2:3]
	v_lshl_add_u64 v[4:5], v[0:1], 0, v[4:5]
	v_lshlrev_b64 v[6:7], 13, v[6:7]
	v_lshlrev_b64 v[172:173], 13, v[172:173]
	v_lshlrev_b64 v[178:179], 13, v[178:179]
	v_lshlrev_b64 v[180:181], 13, v[180:181]
	v_lshl_add_u64 v[2:3], v[0:1], 0, v[2:3]
	v_lshl_add_u64 v[172:173], v[0:1], 0, v[172:173]
	v_lshl_add_u64 v[6:7], v[0:1], 0, v[6:7]
	v_lshl_add_u64 v[180:181], v[0:1], 0, v[180:181]
	v_lshl_add_u64 v[178:179], v[0:1], 0, v[178:179]
	global_load_dword v14, v[4:5], off nt
	global_load_dword v182, v[2:3], off nt
	global_load_dword v183, v[172:173], off nt
	global_load_dword v184, v[6:7], off nt
	global_load_dword v185, v[176:177], off nt
	global_load_dword v186, v[174:175], off nt
	global_load_dword v187, v[180:181], off nt
	global_load_dword v188, v[178:179], off nt
	v_add_u32_e32 v4, s3, v68
	v_add_u32_e32 v2, s3, v63
	v_ashrrev_i32_e32 v5, 31, v4
	v_add_u32_e32 v6, s3, v65
	v_add_u32_e32 v172, s3, v70
	v_add_u32_e32 v174, s3, v67
	v_add_u32_e32 v176, s3, v72
	v_add_u32_e32 v178, s3, v69
	v_add_u32_e32 v180, s3, v74
	v_ashrrev_i32_e32 v3, 31, v2
	v_lshlrev_b64 v[4:5], 13, v[4:5]
	v_ashrrev_i32_e32 v173, 31, v172
	v_ashrrev_i32_e32 v7, 31, v6
	v_ashrrev_i32_e32 v177, 31, v176
	v_ashrrev_i32_e32 v175, 31, v174
	v_ashrrev_i32_e32 v181, 31, v180
	v_ashrrev_i32_e32 v179, 31, v178
	v_lshlrev_b64 v[2:3], 13, v[2:3]
	v_lshl_add_u64 v[4:5], v[0:1], 0, v[4:5]
	v_lshlrev_b64 v[6:7], 13, v[6:7]
	v_lshlrev_b64 v[172:173], 13, v[172:173]
	v_lshlrev_b64 v[174:175], 13, v[174:175]
	v_lshlrev_b64 v[176:177], 13, v[176:177]
	v_lshlrev_b64 v[178:179], 13, v[178:179]
	v_lshlrev_b64 v[180:181], 13, v[180:181]
	v_lshl_add_u64 v[2:3], v[0:1], 0, v[2:3]
	v_lshl_add_u64 v[172:173], v[0:1], 0, v[172:173]
	v_lshl_add_u64 v[6:7], v[0:1], 0, v[6:7]
	v_lshl_add_u64 v[176:177], v[0:1], 0, v[176:177]
	v_lshl_add_u64 v[174:175], v[0:1], 0, v[174:175]
	v_lshl_add_u64 v[180:181], v[0:1], 0, v[180:181]
	v_lshl_add_u64 v[178:179], v[0:1], 0, v[178:179]
	global_load_dword v189, v[4:5], off nt
	global_load_dword v190, v[2:3], off nt
	global_load_dword v191, v[172:173], off nt
	global_load_dword v192, v[6:7], off nt
	global_load_dword v193, v[176:177], off nt
	global_load_dword v194, v[174:175], off nt
	global_load_dword v195, v[180:181], off nt
	global_load_dword v196, v[178:179], off nt
	v_add_u32_e32 v4, s3, v76
	v_add_u32_e32 v174, s3, v75
	v_add_u32_e32 v176, s3, v80
	v_add_u32_e32 v2, s3, v71
	v_ashrrev_i32_e32 v5, 31, v4
	v_add_u32_e32 v6, s3, v73
	v_add_u32_e32 v172, s3, v78
	v_ashrrev_i32_e32 v177, 31, v176
	v_ashrrev_i32_e32 v175, 31, v174
	v_add_u32_e32 v178, s3, v77
	v_add_u32_e32 v180, s3, v82
	v_ashrrev_i32_e32 v3, 31, v2
	v_lshlrev_b64 v[4:5], 13, v[4:5]
	v_ashrrev_i32_e32 v173, 31, v172
	v_ashrrev_i32_e32 v7, 31, v6
	v_lshlrev_b64 v[174:175], 13, v[174:175]
	v_lshlrev_b64 v[176:177], 13, v[176:177]
	v_ashrrev_i32_e32 v181, 31, v180
	v_ashrrev_i32_e32 v179, 31, v178
	v_lshlrev_b64 v[2:3], 13, v[2:3]
	v_lshl_add_u64 v[4:5], v[0:1], 0, v[4:5]
	v_lshlrev_b64 v[6:7], 13, v[6:7]
	v_lshlrev_b64 v[172:173], 13, v[172:173]
	v_lshl_add_u64 v[176:177], v[0:1], 0, v[176:177]
	v_lshl_add_u64 v[174:175], v[0:1], 0, v[174:175]
	v_lshlrev_b64 v[178:179], 13, v[178:179]
	v_lshlrev_b64 v[180:181], 13, v[180:181]
	v_lshl_add_u64 v[2:3], v[0:1], 0, v[2:3]
	v_lshl_add_u64 v[172:173], v[0:1], 0, v[172:173]
	v_lshl_add_u64 v[6:7], v[0:1], 0, v[6:7]
	v_lshl_add_u64 v[180:181], v[0:1], 0, v[180:181]
	v_lshl_add_u64 v[178:179], v[0:1], 0, v[178:179]
	global_load_dword v197, v[4:5], off nt
	global_load_dword v198, v[2:3], off nt
	global_load_dword v199, v[172:173], off nt
	global_load_dword v200, v[6:7], off nt
	global_load_dword v201, v[176:177], off nt
	global_load_dword v202, v[174:175], off nt
	global_load_dword v203, v[180:181], off nt
	global_load_dword v204, v[178:179], off nt
; #define LDS_WAIT() asm volatile("s_waitcnt lgkmcnt(0)" ::: "memory")
;     ...
; #pragma unroll 32
;     for (int i = 0; i < 64; ++i) { const int kk = 2 * i + (lane >> 5); scr[kk * 33 + (lane & 31)] = W[(size_t)(k0 + kk) * N + n0 + (lane & 31)]; }
;     LDS_WAIT(); asm volatile("" ::: "memory");
	v_add_u32_e32 v4, s3, v84
	v_add_u32_e32 v174, s3, v83
	v_add_u32_e32 v176, s3, v88
	v_add_u32_e32 v2, s3, v79
	v_ashrrev_i32_e32 v5, 31, v4
	v_add_u32_e32 v6, s3, v81
	v_add_u32_e32 v172, s3, v86
	v_ashrrev_i32_e32 v177, 31, v176
	v_ashrrev_i32_e32 v175, 31, v174
	v_add_u32_e32 v178, s3, v85
	v_add_u32_e32 v180, s3, v90
	v_ashrrev_i32_e32 v3, 31, v2
	v_lshlrev_b64 v[4:5], 13, v[4:5]
	v_ashrrev_i32_e32 v173, 31, v172
	v_ashrrev_i32_e32 v7, 31, v6
	v_lshlrev_b64 v[174:175], 13, v[174:175]
	v_lshlrev_b64 v[176:177], 13, v[176:177]
	v_ashrrev_i32_e32 v181, 31, v180
	v_ashrrev_i32_e32 v179, 31, v178
	v_lshlrev_b64 v[2:3], 13, v[2:3]
	v_lshl_add_u64 v[4:5], v[0:1], 0, v[4:5]
	v_lshlrev_b64 v[6:7], 13, v[6:7]
	v_lshlrev_b64 v[172:173], 13, v[172:173]
	v_lshl_add_u64 v[176:177], v[0:1], 0, v[176:177]
	v_lshl_add_u64 v[174:175], v[0:1], 0, v[174:175]
	v_lshlrev_b64 v[178:179], 13, v[178:179]
	v_lshlrev_b64 v[180:181], 13, v[180:181]
	v_lshl_add_u64 v[2:3], v[0:1], 0, v[2:3]
	v_lshl_add_u64 v[172:173], v[0:1], 0, v[172:173]
	v_lshl_add_u64 v[6:7], v[0:1], 0, v[6:7]
	v_lshl_add_u64 v[180:181], v[0:1], 0, v[180:181]
	v_lshl_add_u64 v[178:179], v[0:1], 0, v[178:179]
	global_load_dword v205, v[4:5], off nt
	global_load_dword v206, v[2:3], off nt
	global_load_dword v207, v[172:173], off nt
	global_load_dword v208, v[6:7], off nt
	s_nop 0
	global_load_dword v176, v[176:177], off nt
	s_nop 0
	global_load_dword v174, v[174:175], off nt
	s_nop 0
	global_load_dword v175, v[180:181], off nt
	global_load_dword v177, v[178:179], off nt
	v_add_u32_e32 v4, s3, v92
	v_add_u32_e32 v2, s3, v87
	v_ashrrev_i32_e32 v5, 31, v4
	v_ashrrev_i32_e32 v3, 31, v2
	v_lshlrev_b64 v[4:5], 13, v[4:5]
	v_lshlrev_b64 v[2:3], 13, v[2:3]
	v_lshl_add_u64 v[4:5], v[0:1], 0, v[4:5]
	v_lshl_add_u64 v[2:3], v[0:1], 0, v[2:3]
	global_load_dword v178, v[4:5], off nt
	global_load_dword v179, v[2:3], off nt
	v_add_u32_e32 v4, s3, v94
	v_add_u32_e32 v6, s3, v91
	v_add_u32_e32 v172, s3, v96
	v_add_u32_e32 v2, s3, v89
	v_ashrrev_i32_e32 v5, 31, v4
	v_ashrrev_i32_e32 v173, 31, v172
	v_ashrrev_i32_e32 v7, 31, v6
	v_ashrrev_i32_e32 v3, 31, v2
	v_lshlrev_b64 v[4:5], 13, v[4:5]
	v_lshlrev_b64 v[6:7], 13, v[6:7]
	v_lshlrev_b64 v[172:173], 13, v[172:173]
	v_lshlrev_b64 v[2:3], 13, v[2:3]
	v_lshl_add_u64 v[4:5], v[0:1], 0, v[4:5]
	v_lshl_add_u64 v[172:173], v[0:1], 0, v[172:173]
	v_lshl_add_u64 v[6:7], v[0:1], 0, v[6:7]
	v_lshl_add_u64 v[2:3], v[0:1], 0, v[2:3]
	global_load_dword v180, v[4:5], off nt
	global_load_dword v181, v[2:3], off nt
	s_nop 0
	global_load_dword v172, v[172:173], off nt
	s_nop 0
	global_load_dword v6, v[6:7], off nt
	v_add_u32_e32 v4, s3, v98
	v_add_u32_e32 v2, s3, v93
	v_ashrrev_i32_e32 v5, 31, v4
	v_ashrrev_i32_e32 v3, 31, v2
	v_lshlrev_b64 v[4:5], 13, v[4:5]
	v_lshlrev_b64 v[2:3], 13, v[2:3]
	v_lshl_add_u64 v[4:5], v[0:1], 0, v[4:5]
	global_load_dword v4, v[4:5], off nt
	v_lshl_add_u64 v[0:1], v[0:1], 0, v[2:3]
	global_load_dword v0, v[0:1], off nt
	v_add_u32_e32 v1, v97, v132
	s_waitcnt vmcnt(39)
	ds_write_b32 v1, v14
	v_add_u32_e32 v1, v97, v133
	s_waitcnt vmcnt(38)
	ds_write_b32 v1, v182
	v_add_u32_e32 v1, v97, v134
	s_waitcnt vmcnt(37)
	ds_write_b32 v1, v183
	v_add_u32_e32 v1, v97, v135
	s_waitcnt vmcnt(36)
	ds_write_b32 v1, v184
	v_add_u32_e32 v1, v97, v136
	s_waitcnt vmcnt(35)
	ds_write_b32 v1, v185
	v_add_u32_e32 v1, v97, v137
	s_waitcnt vmcnt(34)
	ds_write_b32 v1, v186
	v_add_u32_e32 v1, v97, v138
	s_waitcnt vmcnt(33)
	ds_write_b32 v1, v187
	v_add_u32_e32 v1, v97, v139
	s_waitcnt vmcnt(32)
	ds_write_b32 v1, v188
	v_add_u32_e32 v1, v97, v140
	s_waitcnt vmcnt(31)
	ds_write_b32 v1, v189
	v_add_u32_e32 v1, v97, v141
	s_waitcnt vmcnt(30)
	ds_write_b32 v1, v190
	v_add_u32_e32 v1, v97, v142
	s_waitcnt vmcnt(29)
	ds_write_b32 v1, v191
	v_add_u32_e32 v1, v97, v143
	s_waitcnt vmcnt(28)
	ds_write_b32 v1, v192
	v_add_u32_e32 v1, v97, v144
	s_waitcnt vmcnt(27)
	ds_write_b32 v1, v193
	v_add_u32_e32 v1, v97, v145
	s_waitcnt vmcnt(26)
	ds_write_b32 v1, v194
	v_add_u32_e32 v1, v97, v146
	s_waitcnt vmcnt(25)
	ds_write_b32 v1, v195
	v_add_u32_e32 v1, v97, v147
	s_waitcnt vmcnt(24)
	ds_write_b32 v1, v196
	v_add_u32_e32 v1, v97, v148
	s_waitcnt vmcnt(23)
	ds_write_b32 v1, v197
	v_add_u32_e32 v1, v97, v149
	s_waitcnt vmcnt(22)
	ds_write_b32 v1, v198
	v_add_u32_e32 v1, v97, v150
	s_waitcnt vmcnt(21)
	ds_write_b32 v1, v199
	v_add_u32_e32 v1, v97, v151
	s_waitcnt vmcnt(20)
	ds_write_b32 v1, v200
	v_add_u32_e32 v1, v97, v152
	s_waitcnt vmcnt(19)
	ds_write_b32 v1, v201
	v_add_u32_e32 v1, v97, v153
	s_waitcnt vmcnt(18)
	ds_write_b32 v1, v202
	v_add_u32_e32 v1, v97, v154
	s_waitcnt vmcnt(17)
	ds_write_b32 v1, v203
	v_add_u32_e32 v1, v97, v155
	s_waitcnt vmcnt(16)
	ds_write_b32 v1, v204
	v_add_u32_e32 v1, v97, v156
	s_waitcnt vmcnt(15)
	ds_write_b32 v1, v205
	v_add_u32_e32 v1, v97, v157
	s_waitcnt vmcnt(14)
	ds_write_b32 v1, v206
	v_add_u32_e32 v1, v97, v158
	s_waitcnt vmcnt(13)
	ds_write_b32 v1, v207
	v_add_u32_e32 v1, v97, v159
	s_waitcnt vmcnt(12)
	ds_write_b32 v1, v208
	v_add_u32_e32 v1, v97, v160
	s_waitcnt vmcnt(11)
	ds_write_b32 v1, v176
	v_add_u32_e32 v1, v97, v161
	s_waitcnt vmcnt(10)
; __device__ __forceinline__ unsigned cvt_pk_bf16(float lo, float hi) { unsigned r; asm volatile("v_cvt_pk_bf16_f32 %0, %1, %2" : "=v"(r) : "v"(lo), "v"(hi)); return r; }
; #define GAS __attribute__((address_space(1)))
; #define LAS __attribute__((address_space(3)))
; #define LDS_WAIT() asm volatile("s_waitcnt lgkmcnt(0)" ::: "memory")
;     ...
;     LDS_WAIT(); asm volatile("" ::: "memory");
;     const int c = lane & 15;
;     float gk[8];
;     if (gain) load8f(gain + k0 + 8 * c, gk); else {
; #pragma unroll
;         for (int e = 0; e < 8; ++e) gk[e] = 1.0f; }
; #pragma unroll
;     for (int j = 0; j < 8; ++j) { const int n = (lane >> 4) + 4 * j; const LAS float* s = scr + (8 * c) * 33 + n;
;         v4u o; o.x = cvt_pk_bf16(s[0 * 33] * gk[0], s[1 * 33] * gk[1]); o.y = cvt_pk_bf16(s[2 * 33] * gk[2], s[3 * 33] * gk[3]); o.z = cvt_pk_bf16(s[4 * 33] * gk[4], s[5 * 33] * gk[5]); o.w = cvt_pk_bf16(s[6 * 33] * gk[6], s[7 * 33] * gk[7]);
;         *(GAS v4u*)(WT + (size_t)(nd0 + n) * K + k0 + 8 * c) = o; }
;     LDS_WAIT(); asm volatile("" ::: "memory");
	ds_write_b32 v1, v174
	v_add_u32_e32 v1, v97, v162
	s_waitcnt vmcnt(9)
	ds_write_b32 v1, v175
	v_add_u32_e32 v1, v97, v163
	s_waitcnt vmcnt(8)
	ds_write_b32 v1, v177
	v_add_u32_e32 v1, v97, v164
	s_waitcnt vmcnt(7)
	ds_write_b32 v1, v178
	v_add_u32_e32 v1, v97, v165
	s_waitcnt vmcnt(6)
	ds_write_b32 v1, v179
	v_add_u32_e32 v1, v97, v166
	s_waitcnt vmcnt(5)
	ds_write_b32 v1, v180
	v_add_u32_e32 v1, v97, v167
	s_waitcnt vmcnt(4)
	ds_write_b32 v1, v181
	v_add_u32_e32 v1, v97, v168
	s_waitcnt vmcnt(3)
	ds_write_b32 v1, v172
	v_add_u32_e32 v1, v97, v169
	s_waitcnt vmcnt(2)
	ds_write_b32 v1, v6
	v_add_u32_e32 v1, v97, v170
	s_waitcnt vmcnt(1)
	ds_write_b32 v1, v4
	v_add_u32_e32 v1, v97, v171
	s_waitcnt vmcnt(0)
	ds_write_b32 v1, v0
	s_waitcnt lgkmcnt(0)
	ds_read2_b32 v[0:1], v100 offset1:33
	s_waitcnt lgkmcnt(0)
	v_cvt_pk_bf16_f32 v0, v0, v1
	ds_read2_b32 v[2:3], v100 offset0:66 offset1:99
	s_waitcnt lgkmcnt(0)
	v_cvt_pk_bf16_f32 v1, v2, v3
	ds_read2_b32 v[2:3], v100 offset0:132 offset1:165
	v_lshl_add_u64 v[6:7], v[34:35], 0, s[10:11]
	v_add_u32_e32 v14, s2, v99
	s_waitcnt lgkmcnt(0)
	v_cvt_pk_bf16_f32 v2, v2, v3
	ds_read2_b32 v[4:5], v100 offset0:198 offset1:231
	s_waitcnt lgkmcnt(0)
	v_cvt_pk_bf16_f32 v3, v4, v5
	v_mad_i64_i32 v[172:173], s[24:25], v14, s51, v[6:7]
	ds_read2_b32 v[4:5], v100 offset0:4 offset1:37
	global_store_dwordx4 v[172:173], v[0:3], off
	v_add_u32_e32 v14, s2, v101
	v_mad_i64_i32 v[172:173], s[24:25], v14, s51, v[6:7]
	s_waitcnt lgkmcnt(0)
	v_cvt_pk_bf16_f32 v0, v4, v5
	ds_read2_b32 v[2:3], v100 offset0:70 offset1:103
	s_waitcnt lgkmcnt(0)
	v_cvt_pk_bf16_f32 v1, v2, v3
	ds_read2_b32 v[2:3], v100 offset0:136 offset1:169
	s_waitcnt lgkmcnt(0)
	v_cvt_pk_bf16_f32 v2, v2, v3
	ds_read2_b32 v[4:5], v100 offset0:202 offset1:235
	s_waitcnt lgkmcnt(0)
	v_cvt_pk_bf16_f32 v3, v4, v5
	ds_read2_b32 v[4:5], v100 offset0:8 offset1:41
	global_store_dwordx4 v[172:173], v[0:3], off
	v_add_u32_e32 v14, s2, v102
	v_mad_i64_i32 v[172:173], s[24:25], v14, s51, v[6:7]
	s_waitcnt lgkmcnt(0)
	v_cvt_pk_bf16_f32 v0, v4, v5
	ds_read2_b32 v[2:3], v100 offset0:74 offset1:107
	s_waitcnt lgkmcnt(0)
	v_cvt_pk_bf16_f32 v1, v2, v3
	ds_read2_b32 v[2:3], v100 offset0:140 offset1:173
	s_waitcnt lgkmcnt(0)
	v_cvt_pk_bf16_f32 v2, v2, v3
	ds_read2_b32 v[4:5], v100 offset0:206 offset1:239
	s_waitcnt lgkmcnt(0)
	v_cvt_pk_bf16_f32 v3, v4, v5
	ds_read2_b32 v[4:5], v100 offset0:12 offset1:45
	global_store_dwordx4 v[172:173], v[0:3], off
	v_add_u32_e32 v14, s2, v103
	v_mad_i64_i32 v[172:173], s[24:25], v14, s51, v[6:7]
	s_waitcnt lgkmcnt(0)
	v_cvt_pk_bf16_f32 v0, v4, v5
	ds_read2_b32 v[2:3], v100 offset0:78 offset1:111
	s_waitcnt lgkmcnt(0)
	v_cvt_pk_bf16_f32 v1, v2, v3
	ds_read2_b32 v[2:3], v100 offset0:144 offset1:177
	s_waitcnt lgkmcnt(0)
	v_cvt_pk_bf16_f32 v2, v2, v3
	ds_read2_b32 v[4:5], v100 offset0:210 offset1:243
	s_waitcnt lgkmcnt(0)
	v_cvt_pk_bf16_f32 v3, v4, v5
	ds_read2_b32 v[4:5], v100 offset0:16 offset1:49
	global_store_dwordx4 v[172:173], v[0:3], off
	v_add_u32_e32 v14, s2, v104
	v_mad_i64_i32 v[172:173], s[24:25], v14, s51, v[6:7]
	s_waitcnt lgkmcnt(0)
	v_cvt_pk_bf16_f32 v0, v4, v5
	ds_read2_b32 v[2:3], v100 offset0:82 offset1:115
	s_waitcnt lgkmcnt(0)
	v_cvt_pk_bf16_f32 v1, v2, v3
	ds_read2_b32 v[2:3], v100 offset0:148 offset1:181
	s_waitcnt lgkmcnt(0)
	v_cvt_pk_bf16_f32 v2, v2, v3
	ds_read2_b32 v[4:5], v100 offset0:214 offset1:247
	s_waitcnt lgkmcnt(0)
	v_cvt_pk_bf16_f32 v3, v4, v5
	ds_read2_b32 v[4:5], v100 offset0:20 offset1:53
	global_store_dwordx4 v[172:173], v[0:3], off
	v_add_u32_e32 v14, s2, v105
	v_mad_i64_i32 v[172:173], s[24:25], v14, s51, v[6:7]
	s_waitcnt lgkmcnt(0)
	v_cvt_pk_bf16_f32 v0, v4, v5
	ds_read2_b32 v[2:3], v100 offset0:86 offset1:119
	s_waitcnt lgkmcnt(0)
	v_cvt_pk_bf16_f32 v1, v2, v3
	ds_read2_b32 v[2:3], v100 offset0:152 offset1:185
	s_waitcnt lgkmcnt(0)
	v_cvt_pk_bf16_f32 v2, v2, v3
	ds_read2_b32 v[4:5], v100 offset0:218 offset1:251
	s_waitcnt lgkmcnt(0)
	v_cvt_pk_bf16_f32 v3, v4, v5
	ds_read2_b32 v[4:5], v100 offset0:24 offset1:57
	global_store_dwordx4 v[172:173], v[0:3], off
	v_add_u32_e32 v14, s2, v106
	v_mad_i64_i32 v[172:173], s[24:25], v14, s51, v[6:7]
	s_waitcnt lgkmcnt(0)
	v_cvt_pk_bf16_f32 v0, v4, v5
	ds_read2_b32 v[2:3], v100 offset0:90 offset1:123
	s_waitcnt lgkmcnt(0)
	v_cvt_pk_bf16_f32 v1, v2, v3
	ds_read2_b32 v[2:3], v100 offset0:156 offset1:189
	s_waitcnt lgkmcnt(0)
	v_cvt_pk_bf16_f32 v2, v2, v3
	ds_read2_b32 v[4:5], v100 offset0:222 offset1:255
	s_waitcnt lgkmcnt(0)
	v_cvt_pk_bf16_f32 v3, v4, v5
	ds_read2_b32 v[4:5], v100 offset0:28 offset1:61
	global_store_dwordx4 v[172:173], v[0:3], off
	s_waitcnt lgkmcnt(0)
	s_nop 0
	v_cvt_pk_bf16_f32 v0, v4, v5
	ds_read2_b32 v[2:3], v100 offset0:94 offset1:127
	s_waitcnt lgkmcnt(0)
	v_cvt_pk_bf16_f32 v1, v2, v3
	ds_read2_b32 v[2:3], v100 offset0:160 offset1:193
	s_waitcnt lgkmcnt(0)
	v_cvt_pk_bf16_f32 v2, v2, v3
	v_add_u32_e32 v3, 0x200, v100
	ds_read2_b32 v[4:5], v3 offset0:98 offset1:131
	s_waitcnt lgkmcnt(0)
	v_cvt_pk_bf16_f32 v3, v4, v5
	v_add_u32_e32 v4, s2, v107
	v_mad_i64_i32 v[4:5], s[2:3], v4, s51, v[6:7]
	global_store_dwordx4 v[4:5], v[0:3], off
	s_waitcnt lgkmcnt(0)

; #define LDS_WAIT() asm volatile("s_waitcnt lgkmcnt(0)" ::: "memory")
;     const int nblk = N / 32, kb = item / nblk, nb = item % nblk, k0 = 128 * kb, n0 = 32 * nb;
;     const int nd0 = GLU ? (n0 < 6144 ? 256 * (n0 >> 7) + (n0 & 127) : 256 * ((n0 - 6144) >> 7) + 128 + ((n0 - 6144) & 127)) : n0;
; #pragma unroll 32
;     for (int i = 0; i < 64; ++i) { const int kk = 2 * i + (lane >> 5); scr[kk * 33 + (lane & 31)] = W[(size_t)(k0 + kk) * N + n0 + (lane & 31)]; }
;     LDS_WAIT(); asm volatile("" ::: "memory");
.LBB0_46:
	s_andn2_b64 vcc, exec, s[2:3]
	s_cbranch_vccnz .LBB0_48
	s_load_dwordx2 s[24:25], s[6:7], 0xb8
	s_and_b32 s2, s41, 0x7e0
	s_lshl_b32 s3, s2, 2
	v_lshlrev_b32_e32 v14, 2, v12
	s_waitcnt lgkmcnt(0)
	s_add_u32 s24, s24, s3
	s_addc_u32 s25, s25, 0
	s_and_b32 s3, s43, 0x380
	v_add_u32_e32 v4, s3, v10
	v_add_u32_e32 v2, s3, v9
	v_ashrrev_i32_e32 v5, 31, v4
	v_add_u32_e32 v6, s3, v11
	v_add_u32_e32 v172, s3, v38
	v_add_u32_e32 v174, s3, v13
	v_add_u32_e32 v176, s3, v40
	v_add_u32_e32 v178, s3, v17
	v_add_u32_e32 v180, s3, v42
	v_lshl_add_u64 v[0:1], s[24:25], 0, v[14:15]
	v_ashrrev_i32_e32 v3, 31, v2
	v_lshlrev_b64 v[4:5], 13, v[4:5]
	v_ashrrev_i32_e32 v173, 31, v172
	v_ashrrev_i32_e32 v7, 31, v6
	v_ashrrev_i32_e32 v177, 31, v176
	v_ashrrev_i32_e32 v175, 31, v174
	v_ashrrev_i32_e32 v181, 31, v180
	v_ashrrev_i32_e32 v179, 31, v178
	v_lshlrev_b64 v[2:3], 13, v[2:3]
	v_lshl_add_u64 v[4:5], v[0:1], 0, v[4:5]
	v_lshlrev_b64 v[6:7], 13, v[6:7]
	v_lshlrev_b64 v[172:173], 13, v[172:173]
	v_lshlrev_b64 v[174:175], 13, v[174:175]
	v_lshlrev_b64 v[176:177], 13, v[176:177]
	v_lshlrev_b64 v[178:179], 13, v[178:179]
	v_lshlrev_b64 v[180:181], 13, v[180:181]
	v_lshl_add_u64 v[2:3], v[0:1], 0, v[2:3]
	v_lshl_add_u64 v[172:173], v[0:1], 0, v[172:173]
	v_lshl_add_u64 v[6:7], v[0:1], 0, v[6:7]
	v_lshl_add_u64 v[176:177], v[0:1], 0, v[176:177]
	v_lshl_add_u64 v[174:175], v[0:1], 0, v[174:175]
	v_lshl_add_u64 v[180:181], v[0:1], 0, v[180:181]
	v_lshl_add_u64 v[178:179], v[0:1], 0, v[178:179]
	global_load_dword v14, v[4:5], off nt
	global_load_dword v182, v[2:3], off nt
	global_load_dword v183, v[172:173], off nt
	global_load_dword v184, v[6:7], off nt
	global_load_dword v185, v[176:177], off nt
	global_load_dword v186, v[174:175], off nt
	global_load_dword v187, v[180:181], off nt
	global_load_dword v188, v[178:179], off nt
	v_add_u32_e32 v4, s3, v44
	v_add_u32_e32 v6, s3, v41
	v_add_u32_e32 v172, s3, v46
	v_add_u32_e32 v178, s3, v45
	v_add_u32_e32 v180, s3, v50
	v_add_u32_e32 v2, s3, v39
	v_ashrrev_i32_e32 v5, 31, v4
	v_ashrrev_i32_e32 v173, 31, v172
	v_ashrrev_i32_e32 v7, 31, v6
	v_add_u32_e32 v174, s3, v43
	v_add_u32_e32 v176, s3, v48
	v_ashrrev_i32_e32 v181, 31, v180
	v_ashrrev_i32_e32 v179, 31, v178
	v_ashrrev_i32_e32 v3, 31, v2
	v_lshlrev_b64 v[4:5], 13, v[4:5]
	v_lshlrev_b64 v[6:7], 13, v[6:7]
	v_lshlrev_b64 v[172:173], 13, v[172:173]
	v_ashrrev_i32_e32 v177, 31, v176
	v_ashrrev_i32_e32 v175, 31, v174
	v_lshlrev_b64 v[178:179], 13, v[178:179]
	v_lshlrev_b64 v[180:181], 13, v[180:181]
	v_lshlrev_b64 v[2:3], 13, v[2:3]
	v_lshl_add_u64 v[4:5], v[0:1], 0, v[4:5]
	v_lshl_add_u64 v[172:173], v[0:1], 0, v[172:173]
	v_lshl_add_u64 v[6:7], v[0:1], 0, v[6:7]
	v_lshlrev_b64 v[174:175], 13, v[174:175]
	v_lshlrev_b64 v[176:177], 13, v[176:177]
	v_lshl_add_u64 v[180:181], v[0:1], 0, v[180:181]
	v_lshl_add_u64 v[178:179], v[0:1], 0, v[178:179]
	v_lshl_add_u64 v[2:3], v[0:1], 0, v[2:3]
	v_lshl_add_u64 v[176:177], v[0:1], 0, v[176:177]
	v_lshl_add_u64 v[174:175], v[0:1], 0, v[174:175]
	global_load_dword v189, v[4:5], off nt
	global_load_dword v190, v[2:3], off nt
	global_load_dword v191, v[172:173], off nt
	global_load_dword v192, v[6:7], off nt
	global_load_dword v193, v[176:177], off nt
	global_load_dword v194, v[174:175], off nt
	s_nop 0
	global_load_dword v180, v[180:181], off nt
	s_nop 0
	global_load_dword v178, v[178:179], off nt
	v_add_u32_e32 v4, s3, v52
	v_add_u32_e32 v6, s3, v49
	v_add_u32_e32 v172, s3, v54
	v_add_u32_e32 v2, s3, v47
	v_ashrrev_i32_e32 v5, 31, v4
	v_ashrrev_i32_e32 v173, 31, v172
	v_ashrrev_i32_e32 v7, 31, v6
	v_add_u32_e32 v174, s3, v51
	v_add_u32_e32 v176, s3, v56
	v_ashrrev_i32_e32 v3, 31, v2
	v_lshlrev_b64 v[4:5], 13, v[4:5]
	v_lshlrev_b64 v[6:7], 13, v[6:7]
	v_lshlrev_b64 v[172:173], 13, v[172:173]
	v_ashrrev_i32_e32 v177, 31, v176
	v_ashrrev_i32_e32 v175, 31, v174
	v_lshlrev_b64 v[2:3], 13, v[2:3]
	v_lshl_add_u64 v[4:5], v[0:1], 0, v[4:5]
	v_lshl_add_u64 v[172:173], v[0:1], 0, v[172:173]
	v_lshl_add_u64 v[6:7], v[0:1], 0, v[6:7]
	v_lshlrev_b64 v[174:175], 13, v[174:175]
	v_lshlrev_b64 v[176:177], 13, v[176:177]
	v_lshl_add_u64 v[2:3], v[0:1], 0, v[2:3]
	v_lshl_add_u64 v[176:177], v[0:1], 0, v[176:177]
	v_lshl_add_u64 v[174:175], v[0:1], 0, v[174:175]
	global_load_dword v179, v[4:5], off nt
	global_load_dword v181, v[2:3], off nt
	s_nop 0
	global_load_dword v172, v[172:173], off nt
	s_nop 0
	global_load_dword v6, v[6:7], off nt
	s_nop 0
	global_load_dword v7, v[176:177], off nt
	global_load_dword v173, v[174:175], off nt
	v_add_u32_e32 v4, s3, v58
	v_add_u32_e32 v2, s3, v53
	v_ashrrev_i32_e32 v5, 31, v4
	v_ashrrev_i32_e32 v3, 31, v2
	v_lshlrev_b64 v[4:5], 13, v[4:5]
	v_lshlrev_b64 v[2:3], 13, v[2:3]
	v_lshl_add_u64 v[4:5], v[0:1], 0, v[4:5]
	global_load_dword v4, v[4:5], off nt
	v_lshl_add_u64 v[2:3], v[0:1], 0, v[2:3]
	global_load_dword v2, v[2:3], off nt
	v_add_u32_e32 v3, v97, v108
	v_add_u32_e32 v174, s3, v59
	v_add_u32_e32 v176, s3, v64
	v_ashrrev_i32_e32 v177, 31, v176
	s_waitcnt vmcnt(23)
	ds_write_b32 v3, v14
	v_add_u32_e32 v3, v97, v109
	s_waitcnt vmcnt(22)
	ds_write_b32 v3, v182
	v_add_u32_e32 v3, v97, v110
	s_waitcnt vmcnt(21)
	ds_write_b32 v3, v183
	v_add_u32_e32 v3, v97, v111
	s_waitcnt vmcnt(20)
	ds_write_b32 v3, v184
	v_add_u32_e32 v3, v97, v112
	s_waitcnt vmcnt(19)
	ds_write_b32 v3, v185
	v_add_u32_e32 v3, v97, v113
	s_waitcnt vmcnt(18)
	ds_write_b32 v3, v186
	v_add_u32_e32 v3, v97, v114
	s_waitcnt vmcnt(17)
	ds_write_b32 v3, v187
	v_add_u32_e32 v3, v97, v115
	s_waitcnt vmcnt(16)
; #define LDS_WAIT() asm volatile("s_waitcnt lgkmcnt(0)" ::: "memory")
;     ...
; #pragma unroll 32
;     for (int i = 0; i < 64; ++i) { const int kk = 2 * i + (lane >> 5); scr[kk * 33 + (lane & 31)] = W[(size_t)(k0 + kk) * N + n0 + (lane & 31)]; }
;     LDS_WAIT(); asm volatile("" ::: "memory");
	ds_write_b32 v3, v188
	v_add_u32_e32 v3, v97, v116
	v_ashrrev_i32_e32 v175, 31, v174
	v_lshlrev_b64 v[174:175], 13, v[174:175]
	v_lshlrev_b64 v[176:177], 13, v[176:177]
	v_lshl_add_u64 v[176:177], v[0:1], 0, v[176:177]
	v_lshl_add_u64 v[174:175], v[0:1], 0, v[174:175]
	s_lshl_b32 s10, s3, 1
	s_waitcnt vmcnt(15)
	ds_write_b32 v3, v189
	v_add_u32_e32 v3, v97, v117
	s_waitcnt vmcnt(14)
	ds_write_b32 v3, v190
	v_add_u32_e32 v3, v97, v118
	s_waitcnt vmcnt(13)
	ds_write_b32 v3, v191
	v_add_u32_e32 v3, v97, v119
	s_waitcnt vmcnt(12)
	ds_write_b32 v3, v192
	v_add_u32_e32 v3, v97, v120
	s_waitcnt vmcnt(11)
	ds_write_b32 v3, v193
	v_add_u32_e32 v3, v97, v121
	s_waitcnt vmcnt(10)
	ds_write_b32 v3, v194
	v_add_u32_e32 v3, v97, v122
	s_waitcnt vmcnt(9)
	ds_write_b32 v3, v180
	v_add_u32_e32 v3, v97, v123
	s_waitcnt vmcnt(8)
	ds_write_b32 v3, v178
	v_add_u32_e32 v3, v97, v124
	v_add_u32_e32 v178, s3, v61
	v_add_u32_e32 v180, s3, v66
	s_waitcnt vmcnt(7)
	ds_write_b32 v3, v179
	v_add_u32_e32 v3, v97, v125
	s_waitcnt vmcnt(6)
	ds_write_b32 v3, v181
	v_add_u32_e32 v3, v97, v126
	s_waitcnt vmcnt(5)
	ds_write_b32 v3, v172
	v_add_u32_e32 v3, v97, v127
	s_waitcnt vmcnt(4)
	ds_write_b32 v3, v6
	v_add_u32_e32 v3, v97, v128
	s_waitcnt vmcnt(3)
	ds_write_b32 v3, v7
	v_add_u32_e32 v3, v97, v129
	s_waitcnt vmcnt(2)
	ds_write_b32 v3, v173
	v_add_u32_e32 v3, v97, v130
	v_add_u32_e32 v6, s3, v57
	s_waitcnt vmcnt(1)
	ds_write_b32 v3, v4
	v_add_u32_e32 v3, v97, v131
	v_add_u32_e32 v4, s3, v60
	s_waitcnt vmcnt(0)
	ds_write_b32 v3, v2
	v_add_u32_e32 v2, s3, v55
	v_ashrrev_i32_e32 v5, 31, v4
	v_add_u32_e32 v172, s3, v62
	v_ashrrev_i32_e32 v3, 31, v2
	v_lshlrev_b64 v[4:5], 13, v[4:5]
	v_ashrrev_i32_e32 v173, 31, v172
	v_ashrrev_i32_e32 v7, 31, v6
	v_ashrrev_i32_e32 v181, 31, v180
	v_ashrrev_i32_e32 v179, 31, v178
	v_lshlrev_b64 v[2:3], 13, v[2:3]
	v_lshl_add_u64 v[4:5], v[0:1], 0, v[4:5]
	v_lshlrev_b64 v[6:7], 13, v[6:7]
	v_lshlrev_b64 v[172:173], 13, v[172:173]
	v_lshlrev_b64 v[178:179], 13, v[178:179]
	v_lshlrev_b64 v[180:181], 13, v[180:181]
	v_lshl_add_u64 v[2:3], v[0:1], 0, v[2:3]
	v_lshl_add_u64 v[172:173], v[0:1], 0, v[172:173]
	v_lshl_add_u64 v[6:7], v[0:1], 0, v[6:7]
	v_lshl_add_u64 v[180:181], v[0:1], 0, v[180:181]
	v_lshl_add_u64 v[178:179], v[0:1], 0, v[178:179]
	global_load_dword v14, v[4:5], off nt
	global_load_dword v182, v[2:3], off nt
	global_load_dword v183, v[172:173], off nt
	global_load_dword v184, v[6:7], off nt
	global_load_dword v185, v[176:177], off nt
	global_load_dword v186, v[174:175], off nt
	global_load_dword v187, v[180:181], off nt
	global_load_dword v188, v[178:179], off nt
	v_add_u32_e32 v4, s3, v68
	v_add_u32_e32 v2, s3, v63
	v_ashrrev_i32_e32 v5, 31, v4
	v_add_u32_e32 v6, s3, v65
	v_add_u32_e32 v172, s3, v70
	v_add_u32_e32 v174, s3, v67
	v_add_u32_e32 v176, s3, v72
	v_add_u32_e32 v178, s3, v69
	v_add_u32_e32 v180, s3, v74
	v_ashrrev_i32_e32 v3, 31, v2
	v_lshlrev_b64 v[4:5], 13, v[4:5]
	v_ashrrev_i32_e32 v173, 31, v172
	v_ashrrev_i32_e32 v7, 31, v6
	v_ashrrev_i32_e32 v177, 31, v176
	v_ashrrev_i32_e32 v175, 31, v174
	v_ashrrev_i32_e32 v181, 31, v180
	v_ashrrev_i32_e32 v179, 31, v178
	v_lshlrev_b64 v[2:3], 13, v[2:3]
	v_lshl_add_u64 v[4:5], v[0:1], 0, v[4:5]
	v_lshlrev_b64 v[6:7], 13, v[6:7]
	v_lshlrev_b64 v[172:173], 13, v[172:173]
	v_lshlrev_b64 v[174:175], 13, v[174:175]
	v_lshlrev_b64 v[176:177], 13, v[176:177]
	v_lshlrev_b64 v[178:179], 13, v[178:179]
	v_lshlrev_b64 v[180:181], 13, v[180:181]
	v_lshl_add_u64 v[2:3], v[0:1], 0, v[2:3]
	v_lshl_add_u64 v[172:173], v[0:1], 0, v[172:173]
	v_lshl_add_u64 v[6:7], v[0:1], 0, v[6:7]
	v_lshl_add_u64 v[176:177], v[0:1], 0, v[176:177]
	v_lshl_add_u64 v[174:175], v[0:1], 0, v[174:175]
	v_lshl_add_u64 v[180:181], v[0:1], 0, v[180:181]
	v_lshl_add_u64 v[178:179], v[0:1], 0, v[178:179]
	global_load_dword v189, v[4:5], off nt
	global_load_dword v190, v[2:3], off nt
	global_load_dword v191, v[172:173], off nt
	global_load_dword v192, v[6:7], off nt
	global_load_dword v193, v[176:177], off nt
	global_load_dword v194, v[174:175], off nt
	global_load_dword v195, v[180:181], off nt
	global_load_dword v196, v[178:179], off nt
	v_add_u32_e32 v4, s3, v76
	v_add_u32_e32 v174, s3, v75
	v_add_u32_e32 v176, s3, v80
	v_add_u32_e32 v2, s3, v71
	v_ashrrev_i32_e32 v5, 31, v4
	v_add_u32_e32 v6, s3, v73
	v_add_u32_e32 v172, s3, v78
	v_ashrrev_i32_e32 v177, 31, v176
	v_ashrrev_i32_e32 v175, 31, v174
	v_add_u32_e32 v178, s3, v77
	v_add_u32_e32 v180, s3, v82
	v_ashrrev_i32_e32 v3, 31, v2
	v_lshlrev_b64 v[4:5], 13, v[4:5]
	v_ashrrev_i32_e32 v173, 31, v172
	v_ashrrev_i32_e32 v7, 31, v6
	v_lshlrev_b64 v[174:175], 13, v[174:175]
	v_lshlrev_b64 v[176:177], 13, v[176:177]
	v_ashrrev_i32_e32 v181, 31, v180
	v_ashrrev_i32_e32 v179, 31, v178
	v_lshlrev_b64 v[2:3], 13, v[2:3]
	v_lshl_add_u64 v[4:5], v[0:1], 0, v[4:5]
	v_lshlrev_b64 v[6:7], 13, v[6:7]
	v_lshlrev_b64 v[172:173], 13, v[172:173]
	v_lshl_add_u64 v[176:177], v[0:1], 0, v[176:177]
	v_lshl_add_u64 v[174:175], v[0:1], 0, v[174:175]
	v_lshlrev_b64 v[178:179], 13, v[178:179]
	v_lshlrev_b64 v[180:181], 13, v[180:181]
	v_lshl_add_u64 v[2:3], v[0:1], 0, v[2:3]
	v_lshl_add_u64 v[172:173], v[0:1], 0, v[172:173]
	v_lshl_add_u64 v[6:7], v[0:1], 0, v[6:7]
	v_lshl_add_u64 v[180:181], v[0:1], 0, v[180:181]
	v_lshl_add_u64 v[178:179], v[0:1], 0, v[178:179]
	global_load_dword v197, v[4:5], off nt
	global_load_dword v198, v[2:3], off nt
	global_load_dword v199, v[172:173], off nt
	global_load_dword v200, v[6:7], off nt
	global_load_dword v201, v[176:177], off nt
	global_load_dword v202, v[174:175], off nt
	global_load_dword v203, v[180:181], off nt
	global_load_dword v204, v[178:179], off nt
; #define LDS_WAIT() asm volatile("s_waitcnt lgkmcnt(0)" ::: "memory")
;     ...
; #pragma unroll 32
;     for (int i = 0; i < 64; ++i) { const int kk = 2 * i + (lane >> 5); scr[kk * 33 + (lane & 31)] = W[(size_t)(k0 + kk) * N + n0 + (lane & 31)]; }
;     LDS_WAIT(); asm volatile("" ::: "memory");
	v_add_u32_e32 v4, s3, v84
	v_add_u32_e32 v174, s3, v83
	v_add_u32_e32 v176, s3, v88
	v_add_u32_e32 v2, s3, v79
	v_ashrrev_i32_e32 v5, 31, v4
	v_add_u32_e32 v6, s3, v81
	v_add_u32_e32 v172, s3, v86
	v_ashrrev_i32_e32 v177, 31, v176
	v_ashrrev_i32_e32 v175, 31, v174
	v_add_u32_e32 v178, s3, v85
	v_add_u32_e32 v180, s3, v90
	v_ashrrev_i32_e32 v3, 31, v2
	v_lshlrev_b64 v[4:5], 13, v[4:5]
	v_ashrrev_i32_e32 v173, 31, v172
	v_ashrrev_i32_e32 v7, 31, v6
	v_lshlrev_b64 v[174:175], 13, v[174:175]
	v_lshlrev_b64 v[176:177], 13, v[176:177]
	v_ashrrev_i32_e32 v181, 31, v180
	v_ashrrev_i32_e32 v179, 31, v178
	v_lshlrev_b64 v[2:3], 13, v[2:3]
	v_lshl_add_u64 v[4:5], v[0:1], 0, v[4:5]
	v_lshlrev_b64 v[6:7], 13, v[6:7]
	v_lshlrev_b64 v[172:173], 13, v[172:173]
	v_lshl_add_u64 v[176:177], v[0:1], 0, v[176:177]
	v_lshl_add_u64 v[174:175], v[0:1], 0, v[174:175]
	v_lshlrev_b64 v[178:179], 13, v[178:179]
	v_lshlrev_b64 v[180:181], 13, v[180:181]
	v_lshl_add_u64 v[2:3], v[0:1], 0, v[2:3]
	v_lshl_add_u64 v[172:173], v[0:1], 0, v[172:173]
	v_lshl_add_u64 v[6:7], v[0:1], 0, v[6:7]
	v_lshl_add_u64 v[180:181], v[0:1], 0, v[180:181]
	v_lshl_add_u64 v[178:179], v[0:1], 0, v[178:179]
	global_load_dword v205, v[4:5], off nt
	global_load_dword v206, v[2:3], off nt
	global_load_dword v207, v[172:173], off nt
	global_load_dword v208, v[6:7], off nt
	s_nop 0
	global_load_dword v176, v[176:177], off nt
	s_nop 0
	global_load_dword v174, v[174:175], off nt
	s_nop 0
	global_load_dword v175, v[180:181], off nt
	global_load_dword v177, v[178:179], off nt
	v_add_u32_e32 v4, s3, v92
	v_add_u32_e32 v2, s3, v87
	v_ashrrev_i32_e32 v5, 31, v4
	v_ashrrev_i32_e32 v3, 31, v2
	v_lshlrev_b64 v[4:5], 13, v[4:5]
	v_lshlrev_b64 v[2:3], 13, v[2:3]
	v_lshl_add_u64 v[4:5], v[0:1], 0, v[4:5]
	v_lshl_add_u64 v[2:3], v[0:1], 0, v[2:3]
	global_load_dword v178, v[4:5], off nt
	global_load_dword v179, v[2:3], off nt
	v_add_u32_e32 v4, s3, v94
	v_add_u32_e32 v6, s3, v91
	v_add_u32_e32 v172, s3, v96
	v_add_u32_e32 v2, s3, v89
	v_ashrrev_i32_e32 v5, 31, v4
	v_ashrrev_i32_e32 v173, 31, v172
	v_ashrrev_i32_e32 v7, 31, v6
	v_ashrrev_i32_e32 v3, 31, v2
	v_lshlrev_b64 v[4:5], 13, v[4:5]
	v_lshlrev_b64 v[6:7], 13, v[6:7]
	v_lshlrev_b64 v[172:173], 13, v[172:173]
	v_lshlrev_b64 v[2:3], 13, v[2:3]
	v_lshl_add_u64 v[4:5], v[0:1], 0, v[4:5]
	v_lshl_add_u64 v[172:173], v[0:1], 0, v[172:173]
	v_lshl_add_u64 v[6:7], v[0:1], 0, v[6:7]
	v_lshl_add_u64 v[2:3], v[0:1], 0, v[2:3]
	global_load_dword v180, v[4:5], off nt
	global_load_dword v181, v[2:3], off nt
	s_nop 0
	global_load_dword v172, v[172:173], off nt
	s_nop 0
	global_load_dword v6, v[6:7], off nt
	v_add_u32_e32 v4, s3, v98
	v_add_u32_e32 v2, s3, v93
	v_ashrrev_i32_e32 v5, 31, v4
	v_ashrrev_i32_e32 v3, 31, v2
	v_lshlrev_b64 v[4:5], 13, v[4:5]
	v_lshlrev_b64 v[2:3], 13, v[2:3]
	v_lshl_add_u64 v[4:5], v[0:1], 0, v[4:5]
	global_load_dword v4, v[4:5], off nt
	v_lshl_add_u64 v[0:1], v[0:1], 0, v[2:3]
	global_load_dword v0, v[0:1], off nt
	v_add_u32_e32 v1, v97, v132
	s_waitcnt vmcnt(39)
	ds_write_b32 v1, v14
	v_add_u32_e32 v1, v97, v133
	s_waitcnt vmcnt(38)
	ds_write_b32 v1, v182
	v_add_u32_e32 v1, v97, v134
	s_waitcnt vmcnt(37)
	ds_write_b32 v1, v183
	v_add_u32_e32 v1, v97, v135
	s_waitcnt vmcnt(36)
	ds_write_b32 v1, v184
	v_add_u32_e32 v1, v97, v136
	s_waitcnt vmcnt(35)
	ds_write_b32 v1, v185
	v_add_u32_e32 v1, v97, v137
	s_waitcnt vmcnt(34)
	ds_write_b32 v1, v186
	v_add_u32_e32 v1, v97, v138
	s_waitcnt vmcnt(33)
	ds_write_b32 v1, v187
	v_add_u32_e32 v1, v97, v139
	s_waitcnt vmcnt(32)
	ds_write_b32 v1, v188
	v_add_u32_e32 v1, v97, v140
	s_waitcnt vmcnt(31)
	ds_write_b32 v1, v189
	v_add_u32_e32 v1, v97, v141
	s_waitcnt vmcnt(30)
	ds_write_b32 v1, v190
	v_add_u32_e32 v1, v97, v142
	s_waitcnt vmcnt(29)
	ds_write_b32 v1, v191
	v_add_u32_e32 v1, v97, v143
	s_waitcnt vmcnt(28)
	ds_write_b32 v1, v192
	v_add_u32_e32 v1, v97, v144
	s_waitcnt vmcnt(27)
	ds_write_b32 v1, v193
	v_add_u32_e32 v1, v97, v145
	s_waitcnt vmcnt(26)
	ds_write_b32 v1, v194
	v_add_u32_e32 v1, v97, v146
	s_waitcnt vmcnt(25)
	ds_write_b32 v1, v195
	v_add_u32_e32 v1, v97, v147
	s_waitcnt vmcnt(24)
	ds_write_b32 v1, v196
	v_add_u32_e32 v1, v97, v148
	s_waitcnt vmcnt(23)
	ds_write_b32 v1, v197
	v_add_u32_e32 v1, v97, v149
	s_waitcnt vmcnt(22)
	ds_write_b32 v1, v198
	v_add_u32_e32 v1, v97, v150
	s_waitcnt vmcnt(21)
	ds_write_b32 v1, v199
	v_add_u32_e32 v1, v97, v151
	s_waitcnt vmcnt(20)
	ds_write_b32 v1, v200
	v_add_u32_e32 v1, v97, v152
	s_waitcnt vmcnt(19)
	ds_write_b32 v1, v201
	v_add_u32_e32 v1, v97, v153
	s_waitcnt vmcnt(18)
	ds_write_b32 v1, v202
	v_add_u32_e32 v1, v97, v154
	s_waitcnt vmcnt(17)
	ds_write_b32 v1, v203
	v_add_u32_e32 v1, v97, v155
	s_waitcnt vmcnt(16)
	ds_write_b32 v1, v204
	v_add_u32_e32 v1, v97, v156
	s_waitcnt vmcnt(15)
	ds_write_b32 v1, v205
	v_add_u32_e32 v1, v97, v157
	s_waitcnt vmcnt(14)
	ds_write_b32 v1, v206
	v_add_u32_e32 v1, v97, v158
	s_waitcnt vmcnt(13)
	ds_write_b32 v1, v207
	v_add_u32_e32 v1, v97, v159
	s_waitcnt vmcnt(12)
	ds_write_b32 v1, v208
	v_add_u32_e32 v1, v97, v160
	s_waitcnt vmcnt(11)
	ds_write_b32 v1, v176
	v_add_u32_e32 v1, v97, v161
	s_waitcnt vmcnt(10)
	ds_write_b32 v1, v174
	v_add_u32_e32 v1, v97, v162
	s_waitcnt vmcnt(9)
	ds_write_b32 v1, v175
	v_add_u32_e32 v1, v97, v163
	s_waitcnt vmcnt(8)
	ds_write_b32 v1, v177
	v_add_u32_e32 v1, v97, v164
	s_waitcnt vmcnt(7)
	ds_write_b32 v1, v178
	v_add_u32_e32 v1, v97, v165
	s_waitcnt vmcnt(6)
; __device__ __forceinline__ unsigned cvt_pk_bf16(float lo, float hi) { unsigned r; asm volatile("v_cvt_pk_bf16_f32 %0, %1, %2" : "=v"(r) : "v"(lo), "v"(hi)); return r; }
; #define GAS __attribute__((address_space(1)))
; #define LAS __attribute__((address_space(3)))
; #define LDS_WAIT() asm volatile("s_waitcnt lgkmcnt(0)" ::: "memory")
;     ...
;     LDS_WAIT(); asm volatile("" ::: "memory");
;     const int c = lane & 15;
;     float gk[8];
;     if (gain) load8f(gain + k0 + 8 * c, gk); else {
; #pragma unroll
;         for (int e = 0; e < 8; ++e) gk[e] = 1.0f; }
; #pragma unroll
;     for (int j = 0; j < 8; ++j) { const int n = (lane >> 4) + 4 * j; const LAS float* s = scr + (8 * c) * 33 + n;
;         v4u o; o.x = cvt_pk_bf16(s[0 * 33] * gk[0], s[1 * 33] * gk[1]); o.y = cvt_pk_bf16(s[2 * 33] * gk[2], s[3 * 33] * gk[3]); o.z = cvt_pk_bf16(s[4 * 33] * gk[4], s[5 * 33] * gk[5]); o.w = cvt_pk_bf16(s[6 * 33] * gk[6], s[7 * 33] * gk[7]);
;         *(GAS v4u*)(WT + (size_t)(nd0 + n) * K + k0 + 8 * c) = o; }
;     LDS_WAIT(); asm volatile("" ::: "memory");
	ds_write_b32 v1, v179
	v_add_u32_e32 v1, v97, v166
	s_waitcnt vmcnt(5)
	ds_write_b32 v1, v180
	v_add_u32_e32 v1, v97, v167
	s_waitcnt vmcnt(4)
	ds_write_b32 v1, v181
	v_add_u32_e32 v1, v97, v168
	s_waitcnt vmcnt(3)
	ds_write_b32 v1, v172
	v_add_u32_e32 v1, v97, v169
	s_waitcnt vmcnt(2)
	ds_write_b32 v1, v6
	v_add_u32_e32 v1, v97, v170
	s_waitcnt vmcnt(1)
	ds_write_b32 v1, v4
	v_add_u32_e32 v1, v97, v171
	s_waitcnt vmcnt(0)
	ds_write_b32 v1, v0
	s_waitcnt lgkmcnt(0)
	ds_read2_b32 v[0:1], v100 offset1:33
	s_waitcnt lgkmcnt(0)
	v_cvt_pk_bf16_f32 v0, v0, v1
	ds_read2_b32 v[2:3], v100 offset0:66 offset1:99
	s_waitcnt lgkmcnt(0)
	v_cvt_pk_bf16_f32 v1, v2, v3
	ds_read2_b32 v[2:3], v100 offset0:132 offset1:165
	s_waitcnt lgkmcnt(0)
	v_cvt_pk_bf16_f32 v2, v2, v3
	ds_read2_b32 v[4:5], v100 offset0:198 offset1:231
	s_waitcnt lgkmcnt(0)
	v_cvt_pk_bf16_f32 v3, v4, v5
	v_add_u32_e32 v4, s2, v99
	v_ashrrev_i32_e32 v5, 31, v4
	v_lshl_add_u64 v[6:7], v[20:21], 0, s[10:11]
	v_lshlrev_b64 v[4:5], 11, v[4:5]
	v_lshl_add_u64 v[4:5], v[6:7], 0, v[4:5]
	ds_read2_b32 v[172:173], v100 offset0:4 offset1:37
	global_store_dwordx4 v[4:5], v[0:3], off
	s_waitcnt lgkmcnt(0)
	s_nop 0
	v_cvt_pk_bf16_f32 v0, v172, v173
	ds_read2_b32 v[2:3], v100 offset0:70 offset1:103
	s_waitcnt lgkmcnt(0)
	v_cvt_pk_bf16_f32 v1, v2, v3
	ds_read2_b32 v[2:3], v100 offset0:136 offset1:169
	s_waitcnt lgkmcnt(0)
	v_cvt_pk_bf16_f32 v2, v2, v3
	ds_read2_b32 v[4:5], v100 offset0:202 offset1:235
	s_waitcnt lgkmcnt(0)
	v_cvt_pk_bf16_f32 v3, v4, v5
	v_add_u32_e32 v4, s2, v101
	v_ashrrev_i32_e32 v5, 31, v4
	v_lshlrev_b64 v[4:5], 11, v[4:5]
	v_lshl_add_u64 v[4:5], v[6:7], 0, v[4:5]
	ds_read2_b32 v[172:173], v100 offset0:8 offset1:41
	global_store_dwordx4 v[4:5], v[0:3], off
	s_waitcnt lgkmcnt(0)
	s_nop 0
	v_cvt_pk_bf16_f32 v0, v172, v173
	ds_read2_b32 v[2:3], v100 offset0:74 offset1:107
	s_waitcnt lgkmcnt(0)
	v_cvt_pk_bf16_f32 v1, v2, v3
	ds_read2_b32 v[2:3], v100 offset0:140 offset1:173
	s_waitcnt lgkmcnt(0)
	v_cvt_pk_bf16_f32 v2, v2, v3
	ds_read2_b32 v[4:5], v100 offset0:206 offset1:239
	s_waitcnt lgkmcnt(0)
	v_cvt_pk_bf16_f32 v3, v4, v5
	v_add_u32_e32 v4, s2, v102
	v_ashrrev_i32_e32 v5, 31, v4
	v_lshlrev_b64 v[4:5], 11, v[4:5]
	v_lshl_add_u64 v[4:5], v[6:7], 0, v[4:5]
	ds_read2_b32 v[172:173], v100 offset0:12 offset1:45
	global_store_dwordx4 v[4:5], v[0:3], off
	s_waitcnt lgkmcnt(0)
	s_nop 0
	v_cvt_pk_bf16_f32 v0, v172, v173
	ds_read2_b32 v[2:3], v100 offset0:78 offset1:111
	s_waitcnt lgkmcnt(0)
	v_cvt_pk_bf16_f32 v1, v2, v3
	ds_read2_b32 v[2:3], v100 offset0:144 offset1:177
	s_waitcnt lgkmcnt(0)
	v_cvt_pk_bf16_f32 v2, v2, v3
	ds_read2_b32 v[4:5], v100 offset0:210 offset1:243
	s_waitcnt lgkmcnt(0)
	v_cvt_pk_bf16_f32 v3, v4, v5
	v_add_u32_e32 v4, s2, v103
	v_ashrrev_i32_e32 v5, 31, v4
	v_lshlrev_b64 v[4:5], 11, v[4:5]
	v_lshl_add_u64 v[4:5], v[6:7], 0, v[4:5]
	ds_read2_b32 v[172:173], v100 offset0:16 offset1:49
	global_store_dwordx4 v[4:5], v[0:3], off
	s_waitcnt lgkmcnt(0)
	s_nop 0
	v_cvt_pk_bf16_f32 v0, v172, v173
	ds_read2_b32 v[2:3], v100 offset0:82 offset1:115
	s_waitcnt lgkmcnt(0)
	v_cvt_pk_bf16_f32 v1, v2, v3
	ds_read2_b32 v[2:3], v100 offset0:148 offset1:181
	s_waitcnt lgkmcnt(0)
	v_cvt_pk_bf16_f32 v2, v2, v3
	ds_read2_b32 v[4:5], v100 offset0:214 offset1:247
	s_waitcnt lgkmcnt(0)
	v_cvt_pk_bf16_f32 v3, v4, v5
	v_add_u32_e32 v4, s2, v104
	v_ashrrev_i32_e32 v5, 31, v4
	v_lshlrev_b64 v[4:5], 11, v[4:5]
	v_lshl_add_u64 v[4:5], v[6:7], 0, v[4:5]
	ds_read2_b32 v[172:173], v100 offset0:20 offset1:53
	global_store_dwordx4 v[4:5], v[0:3], off
	s_waitcnt lgkmcnt(0)
	s_nop 0
	v_cvt_pk_bf16_f32 v0, v172, v173
	ds_read2_b32 v[2:3], v100 offset0:86 offset1:119
	s_waitcnt lgkmcnt(0)
	v_cvt_pk_bf16_f32 v1, v2, v3
	ds_read2_b32 v[2:3], v100 offset0:152 offset1:185
	s_waitcnt lgkmcnt(0)
	v_cvt_pk_bf16_f32 v2, v2, v3
	ds_read2_b32 v[4:5], v100 offset0:218 offset1:251
	s_waitcnt lgkmcnt(0)
	v_cvt_pk_bf16_f32 v3, v4, v5
	v_add_u32_e32 v4, s2, v105
	v_ashrrev_i32_e32 v5, 31, v4
	v_lshlrev_b64 v[4:5], 11, v[4:5]
	v_lshl_add_u64 v[4:5], v[6:7], 0, v[4:5]
	ds_read2_b32 v[172:173], v100 offset0:24 offset1:57
	global_store_dwordx4 v[4:5], v[0:3], off
	s_waitcnt lgkmcnt(0)
	s_nop 0
	v_cvt_pk_bf16_f32 v0, v172, v173
	ds_read2_b32 v[2:3], v100 offset0:90 offset1:123
	s_waitcnt lgkmcnt(0)
	v_cvt_pk_bf16_f32 v1, v2, v3
	ds_read2_b32 v[2:3], v100 offset0:156 offset1:189
	s_waitcnt lgkmcnt(0)
	v_cvt_pk_bf16_f32 v2, v2, v3
	ds_read2_b32 v[4:5], v100 offset0:222 offset1:255
	s_waitcnt lgkmcnt(0)
	v_cvt_pk_bf16_f32 v3, v4, v5
	v_add_u32_e32 v4, s2, v106
	v_ashrrev_i32_e32 v5, 31, v4
	v_lshlrev_b64 v[4:5], 11, v[4:5]
	v_lshl_add_u64 v[4:5], v[6:7], 0, v[4:5]
	ds_read2_b32 v[172:173], v100 offset0:28 offset1:61
	global_store_dwordx4 v[4:5], v[0:3], off
	s_waitcnt lgkmcnt(0)
	s_nop 0
	v_cvt_pk_bf16_f32 v0, v172, v173
	ds_read2_b32 v[2:3], v100 offset0:94 offset1:127
	s_waitcnt lgkmcnt(0)
	v_cvt_pk_bf16_f32 v1, v2, v3
	ds_read2_b32 v[2:3], v100 offset0:160 offset1:193
	s_waitcnt lgkmcnt(0)
	v_cvt_pk_bf16_f32 v2, v2, v3
	v_add_u32_e32 v3, 0x200, v100
	ds_read2_b32 v[4:5], v3 offset0:98 offset1:131
	s_waitcnt lgkmcnt(0)
	v_cvt_pk_bf16_f32 v3, v4, v5
	v_add_u32_e32 v4, s2, v107
	v_ashrrev_i32_e32 v5, 31, v4
	v_lshlrev_b64 v[4:5], 11, v[4:5]
	v_lshl_add_u64 v[4:5], v[6:7], 0, v[4:5]
	global_store_dwordx4 v[4:5], v[0:3], off
	s_waitcnt lgkmcnt(0)

; #define LDS_WAIT() asm volatile("s_waitcnt lgkmcnt(0)" ::: "memory")
;     const int nblk = N / 32, kb = item / nblk, nb = item % nblk, k0 = 128 * kb, n0 = 32 * nb;
;     const int nd0 = GLU ? (n0 < 6144 ? 256 * (n0 >> 7) + (n0 & 127) : 256 * ((n0 - 6144) >> 7) + 128 + ((n0 - 6144) & 127)) : n0;
; #pragma unroll 32
;     for (int i = 0; i < 64; ++i) { const int kk = 2 * i + (lane >> 5); scr[kk * 33 + (lane & 31)] = W[(size_t)(k0 + kk) * N + n0 + (lane & 31)]; }
;     LDS_WAIT(); asm volatile("" ::: "memory");
;     ...
;     float gk[8];
;     if (gain) load8f(gain + k0 + 8 * c, gk); else {
.LBB0_49:
	s_andn2_b64 vcc, exec, s[2:3]
	s_cbranch_vccnz .LBB0_51
	s_add_i32 s2, s56, 0x7400
	s_and_b32 s3, s2, 0xffff
	s_mul_i32 s3, s3, 0xe38f
	s_lshr_b32 s10, s3, 24
	s_load_dwordx2 s[38:39], s[6:7], 0xb0
	s_mul_i32 s3, s10, 0x120
	s_sub_i32 s2, s2, s3
	s_lshl_b32 s2, s2, 5
	s_and_b32 s24, s2, 0xffe0
	s_lshl_b32 s25, s24, 2
	s_load_dwordx2 s[2:3], s[6:7], 0x40
	s_waitcnt lgkmcnt(0)
	s_add_u32 s38, s38, s25
	s_addc_u32 s39, s39, 0
	v_lshlrev_b32_e32 v14, 2, v12
	s_lshl_b32 s25, s10, 7
	v_lshl_add_u64 v[0:1], s[38:39], 0, v[14:15]
	v_add_u32_e32 v14, s25, v11
	v_add_u32_e32 v2, s25, v10
	v_mad_i64_i32 v[172:173], s[38:39], v14, s52, v[0:1]
	v_add_u32_e32 v14, s25, v13
	v_add_u32_e32 v4, s25, v9
	v_mad_i64_i32 v[2:3], s[38:39], v2, s52, v[0:1]
	v_add_u32_e32 v6, s25, v38
	v_add_u32_e32 v174, s25, v40
	v_mad_i64_i32 v[176:177], s[38:39], v14, s52, v[0:1]
	v_add_u32_e32 v14, s25, v17
	v_add_u32_e32 v178, s25, v42
	v_mad_i64_i32 v[4:5], s[38:39], v4, s52, v[0:1]
	v_mad_i64_i32 v[6:7], s[38:39], v6, s52, v[0:1]
	v_mad_i64_i32 v[174:175], s[38:39], v174, s52, v[0:1]
	v_mad_i64_i32 v[178:179], s[38:39], v178, s52, v[0:1]
	v_mad_i64_i32 v[180:181], s[38:39], v14, s52, v[0:1]
	global_load_dword v14, v[2:3], off nt
	global_load_dword v182, v[4:5], off nt
	global_load_dword v183, v[6:7], off nt
	global_load_dword v184, v[172:173], off nt
	global_load_dword v185, v[174:175], off nt
	global_load_dword v186, v[176:177], off nt
	global_load_dword v187, v[178:179], off nt
	global_load_dword v188, v[180:181], off nt
	v_add_u32_e32 v2, s25, v44
	v_add_u32_e32 v176, s25, v43
	v_add_u32_e32 v178, s25, v50
	v_add_u32_e32 v4, s25, v39
	v_mad_i64_i32 v[2:3], s[38:39], v2, s52, v[0:1]
	v_add_u32_e32 v172, s25, v41
	v_add_u32_e32 v6, s25, v46
	v_add_u32_e32 v174, s25, v48
	v_mad_i64_i32 v[176:177], s[38:39], v176, s52, v[0:1]
	v_add_u32_e32 v180, s25, v45
	v_mad_i64_i32 v[178:179], s[38:39], v178, s52, v[0:1]
	v_mad_i64_i32 v[4:5], s[38:39], v4, s52, v[0:1]
	v_mad_i64_i32 v[6:7], s[38:39], v6, s52, v[0:1]
	v_mad_i64_i32 v[172:173], s[38:39], v172, s52, v[0:1]
	v_mad_i64_i32 v[174:175], s[38:39], v174, s52, v[0:1]
	v_mad_i64_i32 v[180:181], s[38:39], v180, s52, v[0:1]
	global_load_dword v189, v[2:3], off nt
	global_load_dword v190, v[4:5], off nt
	global_load_dword v191, v[6:7], off nt
	global_load_dword v192, v[172:173], off nt
	global_load_dword v193, v[174:175], off nt
	s_nop 0
	global_load_dword v176, v[176:177], off nt
	s_nop 0
	global_load_dword v177, v[178:179], off nt
	s_nop 0
	global_load_dword v178, v[180:181], off nt
	v_add_u32_e32 v2, s25, v52
	v_mad_i64_i32 v[2:3], s[38:39], v2, s52, v[0:1]
	global_load_dword v179, v[2:3], off nt
	v_add_u32_e32 v4, s25, v47
	v_add_u32_e32 v6, s25, v49
	v_add_u32_e32 v2, s25, v54
	v_mad_i64_i32 v[4:5], s[38:39], v4, s52, v[0:1]
	v_mad_i64_i32 v[2:3], s[38:39], v2, s52, v[0:1]
	v_mad_i64_i32 v[6:7], s[38:39], v6, s52, v[0:1]
	v_add_u32_e32 v172, s25, v56
	v_add_u32_e32 v174, s25, v51
	v_mad_i64_i32 v[172:173], s[38:39], v172, s52, v[0:1]
	global_load_dword v4, v[4:5], off nt
	s_nop 0
	global_load_dword v5, v[2:3], off nt
	s_nop 0
	global_load_dword v6, v[6:7], off nt
	s_nop 0
	global_load_dword v7, v[172:173], off nt
	v_add_u32_e32 v2, s25, v58
	v_mad_i64_i32 v[174:175], s[38:39], v174, s52, v[0:1]
	v_add_u32_e32 v172, s25, v53
	v_mad_i64_i32 v[2:3], s[38:39], v2, s52, v[0:1]
	global_load_dword v173, v[174:175], off nt
	s_nop 0
	global_load_dword v174, v[2:3], off nt
	v_mad_i64_i32 v[2:3], s[38:39], v172, s52, v[0:1]
	global_load_dword v2, v[2:3], off nt
	v_add_u32_e32 v3, v97, v108
	s_waitcnt vmcnt(23)
	ds_write_b32 v3, v14
	v_add_u32_e32 v3, v97, v109
	s_waitcnt vmcnt(22)
	ds_write_b32 v3, v182
	v_add_u32_e32 v3, v97, v110
	s_waitcnt vmcnt(21)
	ds_write_b32 v3, v183
	v_add_u32_e32 v3, v97, v111
	s_waitcnt vmcnt(20)
	ds_write_b32 v3, v184
	v_add_u32_e32 v3, v97, v112
	s_waitcnt vmcnt(19)
	ds_write_b32 v3, v185
	v_add_u32_e32 v3, v97, v113
	s_waitcnt vmcnt(18)
	ds_write_b32 v3, v186
	v_add_u32_e32 v3, v97, v114
	s_waitcnt vmcnt(17)
	ds_write_b32 v3, v187
	v_add_u32_e32 v3, v97, v115
	s_waitcnt vmcnt(16)
	ds_write_b32 v3, v188
	v_add_u32_e32 v3, v97, v116
	v_add_u32_e32 v14, s25, v57
	s_waitcnt vmcnt(15)
	ds_write_b32 v3, v189
	v_add_u32_e32 v3, v97, v117
	s_waitcnt vmcnt(14)
	ds_write_b32 v3, v190
	v_add_u32_e32 v3, v97, v118
	s_waitcnt vmcnt(13)
	ds_write_b32 v3, v191
	v_add_u32_e32 v3, v97, v119
	s_waitcnt vmcnt(12)
	ds_write_b32 v3, v192
	v_add_u32_e32 v3, v97, v120
	s_waitcnt vmcnt(11)
	ds_write_b32 v3, v193
	v_add_u32_e32 v3, v97, v121
	s_waitcnt vmcnt(10)
	ds_write_b32 v3, v176
	v_add_u32_e32 v3, v97, v122
	s_waitcnt vmcnt(9)
	ds_write_b32 v3, v177
	v_add_u32_e32 v3, v97, v123
	s_waitcnt vmcnt(8)
	ds_write_b32 v3, v178
	v_add_u32_e32 v3, v97, v124
	s_waitcnt vmcnt(7)
	ds_write_b32 v3, v179
	v_add_u32_e32 v3, v97, v125
	v_add_u32_e32 v178, s25, v66
	v_mad_i64_i32 v[178:179], s[38:39], v178, s52, v[0:1]
	s_waitcnt vmcnt(6)
	ds_write_b32 v3, v4
	v_add_u32_e32 v3, v97, v126
	s_waitcnt vmcnt(5)
	ds_write_b32 v3, v5
	v_add_u32_e32 v3, v97, v127
	s_waitcnt vmcnt(4)
	ds_write_b32 v3, v6
	v_add_u32_e32 v3, v97, v128
	s_waitcnt vmcnt(3)
	ds_write_b32 v3, v7
	v_add_u32_e32 v3, v97, v129
	v_add_u32_e32 v4, s25, v55
	s_waitcnt vmcnt(2)
	ds_write_b32 v3, v173
	v_add_u32_e32 v3, v97, v130
	s_waitcnt vmcnt(1)
	ds_write_b32 v3, v174
	v_add_u32_e32 v3, v97, v131
	s_waitcnt vmcnt(0)
; #define LDS_WAIT() asm volatile("s_waitcnt lgkmcnt(0)" ::: "memory")
;     ...
; #pragma unroll 32
;     for (int i = 0; i < 64; ++i) { const int kk = 2 * i + (lane >> 5); scr[kk * 33 + (lane & 31)] = W[(size_t)(k0 + kk) * N + n0 + (lane & 31)]; }
;     LDS_WAIT(); asm volatile("" ::: "memory");
	ds_write_b32 v3, v2
	v_add_u32_e32 v2, s25, v60
	v_mad_i64_i32 v[172:173], s[38:39], v14, s52, v[0:1]
	v_add_u32_e32 v14, s25, v59
	v_mad_i64_i32 v[2:3], s[38:39], v2, s52, v[0:1]
	v_add_u32_e32 v6, s25, v62
	v_add_u32_e32 v174, s25, v64
	v_mad_i64_i32 v[176:177], s[38:39], v14, s52, v[0:1]
	v_add_u32_e32 v14, s25, v61
	v_mad_i64_i32 v[4:5], s[38:39], v4, s52, v[0:1]
	v_mad_i64_i32 v[6:7], s[38:39], v6, s52, v[0:1]
	v_mad_i64_i32 v[174:175], s[38:39], v174, s52, v[0:1]
	v_mad_i64_i32 v[180:181], s[38:39], v14, s52, v[0:1]
	global_load_dword v14, v[2:3], off nt
	global_load_dword v182, v[4:5], off nt
	global_load_dword v183, v[6:7], off nt
	global_load_dword v184, v[172:173], off nt
	global_load_dword v185, v[174:175], off nt
	global_load_dword v186, v[176:177], off nt
	global_load_dword v187, v[178:179], off nt
	global_load_dword v188, v[180:181], off nt
	v_add_u32_e32 v2, s25, v68
	v_add_u32_e32 v4, s25, v63
	v_mad_i64_i32 v[2:3], s[38:39], v2, s52, v[0:1]
	v_add_u32_e32 v172, s25, v65
	v_add_u32_e32 v6, s25, v70
	v_add_u32_e32 v176, s25, v67
	v_add_u32_e32 v174, s25, v72
	v_add_u32_e32 v180, s25, v69
	v_add_u32_e32 v178, s25, v74
	v_mad_i64_i32 v[4:5], s[38:39], v4, s52, v[0:1]
	v_mad_i64_i32 v[6:7], s[38:39], v6, s52, v[0:1]
	v_mad_i64_i32 v[172:173], s[38:39], v172, s52, v[0:1]
	v_mad_i64_i32 v[174:175], s[38:39], v174, s52, v[0:1]
	v_mad_i64_i32 v[176:177], s[38:39], v176, s52, v[0:1]
	v_mad_i64_i32 v[178:179], s[38:39], v178, s52, v[0:1]
	v_mad_i64_i32 v[180:181], s[38:39], v180, s52, v[0:1]
	global_load_dword v189, v[2:3], off nt
	global_load_dword v190, v[4:5], off nt
	global_load_dword v191, v[6:7], off nt
	global_load_dword v192, v[172:173], off nt
	global_load_dword v193, v[174:175], off nt
	global_load_dword v194, v[176:177], off nt
	global_load_dword v195, v[178:179], off nt
	global_load_dword v196, v[180:181], off nt
	v_add_u32_e32 v2, s25, v76
	v_add_u32_e32 v4, s25, v71
	v_mad_i64_i32 v[2:3], s[38:39], v2, s52, v[0:1]
	v_add_u32_e32 v172, s25, v73
	v_add_u32_e32 v6, s25, v78
	v_add_u32_e32 v176, s25, v75
	v_add_u32_e32 v174, s25, v80
	v_add_u32_e32 v180, s25, v77
	v_add_u32_e32 v178, s25, v82
	v_mad_i64_i32 v[4:5], s[38:39], v4, s52, v[0:1]
	v_mad_i64_i32 v[6:7], s[38:39], v6, s52, v[0:1]
	v_mad_i64_i32 v[172:173], s[38:39], v172, s52, v[0:1]
	v_mad_i64_i32 v[174:175], s[38:39], v174, s52, v[0:1]
	v_mad_i64_i32 v[176:177], s[38:39], v176, s52, v[0:1]
	v_mad_i64_i32 v[178:179], s[38:39], v178, s52, v[0:1]
	v_mad_i64_i32 v[180:181], s[38:39], v180, s52, v[0:1]
	global_load_dword v197, v[2:3], off nt
	global_load_dword v198, v[4:5], off nt
	global_load_dword v199, v[6:7], off nt
	global_load_dword v200, v[172:173], off nt
	global_load_dword v201, v[174:175], off nt
	global_load_dword v202, v[176:177], off nt
	global_load_dword v203, v[178:179], off nt
	global_load_dword v204, v[180:181], off nt
	v_add_u32_e32 v4, s25, v79
	v_add_u32_e32 v2, s25, v84
	v_add_u32_e32 v6, s25, v86
	v_add_u32_e32 v176, s25, v83
	v_add_u32_e32 v174, s25, v88
	v_mad_i64_i32 v[2:3], s[38:39], v2, s52, v[0:1]
	v_mad_i64_i32 v[4:5], s[38:39], v4, s52, v[0:1]
	v_add_u32_e32 v172, s25, v81
	v_mad_i64_i32 v[6:7], s[38:39], v6, s52, v[0:1]
	v_mad_i64_i32 v[174:175], s[38:39], v174, s52, v[0:1]
	v_mad_i64_i32 v[176:177], s[38:39], v176, s52, v[0:1]
	v_add_u32_e32 v180, s25, v85
	v_add_u32_e32 v178, s25, v90
	v_mad_i64_i32 v[172:173], s[38:39], v172, s52, v[0:1]
	v_mad_i64_i32 v[178:179], s[38:39], v178, s52, v[0:1]
	v_mad_i64_i32 v[180:181], s[38:39], v180, s52, v[0:1]
	global_load_dword v205, v[2:3], off nt
	global_load_dword v206, v[4:5], off nt
	global_load_dword v207, v[6:7], off nt
	global_load_dword v208, v[172:173], off nt
	s_nop 0
	global_load_dword v174, v[174:175], off nt
	s_nop 0
	global_load_dword v175, v[176:177], off nt
	s_nop 0
	global_load_dword v176, v[178:179], off nt
	global_load_dword v177, v[180:181], off nt
	v_add_u32_e32 v4, s25, v87
	v_add_u32_e32 v2, s25, v92
	v_add_u32_e32 v6, s25, v94
	v_mad_i64_i32 v[2:3], s[38:39], v2, s52, v[0:1]
	v_mad_i64_i32 v[4:5], s[38:39], v4, s52, v[0:1]
	v_add_u32_e32 v172, s25, v89
	v_mad_i64_i32 v[6:7], s[38:39], v6, s52, v[0:1]
	v_mad_i64_i32 v[172:173], s[38:39], v172, s52, v[0:1]
	global_load_dword v178, v[2:3], off nt
	global_load_dword v179, v[4:5], off nt
	s_nop 0
	global_load_dword v6, v[6:7], off nt
	s_nop 0
	global_load_dword v7, v[172:173], off nt
	v_add_u32_e32 v4, s25, v91
	v_add_u32_e32 v2, s25, v96
	v_mad_i64_i32 v[2:3], s[38:39], v2, s52, v[0:1]
	v_mad_i64_i32 v[4:5], s[38:39], v4, s52, v[0:1]
	global_load_dword v172, v[2:3], off nt
	s_nop 0
	global_load_dword v4, v[4:5], off nt
	v_add_u32_e32 v2, s25, v98
	v_mad_i64_i32 v[2:3], s[38:39], v2, s52, v[0:1]
	global_load_dword v2, v[2:3], off nt
	v_add_u32_e32 v3, s25, v93
	v_mad_i64_i32 v[0:1], s[38:39], v3, s52, v[0:1]
	global_load_dword v0, v[0:1], off nt
	v_add_u32_e32 v1, v97, v132
	s_waitcnt vmcnt(39)
	ds_write_b32 v1, v14
	v_add_u32_e32 v1, v97, v133
	s_waitcnt vmcnt(38)
	ds_write_b32 v1, v182
	v_add_u32_e32 v1, v97, v134
	s_waitcnt vmcnt(37)
	ds_write_b32 v1, v183
	v_add_u32_e32 v1, v97, v135
	s_waitcnt vmcnt(36)
	ds_write_b32 v1, v184
	v_add_u32_e32 v1, v97, v136
	s_waitcnt vmcnt(35)
	ds_write_b32 v1, v185
	v_add_u32_e32 v1, v97, v137
	s_waitcnt vmcnt(34)
	ds_write_b32 v1, v186
	v_add_u32_e32 v1, v97, v138
	s_waitcnt vmcnt(33)
	ds_write_b32 v1, v187
	v_add_u32_e32 v1, v97, v139
	s_waitcnt vmcnt(32)
	ds_write_b32 v1, v188
	v_add_u32_e32 v1, v97, v140
	s_waitcnt vmcnt(31)
	ds_write_b32 v1, v189
	v_add_u32_e32 v1, v97, v141
	s_waitcnt vmcnt(30)
	ds_write_b32 v1, v190
	v_add_u32_e32 v1, v97, v142
	s_waitcnt vmcnt(29)
; __device__ __forceinline__ unsigned cvt_pk_bf16(float lo, float hi) { unsigned r; asm volatile("v_cvt_pk_bf16_f32 %0, %1, %2" : "=v"(r) : "v"(lo), "v"(hi)); return r; }
; #define GAS __attribute__((address_space(1)))
; #define LAS __attribute__((address_space(3)))
; #define LDS_WAIT() asm volatile("s_waitcnt lgkmcnt(0)" ::: "memory")
;     ...
;     LDS_WAIT(); asm volatile("" ::: "memory");
;     const int c = lane & 15;
;     float gk[8];
;     if (gain) load8f(gain + k0 + 8 * c, gk); else {
; #pragma unroll
;         for (int e = 0; e < 8; ++e) gk[e] = 1.0f; }
; #pragma unroll
;     for (int j = 0; j < 8; ++j) { const int n = (lane >> 4) + 4 * j; const LAS float* s = scr + (8 * c) * 33 + n;
;         v4u o; o.x = cvt_pk_bf16(s[0 * 33] * gk[0], s[1 * 33] * gk[1]); o.y = cvt_pk_bf16(s[2 * 33] * gk[2], s[3 * 33] * gk[3]); o.z = cvt_pk_bf16(s[4 * 33] * gk[4], s[5 * 33] * gk[5]); o.w = cvt_pk_bf16(s[6 * 33] * gk[6], s[7 * 33] * gk[7]);
;         *(GAS v4u*)(WT + (size_t)(nd0 + n) * K + k0 + 8 * c) = o; }
	ds_write_b32 v1, v191
	v_add_u32_e32 v1, v97, v143
	s_waitcnt vmcnt(28)
	ds_write_b32 v1, v192
	v_add_u32_e32 v1, v97, v144
	s_waitcnt vmcnt(27)
	ds_write_b32 v1, v193
	v_add_u32_e32 v1, v97, v145
	s_waitcnt vmcnt(26)
	ds_write_b32 v1, v194
	v_add_u32_e32 v1, v97, v146
	s_waitcnt vmcnt(25)
	ds_write_b32 v1, v195
	v_add_u32_e32 v1, v97, v147
	s_waitcnt vmcnt(24)
	ds_write_b32 v1, v196
	v_add_u32_e32 v1, v97, v148
	s_waitcnt vmcnt(23)
	ds_write_b32 v1, v197
	v_add_u32_e32 v1, v97, v149
	s_waitcnt vmcnt(22)
	ds_write_b32 v1, v198
	v_add_u32_e32 v1, v97, v150
	s_waitcnt vmcnt(21)
	ds_write_b32 v1, v199
	v_add_u32_e32 v1, v97, v151
	s_waitcnt vmcnt(20)
	ds_write_b32 v1, v200
	v_add_u32_e32 v1, v97, v152
	s_waitcnt vmcnt(19)
	ds_write_b32 v1, v201
	v_add_u32_e32 v1, v97, v153
	s_waitcnt vmcnt(18)
	ds_write_b32 v1, v202
	v_add_u32_e32 v1, v97, v154
	s_waitcnt vmcnt(17)
	ds_write_b32 v1, v203
	v_add_u32_e32 v1, v97, v155
	s_waitcnt vmcnt(16)
	ds_write_b32 v1, v204
	v_add_u32_e32 v1, v97, v156
	s_waitcnt vmcnt(15)
	ds_write_b32 v1, v205
	v_add_u32_e32 v1, v97, v157
	s_waitcnt vmcnt(14)
	ds_write_b32 v1, v206
	v_add_u32_e32 v1, v97, v158
	s_waitcnt vmcnt(13)
	ds_write_b32 v1, v207
	v_add_u32_e32 v1, v97, v159
	s_waitcnt vmcnt(12)
	ds_write_b32 v1, v208
	v_add_u32_e32 v1, v97, v160
	s_waitcnt vmcnt(11)
	ds_write_b32 v1, v174
	v_add_u32_e32 v1, v97, v161
	s_waitcnt vmcnt(10)
	ds_write_b32 v1, v175
	v_add_u32_e32 v1, v97, v162
	s_waitcnt vmcnt(9)
	ds_write_b32 v1, v176
	v_add_u32_e32 v1, v97, v163
	s_waitcnt vmcnt(8)
	ds_write_b32 v1, v177
	v_add_u32_e32 v1, v97, v164
	s_waitcnt vmcnt(7)
	ds_write_b32 v1, v178
	v_add_u32_e32 v1, v97, v165
	s_waitcnt vmcnt(6)
	ds_write_b32 v1, v179
	v_add_u32_e32 v1, v97, v166
	s_waitcnt vmcnt(5)
	ds_write_b32 v1, v6
	v_add_u32_e32 v1, v97, v167
	s_waitcnt vmcnt(4)
	ds_write_b32 v1, v7
	v_add_u32_e32 v1, v97, v168
	s_waitcnt vmcnt(3)
	ds_write_b32 v1, v172
	v_add_u32_e32 v1, v97, v169
	s_lshl_b32 s25, s10, 9
	s_waitcnt vmcnt(2)
	ds_write_b32 v1, v4
	v_add_u32_e32 v1, v97, v170
	s_add_u32 s2, s2, s25
	s_waitcnt vmcnt(1)
	ds_write_b32 v1, v2
	v_add_u32_e32 v1, v97, v171
	s_addc_u32 s3, s3, 0
	v_lshlrev_b32_e32 v14, 2, v16
	s_waitcnt vmcnt(0)
	ds_write_b32 v1, v0
	v_lshl_add_u64 v[4:5], s[2:3], 0, v[14:15]
	s_waitcnt lgkmcnt(0)
	v_add_co_u32_e32 v0, vcc, s53, v4
	ds_read2_b32 v[172:173], v100 offset1:33
	s_nop 0
	v_addc_co_u32_e32 v1, vcc, 0, v5, vcc
	global_load_dwordx4 v[0:3], v[0:1], off
	v_lshl_add_u64 v[4:5], v[4:5], 0, s[22:23]
	global_load_dwordx4 v[4:7], v[4:5], off offset:16
	s_lshl_b32 s10, s10, 8
	v_lshl_add_u64 v[178:179], v[22:23], 0, s[10:11]
	s_waitcnt vmcnt(1) lgkmcnt(0)
	v_mul_f32_e32 v14, v0, v172
	v_mul_f32_e32 v172, v1, v173
	v_cvt_pk_bf16_f32 v172, v14, v172
	ds_read2_b32 v[174:175], v100 offset0:66 offset1:99
	s_waitcnt lgkmcnt(0)
	v_mul_f32_e32 v173, v3, v175
	v_mul_f32_e32 v14, v2, v174
	v_cvt_pk_bf16_f32 v173, v14, v173
	ds_read2_b32 v[174:175], v100 offset0:132 offset1:165
	s_waitcnt vmcnt(0) lgkmcnt(0)
	v_mul_f32_e32 v14, v4, v174
	v_mul_f32_e32 v174, v5, v175
	v_cvt_pk_bf16_f32 v174, v14, v174
	ds_read2_b32 v[176:177], v100 offset0:198 offset1:231
	s_waitcnt lgkmcnt(0)
	v_mul_f32_e32 v175, v7, v177
	v_mul_f32_e32 v14, v6, v176
	v_cvt_pk_bf16_f32 v175, v14, v175
	ds_read2_b32 v[180:181], v100 offset0:4 offset1:37
	v_add_u32_e32 v176, s24, v99
	v_ashrrev_i32_e32 v177, 31, v176
	v_lshlrev_b64 v[176:177], 12, v[176:177]
	v_lshl_add_u64 v[176:177], v[178:179], 0, v[176:177]
	global_store_dwordx4 v[176:177], v[172:175], off
	s_waitcnt lgkmcnt(0)
	v_mul_f32_e32 v14, v0, v180
	v_mul_f32_e32 v172, v1, v181
	v_cvt_pk_bf16_f32 v172, v14, v172
	ds_read2_b32 v[174:175], v100 offset0:70 offset1:103
	s_waitcnt lgkmcnt(0)
	v_mul_f32_e32 v173, v3, v175
	v_mul_f32_e32 v14, v2, v174
	v_cvt_pk_bf16_f32 v173, v14, v173
	ds_read2_b32 v[174:175], v100 offset0:136 offset1:169
	s_waitcnt lgkmcnt(0)
	v_mul_f32_e32 v14, v4, v174
	v_mul_f32_e32 v174, v5, v175
	v_cvt_pk_bf16_f32 v174, v14, v174
	ds_read2_b32 v[176:177], v100 offset0:202 offset1:235
	s_waitcnt lgkmcnt(0)
	v_mul_f32_e32 v175, v7, v177
	v_mul_f32_e32 v14, v6, v176
	v_cvt_pk_bf16_f32 v175, v14, v175
	ds_read2_b32 v[180:181], v100 offset0:8 offset1:41
	v_add_u32_e32 v176, s24, v101
	v_ashrrev_i32_e32 v177, 31, v176
	v_lshlrev_b64 v[176:177], 12, v[176:177]
	v_lshl_add_u64 v[176:177], v[178:179], 0, v[176:177]
	global_store_dwordx4 v[176:177], v[172:175], off
	s_waitcnt lgkmcnt(0)
	v_mul_f32_e32 v14, v0, v180
	v_mul_f32_e32 v172, v1, v181
	v_cvt_pk_bf16_f32 v172, v14, v172
	ds_read2_b32 v[174:175], v100 offset0:74 offset1:107
	s_waitcnt lgkmcnt(0)
	v_mul_f32_e32 v173, v3, v175
	v_mul_f32_e32 v14, v2, v174
	v_cvt_pk_bf16_f32 v173, v14, v173
	ds_read2_b32 v[174:175], v100 offset0:140 offset1:173
	s_waitcnt lgkmcnt(0)
; __device__ __forceinline__ unsigned cvt_pk_bf16(float lo, float hi) { unsigned r; asm volatile("v_cvt_pk_bf16_f32 %0, %1, %2" : "=v"(r) : "v"(lo), "v"(hi)); return r; }
; #define GAS __attribute__((address_space(1)))
; #define LAS __attribute__((address_space(3)))
; #define LDS_WAIT() asm volatile("s_waitcnt lgkmcnt(0)" ::: "memory")
;     ...
;     for (int j = 0; j < 8; ++j) { const int n = (lane >> 4) + 4 * j; const LAS float* s = scr + (8 * c) * 33 + n;
;         v4u o; o.x = cvt_pk_bf16(s[0 * 33] * gk[0], s[1 * 33] * gk[1]); o.y = cvt_pk_bf16(s[2 * 33] * gk[2], s[3 * 33] * gk[3]); o.z = cvt_pk_bf16(s[4 * 33] * gk[4], s[5 * 33] * gk[5]); o.w = cvt_pk_bf16(s[6 * 33] * gk[6], s[7 * 33] * gk[7]);
;         *(GAS v4u*)(WT + (size_t)(nd0 + n) * K + k0 + 8 * c) = o; }
;     LDS_WAIT(); asm volatile("" ::: "memory");
	v_mul_f32_e32 v14, v4, v174
	v_mul_f32_e32 v174, v5, v175
	v_cvt_pk_bf16_f32 v174, v14, v174
	ds_read2_b32 v[176:177], v100 offset0:206 offset1:239
	s_waitcnt lgkmcnt(0)
	v_mul_f32_e32 v175, v7, v177
	v_mul_f32_e32 v14, v6, v176
	v_cvt_pk_bf16_f32 v175, v14, v175
	ds_read2_b32 v[180:181], v100 offset0:12 offset1:45
	v_add_u32_e32 v176, s24, v102
	v_ashrrev_i32_e32 v177, 31, v176
	v_lshlrev_b64 v[176:177], 12, v[176:177]
	v_lshl_add_u64 v[176:177], v[178:179], 0, v[176:177]
	global_store_dwordx4 v[176:177], v[172:175], off
	s_waitcnt lgkmcnt(0)
	v_mul_f32_e32 v14, v0, v180
	v_mul_f32_e32 v172, v1, v181
	v_cvt_pk_bf16_f32 v172, v14, v172
	ds_read2_b32 v[174:175], v100 offset0:78 offset1:111
	s_waitcnt lgkmcnt(0)
	v_mul_f32_e32 v173, v3, v175
	v_mul_f32_e32 v14, v2, v174
	v_cvt_pk_bf16_f32 v173, v14, v173
	ds_read2_b32 v[174:175], v100 offset0:144 offset1:177
	s_waitcnt lgkmcnt(0)
	v_mul_f32_e32 v14, v4, v174
	v_mul_f32_e32 v174, v5, v175
	v_cvt_pk_bf16_f32 v174, v14, v174
	ds_read2_b32 v[176:177], v100 offset0:210 offset1:243
	s_waitcnt lgkmcnt(0)
	v_mul_f32_e32 v175, v7, v177
	v_mul_f32_e32 v14, v6, v176
	v_cvt_pk_bf16_f32 v175, v14, v175
	ds_read2_b32 v[180:181], v100 offset0:16 offset1:49
	v_add_u32_e32 v176, s24, v103
	v_ashrrev_i32_e32 v177, 31, v176
	v_lshlrev_b64 v[176:177], 12, v[176:177]
	v_lshl_add_u64 v[176:177], v[178:179], 0, v[176:177]
	global_store_dwordx4 v[176:177], v[172:175], off
	s_waitcnt lgkmcnt(0)
	v_mul_f32_e32 v14, v0, v180
	v_mul_f32_e32 v172, v1, v181
	v_cvt_pk_bf16_f32 v172, v14, v172
	ds_read2_b32 v[174:175], v100 offset0:82 offset1:115
	s_waitcnt lgkmcnt(0)
	v_mul_f32_e32 v173, v3, v175
	v_mul_f32_e32 v14, v2, v174
	v_cvt_pk_bf16_f32 v173, v14, v173
	ds_read2_b32 v[174:175], v100 offset0:148 offset1:181
	s_waitcnt lgkmcnt(0)
	v_mul_f32_e32 v14, v4, v174
	v_mul_f32_e32 v174, v5, v175
	v_cvt_pk_bf16_f32 v174, v14, v174
	ds_read2_b32 v[176:177], v100 offset0:214 offset1:247
	s_waitcnt lgkmcnt(0)
	v_mul_f32_e32 v175, v7, v177
	v_mul_f32_e32 v14, v6, v176
	v_cvt_pk_bf16_f32 v175, v14, v175
	ds_read2_b32 v[180:181], v100 offset0:20 offset1:53
	v_add_u32_e32 v176, s24, v104
	v_ashrrev_i32_e32 v177, 31, v176
	v_lshlrev_b64 v[176:177], 12, v[176:177]
	v_lshl_add_u64 v[176:177], v[178:179], 0, v[176:177]
	global_store_dwordx4 v[176:177], v[172:175], off
	s_waitcnt lgkmcnt(0)
	v_mul_f32_e32 v14, v0, v180
	v_mul_f32_e32 v172, v1, v181
	v_cvt_pk_bf16_f32 v172, v14, v172
	ds_read2_b32 v[174:175], v100 offset0:86 offset1:119
	s_waitcnt lgkmcnt(0)
	v_mul_f32_e32 v173, v3, v175
	v_mul_f32_e32 v14, v2, v174
	v_cvt_pk_bf16_f32 v173, v14, v173
	ds_read2_b32 v[174:175], v100 offset0:152 offset1:185
	s_waitcnt lgkmcnt(0)
	v_mul_f32_e32 v14, v4, v174
	v_mul_f32_e32 v174, v5, v175
	v_cvt_pk_bf16_f32 v174, v14, v174
	ds_read2_b32 v[176:177], v100 offset0:218 offset1:251
	s_waitcnt lgkmcnt(0)
	v_mul_f32_e32 v175, v7, v177
	v_mul_f32_e32 v14, v6, v176
	v_cvt_pk_bf16_f32 v175, v14, v175
	ds_read2_b32 v[180:181], v100 offset0:24 offset1:57
	v_add_u32_e32 v176, s24, v105
	v_ashrrev_i32_e32 v177, 31, v176
	v_lshlrev_b64 v[176:177], 12, v[176:177]
	v_lshl_add_u64 v[176:177], v[178:179], 0, v[176:177]
	global_store_dwordx4 v[176:177], v[172:175], off
	s_waitcnt lgkmcnt(0)
	v_mul_f32_e32 v14, v0, v180
	v_mul_f32_e32 v172, v1, v181
	v_cvt_pk_bf16_f32 v172, v14, v172
	ds_read2_b32 v[174:175], v100 offset0:90 offset1:123
	s_waitcnt lgkmcnt(0)
	v_mul_f32_e32 v173, v3, v175
	v_mul_f32_e32 v14, v2, v174
	v_cvt_pk_bf16_f32 v173, v14, v173
	ds_read2_b32 v[174:175], v100 offset0:156 offset1:189
	s_waitcnt lgkmcnt(0)
	v_mul_f32_e32 v14, v4, v174
	v_mul_f32_e32 v174, v5, v175
	v_cvt_pk_bf16_f32 v174, v14, v174
	ds_read2_b32 v[176:177], v100 offset0:222 offset1:255
	s_waitcnt lgkmcnt(0)
	v_mul_f32_e32 v175, v7, v177
	v_mul_f32_e32 v14, v6, v176
	v_cvt_pk_bf16_f32 v175, v14, v175
	ds_read2_b32 v[180:181], v100 offset0:28 offset1:61
	v_add_u32_e32 v176, s24, v106
	v_ashrrev_i32_e32 v177, 31, v176
	v_lshlrev_b64 v[176:177], 12, v[176:177]
	v_lshl_add_u64 v[176:177], v[178:179], 0, v[176:177]
	s_waitcnt lgkmcnt(0)
	v_mul_f32_e32 v0, v0, v180
	global_store_dwordx4 v[176:177], v[172:175], off
	v_mul_f32_e32 v1, v1, v181
	v_cvt_pk_bf16_f32 v0, v0, v1
	ds_read2_b32 v[172:173], v100 offset0:94 offset1:127
	s_waitcnt lgkmcnt(0)
	v_mul_f32_e32 v1, v2, v172
	v_mul_f32_e32 v2, v3, v173
	v_cvt_pk_bf16_f32 v1, v1, v2
	ds_read2_b32 v[2:3], v100 offset0:160 offset1:193
	s_waitcnt lgkmcnt(0)
	v_mul_f32_e32 v2, v4, v2
	v_mul_f32_e32 v3, v5, v3
	v_cvt_pk_bf16_f32 v2, v2, v3
	v_add_u32_e32 v3, 0x200, v100
	ds_read2_b32 v[4:5], v3 offset0:98 offset1:131
	s_waitcnt lgkmcnt(0)
	v_mul_f32_e32 v3, v6, v4
	v_mul_f32_e32 v4, v7, v5
	v_cvt_pk_bf16_f32 v3, v3, v4
	v_add_u32_e32 v4, s24, v107
	v_ashrrev_i32_e32 v5, 31, v4
	v_lshlrev_b64 v[4:5], 12, v[4:5]
	v_lshl_add_u64 v[4:5], v[178:179], 0, v[4:5]
	global_store_dwordx4 v[4:5], v[0:3], off
	s_waitcnt lgkmcnt(0)

; #define LDS_WAIT() asm volatile("s_waitcnt lgkmcnt(0)" ::: "memory")
;     const int nblk = N / 32, kb = item / nblk, nb = item % nblk, k0 = 128 * kb, n0 = 32 * nb;
;     const int nd0 = GLU ? (n0 < 6144 ? 256 * (n0 >> 7) + (n0 & 127) : 256 * ((n0 - 6144) >> 7) + 128 + ((n0 - 6144) & 127)) : n0;
; #pragma unroll 32
;     for (int i = 0; i < 64; ++i) { const int kk = 2 * i + (lane >> 5); scr[kk * 33 + (lane & 31)] = W[(size_t)(k0 + kk) * N + n0 + (lane & 31)]; }
;     LDS_WAIT(); asm volatile("" ::: "memory");
.LBB0_52:
	s_andn2_b64 vcc, exec, s[2:3]
	s_cbranch_vccnz .LBB0_54
	s_load_dwordx2 s[24:25], s[6:7], 0xa0
	s_and_b32 s2, s41, 0x7e0
	s_lshl_b32 s3, s2, 2
	v_lshlrev_b32_e32 v14, 2, v12
	s_waitcnt lgkmcnt(0)
	s_add_u32 s24, s24, s3
	s_addc_u32 s25, s25, 0
	s_and_b32 s3, s43, 0x780
	v_add_u32_e32 v4, s3, v10
	v_lshl_add_u64 v[0:1], s[24:25], 0, v[14:15]
	v_add_u32_e32 v2, s3, v9
	v_ashrrev_i32_e32 v5, 31, v4
	v_add_u32_e32 v6, s3, v11
	v_add_u32_e32 v172, s3, v38
	v_add_u32_e32 v174, s3, v13
	v_add_u32_e32 v176, s3, v40
	v_add_u32_e32 v178, s3, v17
	v_add_u32_e32 v180, s3, v42
	v_lshl_add_u64 v[0:1], v[0:1], 0, s[0:1]
	v_ashrrev_i32_e32 v3, 31, v2
	v_lshlrev_b64 v[4:5], 13, v[4:5]
	v_ashrrev_i32_e32 v173, 31, v172
	v_ashrrev_i32_e32 v7, 31, v6
	v_ashrrev_i32_e32 v177, 31, v176
	v_ashrrev_i32_e32 v175, 31, v174
	v_ashrrev_i32_e32 v181, 31, v180
	v_ashrrev_i32_e32 v179, 31, v178
	v_lshlrev_b64 v[2:3], 13, v[2:3]
	v_lshl_add_u64 v[4:5], v[0:1], 0, v[4:5]
	v_lshlrev_b64 v[6:7], 13, v[6:7]
	v_lshlrev_b64 v[172:173], 13, v[172:173]
	v_lshlrev_b64 v[174:175], 13, v[174:175]
	v_lshlrev_b64 v[176:177], 13, v[176:177]
	v_lshlrev_b64 v[178:179], 13, v[178:179]
	v_lshlrev_b64 v[180:181], 13, v[180:181]
	v_lshl_add_u64 v[2:3], v[0:1], 0, v[2:3]
	v_lshl_add_u64 v[172:173], v[0:1], 0, v[172:173]
	v_lshl_add_u64 v[6:7], v[0:1], 0, v[6:7]
	v_lshl_add_u64 v[176:177], v[0:1], 0, v[176:177]
	v_lshl_add_u64 v[174:175], v[0:1], 0, v[174:175]
	v_lshl_add_u64 v[180:181], v[0:1], 0, v[180:181]
	v_lshl_add_u64 v[178:179], v[0:1], 0, v[178:179]
	global_load_dword v14, v[4:5], off nt
	global_load_dword v182, v[2:3], off nt
	global_load_dword v183, v[172:173], off nt
	global_load_dword v184, v[6:7], off nt
	global_load_dword v185, v[176:177], off nt
	global_load_dword v186, v[174:175], off nt
	global_load_dword v187, v[180:181], off nt
	global_load_dword v188, v[178:179], off nt
	v_add_u32_e32 v4, s3, v44
	v_add_u32_e32 v6, s3, v41
	v_add_u32_e32 v172, s3, v46
	v_add_u32_e32 v178, s3, v45
	v_add_u32_e32 v180, s3, v50
	v_add_u32_e32 v2, s3, v39
	v_ashrrev_i32_e32 v5, 31, v4
	v_ashrrev_i32_e32 v173, 31, v172
	v_ashrrev_i32_e32 v7, 31, v6
	v_add_u32_e32 v174, s3, v43
	v_add_u32_e32 v176, s3, v48
	v_ashrrev_i32_e32 v181, 31, v180
	v_ashrrev_i32_e32 v179, 31, v178
	v_ashrrev_i32_e32 v3, 31, v2
	v_lshlrev_b64 v[4:5], 13, v[4:5]
	v_lshlrev_b64 v[6:7], 13, v[6:7]
	v_lshlrev_b64 v[172:173], 13, v[172:173]
	v_ashrrev_i32_e32 v177, 31, v176
	v_ashrrev_i32_e32 v175, 31, v174
	v_lshlrev_b64 v[178:179], 13, v[178:179]
	v_lshlrev_b64 v[180:181], 13, v[180:181]
	v_lshlrev_b64 v[2:3], 13, v[2:3]
	v_lshl_add_u64 v[4:5], v[0:1], 0, v[4:5]
	v_lshl_add_u64 v[172:173], v[0:1], 0, v[172:173]
	v_lshl_add_u64 v[6:7], v[0:1], 0, v[6:7]
	v_lshlrev_b64 v[174:175], 13, v[174:175]
	v_lshlrev_b64 v[176:177], 13, v[176:177]
	v_lshl_add_u64 v[180:181], v[0:1], 0, v[180:181]
	v_lshl_add_u64 v[178:179], v[0:1], 0, v[178:179]
	v_lshl_add_u64 v[2:3], v[0:1], 0, v[2:3]
	v_lshl_add_u64 v[176:177], v[0:1], 0, v[176:177]
	v_lshl_add_u64 v[174:175], v[0:1], 0, v[174:175]
	global_load_dword v189, v[4:5], off nt
	global_load_dword v190, v[2:3], off nt
	global_load_dword v191, v[172:173], off nt
	global_load_dword v192, v[6:7], off nt
	global_load_dword v193, v[176:177], off nt
	global_load_dword v194, v[174:175], off nt
	s_nop 0
	global_load_dword v180, v[180:181], off nt
	s_nop 0
	global_load_dword v178, v[178:179], off nt
	v_add_u32_e32 v4, s3, v52
	v_add_u32_e32 v6, s3, v49
	v_add_u32_e32 v172, s3, v54
	v_add_u32_e32 v2, s3, v47
	v_ashrrev_i32_e32 v5, 31, v4
	v_ashrrev_i32_e32 v173, 31, v172
	v_ashrrev_i32_e32 v7, 31, v6
	v_add_u32_e32 v174, s3, v51
	v_add_u32_e32 v176, s3, v56
	v_ashrrev_i32_e32 v3, 31, v2
	v_lshlrev_b64 v[4:5], 13, v[4:5]
	v_lshlrev_b64 v[6:7], 13, v[6:7]
	v_lshlrev_b64 v[172:173], 13, v[172:173]
	v_ashrrev_i32_e32 v177, 31, v176
	v_ashrrev_i32_e32 v175, 31, v174
	v_lshlrev_b64 v[2:3], 13, v[2:3]
	v_lshl_add_u64 v[4:5], v[0:1], 0, v[4:5]
	v_lshl_add_u64 v[172:173], v[0:1], 0, v[172:173]
	v_lshl_add_u64 v[6:7], v[0:1], 0, v[6:7]
	v_lshlrev_b64 v[174:175], 13, v[174:175]
	v_lshlrev_b64 v[176:177], 13, v[176:177]
	v_lshl_add_u64 v[2:3], v[0:1], 0, v[2:3]
	v_lshl_add_u64 v[176:177], v[0:1], 0, v[176:177]
	v_lshl_add_u64 v[174:175], v[0:1], 0, v[174:175]
	global_load_dword v179, v[4:5], off nt
	global_load_dword v181, v[2:3], off nt
	s_nop 0
	global_load_dword v172, v[172:173], off nt
	s_nop 0
	global_load_dword v6, v[6:7], off nt
	s_nop 0
	global_load_dword v7, v[176:177], off nt
	global_load_dword v173, v[174:175], off nt
	v_add_u32_e32 v4, s3, v58
	v_add_u32_e32 v2, s3, v53
	v_ashrrev_i32_e32 v5, 31, v4
	v_ashrrev_i32_e32 v3, 31, v2
	v_lshlrev_b64 v[4:5], 13, v[4:5]
	v_lshlrev_b64 v[2:3], 13, v[2:3]
	v_lshl_add_u64 v[4:5], v[0:1], 0, v[4:5]
	global_load_dword v4, v[4:5], off nt
	v_lshl_add_u64 v[2:3], v[0:1], 0, v[2:3]
	global_load_dword v2, v[2:3], off nt
	v_add_u32_e32 v3, v97, v108
	v_add_u32_e32 v174, s3, v59
	v_add_u32_e32 v176, s3, v64
	v_ashrrev_i32_e32 v177, 31, v176
	s_waitcnt vmcnt(23)
	ds_write_b32 v3, v14
	v_add_u32_e32 v3, v97, v109
	s_waitcnt vmcnt(22)
	ds_write_b32 v3, v182
	v_add_u32_e32 v3, v97, v110
	s_waitcnt vmcnt(21)
	ds_write_b32 v3, v183
	v_add_u32_e32 v3, v97, v111
	s_waitcnt vmcnt(20)
	ds_write_b32 v3, v184
	v_add_u32_e32 v3, v97, v112
	s_waitcnt vmcnt(19)
	ds_write_b32 v3, v185
	v_add_u32_e32 v3, v97, v113
	s_waitcnt vmcnt(18)
	ds_write_b32 v3, v186
	v_add_u32_e32 v3, v97, v114
	s_waitcnt vmcnt(17)
	ds_write_b32 v3, v187
	v_add_u32_e32 v3, v97, v115
	s_waitcnt vmcnt(16)
; #define LDS_WAIT() asm volatile("s_waitcnt lgkmcnt(0)" ::: "memory")
;     ...
; #pragma unroll 32
;     for (int i = 0; i < 64; ++i) { const int kk = 2 * i + (lane >> 5); scr[kk * 33 + (lane & 31)] = W[(size_t)(k0 + kk) * N + n0 + (lane & 31)]; }
;     LDS_WAIT(); asm volatile("" ::: "memory");
	ds_write_b32 v3, v188
	v_add_u32_e32 v3, v97, v116
	v_ashrrev_i32_e32 v175, 31, v174
	v_lshlrev_b64 v[174:175], 13, v[174:175]
	v_lshlrev_b64 v[176:177], 13, v[176:177]
	v_lshl_add_u64 v[176:177], v[0:1], 0, v[176:177]
	v_lshl_add_u64 v[174:175], v[0:1], 0, v[174:175]
	s_lshl_b32 s10, s3, 1
	s_waitcnt vmcnt(15)
	ds_write_b32 v3, v189
	v_add_u32_e32 v3, v97, v117
	s_waitcnt vmcnt(14)
	ds_write_b32 v3, v190
	v_add_u32_e32 v3, v97, v118
	s_waitcnt vmcnt(13)
	ds_write_b32 v3, v191
	v_add_u32_e32 v3, v97, v119
	s_waitcnt vmcnt(12)
	ds_write_b32 v3, v192
	v_add_u32_e32 v3, v97, v120
	s_waitcnt vmcnt(11)
	ds_write_b32 v3, v193
	v_add_u32_e32 v3, v97, v121
	s_waitcnt vmcnt(10)
	ds_write_b32 v3, v194
	v_add_u32_e32 v3, v97, v122
	s_waitcnt vmcnt(9)
	ds_write_b32 v3, v180
	v_add_u32_e32 v3, v97, v123
	s_waitcnt vmcnt(8)
	ds_write_b32 v3, v178
	v_add_u32_e32 v3, v97, v124
	v_add_u32_e32 v178, s3, v61
	v_add_u32_e32 v180, s3, v66
	s_waitcnt vmcnt(7)
	ds_write_b32 v3, v179
	v_add_u32_e32 v3, v97, v125
	s_waitcnt vmcnt(6)
	ds_write_b32 v3, v181
	v_add_u32_e32 v3, v97, v126
	s_waitcnt vmcnt(5)
	ds_write_b32 v3, v172
	v_add_u32_e32 v3, v97, v127
	s_waitcnt vmcnt(4)
	ds_write_b32 v3, v6
	v_add_u32_e32 v3, v97, v128
	s_waitcnt vmcnt(3)
	ds_write_b32 v3, v7
	v_add_u32_e32 v3, v97, v129
	s_waitcnt vmcnt(2)
	ds_write_b32 v3, v173
	v_add_u32_e32 v3, v97, v130
	v_add_u32_e32 v6, s3, v57
	s_waitcnt vmcnt(1)
	ds_write_b32 v3, v4
	v_add_u32_e32 v3, v97, v131
	v_add_u32_e32 v4, s3, v60
	s_waitcnt vmcnt(0)
	ds_write_b32 v3, v2
	v_add_u32_e32 v2, s3, v55
	v_ashrrev_i32_e32 v5, 31, v4
	v_add_u32_e32 v172, s3, v62
	v_ashrrev_i32_e32 v3, 31, v2
	v_lshlrev_b64 v[4:5], 13, v[4:5]
	v_ashrrev_i32_e32 v173, 31, v172
	v_ashrrev_i32_e32 v7, 31, v6
	v_ashrrev_i32_e32 v181, 31, v180
	v_ashrrev_i32_e32 v179, 31, v178
	v_lshlrev_b64 v[2:3], 13, v[2:3]
	v_lshl_add_u64 v[4:5], v[0:1], 0, v[4:5]
	v_lshlrev_b64 v[6:7], 13, v[6:7]
	v_lshlrev_b64 v[172:173], 13, v[172:173]
	v_lshlrev_b64 v[178:179], 13, v[178:179]
	v_lshlrev_b64 v[180:181], 13, v[180:181]
	v_lshl_add_u64 v[2:3], v[0:1], 0, v[2:3]
	v_lshl_add_u64 v[172:173], v[0:1], 0, v[172:173]
	v_lshl_add_u64 v[6:7], v[0:1], 0, v[6:7]
	v_lshl_add_u64 v[180:181], v[0:1], 0, v[180:181]
	v_lshl_add_u64 v[178:179], v[0:1], 0, v[178:179]
	global_load_dword v14, v[4:5], off nt
	global_load_dword v182, v[2:3], off nt
	global_load_dword v183, v[172:173], off nt
	global_load_dword v184, v[6:7], off nt
	global_load_dword v185, v[176:177], off nt
	global_load_dword v186, v[174:175], off nt
	global_load_dword v187, v[180:181], off nt
	global_load_dword v188, v[178:179], off nt
	v_add_u32_e32 v4, s3, v68
	v_add_u32_e32 v2, s3, v63
	v_ashrrev_i32_e32 v5, 31, v4
	v_add_u32_e32 v6, s3, v65
	v_add_u32_e32 v172, s3, v70
	v_add_u32_e32 v174, s3, v67
	v_add_u32_e32 v176, s3, v72
	v_add_u32_e32 v178, s3, v69
	v_add_u32_e32 v180, s3, v74
	v_ashrrev_i32_e32 v3, 31, v2
	v_lshlrev_b64 v[4:5], 13, v[4:5]
	v_ashrrev_i32_e32 v173, 31, v172
	v_ashrrev_i32_e32 v7, 31, v6
	v_ashrrev_i32_e32 v177, 31, v176
	v_ashrrev_i32_e32 v175, 31, v174
	v_ashrrev_i32_e32 v181, 31, v180
	v_ashrrev_i32_e32 v179, 31, v178
	v_lshlrev_b64 v[2:3], 13, v[2:3]
	v_lshl_add_u64 v[4:5], v[0:1], 0, v[4:5]
	v_lshlrev_b64 v[6:7], 13, v[6:7]
	v_lshlrev_b64 v[172:173], 13, v[172:173]
	v_lshlrev_b64 v[174:175], 13, v[174:175]
	v_lshlrev_b64 v[176:177], 13, v[176:177]
	v_lshlrev_b64 v[178:179], 13, v[178:179]
	v_lshlrev_b64 v[180:181], 13, v[180:181]
	v_lshl_add_u64 v[2:3], v[0:1], 0, v[2:3]
	v_lshl_add_u64 v[172:173], v[0:1], 0, v[172:173]
	v_lshl_add_u64 v[6:7], v[0:1], 0, v[6:7]
	v_lshl_add_u64 v[176:177], v[0:1], 0, v[176:177]
	v_lshl_add_u64 v[174:175], v[0:1], 0, v[174:175]
	v_lshl_add_u64 v[180:181], v[0:1], 0, v[180:181]
	v_lshl_add_u64 v[178:179], v[0:1], 0, v[178:179]
	global_load_dword v189, v[4:5], off nt
	global_load_dword v190, v[2:3], off nt
	global_load_dword v191, v[172:173], off nt
	global_load_dword v192, v[6:7], off nt
	global_load_dword v193, v[176:177], off nt
	global_load_dword v194, v[174:175], off nt
	global_load_dword v195, v[180:181], off nt
	global_load_dword v196, v[178:179], off nt
	v_add_u32_e32 v4, s3, v76
	v_add_u32_e32 v174, s3, v75
	v_add_u32_e32 v176, s3, v80
	v_add_u32_e32 v2, s3, v71
	v_ashrrev_i32_e32 v5, 31, v4
	v_add_u32_e32 v6, s3, v73
	v_add_u32_e32 v172, s3, v78
	v_ashrrev_i32_e32 v177, 31, v176
	v_ashrrev_i32_e32 v175, 31, v174
	v_add_u32_e32 v178, s3, v77
	v_add_u32_e32 v180, s3, v82
	v_ashrrev_i32_e32 v3, 31, v2
	v_lshlrev_b64 v[4:5], 13, v[4:5]
	v_ashrrev_i32_e32 v173, 31, v172
	v_ashrrev_i32_e32 v7, 31, v6
	v_lshlrev_b64 v[174:175], 13, v[174:175]
	v_lshlrev_b64 v[176:177], 13, v[176:177]
	v_ashrrev_i32_e32 v181, 31, v180
	v_ashrrev_i32_e32 v179, 31, v178
	v_lshlrev_b64 v[2:3], 13, v[2:3]
	v_lshl_add_u64 v[4:5], v[0:1], 0, v[4:5]
	v_lshlrev_b64 v[6:7], 13, v[6:7]
	v_lshlrev_b64 v[172:173], 13, v[172:173]
	v_lshl_add_u64 v[176:177], v[0:1], 0, v[176:177]
	v_lshl_add_u64 v[174:175], v[0:1], 0, v[174:175]
	v_lshlrev_b64 v[178:179], 13, v[178:179]
	v_lshlrev_b64 v[180:181], 13, v[180:181]
	v_lshl_add_u64 v[2:3], v[0:1], 0, v[2:3]
	v_lshl_add_u64 v[172:173], v[0:1], 0, v[172:173]
	v_lshl_add_u64 v[6:7], v[0:1], 0, v[6:7]
	v_lshl_add_u64 v[180:181], v[0:1], 0, v[180:181]
	v_lshl_add_u64 v[178:179], v[0:1], 0, v[178:179]
	global_load_dword v197, v[4:5], off nt
	global_load_dword v198, v[2:3], off nt
	global_load_dword v199, v[172:173], off nt
	global_load_dword v200, v[6:7], off nt
	global_load_dword v201, v[176:177], off nt
	global_load_dword v202, v[174:175], off nt
	global_load_dword v203, v[180:181], off nt
	global_load_dword v204, v[178:179], off nt
; #define LDS_WAIT() asm volatile("s_waitcnt lgkmcnt(0)" ::: "memory")
;     ...
; #pragma unroll 32
;     for (int i = 0; i < 64; ++i) { const int kk = 2 * i + (lane >> 5); scr[kk * 33 + (lane & 31)] = W[(size_t)(k0 + kk) * N + n0 + (lane & 31)]; }
;     LDS_WAIT(); asm volatile("" ::: "memory");
	v_add_u32_e32 v4, s3, v84
	v_add_u32_e32 v174, s3, v83
	v_add_u32_e32 v176, s3, v88
	v_add_u32_e32 v2, s3, v79
	v_ashrrev_i32_e32 v5, 31, v4
	v_add_u32_e32 v6, s3, v81
	v_add_u32_e32 v172, s3, v86
	v_ashrrev_i32_e32 v177, 31, v176
	v_ashrrev_i32_e32 v175, 31, v174
	v_add_u32_e32 v178, s3, v85
	v_add_u32_e32 v180, s3, v90
	v_ashrrev_i32_e32 v3, 31, v2
	v_lshlrev_b64 v[4:5], 13, v[4:5]
	v_ashrrev_i32_e32 v173, 31, v172
	v_ashrrev_i32_e32 v7, 31, v6
	v_lshlrev_b64 v[174:175], 13, v[174:175]
	v_lshlrev_b64 v[176:177], 13, v[176:177]
	v_ashrrev_i32_e32 v181, 31, v180
	v_ashrrev_i32_e32 v179, 31, v178
	v_lshlrev_b64 v[2:3], 13, v[2:3]
	v_lshl_add_u64 v[4:5], v[0:1], 0, v[4:5]
	v_lshlrev_b64 v[6:7], 13, v[6:7]
	v_lshlrev_b64 v[172:173], 13, v[172:173]
	v_lshl_add_u64 v[176:177], v[0:1], 0, v[176:177]
	v_lshl_add_u64 v[174:175], v[0:1], 0, v[174:175]
	v_lshlrev_b64 v[178:179], 13, v[178:179]
	v_lshlrev_b64 v[180:181], 13, v[180:181]
	v_lshl_add_u64 v[2:3], v[0:1], 0, v[2:3]
	v_lshl_add_u64 v[172:173], v[0:1], 0, v[172:173]
	v_lshl_add_u64 v[6:7], v[0:1], 0, v[6:7]
	v_lshl_add_u64 v[180:181], v[0:1], 0, v[180:181]
	v_lshl_add_u64 v[178:179], v[0:1], 0, v[178:179]
	global_load_dword v205, v[4:5], off nt
	global_load_dword v206, v[2:3], off nt
	global_load_dword v207, v[172:173], off nt
	global_load_dword v208, v[6:7], off nt
	s_nop 0
	global_load_dword v176, v[176:177], off nt
	s_nop 0
	global_load_dword v174, v[174:175], off nt
	s_nop 0
	global_load_dword v175, v[180:181], off nt
	global_load_dword v177, v[178:179], off nt
	v_add_u32_e32 v4, s3, v92
	v_add_u32_e32 v2, s3, v87
	v_ashrrev_i32_e32 v5, 31, v4
	v_ashrrev_i32_e32 v3, 31, v2
	v_lshlrev_b64 v[4:5], 13, v[4:5]
	v_lshlrev_b64 v[2:3], 13, v[2:3]
	v_lshl_add_u64 v[4:5], v[0:1], 0, v[4:5]
	v_lshl_add_u64 v[2:3], v[0:1], 0, v[2:3]
	global_load_dword v178, v[4:5], off nt
	global_load_dword v179, v[2:3], off nt
	v_add_u32_e32 v4, s3, v94
	v_add_u32_e32 v6, s3, v91
	v_add_u32_e32 v172, s3, v96
	v_add_u32_e32 v2, s3, v89
	v_ashrrev_i32_e32 v5, 31, v4
	v_ashrrev_i32_e32 v173, 31, v172
	v_ashrrev_i32_e32 v7, 31, v6
	v_ashrrev_i32_e32 v3, 31, v2
	v_lshlrev_b64 v[4:5], 13, v[4:5]
	v_lshlrev_b64 v[6:7], 13, v[6:7]
	v_lshlrev_b64 v[172:173], 13, v[172:173]
	v_lshlrev_b64 v[2:3], 13, v[2:3]
	v_lshl_add_u64 v[4:5], v[0:1], 0, v[4:5]
	v_lshl_add_u64 v[172:173], v[0:1], 0, v[172:173]
	v_lshl_add_u64 v[6:7], v[0:1], 0, v[6:7]
	v_lshl_add_u64 v[2:3], v[0:1], 0, v[2:3]
	global_load_dword v180, v[4:5], off nt
	global_load_dword v181, v[2:3], off nt
	s_nop 0
	global_load_dword v172, v[172:173], off nt
	s_nop 0
	global_load_dword v6, v[6:7], off nt
	v_add_u32_e32 v4, s3, v98
	v_add_u32_e32 v2, s3, v93
	v_ashrrev_i32_e32 v5, 31, v4
	v_ashrrev_i32_e32 v3, 31, v2
	v_lshlrev_b64 v[4:5], 13, v[4:5]
	v_lshlrev_b64 v[2:3], 13, v[2:3]
	v_lshl_add_u64 v[4:5], v[0:1], 0, v[4:5]
	global_load_dword v4, v[4:5], off nt
	v_lshl_add_u64 v[0:1], v[0:1], 0, v[2:3]
	global_load_dword v0, v[0:1], off nt
	v_add_u32_e32 v1, v97, v132
	s_waitcnt vmcnt(39)
	ds_write_b32 v1, v14
	v_add_u32_e32 v1, v97, v133
	s_waitcnt vmcnt(38)
	ds_write_b32 v1, v182
	v_add_u32_e32 v1, v97, v134
	s_waitcnt vmcnt(37)
	ds_write_b32 v1, v183
	v_add_u32_e32 v1, v97, v135
	s_waitcnt vmcnt(36)
	ds_write_b32 v1, v184
	v_add_u32_e32 v1, v97, v136
	s_waitcnt vmcnt(35)
	ds_write_b32 v1, v185
	v_add_u32_e32 v1, v97, v137
	s_waitcnt vmcnt(34)
	ds_write_b32 v1, v186
	v_add_u32_e32 v1, v97, v138
	s_waitcnt vmcnt(33)
	ds_write_b32 v1, v187
	v_add_u32_e32 v1, v97, v139
	s_waitcnt vmcnt(32)
	ds_write_b32 v1, v188
	v_add_u32_e32 v1, v97, v140
	s_waitcnt vmcnt(31)
	ds_write_b32 v1, v189
	v_add_u32_e32 v1, v97, v141
	s_waitcnt vmcnt(30)
	ds_write_b32 v1, v190
	v_add_u32_e32 v1, v97, v142
	s_waitcnt vmcnt(29)
	ds_write_b32 v1, v191
	v_add_u32_e32 v1, v97, v143
	s_waitcnt vmcnt(28)
	ds_write_b32 v1, v192
	v_add_u32_e32 v1, v97, v144
	s_waitcnt vmcnt(27)
	ds_write_b32 v1, v193
	v_add_u32_e32 v1, v97, v145
	s_waitcnt vmcnt(26)
	ds_write_b32 v1, v194
	v_add_u32_e32 v1, v97, v146
	s_waitcnt vmcnt(25)
	ds_write_b32 v1, v195
	v_add_u32_e32 v1, v97, v147
	s_waitcnt vmcnt(24)
	ds_write_b32 v1, v196
	v_add_u32_e32 v1, v97, v148
	s_waitcnt vmcnt(23)
	ds_write_b32 v1, v197
	v_add_u32_e32 v1, v97, v149
	s_waitcnt vmcnt(22)
	ds_write_b32 v1, v198
	v_add_u32_e32 v1, v97, v150
	s_waitcnt vmcnt(21)
	ds_write_b32 v1, v199
	v_add_u32_e32 v1, v97, v151
	s_waitcnt vmcnt(20)
	ds_write_b32 v1, v200
	v_add_u32_e32 v1, v97, v152
	s_waitcnt vmcnt(19)
	ds_write_b32 v1, v201
	v_add_u32_e32 v1, v97, v153
	s_waitcnt vmcnt(18)
	ds_write_b32 v1, v202
	v_add_u32_e32 v1, v97, v154
	s_waitcnt vmcnt(17)
	ds_write_b32 v1, v203
	v_add_u32_e32 v1, v97, v155
	s_waitcnt vmcnt(16)
	ds_write_b32 v1, v204
	v_add_u32_e32 v1, v97, v156
	s_waitcnt vmcnt(15)
	ds_write_b32 v1, v205
	v_add_u32_e32 v1, v97, v157
	s_waitcnt vmcnt(14)
	ds_write_b32 v1, v206
	v_add_u32_e32 v1, v97, v158
	s_waitcnt vmcnt(13)
	ds_write_b32 v1, v207
	v_add_u32_e32 v1, v97, v159
	s_waitcnt vmcnt(12)
	ds_write_b32 v1, v208
	v_add_u32_e32 v1, v97, v160
	s_waitcnt vmcnt(11)
	ds_write_b32 v1, v176
	v_add_u32_e32 v1, v97, v161
	s_waitcnt vmcnt(10)
	ds_write_b32 v1, v174
	v_add_u32_e32 v1, v97, v162
	s_waitcnt vmcnt(9)
	ds_write_b32 v1, v175
	v_add_u32_e32 v1, v97, v163
	s_waitcnt vmcnt(8)
	ds_write_b32 v1, v177
	v_add_u32_e32 v1, v97, v164
	s_waitcnt vmcnt(7)
	ds_write_b32 v1, v178
	v_add_u32_e32 v1, v97, v165
	s_waitcnt vmcnt(6)
; __device__ __forceinline__ unsigned cvt_pk_bf16(float lo, float hi) { unsigned r; asm volatile("v_cvt_pk_bf16_f32 %0, %1, %2" : "=v"(r) : "v"(lo), "v"(hi)); return r; }
; #define GAS __attribute__((address_space(1)))
; #define LAS __attribute__((address_space(3)))
; #define LDS_WAIT() asm volatile("s_waitcnt lgkmcnt(0)" ::: "memory")
;     ...
;     LDS_WAIT(); asm volatile("" ::: "memory");
;     const int c = lane & 15;
;     float gk[8];
;     if (gain) load8f(gain + k0 + 8 * c, gk); else {
; #pragma unroll
;         for (int e = 0; e < 8; ++e) gk[e] = 1.0f; }
; #pragma unroll
;     for (int j = 0; j < 8; ++j) { const int n = (lane >> 4) + 4 * j; const LAS float* s = scr + (8 * c) * 33 + n;
;         v4u o; o.x = cvt_pk_bf16(s[0 * 33] * gk[0], s[1 * 33] * gk[1]); o.y = cvt_pk_bf16(s[2 * 33] * gk[2], s[3 * 33] * gk[3]); o.z = cvt_pk_bf16(s[4 * 33] * gk[4], s[5 * 33] * gk[5]); o.w = cvt_pk_bf16(s[6 * 33] * gk[6], s[7 * 33] * gk[7]);
;         *(GAS v4u*)(WT + (size_t)(nd0 + n) * K + k0 + 8 * c) = o; }
;     LDS_WAIT(); asm volatile("" ::: "memory");
	ds_write_b32 v1, v179
	v_add_u32_e32 v1, v97, v166
	s_waitcnt vmcnt(5)
	ds_write_b32 v1, v180
	v_add_u32_e32 v1, v97, v167
	s_waitcnt vmcnt(4)
	ds_write_b32 v1, v181
	v_add_u32_e32 v1, v97, v168
	s_waitcnt vmcnt(3)
	ds_write_b32 v1, v172
	v_add_u32_e32 v1, v97, v169
	s_waitcnt vmcnt(2)
	ds_write_b32 v1, v6
	v_add_u32_e32 v1, v97, v170
	s_waitcnt vmcnt(1)
	ds_write_b32 v1, v4
	v_add_u32_e32 v1, v97, v171
	s_waitcnt vmcnt(0)
	ds_write_b32 v1, v0
	s_waitcnt lgkmcnt(0)
	ds_read2_b32 v[0:1], v100 offset1:33
	s_waitcnt lgkmcnt(0)
	v_cvt_pk_bf16_f32 v0, v0, v1
	ds_read2_b32 v[2:3], v100 offset0:66 offset1:99
	s_waitcnt lgkmcnt(0)
	v_cvt_pk_bf16_f32 v1, v2, v3
	ds_read2_b32 v[2:3], v100 offset0:132 offset1:165
	s_waitcnt lgkmcnt(0)
	v_cvt_pk_bf16_f32 v2, v2, v3
	ds_read2_b32 v[4:5], v100 offset0:198 offset1:231
	s_waitcnt lgkmcnt(0)
	v_cvt_pk_bf16_f32 v3, v4, v5
	v_add_u32_e32 v4, s2, v99
	v_ashrrev_i32_e32 v5, 31, v4
	v_lshl_add_u64 v[6:7], v[24:25], 0, s[10:11]
	v_lshlrev_b64 v[4:5], 12, v[4:5]
	v_lshl_add_u64 v[4:5], v[6:7], 0, v[4:5]
	ds_read2_b32 v[172:173], v100 offset0:4 offset1:37
	global_store_dwordx4 v[4:5], v[0:3], off
	s_waitcnt lgkmcnt(0)
	s_nop 0
	v_cvt_pk_bf16_f32 v0, v172, v173
	ds_read2_b32 v[2:3], v100 offset0:70 offset1:103
	s_waitcnt lgkmcnt(0)
	v_cvt_pk_bf16_f32 v1, v2, v3
	ds_read2_b32 v[2:3], v100 offset0:136 offset1:169
	s_waitcnt lgkmcnt(0)
	v_cvt_pk_bf16_f32 v2, v2, v3
	ds_read2_b32 v[4:5], v100 offset0:202 offset1:235
	s_waitcnt lgkmcnt(0)
	v_cvt_pk_bf16_f32 v3, v4, v5
	v_add_u32_e32 v4, s2, v101
	v_ashrrev_i32_e32 v5, 31, v4
	v_lshlrev_b64 v[4:5], 12, v[4:5]
	v_lshl_add_u64 v[4:5], v[6:7], 0, v[4:5]
	ds_read2_b32 v[172:173], v100 offset0:8 offset1:41
	global_store_dwordx4 v[4:5], v[0:3], off
	s_waitcnt lgkmcnt(0)
	s_nop 0
	v_cvt_pk_bf16_f32 v0, v172, v173
	ds_read2_b32 v[2:3], v100 offset0:74 offset1:107
	s_waitcnt lgkmcnt(0)
	v_cvt_pk_bf16_f32 v1, v2, v3
	ds_read2_b32 v[2:3], v100 offset0:140 offset1:173
	s_waitcnt lgkmcnt(0)
	v_cvt_pk_bf16_f32 v2, v2, v3
	ds_read2_b32 v[4:5], v100 offset0:206 offset1:239
	s_waitcnt lgkmcnt(0)
	v_cvt_pk_bf16_f32 v3, v4, v5
	v_add_u32_e32 v4, s2, v102
	v_ashrrev_i32_e32 v5, 31, v4
	v_lshlrev_b64 v[4:5], 12, v[4:5]
	v_lshl_add_u64 v[4:5], v[6:7], 0, v[4:5]
	ds_read2_b32 v[172:173], v100 offset0:12 offset1:45
	global_store_dwordx4 v[4:5], v[0:3], off
	s_waitcnt lgkmcnt(0)
	s_nop 0
	v_cvt_pk_bf16_f32 v0, v172, v173
	ds_read2_b32 v[2:3], v100 offset0:78 offset1:111
	s_waitcnt lgkmcnt(0)
	v_cvt_pk_bf16_f32 v1, v2, v3
	ds_read2_b32 v[2:3], v100 offset0:144 offset1:177
	s_waitcnt lgkmcnt(0)
	v_cvt_pk_bf16_f32 v2, v2, v3
	ds_read2_b32 v[4:5], v100 offset0:210 offset1:243
	s_waitcnt lgkmcnt(0)
	v_cvt_pk_bf16_f32 v3, v4, v5
	v_add_u32_e32 v4, s2, v103
	v_ashrrev_i32_e32 v5, 31, v4
	v_lshlrev_b64 v[4:5], 12, v[4:5]
	v_lshl_add_u64 v[4:5], v[6:7], 0, v[4:5]
	ds_read2_b32 v[172:173], v100 offset0:16 offset1:49
	global_store_dwordx4 v[4:5], v[0:3], off
	s_waitcnt lgkmcnt(0)
	s_nop 0
	v_cvt_pk_bf16_f32 v0, v172, v173
	ds_read2_b32 v[2:3], v100 offset0:82 offset1:115
	s_waitcnt lgkmcnt(0)
	v_cvt_pk_bf16_f32 v1, v2, v3
	ds_read2_b32 v[2:3], v100 offset0:148 offset1:181
	s_waitcnt lgkmcnt(0)
	v_cvt_pk_bf16_f32 v2, v2, v3
	ds_read2_b32 v[4:5], v100 offset0:214 offset1:247
	s_waitcnt lgkmcnt(0)
	v_cvt_pk_bf16_f32 v3, v4, v5
	v_add_u32_e32 v4, s2, v104
	v_ashrrev_i32_e32 v5, 31, v4
	v_lshlrev_b64 v[4:5], 12, v[4:5]
	v_lshl_add_u64 v[4:5], v[6:7], 0, v[4:5]
	ds_read2_b32 v[172:173], v100 offset0:20 offset1:53
	global_store_dwordx4 v[4:5], v[0:3], off
	s_waitcnt lgkmcnt(0)
	s_nop 0
	v_cvt_pk_bf16_f32 v0, v172, v173
	ds_read2_b32 v[2:3], v100 offset0:86 offset1:119
	s_waitcnt lgkmcnt(0)
	v_cvt_pk_bf16_f32 v1, v2, v3
	ds_read2_b32 v[2:3], v100 offset0:152 offset1:185
	s_waitcnt lgkmcnt(0)
	v_cvt_pk_bf16_f32 v2, v2, v3
	ds_read2_b32 v[4:5], v100 offset0:218 offset1:251
	s_waitcnt lgkmcnt(0)
	v_cvt_pk_bf16_f32 v3, v4, v5
	v_add_u32_e32 v4, s2, v105
	v_ashrrev_i32_e32 v5, 31, v4
	v_lshlrev_b64 v[4:5], 12, v[4:5]
	v_lshl_add_u64 v[4:5], v[6:7], 0, v[4:5]
	ds_read2_b32 v[172:173], v100 offset0:24 offset1:57
	global_store_dwordx4 v[4:5], v[0:3], off
	s_waitcnt lgkmcnt(0)
	s_nop 0
	v_cvt_pk_bf16_f32 v0, v172, v173
	ds_read2_b32 v[2:3], v100 offset0:90 offset1:123
	s_waitcnt lgkmcnt(0)
	v_cvt_pk_bf16_f32 v1, v2, v3
	ds_read2_b32 v[2:3], v100 offset0:156 offset1:189
	s_waitcnt lgkmcnt(0)
	v_cvt_pk_bf16_f32 v2, v2, v3
	ds_read2_b32 v[4:5], v100 offset0:222 offset1:255
	s_waitcnt lgkmcnt(0)
	v_cvt_pk_bf16_f32 v3, v4, v5
	v_add_u32_e32 v4, s2, v106
	v_ashrrev_i32_e32 v5, 31, v4
	v_lshlrev_b64 v[4:5], 12, v[4:5]
	v_lshl_add_u64 v[4:5], v[6:7], 0, v[4:5]
	ds_read2_b32 v[172:173], v100 offset0:28 offset1:61
	global_store_dwordx4 v[4:5], v[0:3], off
	s_waitcnt lgkmcnt(0)
	s_nop 0
	v_cvt_pk_bf16_f32 v0, v172, v173
	ds_read2_b32 v[2:3], v100 offset0:94 offset1:127
	s_waitcnt lgkmcnt(0)
	v_cvt_pk_bf16_f32 v1, v2, v3
	ds_read2_b32 v[2:3], v100 offset0:160 offset1:193
	s_waitcnt lgkmcnt(0)
	v_cvt_pk_bf16_f32 v2, v2, v3
	v_add_u32_e32 v3, 0x200, v100
	ds_read2_b32 v[4:5], v3 offset0:98 offset1:131
	s_waitcnt lgkmcnt(0)
	v_cvt_pk_bf16_f32 v3, v4, v5
	v_add_u32_e32 v4, s2, v107
	v_ashrrev_i32_e32 v5, 31, v4
	v_lshlrev_b64 v[4:5], 12, v[4:5]
	v_lshl_add_u64 v[4:5], v[6:7], 0, v[4:5]
	global_store_dwordx4 v[4:5], v[0:3], off
	s_waitcnt lgkmcnt(0)

; #define LDS_WAIT() asm volatile("s_waitcnt lgkmcnt(0)" ::: "memory")
;     const int nblk = N / 32, kb = item / nblk, nb = item % nblk, k0 = 128 * kb, n0 = 32 * nb;
;     const int nd0 = GLU ? (n0 < 6144 ? 256 * (n0 >> 7) + (n0 & 127) : 256 * ((n0 - 6144) >> 7) + 128 + ((n0 - 6144) & 127)) : n0;
; #pragma unroll 32
;     for (int i = 0; i < 64; ++i) { const int kk = 2 * i + (lane >> 5); scr[kk * 33 + (lane & 31)] = W[(size_t)(k0 + kk) * N + n0 + (lane & 31)]; }
;     LDS_WAIT(); asm volatile("" ::: "memory");
.LBB0_55:
	s_andn2_b64 vcc, exec, s[2:3]
	s_cbranch_vccnz .LBB0_57
	s_load_dwordx2 s[2:3], s[6:7], 0x58
	s_load_dwordx2 s[24:25], s[6:7], 0x40
	s_and_b32 s38, s41, 0xfe0
	s_lshl_b32 s10, s38, 2
	v_lshlrev_b32_e32 v14, 2, v12
	s_waitcnt lgkmcnt(0)
	s_add_u32 s58, s2, s10
	s_addc_u32 s59, s3, 0
	s_and_b32 s2, s56, 0x780
	v_add_u32_e32 v4, s2, v10
	v_lshl_add_u64 v[0:1], s[58:59], 0, v[14:15]
	v_add_u32_e32 v2, s2, v9
	v_ashrrev_i32_e32 v5, 31, v4
	v_add_u32_e32 v6, s2, v11
	v_add_u32_e32 v172, s2, v38
	v_add_u32_e32 v174, s2, v13
	v_add_u32_e32 v176, s2, v40
	v_add_u32_e32 v178, s2, v17
	v_add_u32_e32 v180, s2, v42
	v_lshl_add_u64 v[0:1], v[0:1], 0, s[26:27]
	v_ashrrev_i32_e32 v3, 31, v2
	v_lshlrev_b64 v[4:5], 14, v[4:5]
	v_ashrrev_i32_e32 v173, 31, v172
	v_ashrrev_i32_e32 v7, 31, v6
	v_ashrrev_i32_e32 v177, 31, v176
	v_ashrrev_i32_e32 v175, 31, v174
	v_ashrrev_i32_e32 v181, 31, v180
	v_ashrrev_i32_e32 v179, 31, v178
	v_lshlrev_b64 v[2:3], 14, v[2:3]
	v_lshl_add_u64 v[4:5], v[0:1], 0, v[4:5]
	v_lshlrev_b64 v[6:7], 14, v[6:7]
	v_lshlrev_b64 v[172:173], 14, v[172:173]
	v_lshlrev_b64 v[174:175], 14, v[174:175]
	v_lshlrev_b64 v[176:177], 14, v[176:177]
	v_lshlrev_b64 v[178:179], 14, v[178:179]
	v_lshlrev_b64 v[180:181], 14, v[180:181]
	v_lshl_add_u64 v[2:3], v[0:1], 0, v[2:3]
	v_lshl_add_u64 v[172:173], v[0:1], 0, v[172:173]
	v_lshl_add_u64 v[6:7], v[0:1], 0, v[6:7]
	v_lshl_add_u64 v[176:177], v[0:1], 0, v[176:177]
	v_lshl_add_u64 v[174:175], v[0:1], 0, v[174:175]
	v_lshl_add_u64 v[180:181], v[0:1], 0, v[180:181]
	v_lshl_add_u64 v[178:179], v[0:1], 0, v[178:179]
	global_load_dword v14, v[4:5], off nt
	global_load_dword v182, v[2:3], off nt
	global_load_dword v183, v[172:173], off nt
	global_load_dword v184, v[6:7], off nt
	global_load_dword v185, v[176:177], off nt
	global_load_dword v186, v[174:175], off nt
	global_load_dword v187, v[180:181], off nt
	global_load_dword v188, v[178:179], off nt
	v_add_u32_e32 v4, s2, v44
	v_add_u32_e32 v6, s2, v41
	v_add_u32_e32 v172, s2, v46
	v_add_u32_e32 v178, s2, v45
	v_add_u32_e32 v180, s2, v50
	v_add_u32_e32 v2, s2, v39
	v_ashrrev_i32_e32 v5, 31, v4
	v_ashrrev_i32_e32 v173, 31, v172
	v_ashrrev_i32_e32 v7, 31, v6
	v_add_u32_e32 v174, s2, v43
	v_add_u32_e32 v176, s2, v48
	v_ashrrev_i32_e32 v181, 31, v180
	v_ashrrev_i32_e32 v179, 31, v178
	v_ashrrev_i32_e32 v3, 31, v2
	v_lshlrev_b64 v[4:5], 14, v[4:5]
	v_lshlrev_b64 v[6:7], 14, v[6:7]
	v_lshlrev_b64 v[172:173], 14, v[172:173]
	v_ashrrev_i32_e32 v177, 31, v176
	v_ashrrev_i32_e32 v175, 31, v174
	v_lshlrev_b64 v[178:179], 14, v[178:179]
	v_lshlrev_b64 v[180:181], 14, v[180:181]
	v_lshlrev_b64 v[2:3], 14, v[2:3]
	v_lshl_add_u64 v[4:5], v[0:1], 0, v[4:5]
	v_lshl_add_u64 v[172:173], v[0:1], 0, v[172:173]
	v_lshl_add_u64 v[6:7], v[0:1], 0, v[6:7]
	v_lshlrev_b64 v[174:175], 14, v[174:175]
	v_lshlrev_b64 v[176:177], 14, v[176:177]
	v_lshl_add_u64 v[180:181], v[0:1], 0, v[180:181]
	v_lshl_add_u64 v[178:179], v[0:1], 0, v[178:179]
	v_lshl_add_u64 v[2:3], v[0:1], 0, v[2:3]
	v_lshl_add_u64 v[176:177], v[0:1], 0, v[176:177]
	v_lshl_add_u64 v[174:175], v[0:1], 0, v[174:175]
	global_load_dword v189, v[4:5], off nt
	global_load_dword v190, v[2:3], off nt
	global_load_dword v191, v[172:173], off nt
	global_load_dword v192, v[6:7], off nt
	global_load_dword v193, v[176:177], off nt
	global_load_dword v194, v[174:175], off nt
	s_nop 0
	global_load_dword v180, v[180:181], off nt
	s_nop 0
	global_load_dword v178, v[178:179], off nt
	v_add_u32_e32 v4, s2, v52
	v_add_u32_e32 v6, s2, v49
	v_add_u32_e32 v172, s2, v54
	v_add_u32_e32 v2, s2, v47
	v_ashrrev_i32_e32 v5, 31, v4
	v_ashrrev_i32_e32 v173, 31, v172
	v_ashrrev_i32_e32 v7, 31, v6
	v_add_u32_e32 v174, s2, v51
	v_add_u32_e32 v176, s2, v56
	v_ashrrev_i32_e32 v3, 31, v2
	v_lshlrev_b64 v[4:5], 14, v[4:5]
	v_lshlrev_b64 v[6:7], 14, v[6:7]
	v_lshlrev_b64 v[172:173], 14, v[172:173]
	v_ashrrev_i32_e32 v177, 31, v176
	v_ashrrev_i32_e32 v175, 31, v174
	v_lshlrev_b64 v[2:3], 14, v[2:3]
	v_lshl_add_u64 v[4:5], v[0:1], 0, v[4:5]
	v_lshl_add_u64 v[172:173], v[0:1], 0, v[172:173]
	v_lshl_add_u64 v[6:7], v[0:1], 0, v[6:7]
	v_lshlrev_b64 v[174:175], 14, v[174:175]
	v_lshlrev_b64 v[176:177], 14, v[176:177]
	v_lshl_add_u64 v[2:3], v[0:1], 0, v[2:3]
	v_lshl_add_u64 v[176:177], v[0:1], 0, v[176:177]
	v_lshl_add_u64 v[174:175], v[0:1], 0, v[174:175]
	global_load_dword v179, v[4:5], off nt
	global_load_dword v181, v[2:3], off nt
	s_nop 0
	global_load_dword v172, v[172:173], off nt
	s_nop 0
	global_load_dword v6, v[6:7], off nt
	s_nop 0
	global_load_dword v7, v[176:177], off nt
	global_load_dword v173, v[174:175], off nt
	v_add_u32_e32 v4, s2, v58
	v_add_u32_e32 v2, s2, v53
	v_ashrrev_i32_e32 v5, 31, v4
	v_ashrrev_i32_e32 v3, 31, v2
	v_lshlrev_b64 v[4:5], 14, v[4:5]
	v_lshlrev_b64 v[2:3], 14, v[2:3]
	v_lshl_add_u64 v[4:5], v[0:1], 0, v[4:5]
	global_load_dword v4, v[4:5], off nt
	v_lshl_add_u64 v[2:3], v[0:1], 0, v[2:3]
	global_load_dword v2, v[2:3], off nt
	v_add_u32_e32 v3, v97, v108
	v_add_u32_e32 v174, s2, v59
	v_add_u32_e32 v176, s2, v64
	v_add_u32_e32 v196, s2, v74
	s_waitcnt vmcnt(23)
	ds_write_b32 v3, v14
	v_add_u32_e32 v3, v97, v109
	s_waitcnt vmcnt(22)
	ds_write_b32 v3, v182
	v_add_u32_e32 v3, v97, v110
	s_waitcnt vmcnt(21)
	ds_write_b32 v3, v183
	v_add_u32_e32 v3, v97, v111
	s_waitcnt vmcnt(20)
	ds_write_b32 v3, v184
	v_add_u32_e32 v3, v97, v112
	s_waitcnt vmcnt(19)
	ds_write_b32 v3, v185
	v_add_u32_e32 v3, v97, v113
	s_waitcnt vmcnt(18)
	ds_write_b32 v3, v186
	v_add_u32_e32 v3, v97, v114
	s_waitcnt vmcnt(17)
	ds_write_b32 v3, v187
	v_add_u32_e32 v3, v97, v115
	s_waitcnt vmcnt(16)
; #define LDS_WAIT() asm volatile("s_waitcnt lgkmcnt(0)" ::: "memory")
;     ...
; #pragma unroll 32
;     for (int i = 0; i < 64; ++i) { const int kk = 2 * i + (lane >> 5); scr[kk * 33 + (lane & 31)] = W[(size_t)(k0 + kk) * N + n0 + (lane & 31)]; }
;     LDS_WAIT(); asm volatile("" ::: "memory");
	ds_write_b32 v3, v188
	v_add_u32_e32 v3, v97, v116
	v_add_u32_e32 v182, s2, v63
	v_add_u32_e32 v184, s2, v68
	v_add_u32_e32 v186, s2, v65
	v_add_u32_e32 v188, s2, v70
	v_add_u32_e32 v198, s2, v71
	v_add_u32_e32 v200, s2, v76
	v_add_u32_e32 v202, s2, v73
	v_add_u32_e32 v204, s2, v78
	v_add_u32_e32 v206, s2, v80
	v_add_u32_e32 v208, s2, v75
	v_add_u32_e32 v210, s2, v82
	v_add_u32_e32 v212, s2, v77
	v_add_u32_e32 v214, s2, v84
	v_add_u32_e32 v216, s2, v79
	v_add_u32_e32 v218, s2, v86
	v_add_u32_e32 v220, s2, v81
	v_add_u32_e32 v222, s2, v88
	s_waitcnt vmcnt(15)
	ds_write_b32 v3, v189
	v_add_u32_e32 v3, v97, v117
	s_waitcnt vmcnt(14)
	ds_write_b32 v3, v190
	v_add_u32_e32 v3, v97, v118
	s_waitcnt vmcnt(13)
	ds_write_b32 v3, v191
	v_add_u32_e32 v3, v97, v119
	s_waitcnt vmcnt(12)
	ds_write_b32 v3, v192
	v_add_u32_e32 v3, v97, v120
	s_waitcnt vmcnt(11)
	ds_write_b32 v3, v193
	v_add_u32_e32 v3, v97, v121
	s_waitcnt vmcnt(10)
	ds_write_b32 v3, v194
	v_add_u32_e32 v3, v97, v122
	s_waitcnt vmcnt(9)
	ds_write_b32 v3, v180
	v_add_u32_e32 v3, v97, v123
	s_waitcnt vmcnt(8)
	ds_write_b32 v3, v178
	v_add_u32_e32 v3, v97, v124
	v_add_u32_e32 v178, s2, v61
	v_add_u32_e32 v180, s2, v66
	v_add_u32_e32 v190, s2, v67
	v_add_u32_e32 v192, s2, v72
	v_add_u32_e32 v194, s2, v69
	v_add_u32_e32 v224, s2, v83
	v_add_u32_e32 v226, s2, v90
	v_add_u32_e32 v228, s2, v85
	v_add_u32_e32 v230, s2, v92
	v_add_u32_e32 v232, s2, v87
	v_add_u32_e32 v234, s2, v94
	s_waitcnt vmcnt(7)
	ds_write_b32 v3, v179
	v_add_u32_e32 v3, v97, v125
	s_waitcnt vmcnt(6)
	ds_write_b32 v3, v181
	v_add_u32_e32 v3, v97, v126
	s_waitcnt vmcnt(5)
	ds_write_b32 v3, v172
	v_add_u32_e32 v3, v97, v127
	s_waitcnt vmcnt(4)
	ds_write_b32 v3, v6
	v_add_u32_e32 v3, v97, v128
	s_waitcnt vmcnt(3)
	ds_write_b32 v3, v7
	v_add_u32_e32 v3, v97, v129
	s_waitcnt vmcnt(2)
	ds_write_b32 v3, v173
	v_add_u32_e32 v3, v97, v130
	v_add_u32_e32 v6, s2, v57
	s_waitcnt vmcnt(1)
	ds_write_b32 v3, v4
	v_add_u32_e32 v3, v97, v131
	s_waitcnt vmcnt(0)
	ds_write_b32 v3, v2
	v_add_u32_e32 v2, s2, v55
	v_add_u32_e32 v4, s2, v60
	v_add_u32_e32 v172, s2, v62
	v_add_u32_e32 v236, s2, v89
	v_add_u32_e32 v238, s2, v96
	v_add_u32_e32 v240, s2, v91
	v_add_u32_e32 v242, s2, v98
	v_add_u32_e32 v244, s2, v93
	v_ashrrev_i32_e32 v5, 31, v4
	v_ashrrev_i32_e32 v3, 31, v2
	v_ashrrev_i32_e32 v173, 31, v172
	v_ashrrev_i32_e32 v7, 31, v6
	v_ashrrev_i32_e32 v177, 31, v176
	v_ashrrev_i32_e32 v175, 31, v174
	v_ashrrev_i32_e32 v181, 31, v180
	v_ashrrev_i32_e32 v179, 31, v178
	v_ashrrev_i32_e32 v185, 31, v184
	v_ashrrev_i32_e32 v183, 31, v182
	v_ashrrev_i32_e32 v189, 31, v188
	v_ashrrev_i32_e32 v187, 31, v186
	v_ashrrev_i32_e32 v193, 31, v192
	v_ashrrev_i32_e32 v191, 31, v190
	v_ashrrev_i32_e32 v197, 31, v196
	v_ashrrev_i32_e32 v195, 31, v194
	v_ashrrev_i32_e32 v201, 31, v200
	v_ashrrev_i32_e32 v199, 31, v198
	v_ashrrev_i32_e32 v205, 31, v204
	v_ashrrev_i32_e32 v203, 31, v202
	v_ashrrev_i32_e32 v207, 31, v206
	v_ashrrev_i32_e32 v209, 31, v208
	v_ashrrev_i32_e32 v211, 31, v210
	v_ashrrev_i32_e32 v213, 31, v212
	v_ashrrev_i32_e32 v215, 31, v214
	v_ashrrev_i32_e32 v217, 31, v216
	v_ashrrev_i32_e32 v219, 31, v218
	v_ashrrev_i32_e32 v221, 31, v220
	v_ashrrev_i32_e32 v223, 31, v222
	v_ashrrev_i32_e32 v225, 31, v224
	v_ashrrev_i32_e32 v227, 31, v226
	v_ashrrev_i32_e32 v229, 31, v228
	v_ashrrev_i32_e32 v231, 31, v230
	v_ashrrev_i32_e32 v233, 31, v232
	v_ashrrev_i32_e32 v235, 31, v234
	v_ashrrev_i32_e32 v237, 31, v236
	v_ashrrev_i32_e32 v239, 31, v238
	v_ashrrev_i32_e32 v241, 31, v240
	v_ashrrev_i32_e32 v243, 31, v242
	v_ashrrev_i32_e32 v245, 31, v244
	v_lshlrev_b64 v[2:3], 14, v[2:3]
	v_lshlrev_b64 v[4:5], 14, v[4:5]
	v_lshlrev_b64 v[6:7], 14, v[6:7]
	v_lshlrev_b64 v[172:173], 14, v[172:173]
	v_lshlrev_b64 v[174:175], 14, v[174:175]
	v_lshlrev_b64 v[176:177], 14, v[176:177]
	v_lshlrev_b64 v[178:179], 14, v[178:179]
	v_lshlrev_b64 v[180:181], 14, v[180:181]
	v_lshlrev_b64 v[182:183], 14, v[182:183]
	v_lshlrev_b64 v[184:185], 14, v[184:185]
	v_lshlrev_b64 v[186:187], 14, v[186:187]
	v_lshlrev_b64 v[188:189], 14, v[188:189]
	v_lshlrev_b64 v[190:191], 14, v[190:191]
	v_lshlrev_b64 v[192:193], 14, v[192:193]
	v_lshlrev_b64 v[194:195], 14, v[194:195]
	v_lshlrev_b64 v[196:197], 14, v[196:197]
	v_lshlrev_b64 v[198:199], 14, v[198:199]
	v_lshlrev_b64 v[200:201], 14, v[200:201]
	v_lshlrev_b64 v[202:203], 14, v[202:203]
	v_lshlrev_b64 v[204:205], 14, v[204:205]
	v_lshlrev_b64 v[208:209], 14, v[208:209]
	v_lshlrev_b64 v[206:207], 14, v[206:207]
	v_lshlrev_b64 v[212:213], 14, v[212:213]
	v_lshlrev_b64 v[210:211], 14, v[210:211]
	v_lshlrev_b64 v[216:217], 14, v[216:217]
	v_lshlrev_b64 v[214:215], 14, v[214:215]
	v_lshlrev_b64 v[220:221], 14, v[220:221]
	v_lshlrev_b64 v[218:219], 14, v[218:219]
	v_lshlrev_b64 v[224:225], 14, v[224:225]
	v_lshlrev_b64 v[222:223], 14, v[222:223]
	v_lshlrev_b64 v[228:229], 14, v[228:229]
	v_lshlrev_b64 v[226:227], 14, v[226:227]
	v_lshlrev_b64 v[232:233], 14, v[232:233]
	v_lshlrev_b64 v[230:231], 14, v[230:231]
	v_lshlrev_b64 v[236:237], 14, v[236:237]
	v_lshlrev_b64 v[234:235], 14, v[234:235]
	v_lshlrev_b64 v[240:241], 14, v[240:241]
	v_lshlrev_b64 v[238:239], 14, v[238:239]
	v_lshlrev_b64 v[244:245], 14, v[244:245]
	v_lshlrev_b64 v[242:243], 14, v[242:243]
	v_lshl_add_u64 v[4:5], v[0:1], 0, v[4:5]
	v_lshl_add_u64 v[2:3], v[0:1], 0, v[2:3]
	v_lshl_add_u64 v[172:173], v[0:1], 0, v[172:173]
	v_lshl_add_u64 v[6:7], v[0:1], 0, v[6:7]
	v_lshl_add_u64 v[176:177], v[0:1], 0, v[176:177]
	v_lshl_add_u64 v[174:175], v[0:1], 0, v[174:175]
	v_lshl_add_u64 v[180:181], v[0:1], 0, v[180:181]
	v_lshl_add_u64 v[178:179], v[0:1], 0, v[178:179]
; #define LDS_WAIT() asm volatile("s_waitcnt lgkmcnt(0)" ::: "memory")
;     ...
; #pragma unroll 32
;     for (int i = 0; i < 64; ++i) { const int kk = 2 * i + (lane >> 5); scr[kk * 33 + (lane & 31)] = W[(size_t)(k0 + kk) * N + n0 + (lane & 31)]; }
;     LDS_WAIT(); asm volatile("" ::: "memory");
	v_lshl_add_u64 v[184:185], v[0:1], 0, v[184:185]
	v_lshl_add_u64 v[182:183], v[0:1], 0, v[182:183]
	v_lshl_add_u64 v[188:189], v[0:1], 0, v[188:189]
	v_lshl_add_u64 v[186:187], v[0:1], 0, v[186:187]
	v_lshl_add_u64 v[192:193], v[0:1], 0, v[192:193]
	v_lshl_add_u64 v[190:191], v[0:1], 0, v[190:191]
	v_lshl_add_u64 v[196:197], v[0:1], 0, v[196:197]
	v_lshl_add_u64 v[194:195], v[0:1], 0, v[194:195]
	v_lshl_add_u64 v[200:201], v[0:1], 0, v[200:201]
	v_lshl_add_u64 v[198:199], v[0:1], 0, v[198:199]
	v_lshl_add_u64 v[204:205], v[0:1], 0, v[204:205]
	v_lshl_add_u64 v[202:203], v[0:1], 0, v[202:203]
	v_lshl_add_u64 v[206:207], v[0:1], 0, v[206:207]
	v_lshl_add_u64 v[208:209], v[0:1], 0, v[208:209]
	v_lshl_add_u64 v[210:211], v[0:1], 0, v[210:211]
	v_lshl_add_u64 v[212:213], v[0:1], 0, v[212:213]
	v_lshl_add_u64 v[214:215], v[0:1], 0, v[214:215]
	v_lshl_add_u64 v[216:217], v[0:1], 0, v[216:217]
	v_lshl_add_u64 v[218:219], v[0:1], 0, v[218:219]
	v_lshl_add_u64 v[220:221], v[0:1], 0, v[220:221]
	v_lshl_add_u64 v[222:223], v[0:1], 0, v[222:223]
	v_lshl_add_u64 v[224:225], v[0:1], 0, v[224:225]
	v_lshl_add_u64 v[226:227], v[0:1], 0, v[226:227]
	v_lshl_add_u64 v[228:229], v[0:1], 0, v[228:229]
	v_lshl_add_u64 v[230:231], v[0:1], 0, v[230:231]
	v_lshl_add_u64 v[232:233], v[0:1], 0, v[232:233]
	v_lshl_add_u64 v[234:235], v[0:1], 0, v[234:235]
	v_lshl_add_u64 v[236:237], v[0:1], 0, v[236:237]
	v_lshl_add_u64 v[238:239], v[0:1], 0, v[238:239]
	v_lshl_add_u64 v[240:241], v[0:1], 0, v[240:241]
	v_lshl_add_u64 v[242:243], v[0:1], 0, v[242:243]
	v_lshl_add_u64 v[0:1], v[0:1], 0, v[244:245]
	global_load_dword v4, v[4:5], off nt
	s_nop 0
	global_load_dword v2, v[2:3], off nt
	s_nop 0
	global_load_dword v3, v[172:173], off nt
	global_load_dword v5, v[6:7], off nt
	s_nop 0
	global_load_dword v6, v[176:177], off nt
	global_load_dword v7, v[174:175], off nt
	global_load_dword v14, v[180:181], off nt
	global_load_dword v172, v[178:179], off nt
	global_load_dword v173, v[184:185], off nt
	s_nop 0
	global_load_dword v174, v[182:183], off nt
	global_load_dword v175, v[188:189], off nt
	global_load_dword v176, v[186:187], off nt
	global_load_dword v177, v[192:193], off nt
	global_load_dword v178, v[190:191], off nt
	global_load_dword v179, v[196:197], off nt
	global_load_dword v180, v[194:195], off nt
	global_load_dword v181, v[200:201], off nt
	global_load_dword v182, v[198:199], off nt
	global_load_dword v183, v[204:205], off nt
	global_load_dword v184, v[202:203], off nt
	global_load_dword v185, v[206:207], off nt
	global_load_dword v186, v[208:209], off nt
	global_load_dword v187, v[210:211], off nt
	global_load_dword v188, v[212:213], off nt
	global_load_dword v189, v[214:215], off nt
	global_load_dword v190, v[216:217], off nt
	global_load_dword v191, v[218:219], off nt
	global_load_dword v192, v[220:221], off nt
	global_load_dword v193, v[222:223], off nt
	global_load_dword v194, v[224:225], off nt
	global_load_dword v195, v[226:227], off nt
	global_load_dword v196, v[228:229], off nt
	global_load_dword v197, v[230:231], off nt
	global_load_dword v198, v[232:233], off nt
	global_load_dword v199, v[234:235], off nt
	global_load_dword v200, v[236:237], off nt
	global_load_dword v201, v[238:239], off nt
	global_load_dword v202, v[240:241], off nt
	global_load_dword v203, v[242:243], off nt
	s_nop 0
	global_load_dword v0, v[0:1], off nt
	v_add_u32_e32 v1, v97, v132
	s_lshl_b32 s3, s2, 2
	s_add_u32 s24, s24, s3
	s_addc_u32 s25, s25, 0
	s_lshl_b32 s10, s2, 1
	s_waitcnt vmcnt(39)
	ds_write_b32 v1, v4
	v_add_u32_e32 v1, v97, v133
	s_waitcnt vmcnt(38)
	ds_write_b32 v1, v2
	v_add_u32_e32 v1, v97, v134
	s_waitcnt vmcnt(37)
	ds_write_b32 v1, v3
	v_add_u32_e32 v1, v97, v135
	s_waitcnt vmcnt(36)
	ds_write_b32 v1, v5
	v_add_u32_e32 v1, v97, v136
	s_waitcnt vmcnt(35)
	ds_write_b32 v1, v6
	v_add_u32_e32 v1, v97, v137
	s_waitcnt vmcnt(34)
	ds_write_b32 v1, v7
	v_add_u32_e32 v1, v97, v138
	s_waitcnt vmcnt(33)
	ds_write_b32 v1, v14
	v_add_u32_e32 v1, v97, v139
	s_waitcnt vmcnt(32)
	ds_write_b32 v1, v172
	v_add_u32_e32 v1, v97, v140
	s_waitcnt vmcnt(31)
	ds_write_b32 v1, v173
	v_add_u32_e32 v1, v97, v141
	s_waitcnt vmcnt(30)
	ds_write_b32 v1, v174
	v_add_u32_e32 v1, v97, v142
	s_waitcnt vmcnt(29)
	ds_write_b32 v1, v175
	v_add_u32_e32 v1, v97, v143
	s_waitcnt vmcnt(28)
	ds_write_b32 v1, v176
	v_add_u32_e32 v1, v97, v144
	s_waitcnt vmcnt(27)
	ds_write_b32 v1, v177
	v_add_u32_e32 v1, v97, v145
	s_waitcnt vmcnt(26)
	ds_write_b32 v1, v178
	v_add_u32_e32 v1, v97, v146
	s_waitcnt vmcnt(25)
	ds_write_b32 v1, v179
	v_add_u32_e32 v1, v97, v147
	s_waitcnt vmcnt(24)
	ds_write_b32 v1, v180
	v_add_u32_e32 v1, v97, v148
	s_waitcnt vmcnt(23)
	ds_write_b32 v1, v181
	v_add_u32_e32 v1, v97, v149
	s_waitcnt vmcnt(22)
	ds_write_b32 v1, v182
	v_add_u32_e32 v1, v97, v150
	s_waitcnt vmcnt(21)
	ds_write_b32 v1, v183
	v_add_u32_e32 v1, v97, v151
	s_waitcnt vmcnt(20)
	ds_write_b32 v1, v184
	v_add_u32_e32 v1, v97, v152
	s_waitcnt vmcnt(19)
	ds_write_b32 v1, v185
	v_add_u32_e32 v1, v97, v153
	s_waitcnt vmcnt(18)
	ds_write_b32 v1, v186
	v_add_u32_e32 v1, v97, v154
	s_waitcnt vmcnt(17)
	ds_write_b32 v1, v187
	v_add_u32_e32 v1, v97, v155
	s_waitcnt vmcnt(16)
	ds_write_b32 v1, v188
	v_add_u32_e32 v1, v97, v156
	s_waitcnt vmcnt(15)
	ds_write_b32 v1, v189
	v_add_u32_e32 v1, v97, v157
	s_waitcnt vmcnt(14)
	ds_write_b32 v1, v190
	v_add_u32_e32 v1, v97, v158
	s_waitcnt vmcnt(13)
	ds_write_b32 v1, v191
	v_add_u32_e32 v1, v97, v159
	s_waitcnt vmcnt(12)
	ds_write_b32 v1, v192
	v_add_u32_e32 v1, v97, v160
	s_waitcnt vmcnt(11)
	ds_write_b32 v1, v193
	v_add_u32_e32 v1, v97, v161
	s_waitcnt vmcnt(10)
; __device__ __forceinline__ unsigned cvt_pk_bf16(float lo, float hi) { unsigned r; asm volatile("v_cvt_pk_bf16_f32 %0, %1, %2" : "=v"(r) : "v"(lo), "v"(hi)); return r; }
; #define GAS __attribute__((address_space(1)))
; #define LAS __attribute__((address_space(3)))
; #define LDS_WAIT() asm volatile("s_waitcnt lgkmcnt(0)" ::: "memory")
;     ...
;     LDS_WAIT(); asm volatile("" ::: "memory");
;     const int c = lane & 15;
;     float gk[8];
;     if (gain) load8f(gain + k0 + 8 * c, gk); else {
; #pragma unroll
;         for (int e = 0; e < 8; ++e) gk[e] = 1.0f; }
; #pragma unroll
;     for (int j = 0; j < 8; ++j) { const int n = (lane >> 4) + 4 * j; const LAS float* s = scr + (8 * c) * 33 + n;
;         v4u o; o.x = cvt_pk_bf16(s[0 * 33] * gk[0], s[1 * 33] * gk[1]); o.y = cvt_pk_bf16(s[2 * 33] * gk[2], s[3 * 33] * gk[3]); o.z = cvt_pk_bf16(s[4 * 33] * gk[4], s[5 * 33] * gk[5]); o.w = cvt_pk_bf16(s[6 * 33] * gk[6], s[7 * 33] * gk[7]);
;         *(GAS v4u*)(WT + (size_t)(nd0 + n) * K + k0 + 8 * c) = o; }
	ds_write_b32 v1, v194
	v_add_u32_e32 v1, v97, v162
	s_waitcnt vmcnt(9)
	ds_write_b32 v1, v195
	v_add_u32_e32 v1, v97, v163
	s_waitcnt vmcnt(8)
	ds_write_b32 v1, v196
	v_add_u32_e32 v1, v97, v164
	s_waitcnt vmcnt(7)
	ds_write_b32 v1, v197
	v_add_u32_e32 v1, v97, v165
	s_waitcnt vmcnt(6)
	ds_write_b32 v1, v198
	v_add_u32_e32 v1, v97, v166
	s_waitcnt vmcnt(5)
	ds_write_b32 v1, v199
	v_add_u32_e32 v1, v97, v167
	s_waitcnt vmcnt(4)
	ds_write_b32 v1, v200
	v_add_u32_e32 v1, v97, v168
	s_waitcnt vmcnt(3)
	ds_write_b32 v1, v201
	v_add_u32_e32 v1, v97, v169
	s_waitcnt vmcnt(2)
	ds_write_b32 v1, v202
	v_add_u32_e32 v1, v97, v170
	s_waitcnt vmcnt(1)
	ds_write_b32 v1, v203
	v_add_u32_e32 v1, v97, v171
	v_lshlrev_b32_e32 v14, 2, v16
	s_waitcnt vmcnt(0)
	ds_write_b32 v1, v0
	v_lshl_add_u64 v[4:5], s[24:25], 0, v[14:15]
	s_waitcnt lgkmcnt(0)
	v_add_co_u32_e32 v0, vcc, s54, v4
	ds_read2_b32 v[172:173], v100 offset1:33
	s_nop 0
	v_addc_co_u32_e32 v1, vcc, 0, v5, vcc
	global_load_dwordx4 v[0:3], v[0:1], off
	v_lshl_add_u64 v[4:5], v[4:5], 0, s[28:29]
	global_load_dwordx4 v[4:7], v[4:5], off offset:16
	v_lshl_add_u64 v[178:179], v[26:27], 0, s[10:11]
	s_waitcnt vmcnt(1) lgkmcnt(0)
	v_mul_f32_e32 v14, v0, v172
	v_mul_f32_e32 v172, v1, v173
	v_cvt_pk_bf16_f32 v172, v14, v172
	ds_read2_b32 v[174:175], v100 offset0:66 offset1:99
	s_waitcnt lgkmcnt(0)
	v_mul_f32_e32 v173, v3, v175
	v_mul_f32_e32 v14, v2, v174
	v_cvt_pk_bf16_f32 v173, v14, v173
	ds_read2_b32 v[174:175], v100 offset0:132 offset1:165
	s_waitcnt vmcnt(0) lgkmcnt(0)
	v_mul_f32_e32 v14, v4, v174
	v_mul_f32_e32 v174, v5, v175
	v_cvt_pk_bf16_f32 v174, v14, v174
	ds_read2_b32 v[176:177], v100 offset0:198 offset1:231
	s_waitcnt lgkmcnt(0)
	v_mul_f32_e32 v175, v7, v177
	v_mul_f32_e32 v14, v6, v176
	v_cvt_pk_bf16_f32 v175, v14, v175
	ds_read2_b32 v[180:181], v100 offset0:4 offset1:37
	v_add_u32_e32 v176, s38, v99
	v_ashrrev_i32_e32 v177, 31, v176
	v_lshlrev_b64 v[176:177], 12, v[176:177]
	v_lshl_add_u64 v[176:177], v[178:179], 0, v[176:177]
	global_store_dwordx4 v[176:177], v[172:175], off
	s_waitcnt lgkmcnt(0)
	v_mul_f32_e32 v14, v0, v180
	v_mul_f32_e32 v172, v1, v181
	v_cvt_pk_bf16_f32 v172, v14, v172
	ds_read2_b32 v[174:175], v100 offset0:70 offset1:103
	s_waitcnt lgkmcnt(0)
	v_mul_f32_e32 v173, v3, v175
	v_mul_f32_e32 v14, v2, v174
	v_cvt_pk_bf16_f32 v173, v14, v173
	ds_read2_b32 v[174:175], v100 offset0:136 offset1:169
	s_waitcnt lgkmcnt(0)
	v_mul_f32_e32 v14, v4, v174
	v_mul_f32_e32 v174, v5, v175
	v_cvt_pk_bf16_f32 v174, v14, v174
	ds_read2_b32 v[176:177], v100 offset0:202 offset1:235
	s_waitcnt lgkmcnt(0)
	v_mul_f32_e32 v175, v7, v177
	v_mul_f32_e32 v14, v6, v176
	v_cvt_pk_bf16_f32 v175, v14, v175
	ds_read2_b32 v[180:181], v100 offset0:8 offset1:41
	v_add_u32_e32 v176, s38, v101
	v_ashrrev_i32_e32 v177, 31, v176
	v_lshlrev_b64 v[176:177], 12, v[176:177]
	v_lshl_add_u64 v[176:177], v[178:179], 0, v[176:177]
	global_store_dwordx4 v[176:177], v[172:175], off
	s_waitcnt lgkmcnt(0)
	v_mul_f32_e32 v14, v0, v180
	v_mul_f32_e32 v172, v1, v181
	v_cvt_pk_bf16_f32 v172, v14, v172
	ds_read2_b32 v[174:175], v100 offset0:74 offset1:107
	s_waitcnt lgkmcnt(0)
	v_mul_f32_e32 v173, v3, v175
	v_mul_f32_e32 v14, v2, v174
	v_cvt_pk_bf16_f32 v173, v14, v173
	ds_read2_b32 v[174:175], v100 offset0:140 offset1:173
	s_waitcnt lgkmcnt(0)
	v_mul_f32_e32 v14, v4, v174
	v_mul_f32_e32 v174, v5, v175
	v_cvt_pk_bf16_f32 v174, v14, v174
	ds_read2_b32 v[176:177], v100 offset0:206 offset1:239
	s_waitcnt lgkmcnt(0)
	v_mul_f32_e32 v175, v7, v177
	v_mul_f32_e32 v14, v6, v176
	v_cvt_pk_bf16_f32 v175, v14, v175
	ds_read2_b32 v[180:181], v100 offset0:12 offset1:45
	v_add_u32_e32 v176, s38, v102
	v_ashrrev_i32_e32 v177, 31, v176
	v_lshlrev_b64 v[176:177], 12, v[176:177]
	v_lshl_add_u64 v[176:177], v[178:179], 0, v[176:177]
	global_store_dwordx4 v[176:177], v[172:175], off
	s_waitcnt lgkmcnt(0)
	v_mul_f32_e32 v14, v0, v180
	v_mul_f32_e32 v172, v1, v181
	v_cvt_pk_bf16_f32 v172, v14, v172
	ds_read2_b32 v[174:175], v100 offset0:78 offset1:111
	s_waitcnt lgkmcnt(0)
; __device__ __forceinline__ unsigned cvt_pk_bf16(float lo, float hi) { unsigned r; asm volatile("v_cvt_pk_bf16_f32 %0, %1, %2" : "=v"(r) : "v"(lo), "v"(hi)); return r; }
; #define GAS __attribute__((address_space(1)))
; #define LAS __attribute__((address_space(3)))
; #define LDS_WAIT() asm volatile("s_waitcnt lgkmcnt(0)" ::: "memory")
;     ...
;     for (int j = 0; j < 8; ++j) { const int n = (lane >> 4) + 4 * j; const LAS float* s = scr + (8 * c) * 33 + n;
;         v4u o; o.x = cvt_pk_bf16(s[0 * 33] * gk[0], s[1 * 33] * gk[1]); o.y = cvt_pk_bf16(s[2 * 33] * gk[2], s[3 * 33] * gk[3]); o.z = cvt_pk_bf16(s[4 * 33] * gk[4], s[5 * 33] * gk[5]); o.w = cvt_pk_bf16(s[6 * 33] * gk[6], s[7 * 33] * gk[7]);
;         *(GAS v4u*)(WT + (size_t)(nd0 + n) * K + k0 + 8 * c) = o; }
;     LDS_WAIT(); asm volatile("" ::: "memory");
	v_mul_f32_e32 v173, v3, v175
	v_mul_f32_e32 v14, v2, v174
	v_cvt_pk_bf16_f32 v173, v14, v173
	ds_read2_b32 v[174:175], v100 offset0:144 offset1:177
	s_waitcnt lgkmcnt(0)
	v_mul_f32_e32 v14, v4, v174
	v_mul_f32_e32 v174, v5, v175
	v_cvt_pk_bf16_f32 v174, v14, v174
	ds_read2_b32 v[176:177], v100 offset0:210 offset1:243
	s_waitcnt lgkmcnt(0)
	v_mul_f32_e32 v175, v7, v177
	v_mul_f32_e32 v14, v6, v176
	v_cvt_pk_bf16_f32 v175, v14, v175
	ds_read2_b32 v[180:181], v100 offset0:16 offset1:49
	v_add_u32_e32 v176, s38, v103
	v_ashrrev_i32_e32 v177, 31, v176
	v_lshlrev_b64 v[176:177], 12, v[176:177]
	v_lshl_add_u64 v[176:177], v[178:179], 0, v[176:177]
	global_store_dwordx4 v[176:177], v[172:175], off
	s_waitcnt lgkmcnt(0)
	v_mul_f32_e32 v14, v0, v180
	v_mul_f32_e32 v172, v1, v181
	v_cvt_pk_bf16_f32 v172, v14, v172
	ds_read2_b32 v[174:175], v100 offset0:82 offset1:115
	s_waitcnt lgkmcnt(0)
	v_mul_f32_e32 v173, v3, v175
	v_mul_f32_e32 v14, v2, v174
	v_cvt_pk_bf16_f32 v173, v14, v173
	ds_read2_b32 v[174:175], v100 offset0:148 offset1:181
	s_waitcnt lgkmcnt(0)
	v_mul_f32_e32 v14, v4, v174
	v_mul_f32_e32 v174, v5, v175
	v_cvt_pk_bf16_f32 v174, v14, v174
	ds_read2_b32 v[176:177], v100 offset0:214 offset1:247
	s_waitcnt lgkmcnt(0)
	v_mul_f32_e32 v175, v7, v177
	v_mul_f32_e32 v14, v6, v176
	v_cvt_pk_bf16_f32 v175, v14, v175
	ds_read2_b32 v[180:181], v100 offset0:20 offset1:53
	v_add_u32_e32 v176, s38, v104
	v_ashrrev_i32_e32 v177, 31, v176
	v_lshlrev_b64 v[176:177], 12, v[176:177]
	v_lshl_add_u64 v[176:177], v[178:179], 0, v[176:177]
	global_store_dwordx4 v[176:177], v[172:175], off
	s_waitcnt lgkmcnt(0)
	v_mul_f32_e32 v14, v0, v180
	v_mul_f32_e32 v172, v1, v181
	v_cvt_pk_bf16_f32 v172, v14, v172
	ds_read2_b32 v[174:175], v100 offset0:86 offset1:119
	s_waitcnt lgkmcnt(0)
	v_mul_f32_e32 v173, v3, v175
	v_mul_f32_e32 v14, v2, v174
	v_cvt_pk_bf16_f32 v173, v14, v173
	ds_read2_b32 v[174:175], v100 offset0:152 offset1:185
	s_waitcnt lgkmcnt(0)
	v_mul_f32_e32 v14, v4, v174
	v_mul_f32_e32 v174, v5, v175
	v_cvt_pk_bf16_f32 v174, v14, v174
	ds_read2_b32 v[176:177], v100 offset0:218 offset1:251
	s_waitcnt lgkmcnt(0)
	v_mul_f32_e32 v175, v7, v177
	v_mul_f32_e32 v14, v6, v176
	v_cvt_pk_bf16_f32 v175, v14, v175
	ds_read2_b32 v[180:181], v100 offset0:24 offset1:57
	v_add_u32_e32 v176, s38, v105
	v_ashrrev_i32_e32 v177, 31, v176
	v_lshlrev_b64 v[176:177], 12, v[176:177]
	v_lshl_add_u64 v[176:177], v[178:179], 0, v[176:177]
	global_store_dwordx4 v[176:177], v[172:175], off
	s_waitcnt lgkmcnt(0)
	v_mul_f32_e32 v14, v0, v180
	v_mul_f32_e32 v172, v1, v181
	v_cvt_pk_bf16_f32 v172, v14, v172
	ds_read2_b32 v[174:175], v100 offset0:90 offset1:123
	s_waitcnt lgkmcnt(0)
	v_mul_f32_e32 v173, v3, v175
	v_mul_f32_e32 v14, v2, v174
	v_cvt_pk_bf16_f32 v173, v14, v173
	ds_read2_b32 v[174:175], v100 offset0:156 offset1:189
	s_waitcnt lgkmcnt(0)
	v_mul_f32_e32 v14, v4, v174
	v_mul_f32_e32 v174, v5, v175
	v_cvt_pk_bf16_f32 v174, v14, v174
	ds_read2_b32 v[176:177], v100 offset0:222 offset1:255
	s_waitcnt lgkmcnt(0)
	v_mul_f32_e32 v175, v7, v177
	v_mul_f32_e32 v14, v6, v176
	v_cvt_pk_bf16_f32 v175, v14, v175
	ds_read2_b32 v[180:181], v100 offset0:28 offset1:61
	v_add_u32_e32 v176, s38, v106
	v_ashrrev_i32_e32 v177, 31, v176
	v_lshlrev_b64 v[176:177], 12, v[176:177]
	v_lshl_add_u64 v[176:177], v[178:179], 0, v[176:177]
	s_waitcnt lgkmcnt(0)
	v_mul_f32_e32 v0, v0, v180
	global_store_dwordx4 v[176:177], v[172:175], off
	v_mul_f32_e32 v1, v1, v181
	v_cvt_pk_bf16_f32 v0, v0, v1
	ds_read2_b32 v[172:173], v100 offset0:94 offset1:127
	s_waitcnt lgkmcnt(0)
	v_mul_f32_e32 v1, v2, v172
	v_mul_f32_e32 v2, v3, v173
	v_cvt_pk_bf16_f32 v1, v1, v2
	ds_read2_b32 v[2:3], v100 offset0:160 offset1:193
	s_waitcnt lgkmcnt(0)
	v_mul_f32_e32 v2, v4, v2
	v_mul_f32_e32 v3, v5, v3
	v_cvt_pk_bf16_f32 v2, v2, v3
	v_add_u32_e32 v3, 0x200, v100
	ds_read2_b32 v[4:5], v3 offset0:98 offset1:131
	s_waitcnt lgkmcnt(0)
	v_mul_f32_e32 v3, v6, v4
	v_mul_f32_e32 v4, v7, v5
	v_cvt_pk_bf16_f32 v3, v3, v4
	v_add_u32_e32 v4, s38, v107
	v_ashrrev_i32_e32 v5, 31, v4
	v_lshlrev_b64 v[4:5], 12, v[4:5]
	v_lshl_add_u64 v[4:5], v[178:179], 0, v[4:5]
	global_store_dwordx4 v[4:5], v[0:3], off
	s_waitcnt lgkmcnt(0)

;     const int nblk = N / 32, kb = item / nblk, nb = item % nblk, k0 = 128 * kb, n0 = 32 * nb;
;     const int nd0 = GLU ? (n0 < 6144 ? 256 * (n0 >> 7) + (n0 & 127) : 256 * ((n0 - 6144) >> 7) + 128 + ((n0 - 6144) & 127)) : n0;
; #pragma unroll 32
;     for (int i = 0; i < 64; ++i) { const int kk = 2 * i + (lane >> 5); scr[kk * 33 + (lane & 31)] = W[(size_t)(k0 + kk) * N + n0 + (lane & 31)]; }
.LBB0_58:
	s_andn2_b64 vcc, exec, s[2:3]
	s_cbranch_vccnz .LBB0_60
	s_load_dwordx2 s[24:25], s[6:7], 0xb8
	s_and_b32 s2, s41, 0x7e0
	s_lshl_b32 s3, s2, 2
	v_lshlrev_b32_e32 v14, 2, v12
	s_waitcnt lgkmcnt(0)
	s_add_u32 s24, s24, s3
	s_addc_u32 s25, s25, 0
	s_and_b32 s3, s43, 0x380
	v_add_u32_e32 v4, s3, v10
	v_lshl_add_u64 v[0:1], s[24:25], 0, v[14:15]
	v_add_u32_e32 v2, s3, v9
	v_ashrrev_i32_e32 v5, 31, v4
	v_add_u32_e32 v6, s3, v11
	v_add_u32_e32 v172, s3, v38
	v_add_u32_e32 v174, s3, v13
	v_add_u32_e32 v176, s3, v40
	v_add_u32_e32 v178, s3, v17
	v_add_u32_e32 v180, s3, v42
	v_lshl_add_u64 v[0:1], v[0:1], 0, s[30:31]
	v_ashrrev_i32_e32 v3, 31, v2
	v_lshlrev_b64 v[4:5], 13, v[4:5]
	v_ashrrev_i32_e32 v173, 31, v172
	v_ashrrev_i32_e32 v7, 31, v6
	v_ashrrev_i32_e32 v177, 31, v176
	v_ashrrev_i32_e32 v175, 31, v174
	v_ashrrev_i32_e32 v181, 31, v180
	v_ashrrev_i32_e32 v179, 31, v178
	v_lshlrev_b64 v[2:3], 13, v[2:3]
	v_lshl_add_u64 v[4:5], v[0:1], 0, v[4:5]
	v_lshlrev_b64 v[6:7], 13, v[6:7]
	v_lshlrev_b64 v[172:173], 13, v[172:173]
	v_lshlrev_b64 v[174:175], 13, v[174:175]
	v_lshlrev_b64 v[176:177], 13, v[176:177]
	v_lshlrev_b64 v[178:179], 13, v[178:179]
	v_lshlrev_b64 v[180:181], 13, v[180:181]
	v_lshl_add_u64 v[2:3], v[0:1], 0, v[2:3]
	v_lshl_add_u64 v[172:173], v[0:1], 0, v[172:173]
	v_lshl_add_u64 v[6:7], v[0:1], 0, v[6:7]
	v_lshl_add_u64 v[176:177], v[0:1], 0, v[176:177]
	v_lshl_add_u64 v[174:175], v[0:1], 0, v[174:175]
	v_lshl_add_u64 v[180:181], v[0:1], 0, v[180:181]
	v_lshl_add_u64 v[178:179], v[0:1], 0, v[178:179]
	global_load_dword v14, v[4:5], off nt
	global_load_dword v182, v[2:3], off nt
	global_load_dword v183, v[172:173], off nt
	global_load_dword v184, v[6:7], off nt
	global_load_dword v185, v[176:177], off nt
	global_load_dword v186, v[174:175], off nt
	global_load_dword v187, v[180:181], off nt
	global_load_dword v188, v[178:179], off nt
	v_add_u32_e32 v4, s3, v44
	v_add_u32_e32 v6, s3, v41
	v_add_u32_e32 v172, s3, v46
	v_add_u32_e32 v178, s3, v45
	v_add_u32_e32 v180, s3, v50
	v_add_u32_e32 v2, s3, v39
	v_ashrrev_i32_e32 v5, 31, v4
	v_ashrrev_i32_e32 v173, 31, v172
	v_ashrrev_i32_e32 v7, 31, v6
	v_add_u32_e32 v174, s3, v43
	v_add_u32_e32 v176, s3, v48
	v_ashrrev_i32_e32 v181, 31, v180
	v_ashrrev_i32_e32 v179, 31, v178
	v_ashrrev_i32_e32 v3, 31, v2
	v_lshlrev_b64 v[4:5], 13, v[4:5]
	v_lshlrev_b64 v[6:7], 13, v[6:7]
	v_lshlrev_b64 v[172:173], 13, v[172:173]
	v_ashrrev_i32_e32 v177, 31, v176
	v_ashrrev_i32_e32 v175, 31, v174
	v_lshlrev_b64 v[178:179], 13, v[178:179]
	v_lshlrev_b64 v[180:181], 13, v[180:181]
	v_lshlrev_b64 v[2:3], 13, v[2:3]
	v_lshl_add_u64 v[4:5], v[0:1], 0, v[4:5]
	v_lshl_add_u64 v[172:173], v[0:1], 0, v[172:173]
	v_lshl_add_u64 v[6:7], v[0:1], 0, v[6:7]
	v_lshlrev_b64 v[174:175], 13, v[174:175]
	v_lshlrev_b64 v[176:177], 13, v[176:177]
	v_lshl_add_u64 v[180:181], v[0:1], 0, v[180:181]
	v_lshl_add_u64 v[178:179], v[0:1], 0, v[178:179]
	v_lshl_add_u64 v[2:3], v[0:1], 0, v[2:3]
	v_lshl_add_u64 v[176:177], v[0:1], 0, v[176:177]
	v_lshl_add_u64 v[174:175], v[0:1], 0, v[174:175]
	global_load_dword v189, v[4:5], off nt
	global_load_dword v190, v[2:3], off nt
	global_load_dword v191, v[172:173], off nt
	global_load_dword v192, v[6:7], off nt
	global_load_dword v193, v[176:177], off nt
	global_load_dword v194, v[174:175], off nt
	s_nop 0
	global_load_dword v180, v[180:181], off nt
	s_nop 0
	global_load_dword v178, v[178:179], off nt
	v_add_u32_e32 v4, s3, v52
	v_add_u32_e32 v6, s3, v49
	v_add_u32_e32 v172, s3, v54
	v_add_u32_e32 v2, s3, v47
	v_ashrrev_i32_e32 v5, 31, v4
	v_ashrrev_i32_e32 v173, 31, v172
	v_ashrrev_i32_e32 v7, 31, v6
	v_add_u32_e32 v174, s3, v51
	v_add_u32_e32 v176, s3, v56
	v_ashrrev_i32_e32 v3, 31, v2
	v_lshlrev_b64 v[4:5], 13, v[4:5]
	v_lshlrev_b64 v[6:7], 13, v[6:7]
	v_lshlrev_b64 v[172:173], 13, v[172:173]
	v_ashrrev_i32_e32 v177, 31, v176
	v_ashrrev_i32_e32 v175, 31, v174
	v_lshlrev_b64 v[2:3], 13, v[2:3]
	v_lshl_add_u64 v[4:5], v[0:1], 0, v[4:5]
	v_lshl_add_u64 v[172:173], v[0:1], 0, v[172:173]
	v_lshl_add_u64 v[6:7], v[0:1], 0, v[6:7]
	v_lshlrev_b64 v[174:175], 13, v[174:175]
	v_lshlrev_b64 v[176:177], 13, v[176:177]
	v_lshl_add_u64 v[2:3], v[0:1], 0, v[2:3]
	v_lshl_add_u64 v[176:177], v[0:1], 0, v[176:177]
	v_lshl_add_u64 v[174:175], v[0:1], 0, v[174:175]
	global_load_dword v179, v[4:5], off nt
	global_load_dword v181, v[2:3], off nt
	s_nop 0
	global_load_dword v172, v[172:173], off nt
	s_nop 0
	global_load_dword v6, v[6:7], off nt
	s_nop 0
	global_load_dword v7, v[176:177], off nt
	global_load_dword v173, v[174:175], off nt
	v_add_u32_e32 v4, s3, v58
	v_add_u32_e32 v2, s3, v53
	v_ashrrev_i32_e32 v5, 31, v4
	v_ashrrev_i32_e32 v3, 31, v2
	v_lshlrev_b64 v[4:5], 13, v[4:5]
	v_lshlrev_b64 v[2:3], 13, v[2:3]
	v_lshl_add_u64 v[4:5], v[0:1], 0, v[4:5]
	global_load_dword v4, v[4:5], off nt
	v_lshl_add_u64 v[2:3], v[0:1], 0, v[2:3]
	global_load_dword v2, v[2:3], off nt
	v_add_u32_e32 v3, v97, v108
	v_add_u32_e32 v174, s3, v59
	v_add_u32_e32 v176, s3, v64
	v_ashrrev_i32_e32 v177, 31, v176
	s_waitcnt vmcnt(23)
	ds_write_b32 v3, v14
	v_add_u32_e32 v3, v97, v109
	s_waitcnt vmcnt(22)
	ds_write_b32 v3, v182
	v_add_u32_e32 v3, v97, v110
	s_waitcnt vmcnt(21)
	ds_write_b32 v3, v183
	v_add_u32_e32 v3, v97, v111
	s_waitcnt vmcnt(20)
	ds_write_b32 v3, v184
	v_add_u32_e32 v3, v97, v112
	s_waitcnt vmcnt(19)
	ds_write_b32 v3, v185
	v_add_u32_e32 v3, v97, v113
	s_waitcnt vmcnt(18)
	ds_write_b32 v3, v186
	v_add_u32_e32 v3, v97, v114
	s_waitcnt vmcnt(17)
	ds_write_b32 v3, v187
	v_add_u32_e32 v3, v97, v115
	s_waitcnt vmcnt(16)
;     ...
;     for (int i = 0; i < 64; ++i) { const int kk = 2 * i + (lane >> 5); scr[kk * 33 + (lane & 31)] = W[(size_t)(k0 + kk) * N + n0 + (lane & 31)]; }
	ds_write_b32 v3, v188
	v_add_u32_e32 v3, v97, v116
	v_ashrrev_i32_e32 v175, 31, v174
	v_lshlrev_b64 v[174:175], 13, v[174:175]
	v_lshlrev_b64 v[176:177], 13, v[176:177]
	v_lshl_add_u64 v[176:177], v[0:1], 0, v[176:177]
	v_lshl_add_u64 v[174:175], v[0:1], 0, v[174:175]
	s_lshl_b32 s10, s3, 1
	s_waitcnt vmcnt(15)
	ds_write_b32 v3, v189
	v_add_u32_e32 v3, v97, v117
	s_waitcnt vmcnt(14)
	ds_write_b32 v3, v190
	v_add_u32_e32 v3, v97, v118
	s_waitcnt vmcnt(13)
	ds_write_b32 v3, v191
	v_add_u32_e32 v3, v97, v119
	s_waitcnt vmcnt(12)
	ds_write_b32 v3, v192
	v_add_u32_e32 v3, v97, v120
	s_waitcnt vmcnt(11)
	ds_write_b32 v3, v193
	v_add_u32_e32 v3, v97, v121
	s_waitcnt vmcnt(10)
	ds_write_b32 v3, v194
	v_add_u32_e32 v3, v97, v122
	s_waitcnt vmcnt(9)
	ds_write_b32 v3, v180
	v_add_u32_e32 v3, v97, v123
	s_waitcnt vmcnt(8)
	ds_write_b32 v3, v178
	v_add_u32_e32 v3, v97, v124
	v_add_u32_e32 v178, s3, v61
	v_add_u32_e32 v180, s3, v66
	s_waitcnt vmcnt(7)
	ds_write_b32 v3, v179
	v_add_u32_e32 v3, v97, v125
	s_waitcnt vmcnt(6)
	ds_write_b32 v3, v181
	v_add_u32_e32 v3, v97, v126
	s_waitcnt vmcnt(5)
	ds_write_b32 v3, v172
	v_add_u32_e32 v3, v97, v127
	s_waitcnt vmcnt(4)
	ds_write_b32 v3, v6
	v_add_u32_e32 v3, v97, v128
	s_waitcnt vmcnt(3)
	ds_write_b32 v3, v7
	v_add_u32_e32 v3, v97, v129
	s_waitcnt vmcnt(2)
	ds_write_b32 v3, v173
	v_add_u32_e32 v3, v97, v130
	v_add_u32_e32 v6, s3, v57
	s_waitcnt vmcnt(1)
	ds_write_b32 v3, v4
	v_add_u32_e32 v3, v97, v131
	v_add_u32_e32 v4, s3, v60
	s_waitcnt vmcnt(0)
	ds_write_b32 v3, v2
	v_add_u32_e32 v2, s3, v55
	v_ashrrev_i32_e32 v5, 31, v4
	v_add_u32_e32 v172, s3, v62
	v_ashrrev_i32_e32 v3, 31, v2
	v_lshlrev_b64 v[4:5], 13, v[4:5]
	v_ashrrev_i32_e32 v173, 31, v172
	v_ashrrev_i32_e32 v7, 31, v6
	v_ashrrev_i32_e32 v181, 31, v180
	v_ashrrev_i32_e32 v179, 31, v178
	v_lshlrev_b64 v[2:3], 13, v[2:3]
	v_lshl_add_u64 v[4:5], v[0:1], 0, v[4:5]
	v_lshlrev_b64 v[6:7], 13, v[6:7]
	v_lshlrev_b64 v[172:173], 13, v[172:173]
	v_lshlrev_b64 v[178:179], 13, v[178:179]
	v_lshlrev_b64 v[180:181], 13, v[180:181]
	v_lshl_add_u64 v[2:3], v[0:1], 0, v[2:3]
	v_lshl_add_u64 v[172:173], v[0:1], 0, v[172:173]
	v_lshl_add_u64 v[6:7], v[0:1], 0, v[6:7]
	v_lshl_add_u64 v[180:181], v[0:1], 0, v[180:181]
	v_lshl_add_u64 v[178:179], v[0:1], 0, v[178:179]
	global_load_dword v14, v[4:5], off nt
	global_load_dword v182, v[2:3], off nt
	global_load_dword v183, v[172:173], off nt
	global_load_dword v184, v[6:7], off nt
	global_load_dword v185, v[176:177], off nt
	global_load_dword v186, v[174:175], off nt
	global_load_dword v187, v[180:181], off nt
	global_load_dword v188, v[178:179], off nt
	v_add_u32_e32 v4, s3, v68
	v_add_u32_e32 v2, s3, v63
	v_ashrrev_i32_e32 v5, 31, v4
	v_add_u32_e32 v6, s3, v65
	v_add_u32_e32 v172, s3, v70
	v_add_u32_e32 v174, s3, v67
	v_add_u32_e32 v176, s3, v72
	v_add_u32_e32 v178, s3, v69
	v_add_u32_e32 v180, s3, v74
	v_ashrrev_i32_e32 v3, 31, v2
	v_lshlrev_b64 v[4:5], 13, v[4:5]
	v_ashrrev_i32_e32 v173, 31, v172
	v_ashrrev_i32_e32 v7, 31, v6
	v_ashrrev_i32_e32 v177, 31, v176
	v_ashrrev_i32_e32 v175, 31, v174
	v_ashrrev_i32_e32 v181, 31, v180
	v_ashrrev_i32_e32 v179, 31, v178
	v_lshlrev_b64 v[2:3], 13, v[2:3]
	v_lshl_add_u64 v[4:5], v[0:1], 0, v[4:5]
	v_lshlrev_b64 v[6:7], 13, v[6:7]
	v_lshlrev_b64 v[172:173], 13, v[172:173]
	v_lshlrev_b64 v[174:175], 13, v[174:175]
	v_lshlrev_b64 v[176:177], 13, v[176:177]
	v_lshlrev_b64 v[178:179], 13, v[178:179]
	v_lshlrev_b64 v[180:181], 13, v[180:181]
	v_lshl_add_u64 v[2:3], v[0:1], 0, v[2:3]
	v_lshl_add_u64 v[172:173], v[0:1], 0, v[172:173]
	v_lshl_add_u64 v[6:7], v[0:1], 0, v[6:7]
	v_lshl_add_u64 v[176:177], v[0:1], 0, v[176:177]
	v_lshl_add_u64 v[174:175], v[0:1], 0, v[174:175]
	v_lshl_add_u64 v[180:181], v[0:1], 0, v[180:181]
	v_lshl_add_u64 v[178:179], v[0:1], 0, v[178:179]
	global_load_dword v189, v[4:5], off nt
	global_load_dword v190, v[2:3], off nt
	global_load_dword v191, v[172:173], off nt
	global_load_dword v192, v[6:7], off nt
	global_load_dword v193, v[176:177], off nt
	global_load_dword v194, v[174:175], off nt
	global_load_dword v195, v[180:181], off nt
	global_load_dword v196, v[178:179], off nt
	v_add_u32_e32 v4, s3, v76
	v_add_u32_e32 v174, s3, v75
	v_add_u32_e32 v176, s3, v80
	v_add_u32_e32 v2, s3, v71
	v_ashrrev_i32_e32 v5, 31, v4
	v_add_u32_e32 v6, s3, v73
	v_add_u32_e32 v172, s3, v78
	v_ashrrev_i32_e32 v177, 31, v176
	v_ashrrev_i32_e32 v175, 31, v174
	v_add_u32_e32 v178, s3, v77
	v_add_u32_e32 v180, s3, v82
	v_ashrrev_i32_e32 v3, 31, v2
	v_lshlrev_b64 v[4:5], 13, v[4:5]
	v_ashrrev_i32_e32 v173, 31, v172
	v_ashrrev_i32_e32 v7, 31, v6
	v_lshlrev_b64 v[174:175], 13, v[174:175]
	v_lshlrev_b64 v[176:177], 13, v[176:177]
	v_ashrrev_i32_e32 v181, 31, v180
	v_ashrrev_i32_e32 v179, 31, v178
	v_lshlrev_b64 v[2:3], 13, v[2:3]
	v_lshl_add_u64 v[4:5], v[0:1], 0, v[4:5]
	v_lshlrev_b64 v[6:7], 13, v[6:7]
	v_lshlrev_b64 v[172:173], 13, v[172:173]
	v_lshl_add_u64 v[176:177], v[0:1], 0, v[176:177]
	v_lshl_add_u64 v[174:175], v[0:1], 0, v[174:175]
	v_lshlrev_b64 v[178:179], 13, v[178:179]
	v_lshlrev_b64 v[180:181], 13, v[180:181]
	v_lshl_add_u64 v[2:3], v[0:1], 0, v[2:3]
	v_lshl_add_u64 v[172:173], v[0:1], 0, v[172:173]
	v_lshl_add_u64 v[6:7], v[0:1], 0, v[6:7]
	v_lshl_add_u64 v[180:181], v[0:1], 0, v[180:181]
	v_lshl_add_u64 v[178:179], v[0:1], 0, v[178:179]
	global_load_dword v197, v[4:5], off nt
	global_load_dword v198, v[2:3], off nt
	global_load_dword v199, v[172:173], off nt
	global_load_dword v200, v[6:7], off nt
	global_load_dword v201, v[176:177], off nt
	global_load_dword v202, v[174:175], off nt
	global_load_dword v203, v[180:181], off nt
	global_load_dword v204, v[178:179], off nt
;     ...
;     for (int i = 0; i < 64; ++i) { const int kk = 2 * i + (lane >> 5); scr[kk * 33 + (lane & 31)] = W[(size_t)(k0 + kk) * N + n0 + (lane & 31)]; }
	v_add_u32_e32 v4, s3, v84
	v_add_u32_e32 v174, s3, v83
	v_add_u32_e32 v176, s3, v88
	v_add_u32_e32 v2, s3, v79
	v_ashrrev_i32_e32 v5, 31, v4
	v_add_u32_e32 v6, s3, v81
	v_add_u32_e32 v172, s3, v86
	v_ashrrev_i32_e32 v177, 31, v176
	v_ashrrev_i32_e32 v175, 31, v174
	v_add_u32_e32 v178, s3, v85
	v_add_u32_e32 v180, s3, v90
	v_ashrrev_i32_e32 v3, 31, v2
	v_lshlrev_b64 v[4:5], 13, v[4:5]
	v_ashrrev_i32_e32 v173, 31, v172
	v_ashrrev_i32_e32 v7, 31, v6
	v_lshlrev_b64 v[174:175], 13, v[174:175]
	v_lshlrev_b64 v[176:177], 13, v[176:177]
	v_ashrrev_i32_e32 v181, 31, v180
	v_ashrrev_i32_e32 v179, 31, v178
	v_lshlrev_b64 v[2:3], 13, v[2:3]
	v_lshl_add_u64 v[4:5], v[0:1], 0, v[4:5]
	v_lshlrev_b64 v[6:7], 13, v[6:7]
	v_lshlrev_b64 v[172:173], 13, v[172:173]
	v_lshl_add_u64 v[176:177], v[0:1], 0, v[176:177]
	v_lshl_add_u64 v[174:175], v[0:1], 0, v[174:175]
	v_lshlrev_b64 v[178:179], 13, v[178:179]
	v_lshlrev_b64 v[180:181], 13, v[180:181]
	v_lshl_add_u64 v[2:3], v[0:1], 0, v[2:3]
	v_lshl_add_u64 v[172:173], v[0:1], 0, v[172:173]
	v_lshl_add_u64 v[6:7], v[0:1], 0, v[6:7]
	v_lshl_add_u64 v[180:181], v[0:1], 0, v[180:181]
	v_lshl_add_u64 v[178:179], v[0:1], 0, v[178:179]
	global_load_dword v205, v[4:5], off nt
	global_load_dword v206, v[2:3], off nt
	global_load_dword v207, v[172:173], off nt
	global_load_dword v208, v[6:7], off nt
	s_nop 0
	global_load_dword v176, v[176:177], off nt
	s_nop 0
	global_load_dword v174, v[174:175], off nt
	s_nop 0
	global_load_dword v175, v[180:181], off nt
	global_load_dword v177, v[178:179], off nt
	v_add_u32_e32 v4, s3, v92
	v_add_u32_e32 v2, s3, v87
	v_ashrrev_i32_e32 v5, 31, v4
	v_ashrrev_i32_e32 v3, 31, v2
	v_lshlrev_b64 v[4:5], 13, v[4:5]
	v_lshlrev_b64 v[2:3], 13, v[2:3]
	v_lshl_add_u64 v[4:5], v[0:1], 0, v[4:5]
	v_lshl_add_u64 v[2:3], v[0:1], 0, v[2:3]
	global_load_dword v178, v[4:5], off nt
	global_load_dword v179, v[2:3], off nt
	v_add_u32_e32 v4, s3, v94
	v_add_u32_e32 v6, s3, v91
	v_add_u32_e32 v172, s3, v96
	v_add_u32_e32 v2, s3, v89
	v_ashrrev_i32_e32 v5, 31, v4
	v_ashrrev_i32_e32 v173, 31, v172
	v_ashrrev_i32_e32 v7, 31, v6
	v_ashrrev_i32_e32 v3, 31, v2
	v_lshlrev_b64 v[4:5], 13, v[4:5]
	v_lshlrev_b64 v[6:7], 13, v[6:7]
	v_lshlrev_b64 v[172:173], 13, v[172:173]
	v_lshlrev_b64 v[2:3], 13, v[2:3]
	v_lshl_add_u64 v[4:5], v[0:1], 0, v[4:5]
	v_lshl_add_u64 v[172:173], v[0:1], 0, v[172:173]
	v_lshl_add_u64 v[6:7], v[0:1], 0, v[6:7]
	v_lshl_add_u64 v[2:3], v[0:1], 0, v[2:3]
	global_load_dword v180, v[4:5], off nt
	global_load_dword v181, v[2:3], off nt
	s_nop 0
	global_load_dword v172, v[172:173], off nt
	s_nop 0
	global_load_dword v6, v[6:7], off nt
	v_add_u32_e32 v4, s3, v98
	v_add_u32_e32 v2, s3, v93
	v_ashrrev_i32_e32 v5, 31, v4
	v_ashrrev_i32_e32 v3, 31, v2
	v_lshlrev_b64 v[4:5], 13, v[4:5]
	v_lshlrev_b64 v[2:3], 13, v[2:3]
	v_lshl_add_u64 v[4:5], v[0:1], 0, v[4:5]
	global_load_dword v4, v[4:5], off nt
	v_lshl_add_u64 v[0:1], v[0:1], 0, v[2:3]
	global_load_dword v0, v[0:1], off nt
	v_add_u32_e32 v1, v97, v132
	s_waitcnt vmcnt(39)
	ds_write_b32 v1, v14
	v_add_u32_e32 v1, v97, v133
	s_waitcnt vmcnt(38)
	ds_write_b32 v1, v182
	v_add_u32_e32 v1, v97, v134
	s_waitcnt vmcnt(37)
	ds_write_b32 v1, v183
	v_add_u32_e32 v1, v97, v135
	s_waitcnt vmcnt(36)
	ds_write_b32 v1, v184
	v_add_u32_e32 v1, v97, v136
	s_waitcnt vmcnt(35)
	ds_write_b32 v1, v185
	v_add_u32_e32 v1, v97, v137
	s_waitcnt vmcnt(34)
	ds_write_b32 v1, v186
	v_add_u32_e32 v1, v97, v138
	s_waitcnt vmcnt(33)
	ds_write_b32 v1, v187
	v_add_u32_e32 v1, v97, v139
	s_waitcnt vmcnt(32)
	ds_write_b32 v1, v188
	v_add_u32_e32 v1, v97, v140
	s_waitcnt vmcnt(31)
	ds_write_b32 v1, v189
	v_add_u32_e32 v1, v97, v141
	s_waitcnt vmcnt(30)
	ds_write_b32 v1, v190
	v_add_u32_e32 v1, v97, v142
	s_waitcnt vmcnt(29)
	ds_write_b32 v1, v191
	v_add_u32_e32 v1, v97, v143
	s_waitcnt vmcnt(28)
	ds_write_b32 v1, v192
	v_add_u32_e32 v1, v97, v144
	s_waitcnt vmcnt(27)
	ds_write_b32 v1, v193
	v_add_u32_e32 v1, v97, v145
	s_waitcnt vmcnt(26)
	ds_write_b32 v1, v194
	v_add_u32_e32 v1, v97, v146
	s_waitcnt vmcnt(25)
	ds_write_b32 v1, v195
	v_add_u32_e32 v1, v97, v147
	s_waitcnt vmcnt(24)
	ds_write_b32 v1, v196
	v_add_u32_e32 v1, v97, v148
	s_waitcnt vmcnt(23)
	ds_write_b32 v1, v197
	v_add_u32_e32 v1, v97, v149
	s_waitcnt vmcnt(22)
	ds_write_b32 v1, v198
	v_add_u32_e32 v1, v97, v150
	s_waitcnt vmcnt(21)
	ds_write_b32 v1, v199
	v_add_u32_e32 v1, v97, v151
	s_waitcnt vmcnt(20)
	ds_write_b32 v1, v200
	v_add_u32_e32 v1, v97, v152
	s_waitcnt vmcnt(19)
	ds_write_b32 v1, v201
	v_add_u32_e32 v1, v97, v153
	s_waitcnt vmcnt(18)
	ds_write_b32 v1, v202
	v_add_u32_e32 v1, v97, v154
	s_waitcnt vmcnt(17)
	ds_write_b32 v1, v203
	v_add_u32_e32 v1, v97, v155
	s_waitcnt vmcnt(16)
	ds_write_b32 v1, v204
	v_add_u32_e32 v1, v97, v156
	s_waitcnt vmcnt(15)
	ds_write_b32 v1, v205
	v_add_u32_e32 v1, v97, v157
	s_waitcnt vmcnt(14)
	ds_write_b32 v1, v206
	v_add_u32_e32 v1, v97, v158
	s_waitcnt vmcnt(13)
	ds_write_b32 v1, v207
	v_add_u32_e32 v1, v97, v159
	s_waitcnt vmcnt(12)
	ds_write_b32 v1, v208
	v_add_u32_e32 v1, v97, v160
	s_waitcnt vmcnt(11)
	ds_write_b32 v1, v176
	v_add_u32_e32 v1, v97, v161
	s_waitcnt vmcnt(10)
	ds_write_b32 v1, v174
	v_add_u32_e32 v1, v97, v162
	s_waitcnt vmcnt(9)
	ds_write_b32 v1, v175
	v_add_u32_e32 v1, v97, v163
	s_waitcnt vmcnt(8)
	ds_write_b32 v1, v177
	v_add_u32_e32 v1, v97, v164
	s_waitcnt vmcnt(7)
	ds_write_b32 v1, v178
	v_add_u32_e32 v1, v97, v165
	s_waitcnt vmcnt(6)
; __device__ __forceinline__ unsigned cvt_pk_bf16(float lo, float hi) { unsigned r; asm volatile("v_cvt_pk_bf16_f32 %0, %1, %2" : "=v"(r) : "v"(lo), "v"(hi)); return r; }
; #define GAS __attribute__((address_space(1)))
; #define LAS __attribute__((address_space(3)))
; #define LDS_WAIT() asm volatile("s_waitcnt lgkmcnt(0)" ::: "memory")
;     ...
;     LDS_WAIT(); asm volatile("" ::: "memory");
;     const int c = lane & 15;
;     float gk[8];
;     if (gain) load8f(gain + k0 + 8 * c, gk); else {
; #pragma unroll
;         for (int e = 0; e < 8; ++e) gk[e] = 1.0f; }
; #pragma unroll
;     for (int j = 0; j < 8; ++j) { const int n = (lane >> 4) + 4 * j; const LAS float* s = scr + (8 * c) * 33 + n;
;         v4u o; o.x = cvt_pk_bf16(s[0 * 33] * gk[0], s[1 * 33] * gk[1]); o.y = cvt_pk_bf16(s[2 * 33] * gk[2], s[3 * 33] * gk[3]); o.z = cvt_pk_bf16(s[4 * 33] * gk[4], s[5 * 33] * gk[5]); o.w = cvt_pk_bf16(s[6 * 33] * gk[6], s[7 * 33] * gk[7]);
;         *(GAS v4u*)(WT + (size_t)(nd0 + n) * K + k0 + 8 * c) = o; }
;     LDS_WAIT(); asm volatile("" ::: "memory");
	ds_write_b32 v1, v179
	v_add_u32_e32 v1, v97, v166
	s_waitcnt vmcnt(5)
	ds_write_b32 v1, v180
	v_add_u32_e32 v1, v97, v167
	s_waitcnt vmcnt(4)
	ds_write_b32 v1, v181
	v_add_u32_e32 v1, v97, v168
	s_waitcnt vmcnt(3)
	ds_write_b32 v1, v172
	v_add_u32_e32 v1, v97, v169
	s_waitcnt vmcnt(2)
	ds_write_b32 v1, v6
	v_add_u32_e32 v1, v97, v170
	s_waitcnt vmcnt(1)
	ds_write_b32 v1, v4
	v_add_u32_e32 v1, v97, v171
	s_waitcnt vmcnt(0)
	ds_write_b32 v1, v0
	s_waitcnt lgkmcnt(0)
	ds_read2_b32 v[0:1], v100 offset1:33
	s_waitcnt lgkmcnt(0)
	v_cvt_pk_bf16_f32 v0, v0, v1
	ds_read2_b32 v[2:3], v100 offset0:66 offset1:99
	s_waitcnt lgkmcnt(0)
	v_cvt_pk_bf16_f32 v1, v2, v3
	ds_read2_b32 v[2:3], v100 offset0:132 offset1:165
	s_waitcnt lgkmcnt(0)
	v_cvt_pk_bf16_f32 v2, v2, v3
	ds_read2_b32 v[4:5], v100 offset0:198 offset1:231
	s_waitcnt lgkmcnt(0)
	v_cvt_pk_bf16_f32 v3, v4, v5
	v_add_u32_e32 v4, s2, v99
	v_ashrrev_i32_e32 v5, 31, v4
	v_lshl_add_u64 v[6:7], v[28:29], 0, s[10:11]
	v_lshlrev_b64 v[4:5], 11, v[4:5]
	v_lshl_add_u64 v[4:5], v[6:7], 0, v[4:5]
	ds_read2_b32 v[172:173], v100 offset0:4 offset1:37
	global_store_dwordx4 v[4:5], v[0:3], off
	s_waitcnt lgkmcnt(0)
	s_nop 0
	v_cvt_pk_bf16_f32 v0, v172, v173
	ds_read2_b32 v[2:3], v100 offset0:70 offset1:103
	s_waitcnt lgkmcnt(0)
	v_cvt_pk_bf16_f32 v1, v2, v3
	ds_read2_b32 v[2:3], v100 offset0:136 offset1:169
	s_waitcnt lgkmcnt(0)
	v_cvt_pk_bf16_f32 v2, v2, v3
	ds_read2_b32 v[4:5], v100 offset0:202 offset1:235
	s_waitcnt lgkmcnt(0)
	v_cvt_pk_bf16_f32 v3, v4, v5
	v_add_u32_e32 v4, s2, v101
	v_ashrrev_i32_e32 v5, 31, v4
	v_lshlrev_b64 v[4:5], 11, v[4:5]
	v_lshl_add_u64 v[4:5], v[6:7], 0, v[4:5]
	ds_read2_b32 v[172:173], v100 offset0:8 offset1:41
	global_store_dwordx4 v[4:5], v[0:3], off
	s_waitcnt lgkmcnt(0)
	s_nop 0
	v_cvt_pk_bf16_f32 v0, v172, v173
	ds_read2_b32 v[2:3], v100 offset0:74 offset1:107
	s_waitcnt lgkmcnt(0)
	v_cvt_pk_bf16_f32 v1, v2, v3
	ds_read2_b32 v[2:3], v100 offset0:140 offset1:173
	s_waitcnt lgkmcnt(0)
	v_cvt_pk_bf16_f32 v2, v2, v3
	ds_read2_b32 v[4:5], v100 offset0:206 offset1:239
	s_waitcnt lgkmcnt(0)
	v_cvt_pk_bf16_f32 v3, v4, v5
	v_add_u32_e32 v4, s2, v102
	v_ashrrev_i32_e32 v5, 31, v4
	v_lshlrev_b64 v[4:5], 11, v[4:5]
	v_lshl_add_u64 v[4:5], v[6:7], 0, v[4:5]
	ds_read2_b32 v[172:173], v100 offset0:12 offset1:45
	global_store_dwordx4 v[4:5], v[0:3], off
	s_waitcnt lgkmcnt(0)
	s_nop 0
	v_cvt_pk_bf16_f32 v0, v172, v173
	ds_read2_b32 v[2:3], v100 offset0:78 offset1:111
	s_waitcnt lgkmcnt(0)
	v_cvt_pk_bf16_f32 v1, v2, v3
	ds_read2_b32 v[2:3], v100 offset0:144 offset1:177
	s_waitcnt lgkmcnt(0)
	v_cvt_pk_bf16_f32 v2, v2, v3
	ds_read2_b32 v[4:5], v100 offset0:210 offset1:243
	s_waitcnt lgkmcnt(0)
	v_cvt_pk_bf16_f32 v3, v4, v5
	v_add_u32_e32 v4, s2, v103
	v_ashrrev_i32_e32 v5, 31, v4
	v_lshlrev_b64 v[4:5], 11, v[4:5]
	v_lshl_add_u64 v[4:5], v[6:7], 0, v[4:5]
	ds_read2_b32 v[172:173], v100 offset0:16 offset1:49
	global_store_dwordx4 v[4:5], v[0:3], off
	s_waitcnt lgkmcnt(0)
	s_nop 0
	v_cvt_pk_bf16_f32 v0, v172, v173
	ds_read2_b32 v[2:3], v100 offset0:82 offset1:115
	s_waitcnt lgkmcnt(0)
	v_cvt_pk_bf16_f32 v1, v2, v3
	ds_read2_b32 v[2:3], v100 offset0:148 offset1:181
	s_waitcnt lgkmcnt(0)
	v_cvt_pk_bf16_f32 v2, v2, v3
	ds_read2_b32 v[4:5], v100 offset0:214 offset1:247
	s_waitcnt lgkmcnt(0)
	v_cvt_pk_bf16_f32 v3, v4, v5
	v_add_u32_e32 v4, s2, v104
	v_ashrrev_i32_e32 v5, 31, v4
	v_lshlrev_b64 v[4:5], 11, v[4:5]
	v_lshl_add_u64 v[4:5], v[6:7], 0, v[4:5]
	ds_read2_b32 v[172:173], v100 offset0:20 offset1:53
	global_store_dwordx4 v[4:5], v[0:3], off
	s_waitcnt lgkmcnt(0)
	s_nop 0
	v_cvt_pk_bf16_f32 v0, v172, v173
	ds_read2_b32 v[2:3], v100 offset0:86 offset1:119
	s_waitcnt lgkmcnt(0)
	v_cvt_pk_bf16_f32 v1, v2, v3
	ds_read2_b32 v[2:3], v100 offset0:152 offset1:185
	s_waitcnt lgkmcnt(0)
	v_cvt_pk_bf16_f32 v2, v2, v3
	ds_read2_b32 v[4:5], v100 offset0:218 offset1:251
	s_waitcnt lgkmcnt(0)
	v_cvt_pk_bf16_f32 v3, v4, v5
	v_add_u32_e32 v4, s2, v105
	v_ashrrev_i32_e32 v5, 31, v4
	v_lshlrev_b64 v[4:5], 11, v[4:5]
	v_lshl_add_u64 v[4:5], v[6:7], 0, v[4:5]
	ds_read2_b32 v[172:173], v100 offset0:24 offset1:57
	global_store_dwordx4 v[4:5], v[0:3], off
	s_waitcnt lgkmcnt(0)
	s_nop 0
	v_cvt_pk_bf16_f32 v0, v172, v173
	ds_read2_b32 v[2:3], v100 offset0:90 offset1:123
	s_waitcnt lgkmcnt(0)
	v_cvt_pk_bf16_f32 v1, v2, v3
	ds_read2_b32 v[2:3], v100 offset0:156 offset1:189
	s_waitcnt lgkmcnt(0)
	v_cvt_pk_bf16_f32 v2, v2, v3
	ds_read2_b32 v[4:5], v100 offset0:222 offset1:255
	s_waitcnt lgkmcnt(0)
	v_cvt_pk_bf16_f32 v3, v4, v5
	v_add_u32_e32 v4, s2, v106
	v_ashrrev_i32_e32 v5, 31, v4
	v_lshlrev_b64 v[4:5], 11, v[4:5]
	v_lshl_add_u64 v[4:5], v[6:7], 0, v[4:5]
	ds_read2_b32 v[172:173], v100 offset0:28 offset1:61
	global_store_dwordx4 v[4:5], v[0:3], off
	s_waitcnt lgkmcnt(0)
	s_nop 0
	v_cvt_pk_bf16_f32 v0, v172, v173
	ds_read2_b32 v[2:3], v100 offset0:94 offset1:127
	s_waitcnt lgkmcnt(0)
	v_cvt_pk_bf16_f32 v1, v2, v3
	ds_read2_b32 v[2:3], v100 offset0:160 offset1:193
	s_waitcnt lgkmcnt(0)
	v_cvt_pk_bf16_f32 v2, v2, v3
	v_add_u32_e32 v3, 0x200, v100
	ds_read2_b32 v[4:5], v3 offset0:98 offset1:131
	s_waitcnt lgkmcnt(0)
	v_cvt_pk_bf16_f32 v3, v4, v5
	v_add_u32_e32 v4, s2, v107
	v_ashrrev_i32_e32 v5, 31, v4
	v_lshlrev_b64 v[4:5], 11, v[4:5]
	v_lshl_add_u64 v[4:5], v[6:7], 0, v[4:5]
	global_store_dwordx4 v[4:5], v[0:3], off
	s_waitcnt lgkmcnt(0)

;     const int nblk = N / 32, kb = item / nblk, nb = item % nblk, k0 = 128 * kb, n0 = 32 * nb;
;     const int nd0 = GLU ? (n0 < 6144 ? 256 * (n0 >> 7) + (n0 & 127) : 256 * ((n0 - 6144) >> 7) + 128 + ((n0 - 6144) & 127)) : n0;
; #pragma unroll 32
;     for (int i = 0; i < 64; ++i) { const int kk = 2 * i + (lane >> 5); scr[kk * 33 + (lane & 31)] = W[(size_t)(k0 + kk) * N + n0 + (lane & 31)]; }
.LBB0_61:
	s_andn2_b64 vcc, exec, s[2:3]
	s_cbranch_vccnz .LBB0_63
	s_add_i32 s2, s56, 0x9400
	s_and_b32 s3, s2, 0xffff
	s_mul_i32 s3, s3, 0xe38f
	s_lshr_b32 s10, s3, 24
	s_load_dwordx2 s[38:39], s[6:7], 0xb0
	s_mul_i32 s3, s10, 0x120
	s_sub_i32 s2, s2, s3
	s_lshl_b32 s2, s2, 5
	s_and_b32 s24, s2, 0xffe0
	s_lshl_b32 s25, s24, 2
	s_load_dwordx2 s[2:3], s[6:7], 0x40
	s_waitcnt lgkmcnt(0)
	s_add_u32 s38, s38, s25
	s_addc_u32 s39, s39, 0
	v_lshlrev_b32_e32 v14, 2, v12
	v_lshl_add_u64 v[0:1], s[38:39], 0, v[14:15]
	s_lshl_b32 s25, s10, 7
	v_lshl_add_u64 v[0:1], v[0:1], 0, s[34:35]
	v_add_u32_e32 v14, s25, v11
	v_add_u32_e32 v2, s25, v10
	v_mad_i64_i32 v[172:173], s[38:39], v14, s52, v[0:1]
	v_add_u32_e32 v14, s25, v13
	v_add_u32_e32 v4, s25, v9
	v_mad_i64_i32 v[2:3], s[38:39], v2, s52, v[0:1]
	v_add_u32_e32 v6, s25, v38
	v_add_u32_e32 v174, s25, v40
	v_mad_i64_i32 v[176:177], s[38:39], v14, s52, v[0:1]
	v_add_u32_e32 v14, s25, v17
	v_add_u32_e32 v178, s25, v42
	v_mad_i64_i32 v[4:5], s[38:39], v4, s52, v[0:1]
	v_mad_i64_i32 v[6:7], s[38:39], v6, s52, v[0:1]
	v_mad_i64_i32 v[174:175], s[38:39], v174, s52, v[0:1]
	v_mad_i64_i32 v[178:179], s[38:39], v178, s52, v[0:1]
	v_mad_i64_i32 v[180:181], s[38:39], v14, s52, v[0:1]
	global_load_dword v14, v[2:3], off nt
	global_load_dword v182, v[4:5], off nt
	global_load_dword v183, v[6:7], off nt
	global_load_dword v184, v[172:173], off nt
	global_load_dword v185, v[174:175], off nt
	global_load_dword v186, v[176:177], off nt
	global_load_dword v187, v[178:179], off nt
	global_load_dword v188, v[180:181], off nt
	v_add_u32_e32 v2, s25, v44
	v_add_u32_e32 v176, s25, v43
	v_add_u32_e32 v178, s25, v50
	v_add_u32_e32 v4, s25, v39
	v_mad_i64_i32 v[2:3], s[38:39], v2, s52, v[0:1]
	v_add_u32_e32 v172, s25, v41
	v_add_u32_e32 v6, s25, v46
	v_add_u32_e32 v174, s25, v48
	v_mad_i64_i32 v[176:177], s[38:39], v176, s52, v[0:1]
	v_add_u32_e32 v180, s25, v45
	v_mad_i64_i32 v[178:179], s[38:39], v178, s52, v[0:1]
	v_mad_i64_i32 v[4:5], s[38:39], v4, s52, v[0:1]
	v_mad_i64_i32 v[6:7], s[38:39], v6, s52, v[0:1]
	v_mad_i64_i32 v[172:173], s[38:39], v172, s52, v[0:1]
	v_mad_i64_i32 v[174:175], s[38:39], v174, s52, v[0:1]
	v_mad_i64_i32 v[180:181], s[38:39], v180, s52, v[0:1]
	global_load_dword v189, v[2:3], off nt
	global_load_dword v190, v[4:5], off nt
	global_load_dword v191, v[6:7], off nt
	global_load_dword v192, v[172:173], off nt
	global_load_dword v193, v[174:175], off nt
	s_nop 0
	global_load_dword v176, v[176:177], off nt
	s_nop 0
	global_load_dword v177, v[178:179], off nt
	s_nop 0
	global_load_dword v178, v[180:181], off nt
	v_add_u32_e32 v2, s25, v52
	v_mad_i64_i32 v[2:3], s[38:39], v2, s52, v[0:1]
	global_load_dword v179, v[2:3], off nt
	v_add_u32_e32 v4, s25, v47
	v_add_u32_e32 v6, s25, v49
	v_add_u32_e32 v2, s25, v54
	v_mad_i64_i32 v[4:5], s[38:39], v4, s52, v[0:1]
	v_mad_i64_i32 v[2:3], s[38:39], v2, s52, v[0:1]
	v_mad_i64_i32 v[6:7], s[38:39], v6, s52, v[0:1]
	v_add_u32_e32 v172, s25, v56
	v_add_u32_e32 v174, s25, v51
	v_mad_i64_i32 v[172:173], s[38:39], v172, s52, v[0:1]
	global_load_dword v4, v[4:5], off nt
	s_nop 0
	global_load_dword v5, v[2:3], off nt
	s_nop 0
	global_load_dword v6, v[6:7], off nt
	s_nop 0
	global_load_dword v7, v[172:173], off nt
	v_add_u32_e32 v2, s25, v58
	v_mad_i64_i32 v[174:175], s[38:39], v174, s52, v[0:1]
	v_add_u32_e32 v172, s25, v53
	v_mad_i64_i32 v[2:3], s[38:39], v2, s52, v[0:1]
	global_load_dword v173, v[174:175], off nt
	s_nop 0
	global_load_dword v174, v[2:3], off nt
	v_mad_i64_i32 v[2:3], s[38:39], v172, s52, v[0:1]
	global_load_dword v2, v[2:3], off nt
	v_add_u32_e32 v3, v97, v108
	s_waitcnt vmcnt(23)
	ds_write_b32 v3, v14
	v_add_u32_e32 v3, v97, v109
	s_waitcnt vmcnt(22)
	ds_write_b32 v3, v182
	v_add_u32_e32 v3, v97, v110
	s_waitcnt vmcnt(21)
	ds_write_b32 v3, v183
	v_add_u32_e32 v3, v97, v111
	s_waitcnt vmcnt(20)
	ds_write_b32 v3, v184
	v_add_u32_e32 v3, v97, v112
	s_waitcnt vmcnt(19)
	ds_write_b32 v3, v185
	v_add_u32_e32 v3, v97, v113
	s_waitcnt vmcnt(18)
	ds_write_b32 v3, v186
	v_add_u32_e32 v3, v97, v114
	s_waitcnt vmcnt(17)
	ds_write_b32 v3, v187
	v_add_u32_e32 v3, v97, v115
	s_waitcnt vmcnt(16)
	ds_write_b32 v3, v188
	v_add_u32_e32 v3, v97, v116
	v_add_u32_e32 v14, s25, v57
	s_waitcnt vmcnt(15)
	ds_write_b32 v3, v189
	v_add_u32_e32 v3, v97, v117
	s_waitcnt vmcnt(14)
	ds_write_b32 v3, v190
	v_add_u32_e32 v3, v97, v118
	s_waitcnt vmcnt(13)
	ds_write_b32 v3, v191
	v_add_u32_e32 v3, v97, v119
	s_waitcnt vmcnt(12)
	ds_write_b32 v3, v192
	v_add_u32_e32 v3, v97, v120
	s_waitcnt vmcnt(11)
	ds_write_b32 v3, v193
	v_add_u32_e32 v3, v97, v121
	s_waitcnt vmcnt(10)
	ds_write_b32 v3, v176
	v_add_u32_e32 v3, v97, v122
	s_waitcnt vmcnt(9)
	ds_write_b32 v3, v177
	v_add_u32_e32 v3, v97, v123
	s_waitcnt vmcnt(8)
	ds_write_b32 v3, v178
	v_add_u32_e32 v3, v97, v124
	s_waitcnt vmcnt(7)
	ds_write_b32 v3, v179
	v_add_u32_e32 v3, v97, v125
	v_add_u32_e32 v178, s25, v66
	v_mad_i64_i32 v[178:179], s[38:39], v178, s52, v[0:1]
	s_waitcnt vmcnt(6)
	ds_write_b32 v3, v4
	v_add_u32_e32 v3, v97, v126
	s_waitcnt vmcnt(5)
	ds_write_b32 v3, v5
	v_add_u32_e32 v3, v97, v127
	s_waitcnt vmcnt(4)
	ds_write_b32 v3, v6
	v_add_u32_e32 v3, v97, v128
	s_waitcnt vmcnt(3)
	ds_write_b32 v3, v7
	v_add_u32_e32 v3, v97, v129
	v_add_u32_e32 v4, s25, v55
	s_waitcnt vmcnt(2)
	ds_write_b32 v3, v173
	v_add_u32_e32 v3, v97, v130
	s_waitcnt vmcnt(1)
	ds_write_b32 v3, v174
	v_add_u32_e32 v3, v97, v131
	s_waitcnt vmcnt(0)
;     ...
;     for (int i = 0; i < 64; ++i) { const int kk = 2 * i + (lane >> 5); scr[kk * 33 + (lane & 31)] = W[(size_t)(k0 + kk) * N + n0 + (lane & 31)]; }
	ds_write_b32 v3, v2
	v_add_u32_e32 v2, s25, v60
	v_mad_i64_i32 v[172:173], s[38:39], v14, s52, v[0:1]
	v_add_u32_e32 v14, s25, v59
	v_mad_i64_i32 v[2:3], s[38:39], v2, s52, v[0:1]
	v_add_u32_e32 v6, s25, v62
	v_add_u32_e32 v174, s25, v64
	v_mad_i64_i32 v[176:177], s[38:39], v14, s52, v[0:1]
	v_add_u32_e32 v14, s25, v61
	v_mad_i64_i32 v[4:5], s[38:39], v4, s52, v[0:1]
	v_mad_i64_i32 v[6:7], s[38:39], v6, s52, v[0:1]
	v_mad_i64_i32 v[174:175], s[38:39], v174, s52, v[0:1]
	v_mad_i64_i32 v[180:181], s[38:39], v14, s52, v[0:1]
	global_load_dword v14, v[2:3], off nt
	global_load_dword v182, v[4:5], off nt
	global_load_dword v183, v[6:7], off nt
	global_load_dword v184, v[172:173], off nt
	global_load_dword v185, v[174:175], off nt
	global_load_dword v186, v[176:177], off nt
	global_load_dword v187, v[178:179], off nt
	global_load_dword v188, v[180:181], off nt
	v_add_u32_e32 v2, s25, v68
	v_add_u32_e32 v4, s25, v63
	v_mad_i64_i32 v[2:3], s[38:39], v2, s52, v[0:1]
	v_add_u32_e32 v172, s25, v65
	v_add_u32_e32 v6, s25, v70
	v_add_u32_e32 v176, s25, v67
	v_add_u32_e32 v174, s25, v72
	v_add_u32_e32 v180, s25, v69
	v_add_u32_e32 v178, s25, v74
	v_mad_i64_i32 v[4:5], s[38:39], v4, s52, v[0:1]
	v_mad_i64_i32 v[6:7], s[38:39], v6, s52, v[0:1]
	v_mad_i64_i32 v[172:173], s[38:39], v172, s52, v[0:1]
	v_mad_i64_i32 v[174:175], s[38:39], v174, s52, v[0:1]
	v_mad_i64_i32 v[176:177], s[38:39], v176, s52, v[0:1]
	v_mad_i64_i32 v[178:179], s[38:39], v178, s52, v[0:1]
	v_mad_i64_i32 v[180:181], s[38:39], v180, s52, v[0:1]
	global_load_dword v189, v[2:3], off nt
	global_load_dword v190, v[4:5], off nt
	global_load_dword v191, v[6:7], off nt
	global_load_dword v192, v[172:173], off nt
	global_load_dword v193, v[174:175], off nt
	global_load_dword v194, v[176:177], off nt
	global_load_dword v195, v[178:179], off nt
	global_load_dword v196, v[180:181], off nt
	v_add_u32_e32 v2, s25, v76
	v_add_u32_e32 v4, s25, v71
	v_mad_i64_i32 v[2:3], s[38:39], v2, s52, v[0:1]
	v_add_u32_e32 v172, s25, v73
	v_add_u32_e32 v6, s25, v78
	v_add_u32_e32 v176, s25, v75
	v_add_u32_e32 v174, s25, v80
	v_add_u32_e32 v180, s25, v77
	v_add_u32_e32 v178, s25, v82
	v_mad_i64_i32 v[4:5], s[38:39], v4, s52, v[0:1]
	v_mad_i64_i32 v[6:7], s[38:39], v6, s52, v[0:1]
	v_mad_i64_i32 v[172:173], s[38:39], v172, s52, v[0:1]
	v_mad_i64_i32 v[174:175], s[38:39], v174, s52, v[0:1]
	v_mad_i64_i32 v[176:177], s[38:39], v176, s52, v[0:1]
	v_mad_i64_i32 v[178:179], s[38:39], v178, s52, v[0:1]
	v_mad_i64_i32 v[180:181], s[38:39], v180, s52, v[0:1]
	global_load_dword v197, v[2:3], off nt
	global_load_dword v198, v[4:5], off nt
	global_load_dword v199, v[6:7], off nt
	global_load_dword v200, v[172:173], off nt
	global_load_dword v201, v[174:175], off nt
	global_load_dword v202, v[176:177], off nt
	global_load_dword v203, v[178:179], off nt
	global_load_dword v204, v[180:181], off nt
	v_add_u32_e32 v4, s25, v79
	v_add_u32_e32 v2, s25, v84
	v_add_u32_e32 v6, s25, v86
	v_add_u32_e32 v176, s25, v83
	v_add_u32_e32 v174, s25, v88
	v_mad_i64_i32 v[2:3], s[38:39], v2, s52, v[0:1]
	v_mad_i64_i32 v[4:5], s[38:39], v4, s52, v[0:1]
	v_add_u32_e32 v172, s25, v81
	v_mad_i64_i32 v[6:7], s[38:39], v6, s52, v[0:1]
	v_mad_i64_i32 v[174:175], s[38:39], v174, s52, v[0:1]
	v_mad_i64_i32 v[176:177], s[38:39], v176, s52, v[0:1]
	v_add_u32_e32 v180, s25, v85
	v_add_u32_e32 v178, s25, v90
	v_mad_i64_i32 v[172:173], s[38:39], v172, s52, v[0:1]
	v_mad_i64_i32 v[178:179], s[38:39], v178, s52, v[0:1]
	v_mad_i64_i32 v[180:181], s[38:39], v180, s52, v[0:1]
	global_load_dword v205, v[2:3], off nt
	global_load_dword v206, v[4:5], off nt
	global_load_dword v207, v[6:7], off nt
	global_load_dword v208, v[172:173], off nt
	s_nop 0
	global_load_dword v174, v[174:175], off nt
	s_nop 0
	global_load_dword v175, v[176:177], off nt
	s_nop 0
	global_load_dword v176, v[178:179], off nt
	global_load_dword v177, v[180:181], off nt
	v_add_u32_e32 v4, s25, v87
	v_add_u32_e32 v2, s25, v92
	v_add_u32_e32 v6, s25, v94
	v_mad_i64_i32 v[2:3], s[38:39], v2, s52, v[0:1]
	v_mad_i64_i32 v[4:5], s[38:39], v4, s52, v[0:1]
	v_add_u32_e32 v172, s25, v89
	v_mad_i64_i32 v[6:7], s[38:39], v6, s52, v[0:1]
	v_mad_i64_i32 v[172:173], s[38:39], v172, s52, v[0:1]
	global_load_dword v178, v[2:3], off nt
	global_load_dword v179, v[4:5], off nt
	s_nop 0
	global_load_dword v6, v[6:7], off nt
	s_nop 0
	global_load_dword v7, v[172:173], off nt
	v_add_u32_e32 v4, s25, v91
	v_add_u32_e32 v2, s25, v96
	v_mad_i64_i32 v[2:3], s[38:39], v2, s52, v[0:1]
	v_mad_i64_i32 v[4:5], s[38:39], v4, s52, v[0:1]
	global_load_dword v172, v[2:3], off nt
	s_nop 0
	global_load_dword v4, v[4:5], off nt
	v_add_u32_e32 v2, s25, v98
	v_mad_i64_i32 v[2:3], s[38:39], v2, s52, v[0:1]
	global_load_dword v2, v[2:3], off nt
	v_add_u32_e32 v3, s25, v93
	v_mad_i64_i32 v[0:1], s[38:39], v3, s52, v[0:1]
	global_load_dword v0, v[0:1], off nt
	v_add_u32_e32 v1, v97, v132
	s_waitcnt vmcnt(39)
	ds_write_b32 v1, v14
	v_add_u32_e32 v1, v97, v133
	s_waitcnt vmcnt(38)
	ds_write_b32 v1, v182
	v_add_u32_e32 v1, v97, v134
	s_waitcnt vmcnt(37)
	ds_write_b32 v1, v183
	v_add_u32_e32 v1, v97, v135
	s_waitcnt vmcnt(36)
	ds_write_b32 v1, v184
	v_add_u32_e32 v1, v97, v136
	s_waitcnt vmcnt(35)
	ds_write_b32 v1, v185
	v_add_u32_e32 v1, v97, v137
	s_waitcnt vmcnt(34)
	ds_write_b32 v1, v186
	v_add_u32_e32 v1, v97, v138
	s_waitcnt vmcnt(33)
	ds_write_b32 v1, v187
	v_add_u32_e32 v1, v97, v139
	s_waitcnt vmcnt(32)
	ds_write_b32 v1, v188
	v_add_u32_e32 v1, v97, v140
	s_waitcnt vmcnt(31)
	ds_write_b32 v1, v189
	v_add_u32_e32 v1, v97, v141
	s_waitcnt vmcnt(30)
	ds_write_b32 v1, v190
	v_add_u32_e32 v1, v97, v142
	s_waitcnt vmcnt(29)
; __device__ __forceinline__ unsigned cvt_pk_bf16(float lo, float hi) { unsigned r; asm volatile("v_cvt_pk_bf16_f32 %0, %1, %2" : "=v"(r) : "v"(lo), "v"(hi)); return r; }
; #define GAS __attribute__((address_space(1)))
; #define LAS __attribute__((address_space(3)))
; #define LDS_WAIT() asm volatile("s_waitcnt lgkmcnt(0)" ::: "memory")
;     ...
;     LDS_WAIT(); asm volatile("" ::: "memory");
;     const int c = lane & 15;
;     float gk[8];
;     if (gain) load8f(gain + k0 + 8 * c, gk); else {
; #pragma unroll
;         for (int e = 0; e < 8; ++e) gk[e] = 1.0f; }
; #pragma unroll
;     for (int j = 0; j < 8; ++j) { const int n = (lane >> 4) + 4 * j; const LAS float* s = scr + (8 * c) * 33 + n;
;         v4u o; o.x = cvt_pk_bf16(s[0 * 33] * gk[0], s[1 * 33] * gk[1]); o.y = cvt_pk_bf16(s[2 * 33] * gk[2], s[3 * 33] * gk[3]); o.z = cvt_pk_bf16(s[4 * 33] * gk[4], s[5 * 33] * gk[5]); o.w = cvt_pk_bf16(s[6 * 33] * gk[6], s[7 * 33] * gk[7]);
;         *(GAS v4u*)(WT + (size_t)(nd0 + n) * K + k0 + 8 * c) = o; }
	ds_write_b32 v1, v191
	v_add_u32_e32 v1, v97, v143
	s_waitcnt vmcnt(28)
	ds_write_b32 v1, v192
	v_add_u32_e32 v1, v97, v144
	s_waitcnt vmcnt(27)
	ds_write_b32 v1, v193
	v_add_u32_e32 v1, v97, v145
	s_waitcnt vmcnt(26)
	ds_write_b32 v1, v194
	v_add_u32_e32 v1, v97, v146
	s_waitcnt vmcnt(25)
	ds_write_b32 v1, v195
	v_add_u32_e32 v1, v97, v147
	s_waitcnt vmcnt(24)
	ds_write_b32 v1, v196
	v_add_u32_e32 v1, v97, v148
	s_waitcnt vmcnt(23)
	ds_write_b32 v1, v197
	v_add_u32_e32 v1, v97, v149
	s_waitcnt vmcnt(22)
	ds_write_b32 v1, v198
	v_add_u32_e32 v1, v97, v150
	s_waitcnt vmcnt(21)
	ds_write_b32 v1, v199
	v_add_u32_e32 v1, v97, v151
	s_waitcnt vmcnt(20)
	ds_write_b32 v1, v200
	v_add_u32_e32 v1, v97, v152
	s_waitcnt vmcnt(19)
	ds_write_b32 v1, v201
	v_add_u32_e32 v1, v97, v153
	s_waitcnt vmcnt(18)
	ds_write_b32 v1, v202
	v_add_u32_e32 v1, v97, v154
	s_waitcnt vmcnt(17)
	ds_write_b32 v1, v203
	v_add_u32_e32 v1, v97, v155
	s_waitcnt vmcnt(16)
	ds_write_b32 v1, v204
	v_add_u32_e32 v1, v97, v156
	s_waitcnt vmcnt(15)
	ds_write_b32 v1, v205
	v_add_u32_e32 v1, v97, v157
	s_waitcnt vmcnt(14)
	ds_write_b32 v1, v206
	v_add_u32_e32 v1, v97, v158
	s_waitcnt vmcnt(13)
	ds_write_b32 v1, v207
	v_add_u32_e32 v1, v97, v159
	s_waitcnt vmcnt(12)
	ds_write_b32 v1, v208
	v_add_u32_e32 v1, v97, v160
	s_waitcnt vmcnt(11)
	ds_write_b32 v1, v174
	v_add_u32_e32 v1, v97, v161
	s_waitcnt vmcnt(10)
	ds_write_b32 v1, v175
	v_add_u32_e32 v1, v97, v162
	s_waitcnt vmcnt(9)
	ds_write_b32 v1, v176
	v_add_u32_e32 v1, v97, v163
	s_waitcnt vmcnt(8)
	ds_write_b32 v1, v177
	v_add_u32_e32 v1, v97, v164
	s_waitcnt vmcnt(7)
	ds_write_b32 v1, v178
	v_add_u32_e32 v1, v97, v165
	s_waitcnt vmcnt(6)
	ds_write_b32 v1, v179
	v_add_u32_e32 v1, v97, v166
	s_waitcnt vmcnt(5)
	ds_write_b32 v1, v6
	v_add_u32_e32 v1, v97, v167
	s_waitcnt vmcnt(4)
	ds_write_b32 v1, v7
	v_add_u32_e32 v1, v97, v168
	s_waitcnt vmcnt(3)
	ds_write_b32 v1, v172
	v_add_u32_e32 v1, v97, v169
	s_lshl_b32 s25, s10, 9
	s_waitcnt vmcnt(2)
	ds_write_b32 v1, v4
	v_add_u32_e32 v1, v97, v170
	s_add_u32 s2, s2, s25
	s_waitcnt vmcnt(1)
	ds_write_b32 v1, v2
	v_add_u32_e32 v1, v97, v171
	s_addc_u32 s3, s3, 0
	v_lshlrev_b32_e32 v14, 2, v16
	s_waitcnt vmcnt(0)
	ds_write_b32 v1, v0
	v_lshl_add_u64 v[4:5], s[2:3], 0, v[14:15]
	s_waitcnt lgkmcnt(0)
	v_add_co_u32_e32 v0, vcc, s55, v4
	ds_read2_b32 v[172:173], v100 offset1:33
	s_nop 0
	v_addc_co_u32_e32 v1, vcc, 0, v5, vcc
	global_load_dwordx4 v[0:3], v[0:1], off
	v_lshl_add_u64 v[4:5], v[4:5], 0, s[36:37]
	global_load_dwordx4 v[4:7], v[4:5], off offset:16
	s_lshl_b32 s10, s10, 8
	v_lshl_add_u64 v[178:179], v[30:31], 0, s[10:11]
	s_waitcnt vmcnt(1) lgkmcnt(0)
	v_mul_f32_e32 v14, v0, v172
	v_mul_f32_e32 v172, v1, v173
	v_cvt_pk_bf16_f32 v172, v14, v172
	ds_read2_b32 v[174:175], v100 offset0:66 offset1:99
	s_waitcnt lgkmcnt(0)
	v_mul_f32_e32 v173, v3, v175
	v_mul_f32_e32 v14, v2, v174
	v_cvt_pk_bf16_f32 v173, v14, v173
	ds_read2_b32 v[174:175], v100 offset0:132 offset1:165
	s_waitcnt vmcnt(0) lgkmcnt(0)
	v_mul_f32_e32 v14, v4, v174
	v_mul_f32_e32 v174, v5, v175
	v_cvt_pk_bf16_f32 v174, v14, v174
	ds_read2_b32 v[176:177], v100 offset0:198 offset1:231
	s_waitcnt lgkmcnt(0)
	v_mul_f32_e32 v175, v7, v177
	v_mul_f32_e32 v14, v6, v176
	v_cvt_pk_bf16_f32 v175, v14, v175
	ds_read2_b32 v[180:181], v100 offset0:4 offset1:37
	v_add_u32_e32 v176, s24, v99
	v_ashrrev_i32_e32 v177, 31, v176
	v_lshlrev_b64 v[176:177], 12, v[176:177]
	v_lshl_add_u64 v[176:177], v[178:179], 0, v[176:177]
	global_store_dwordx4 v[176:177], v[172:175], off
	s_waitcnt lgkmcnt(0)
	v_mul_f32_e32 v14, v0, v180
	v_mul_f32_e32 v172, v1, v181
	v_cvt_pk_bf16_f32 v172, v14, v172
	ds_read2_b32 v[174:175], v100 offset0:70 offset1:103
	s_waitcnt lgkmcnt(0)
	v_mul_f32_e32 v173, v3, v175
	v_mul_f32_e32 v14, v2, v174
	v_cvt_pk_bf16_f32 v173, v14, v173
	ds_read2_b32 v[174:175], v100 offset0:136 offset1:169
	s_waitcnt lgkmcnt(0)
	v_mul_f32_e32 v14, v4, v174
	v_mul_f32_e32 v174, v5, v175
	v_cvt_pk_bf16_f32 v174, v14, v174
	ds_read2_b32 v[176:177], v100 offset0:202 offset1:235
	s_waitcnt lgkmcnt(0)
	v_mul_f32_e32 v175, v7, v177
	v_mul_f32_e32 v14, v6, v176
	v_cvt_pk_bf16_f32 v175, v14, v175
	ds_read2_b32 v[180:181], v100 offset0:8 offset1:41
	v_add_u32_e32 v176, s24, v101
	v_ashrrev_i32_e32 v177, 31, v176
	v_lshlrev_b64 v[176:177], 12, v[176:177]
	v_lshl_add_u64 v[176:177], v[178:179], 0, v[176:177]
	global_store_dwordx4 v[176:177], v[172:175], off
	s_waitcnt lgkmcnt(0)
	v_mul_f32_e32 v14, v0, v180
	v_mul_f32_e32 v172, v1, v181
	v_cvt_pk_bf16_f32 v172, v14, v172
	ds_read2_b32 v[174:175], v100 offset0:74 offset1:107
	s_waitcnt lgkmcnt(0)
	v_mul_f32_e32 v173, v3, v175
	v_mul_f32_e32 v14, v2, v174
	v_cvt_pk_bf16_f32 v173, v14, v173
	ds_read2_b32 v[174:175], v100 offset0:140 offset1:173
	s_waitcnt lgkmcnt(0)
; __device__ __forceinline__ unsigned cvt_pk_bf16(float lo, float hi) { unsigned r; asm volatile("v_cvt_pk_bf16_f32 %0, %1, %2" : "=v"(r) : "v"(lo), "v"(hi)); return r; }
; #define GAS __attribute__((address_space(1)))
; #define LAS __attribute__((address_space(3)))
; #define LDS_WAIT() asm volatile("s_waitcnt lgkmcnt(0)" ::: "memory")
;     ...
;     for (int j = 0; j < 8; ++j) { const int n = (lane >> 4) + 4 * j; const LAS float* s = scr + (8 * c) * 33 + n;
;         v4u o; o.x = cvt_pk_bf16(s[0 * 33] * gk[0], s[1 * 33] * gk[1]); o.y = cvt_pk_bf16(s[2 * 33] * gk[2], s[3 * 33] * gk[3]); o.z = cvt_pk_bf16(s[4 * 33] * gk[4], s[5 * 33] * gk[5]); o.w = cvt_pk_bf16(s[6 * 33] * gk[6], s[7 * 33] * gk[7]);
;         *(GAS v4u*)(WT + (size_t)(nd0 + n) * K + k0 + 8 * c) = o; }
;     LDS_WAIT(); asm volatile("" ::: "memory");
	v_mul_f32_e32 v14, v4, v174
	v_mul_f32_e32 v174, v5, v175
	v_cvt_pk_bf16_f32 v174, v14, v174
	ds_read2_b32 v[176:177], v100 offset0:206 offset1:239
	s_waitcnt lgkmcnt(0)
	v_mul_f32_e32 v175, v7, v177
	v_mul_f32_e32 v14, v6, v176
	v_cvt_pk_bf16_f32 v175, v14, v175
	ds_read2_b32 v[180:181], v100 offset0:12 offset1:45
	v_add_u32_e32 v176, s24, v102
	v_ashrrev_i32_e32 v177, 31, v176
	v_lshlrev_b64 v[176:177], 12, v[176:177]
	v_lshl_add_u64 v[176:177], v[178:179], 0, v[176:177]
	global_store_dwordx4 v[176:177], v[172:175], off
	s_waitcnt lgkmcnt(0)
	v_mul_f32_e32 v14, v0, v180
	v_mul_f32_e32 v172, v1, v181
	v_cvt_pk_bf16_f32 v172, v14, v172
	ds_read2_b32 v[174:175], v100 offset0:78 offset1:111
	s_waitcnt lgkmcnt(0)
	v_mul_f32_e32 v173, v3, v175
	v_mul_f32_e32 v14, v2, v174
	v_cvt_pk_bf16_f32 v173, v14, v173
	ds_read2_b32 v[174:175], v100 offset0:144 offset1:177
	s_waitcnt lgkmcnt(0)
	v_mul_f32_e32 v14, v4, v174
	v_mul_f32_e32 v174, v5, v175
	v_cvt_pk_bf16_f32 v174, v14, v174
	ds_read2_b32 v[176:177], v100 offset0:210 offset1:243
	s_waitcnt lgkmcnt(0)
	v_mul_f32_e32 v175, v7, v177
	v_mul_f32_e32 v14, v6, v176
	v_cvt_pk_bf16_f32 v175, v14, v175
	ds_read2_b32 v[180:181], v100 offset0:16 offset1:49
	v_add_u32_e32 v176, s24, v103
	v_ashrrev_i32_e32 v177, 31, v176
	v_lshlrev_b64 v[176:177], 12, v[176:177]
	v_lshl_add_u64 v[176:177], v[178:179], 0, v[176:177]
	global_store_dwordx4 v[176:177], v[172:175], off
	s_waitcnt lgkmcnt(0)
	v_mul_f32_e32 v14, v0, v180
	v_mul_f32_e32 v172, v1, v181
	v_cvt_pk_bf16_f32 v172, v14, v172
	ds_read2_b32 v[174:175], v100 offset0:82 offset1:115
	s_waitcnt lgkmcnt(0)
	v_mul_f32_e32 v173, v3, v175
	v_mul_f32_e32 v14, v2, v174
	v_cvt_pk_bf16_f32 v173, v14, v173
	ds_read2_b32 v[174:175], v100 offset0:148 offset1:181
	s_waitcnt lgkmcnt(0)
	v_mul_f32_e32 v14, v4, v174
	v_mul_f32_e32 v174, v5, v175
	v_cvt_pk_bf16_f32 v174, v14, v174
	ds_read2_b32 v[176:177], v100 offset0:214 offset1:247
	s_waitcnt lgkmcnt(0)
	v_mul_f32_e32 v175, v7, v177
	v_mul_f32_e32 v14, v6, v176
	v_cvt_pk_bf16_f32 v175, v14, v175
	ds_read2_b32 v[180:181], v100 offset0:20 offset1:53
	v_add_u32_e32 v176, s24, v104
	v_ashrrev_i32_e32 v177, 31, v176
	v_lshlrev_b64 v[176:177], 12, v[176:177]
	v_lshl_add_u64 v[176:177], v[178:179], 0, v[176:177]
	global_store_dwordx4 v[176:177], v[172:175], off
	s_waitcnt lgkmcnt(0)
	v_mul_f32_e32 v14, v0, v180
	v_mul_f32_e32 v172, v1, v181
	v_cvt_pk_bf16_f32 v172, v14, v172
	ds_read2_b32 v[174:175], v100 offset0:86 offset1:119
	s_waitcnt lgkmcnt(0)
	v_mul_f32_e32 v173, v3, v175
	v_mul_f32_e32 v14, v2, v174
	v_cvt_pk_bf16_f32 v173, v14, v173
	ds_read2_b32 v[174:175], v100 offset0:152 offset1:185
	s_waitcnt lgkmcnt(0)
	v_mul_f32_e32 v14, v4, v174
	v_mul_f32_e32 v174, v5, v175
	v_cvt_pk_bf16_f32 v174, v14, v174
	ds_read2_b32 v[176:177], v100 offset0:218 offset1:251
	s_waitcnt lgkmcnt(0)
	v_mul_f32_e32 v175, v7, v177
	v_mul_f32_e32 v14, v6, v176
	v_cvt_pk_bf16_f32 v175, v14, v175
	ds_read2_b32 v[180:181], v100 offset0:24 offset1:57
	v_add_u32_e32 v176, s24, v105
	v_ashrrev_i32_e32 v177, 31, v176
	v_lshlrev_b64 v[176:177], 12, v[176:177]
	v_lshl_add_u64 v[176:177], v[178:179], 0, v[176:177]
	global_store_dwordx4 v[176:177], v[172:175], off
	s_waitcnt lgkmcnt(0)
	v_mul_f32_e32 v14, v0, v180
	v_mul_f32_e32 v172, v1, v181
	v_cvt_pk_bf16_f32 v172, v14, v172
	ds_read2_b32 v[174:175], v100 offset0:90 offset1:123
	s_waitcnt lgkmcnt(0)
	v_mul_f32_e32 v173, v3, v175
	v_mul_f32_e32 v14, v2, v174
	v_cvt_pk_bf16_f32 v173, v14, v173
	ds_read2_b32 v[174:175], v100 offset0:156 offset1:189
	s_waitcnt lgkmcnt(0)
	v_mul_f32_e32 v14, v4, v174
	v_mul_f32_e32 v174, v5, v175
	v_cvt_pk_bf16_f32 v174, v14, v174
	ds_read2_b32 v[176:177], v100 offset0:222 offset1:255
	s_waitcnt lgkmcnt(0)
	v_mul_f32_e32 v175, v7, v177
	v_mul_f32_e32 v14, v6, v176
	v_cvt_pk_bf16_f32 v175, v14, v175
	ds_read2_b32 v[180:181], v100 offset0:28 offset1:61
	v_add_u32_e32 v176, s24, v106
	v_ashrrev_i32_e32 v177, 31, v176
	v_lshlrev_b64 v[176:177], 12, v[176:177]
	v_lshl_add_u64 v[176:177], v[178:179], 0, v[176:177]
	s_waitcnt lgkmcnt(0)
	v_mul_f32_e32 v0, v0, v180
	global_store_dwordx4 v[176:177], v[172:175], off
	v_mul_f32_e32 v1, v1, v181
	v_cvt_pk_bf16_f32 v0, v0, v1
	ds_read2_b32 v[172:173], v100 offset0:94 offset1:127
	s_waitcnt lgkmcnt(0)
	v_mul_f32_e32 v1, v2, v172
	v_mul_f32_e32 v2, v3, v173
	v_cvt_pk_bf16_f32 v1, v1, v2
	ds_read2_b32 v[2:3], v100 offset0:160 offset1:193
	s_waitcnt lgkmcnt(0)
	v_mul_f32_e32 v2, v4, v2
	v_mul_f32_e32 v3, v5, v3
	v_cvt_pk_bf16_f32 v2, v2, v3
	v_add_u32_e32 v3, 0x200, v100
	ds_read2_b32 v[4:5], v3 offset0:98 offset1:131
	s_waitcnt lgkmcnt(0)
	v_mul_f32_e32 v3, v6, v4
	v_mul_f32_e32 v4, v7, v5
	v_cvt_pk_bf16_f32 v3, v3, v4
	v_add_u32_e32 v4, s24, v107
	v_ashrrev_i32_e32 v5, 31, v4
	v_lshlrev_b64 v[4:5], 12, v[4:5]
	v_lshl_add_u64 v[4:5], v[178:179], 0, v[4:5]
	global_store_dwordx4 v[4:5], v[0:3], off
	s_waitcnt lgkmcnt(0)

; #define LDS_WAIT() asm volatile("s_waitcnt lgkmcnt(0)" ::: "memory")
;     const int nblk = N / 32, kb = item / nblk, nb = item % nblk, k0 = 128 * kb, n0 = 32 * nb;
;     const int nd0 = GLU ? (n0 < 6144 ? 256 * (n0 >> 7) + (n0 & 127) : 256 * ((n0 - 6144) >> 7) + 128 + ((n0 - 6144) & 127)) : n0;
; #pragma unroll 32
;     for (int i = 0; i < 64; ++i) { const int kk = 2 * i + (lane >> 5); scr[kk * 33 + (lane & 31)] = W[(size_t)(k0 + kk) * N + n0 + (lane & 31)]; }
;     LDS_WAIT(); asm volatile("" ::: "memory");
;     const int c = lane & 15;
;     float gk[8];
;     if (gain) load8f(gain + k0 + 8 * c, gk); else {
.LBB0_69:
	s_and_b32 s24, s38, 0xffff
	s_sub_u32 s38, 3, s24
	s_mul_i32 s25, s38, 0x1800000
	s_lshl_b32 s24, s25, 2
	s_waitcnt lgkmcnt(0)
	s_add_u32 s2, s2, s24
	s_addc_u32 s3, s3, 0
	s_lshl_b32 s24, s39, 7
	s_lshl_b32 s39, s57, 2
	s_add_u32 s2, s2, s39
	s_addc_u32 s3, s3, 0
	v_lshlrev_b32_e32 v14, 2, v12
	s_and_b32 s24, s24, 0x7f80
	v_lshl_add_u64 v[0:1], s[2:3], 0, v[14:15]
	v_add_u32_e32 v14, s24, v11
	v_add_u32_e32 v2, s24, v10
	v_mad_i64_i32 v[172:173], s[2:3], v14, s50, v[0:1]
	v_add_u32_e32 v14, s24, v13
	v_add_u32_e32 v4, s24, v9
	v_mad_i64_i32 v[2:3], s[2:3], v2, s50, v[0:1]
	v_add_u32_e32 v6, s24, v38
	v_add_u32_e32 v174, s24, v40
	v_mad_i64_i32 v[176:177], s[2:3], v14, s50, v[0:1]
	v_add_u32_e32 v14, s24, v17
	v_add_u32_e32 v178, s24, v42
	v_mad_i64_i32 v[4:5], s[2:3], v4, s50, v[0:1]
	v_mad_i64_i32 v[6:7], s[2:3], v6, s50, v[0:1]
	v_mad_i64_i32 v[174:175], s[2:3], v174, s50, v[0:1]
	v_mad_i64_i32 v[178:179], s[2:3], v178, s50, v[0:1]
	v_mad_i64_i32 v[180:181], s[2:3], v14, s50, v[0:1]
	global_load_dword v14, v[2:3], off nt
	global_load_dword v182, v[4:5], off nt
	global_load_dword v183, v[6:7], off nt
	global_load_dword v184, v[172:173], off nt
	global_load_dword v185, v[174:175], off nt
	global_load_dword v186, v[176:177], off nt
	global_load_dword v187, v[178:179], off nt
	global_load_dword v188, v[180:181], off nt
	v_add_u32_e32 v2, s24, v44
	v_add_u32_e32 v176, s24, v43
	v_add_u32_e32 v178, s24, v50
	v_add_u32_e32 v4, s24, v39
	v_mad_i64_i32 v[2:3], s[2:3], v2, s50, v[0:1]
	v_add_u32_e32 v172, s24, v41
	v_add_u32_e32 v6, s24, v46
	v_add_u32_e32 v174, s24, v48
	v_mad_i64_i32 v[176:177], s[2:3], v176, s50, v[0:1]
	v_add_u32_e32 v180, s24, v45
	v_mad_i64_i32 v[178:179], s[2:3], v178, s50, v[0:1]
	v_mad_i64_i32 v[4:5], s[2:3], v4, s50, v[0:1]
	v_mad_i64_i32 v[6:7], s[2:3], v6, s50, v[0:1]
	v_mad_i64_i32 v[172:173], s[2:3], v172, s50, v[0:1]
	v_mad_i64_i32 v[174:175], s[2:3], v174, s50, v[0:1]
	v_mad_i64_i32 v[180:181], s[2:3], v180, s50, v[0:1]
	global_load_dword v189, v[2:3], off nt
	global_load_dword v190, v[4:5], off nt
	global_load_dword v191, v[6:7], off nt
	global_load_dword v192, v[172:173], off nt
	global_load_dword v193, v[174:175], off nt
	s_nop 0
	global_load_dword v176, v[176:177], off nt
	s_nop 0
	global_load_dword v177, v[178:179], off nt
	s_nop 0
	global_load_dword v178, v[180:181], off nt
	v_add_u32_e32 v2, s24, v52
	v_mad_i64_i32 v[2:3], s[2:3], v2, s50, v[0:1]
	global_load_dword v179, v[2:3], off nt
	v_add_u32_e32 v4, s24, v47
	v_add_u32_e32 v6, s24, v49
	v_add_u32_e32 v2, s24, v54
	v_mad_i64_i32 v[4:5], s[2:3], v4, s50, v[0:1]
	v_mad_i64_i32 v[2:3], s[2:3], v2, s50, v[0:1]
	v_mad_i64_i32 v[6:7], s[2:3], v6, s50, v[0:1]
	v_add_u32_e32 v172, s24, v56
	v_add_u32_e32 v174, s24, v51
	v_mad_i64_i32 v[172:173], s[2:3], v172, s50, v[0:1]
	global_load_dword v4, v[4:5], off nt
	s_nop 0
	global_load_dword v5, v[2:3], off nt
	s_nop 0
	global_load_dword v6, v[6:7], off nt
	s_nop 0
	global_load_dword v7, v[172:173], off nt
	v_add_u32_e32 v2, s24, v58
	v_mad_i64_i32 v[174:175], s[2:3], v174, s50, v[0:1]
	v_add_u32_e32 v172, s24, v53
	v_mad_i64_i32 v[2:3], s[2:3], v2, s50, v[0:1]
	global_load_dword v173, v[174:175], off nt
	s_nop 0
	global_load_dword v174, v[2:3], off nt
	v_mad_i64_i32 v[2:3], s[2:3], v172, s50, v[0:1]
	global_load_dword v2, v[2:3], off nt
	v_add_u32_e32 v3, v97, v108
	s_load_dwordx2 s[2:3], s[6:7], 0x48
	s_waitcnt lgkmcnt(0)
	s_cmp_eq_u64 s[2:3], 0
	s_waitcnt vmcnt(23)
	ds_write_b32 v3, v14
	v_add_u32_e32 v3, v97, v109
	s_waitcnt vmcnt(22)
	ds_write_b32 v3, v182
	v_add_u32_e32 v3, v97, v110
	s_waitcnt vmcnt(21)
	ds_write_b32 v3, v183
	v_add_u32_e32 v3, v97, v111
	s_waitcnt vmcnt(20)
	ds_write_b32 v3, v184
	v_add_u32_e32 v3, v97, v112
	s_waitcnt vmcnt(19)
	ds_write_b32 v3, v185
	v_add_u32_e32 v3, v97, v113
	s_waitcnt vmcnt(18)
	ds_write_b32 v3, v186
	v_add_u32_e32 v3, v97, v114
	s_waitcnt vmcnt(17)
	ds_write_b32 v3, v187
	v_add_u32_e32 v3, v97, v115
	s_waitcnt vmcnt(16)
	ds_write_b32 v3, v188
	v_add_u32_e32 v3, v97, v116
	v_add_u32_e32 v14, s24, v57
	s_waitcnt vmcnt(15)
	ds_write_b32 v3, v189
	v_add_u32_e32 v3, v97, v117
	s_waitcnt vmcnt(14)
	ds_write_b32 v3, v190
	v_add_u32_e32 v3, v97, v118
	s_waitcnt vmcnt(13)
	ds_write_b32 v3, v191
	v_add_u32_e32 v3, v97, v119
	s_waitcnt vmcnt(12)
	ds_write_b32 v3, v192
	v_add_u32_e32 v3, v97, v120
	s_waitcnt vmcnt(11)
	ds_write_b32 v3, v193
	v_add_u32_e32 v3, v97, v121
	s_waitcnt vmcnt(10)
	ds_write_b32 v3, v176
	v_add_u32_e32 v3, v97, v122
	s_waitcnt vmcnt(9)
	ds_write_b32 v3, v177
	v_add_u32_e32 v3, v97, v123
	s_waitcnt vmcnt(8)
	ds_write_b32 v3, v178
	v_add_u32_e32 v3, v97, v124
	s_waitcnt vmcnt(7)
	ds_write_b32 v3, v179
	v_add_u32_e32 v3, v97, v125
	v_add_u32_e32 v178, s24, v66
	v_mad_i64_i32 v[178:179], s[58:59], v178, s50, v[0:1]
	s_waitcnt vmcnt(6)
	ds_write_b32 v3, v4
	v_add_u32_e32 v3, v97, v126
	s_waitcnt vmcnt(5)
	ds_write_b32 v3, v5
	v_add_u32_e32 v3, v97, v127
	s_waitcnt vmcnt(4)
	ds_write_b32 v3, v6
	v_add_u32_e32 v3, v97, v128
	s_waitcnt vmcnt(3)
	ds_write_b32 v3, v7
	v_add_u32_e32 v3, v97, v129
	v_add_u32_e32 v4, s24, v55
	s_waitcnt vmcnt(2)
	ds_write_b32 v3, v173
	v_add_u32_e32 v3, v97, v130
	s_waitcnt vmcnt(1)
	ds_write_b32 v3, v174
	v_add_u32_e32 v3, v97, v131
	s_waitcnt vmcnt(0)
;     ...
;     for (int i = 0; i < 64; ++i) { const int kk = 2 * i + (lane >> 5); scr[kk * 33 + (lane & 31)] = W[(size_t)(k0 + kk) * N + n0 + (lane & 31)]; }
	ds_write_b32 v3, v2
	v_add_u32_e32 v2, s24, v60
	v_mad_i64_i32 v[172:173], s[58:59], v14, s50, v[0:1]
	v_add_u32_e32 v14, s24, v59
	v_mad_i64_i32 v[2:3], s[58:59], v2, s50, v[0:1]
	v_add_u32_e32 v6, s24, v62
	v_add_u32_e32 v174, s24, v64
	v_mad_i64_i32 v[176:177], s[58:59], v14, s50, v[0:1]
	v_add_u32_e32 v14, s24, v61
	v_mad_i64_i32 v[4:5], s[58:59], v4, s50, v[0:1]
	v_mad_i64_i32 v[6:7], s[58:59], v6, s50, v[0:1]
	v_mad_i64_i32 v[174:175], s[58:59], v174, s50, v[0:1]
	v_mad_i64_i32 v[180:181], s[58:59], v14, s50, v[0:1]
	global_load_dword v14, v[2:3], off nt
	global_load_dword v182, v[4:5], off nt
	global_load_dword v183, v[6:7], off nt
	global_load_dword v184, v[172:173], off nt
	global_load_dword v185, v[174:175], off nt
	global_load_dword v186, v[176:177], off nt
	global_load_dword v187, v[178:179], off nt
	global_load_dword v188, v[180:181], off nt
	v_add_u32_e32 v2, s24, v68
	v_add_u32_e32 v4, s24, v63
	v_mad_i64_i32 v[2:3], s[58:59], v2, s50, v[0:1]
	v_add_u32_e32 v172, s24, v65
	v_add_u32_e32 v6, s24, v70
	v_add_u32_e32 v176, s24, v67
	v_add_u32_e32 v174, s24, v72
	v_add_u32_e32 v180, s24, v69
	v_add_u32_e32 v178, s24, v74
	v_mad_i64_i32 v[4:5], s[58:59], v4, s50, v[0:1]
	v_mad_i64_i32 v[6:7], s[58:59], v6, s50, v[0:1]
	v_mad_i64_i32 v[172:173], s[58:59], v172, s50, v[0:1]
	v_mad_i64_i32 v[174:175], s[58:59], v174, s50, v[0:1]
	v_mad_i64_i32 v[176:177], s[58:59], v176, s50, v[0:1]
	v_mad_i64_i32 v[178:179], s[58:59], v178, s50, v[0:1]
	v_mad_i64_i32 v[180:181], s[58:59], v180, s50, v[0:1]
	global_load_dword v189, v[2:3], off nt
	global_load_dword v190, v[4:5], off nt
	global_load_dword v191, v[6:7], off nt
	global_load_dword v192, v[172:173], off nt
	global_load_dword v193, v[174:175], off nt
	global_load_dword v194, v[176:177], off nt
	global_load_dword v195, v[178:179], off nt
	global_load_dword v196, v[180:181], off nt
	v_add_u32_e32 v2, s24, v76
	v_add_u32_e32 v4, s24, v71
	v_mad_i64_i32 v[2:3], s[58:59], v2, s50, v[0:1]
	v_add_u32_e32 v172, s24, v73
	v_add_u32_e32 v6, s24, v78
	v_add_u32_e32 v176, s24, v75
	v_add_u32_e32 v174, s24, v80
	v_add_u32_e32 v180, s24, v77
	v_add_u32_e32 v178, s24, v82
	v_mad_i64_i32 v[4:5], s[58:59], v4, s50, v[0:1]
	v_mad_i64_i32 v[6:7], s[58:59], v6, s50, v[0:1]
	v_mad_i64_i32 v[172:173], s[58:59], v172, s50, v[0:1]
	v_mad_i64_i32 v[174:175], s[58:59], v174, s50, v[0:1]
	v_mad_i64_i32 v[176:177], s[58:59], v176, s50, v[0:1]
	v_mad_i64_i32 v[178:179], s[58:59], v178, s50, v[0:1]
	v_mad_i64_i32 v[180:181], s[58:59], v180, s50, v[0:1]
	global_load_dword v197, v[2:3], off nt
	global_load_dword v198, v[4:5], off nt
	global_load_dword v199, v[6:7], off nt
	global_load_dword v200, v[172:173], off nt
	global_load_dword v201, v[174:175], off nt
	global_load_dword v202, v[176:177], off nt
	global_load_dword v203, v[178:179], off nt
	global_load_dword v204, v[180:181], off nt
	v_add_u32_e32 v2, s24, v84
	v_add_u32_e32 v176, s24, v83
	v_add_u32_e32 v178, s24, v90
	v_add_u32_e32 v4, s24, v79
	v_mad_i64_i32 v[2:3], s[58:59], v2, s50, v[0:1]
	v_add_u32_e32 v172, s24, v81
	v_add_u32_e32 v6, s24, v86
	v_add_u32_e32 v174, s24, v88
	v_mad_i64_i32 v[176:177], s[58:59], v176, s50, v[0:1]
	v_add_u32_e32 v180, s24, v85
	v_mad_i64_i32 v[178:179], s[58:59], v178, s50, v[0:1]
	v_mad_i64_i32 v[4:5], s[58:59], v4, s50, v[0:1]
	v_mad_i64_i32 v[6:7], s[58:59], v6, s50, v[0:1]
	v_mad_i64_i32 v[172:173], s[58:59], v172, s50, v[0:1]
	v_mad_i64_i32 v[174:175], s[58:59], v174, s50, v[0:1]
	v_mad_i64_i32 v[180:181], s[58:59], v180, s50, v[0:1]
	global_load_dword v205, v[2:3], off nt
	global_load_dword v206, v[4:5], off nt
	global_load_dword v207, v[6:7], off nt
	global_load_dword v208, v[172:173], off nt
	global_load_dword v209, v[174:175], off nt
	s_nop 0
	global_load_dword v176, v[176:177], off nt
	s_nop 0
	global_load_dword v177, v[178:179], off nt
	s_nop 0
	global_load_dword v178, v[180:181], off nt
	v_add_u32_e32 v2, s24, v92
	v_mad_i64_i32 v[2:3], s[58:59], v2, s50, v[0:1]
	global_load_dword v179, v[2:3], off nt
	v_add_u32_e32 v4, s24, v87
	v_add_u32_e32 v6, s24, v89
	v_add_u32_e32 v2, s24, v94
	v_mad_i64_i32 v[4:5], s[58:59], v4, s50, v[0:1]
	v_mad_i64_i32 v[2:3], s[58:59], v2, s50, v[0:1]
	v_mad_i64_i32 v[6:7], s[58:59], v6, s50, v[0:1]
	v_add_u32_e32 v172, s24, v96
	v_add_u32_e32 v174, s24, v91
	v_mad_i64_i32 v[172:173], s[58:59], v172, s50, v[0:1]
	global_load_dword v4, v[4:5], off nt
	s_nop 0
	global_load_dword v5, v[2:3], off nt
	s_nop 0
	global_load_dword v6, v[6:7], off nt
	s_nop 0
	global_load_dword v7, v[172:173], off nt
	v_add_u32_e32 v2, s24, v98
	v_mad_i64_i32 v[174:175], s[58:59], v174, s50, v[0:1]
	v_add_u32_e32 v172, s24, v93
	v_mad_i64_i32 v[2:3], s[58:59], v2, s50, v[0:1]
	global_load_dword v173, v[174:175], off nt
	s_nop 0
	global_load_dword v2, v[2:3], off nt
	v_mad_i64_i32 v[0:1], s[58:59], v172, s50, v[0:1]
	global_load_dword v0, v[0:1], off nt
	v_add_u32_e32 v1, v97, v132
	s_waitcnt vmcnt(39)
; #define LDS_WAIT() asm volatile("s_waitcnt lgkmcnt(0)" ::: "memory")
;     ...
;     for (int i = 0; i < 64; ++i) { const int kk = 2 * i + (lane >> 5); scr[kk * 33 + (lane & 31)] = W[(size_t)(k0 + kk) * N + n0 + (lane & 31)]; }
;     LDS_WAIT(); asm volatile("" ::: "memory");
;     const int c = lane & 15;
;     float gk[8];
;     if (gain) load8f(gain + k0 + 8 * c, gk); else {
	ds_write_b32 v1, v14
	v_add_u32_e32 v1, v97, v133
	s_waitcnt vmcnt(38)
	ds_write_b32 v1, v182
	v_add_u32_e32 v1, v97, v134
	s_waitcnt vmcnt(37)
	ds_write_b32 v1, v183
	v_add_u32_e32 v1, v97, v135
	s_waitcnt vmcnt(36)
	ds_write_b32 v1, v184
	v_add_u32_e32 v1, v97, v136
	s_waitcnt vmcnt(35)
	ds_write_b32 v1, v185
	v_add_u32_e32 v1, v97, v137
	s_waitcnt vmcnt(34)
	ds_write_b32 v1, v186
	v_add_u32_e32 v1, v97, v138
	s_waitcnt vmcnt(33)
	ds_write_b32 v1, v187
	v_add_u32_e32 v1, v97, v139
	s_waitcnt vmcnt(32)
	ds_write_b32 v1, v188
	v_add_u32_e32 v1, v97, v140
	s_waitcnt vmcnt(31)
	ds_write_b32 v1, v189
	v_add_u32_e32 v1, v97, v141
	s_waitcnt vmcnt(30)
	ds_write_b32 v1, v190
	v_add_u32_e32 v1, v97, v142
	s_waitcnt vmcnt(29)
	ds_write_b32 v1, v191
	v_add_u32_e32 v1, v97, v143
	s_waitcnt vmcnt(28)
	ds_write_b32 v1, v192
	v_add_u32_e32 v1, v97, v144
	s_waitcnt vmcnt(27)
	ds_write_b32 v1, v193
	v_add_u32_e32 v1, v97, v145
	s_waitcnt vmcnt(26)
	ds_write_b32 v1, v194
	v_add_u32_e32 v1, v97, v146
	s_waitcnt vmcnt(25)
	ds_write_b32 v1, v195
	v_add_u32_e32 v1, v97, v147
	s_waitcnt vmcnt(24)
	ds_write_b32 v1, v196
	v_add_u32_e32 v1, v97, v148
	s_waitcnt vmcnt(23)
	ds_write_b32 v1, v197
	v_add_u32_e32 v1, v97, v149
	s_waitcnt vmcnt(22)
	ds_write_b32 v1, v198
	v_add_u32_e32 v1, v97, v150
	s_waitcnt vmcnt(21)
	ds_write_b32 v1, v199
	v_add_u32_e32 v1, v97, v151
	s_waitcnt vmcnt(20)
	ds_write_b32 v1, v200
	v_add_u32_e32 v1, v97, v152
	s_waitcnt vmcnt(19)
	ds_write_b32 v1, v201
	v_add_u32_e32 v1, v97, v153
	s_waitcnt vmcnt(18)
	ds_write_b32 v1, v202
	v_add_u32_e32 v1, v97, v154
	s_waitcnt vmcnt(17)
	ds_write_b32 v1, v203
	v_add_u32_e32 v1, v97, v155
	s_waitcnt vmcnt(16)
	ds_write_b32 v1, v204
	v_add_u32_e32 v1, v97, v156
	s_waitcnt vmcnt(15)
	ds_write_b32 v1, v205
	v_add_u32_e32 v1, v97, v157
	s_waitcnt vmcnt(14)
	ds_write_b32 v1, v206
	v_add_u32_e32 v1, v97, v158
	s_waitcnt vmcnt(13)
	ds_write_b32 v1, v207
	v_add_u32_e32 v1, v97, v159
	s_waitcnt vmcnt(12)
	ds_write_b32 v1, v208
	v_add_u32_e32 v1, v97, v160
	s_waitcnt vmcnt(11)
	ds_write_b32 v1, v209
	v_add_u32_e32 v1, v97, v161
	s_waitcnt vmcnt(10)
	ds_write_b32 v1, v176
	v_add_u32_e32 v1, v97, v162
	s_waitcnt vmcnt(9)
	ds_write_b32 v1, v177
	v_add_u32_e32 v1, v97, v163
	s_waitcnt vmcnt(8)
	ds_write_b32 v1, v178
	v_add_u32_e32 v1, v97, v164
	s_waitcnt vmcnt(7)
	ds_write_b32 v1, v179
	v_add_u32_e32 v1, v97, v165
	s_waitcnt vmcnt(6)
	ds_write_b32 v1, v4
	v_add_u32_e32 v1, v97, v166
	s_waitcnt vmcnt(5)
	ds_write_b32 v1, v5
	v_add_u32_e32 v1, v97, v167
	s_waitcnt vmcnt(4)
	ds_write_b32 v1, v6
	v_add_u32_e32 v1, v97, v168
	s_waitcnt vmcnt(3)
	ds_write_b32 v1, v7
	v_add_u32_e32 v1, v97, v169
	s_waitcnt vmcnt(2)
	ds_write_b32 v1, v173
	v_add_u32_e32 v1, v97, v170
	s_waitcnt vmcnt(1)
	ds_write_b32 v1, v2
	v_add_u32_e32 v1, v97, v171
	s_waitcnt vmcnt(0)
	ds_write_b32 v1, v0
	s_waitcnt lgkmcnt(0)
	s_cbranch_scc1 .LBB0_71
	s_lshl_b32 s38, s38, 13
	s_add_u32 s2, s2, s38
	s_addc_u32 s3, s3, 0
	s_lshl_b32 s38, s24, 2
	s_add_u32 s2, s2, s38
	s_addc_u32 s3, s3, 0
	v_lshlrev_b32_e32 v0, 2, v16
	global_load_dwordx4 v[4:7], v0, s[2:3]
	s_nop 0
	global_load_dwordx4 v[0:3], v0, s[2:3] offset:16
	s_branch .LBB0_72

;     const int nblk = N / 32, kb = item / nblk, nb = item % nblk, k0 = 128 * kb, n0 = 32 * nb;
;     const int nd0 = GLU ? (n0 < 6144 ? 256 * (n0 >> 7) + (n0 & 127) : 256 * ((n0 - 6144) >> 7) + 128 + ((n0 - 6144) & 127)) : n0;
; #pragma unroll 32
;     for (int i = 0; i < 64; ++i) { const int kk = 2 * i + (lane >> 5); scr[kk * 33 + (lane & 31)] = W[(size_t)(k0 + kk) * N + n0 + (lane & 31)]; }
.LBB0_74:
	s_andn2_b64 vcc, exec, s[2:3]
	s_cbranch_vccnz .LBB0_10
	s_mul_hi_i32 s2, s56, 0xd5555555
	s_lshr_b32 s3, s2, 31
	s_ashr_i32 s2, s2, 9
	s_add_i32 s10, s2, s3
	s_mul_hi_i32 s2, s56, 0x2aaaaaab
	s_lshr_b32 s3, s2, 31
	s_lshr_b32 s2, s2, 9
	s_add_i32 s2, s2, s3
	s_mulk_i32 s2, 0xc00
	s_sub_i32 s57, s56, s2
	s_load_dwordx2 s[2:3], s[6:7], 0xd8
	s_add_i32 s10, s10, 3
	s_mul_hi_u32 s25, s10, 0xc00000
	s_mul_i32 s24, s10, 0xc00000
	s_lshl_b64 s[38:39], s[24:25], 2
	s_waitcnt lgkmcnt(0)
	s_add_u32 s10, s2, s38
	s_sext_i32_i16 s2, s57
	s_addc_u32 s59, s3, s39
	s_bfe_u32 s2, s2, 0x60019
	s_add_i32 s2, s57, s2
	s_sext_i32_i16 s60, s2
	s_and_b32 s2, s2, 0xffc0
	s_sub_i32 s2, s57, s2
	s_sext_i32_i16 s2, s2
	s_lshl_b32 s2, s2, 5
	s_ashr_i32 s3, s2, 31
	s_lshl_b64 s[38:39], s[2:3], 2
	s_add_u32 s58, s10, s38
	s_addc_u32 s59, s59, s39
	s_lshl_b32 s3, s60, 1
	s_and_b32 s38, s3, 0xffffff80
	v_add_u32_e32 v0, s38, v10
	v_add_u32_e32 v4, s38, v9
	v_add_u32_e32 v6, s38, v38
	v_add_u32_e32 v174, s38, v40
	v_add_u32_e32 v176, s38, v13
	v_lshlrev_b32_e32 v14, 2, v12
	v_ashrrev_i32_e32 v1, 31, v0
	v_ashrrev_i32_e32 v5, 31, v4
	v_ashrrev_i32_e32 v7, 31, v6
	v_add_u32_e32 v172, s38, v11
	v_ashrrev_i32_e32 v175, 31, v174
	v_ashrrev_i32_e32 v177, 31, v176
	v_add_u32_e32 v178, s38, v42
	v_add_u32_e32 v180, s38, v17
	v_lshlrev_b64 v[2:3], 13, v[0:1]
	v_lshl_add_u64 v[0:1], s[58:59], 0, v[14:15]
	v_lshlrev_b64 v[4:5], 13, v[4:5]
	v_lshlrev_b64 v[6:7], 13, v[6:7]
	v_ashrrev_i32_e32 v173, 31, v172
	v_lshlrev_b64 v[174:175], 13, v[174:175]
	v_lshlrev_b64 v[176:177], 13, v[176:177]
	v_ashrrev_i32_e32 v179, 31, v178
	v_ashrrev_i32_e32 v181, 31, v180
	v_lshl_add_u64 v[2:3], v[0:1], 0, v[2:3]
	v_lshl_add_u64 v[4:5], v[0:1], 0, v[4:5]
	v_lshl_add_u64 v[6:7], v[0:1], 0, v[6:7]
	v_lshlrev_b64 v[172:173], 13, v[172:173]
	v_lshl_add_u64 v[174:175], v[0:1], 0, v[174:175]
	v_lshl_add_u64 v[176:177], v[0:1], 0, v[176:177]
	v_lshlrev_b64 v[178:179], 13, v[178:179]
	v_lshlrev_b64 v[180:181], 13, v[180:181]
	v_lshl_add_u64 v[172:173], v[0:1], 0, v[172:173]
	v_lshl_add_u64 v[178:179], v[0:1], 0, v[178:179]
	v_lshl_add_u64 v[180:181], v[0:1], 0, v[180:181]
	global_load_dword v14, v[2:3], off nt
	global_load_dword v182, v[4:5], off nt
	global_load_dword v183, v[6:7], off nt
	global_load_dword v184, v[172:173], off nt
	global_load_dword v185, v[174:175], off nt
	global_load_dword v186, v[176:177], off nt
	global_load_dword v187, v[178:179], off nt
	global_load_dword v188, v[180:181], off nt
	v_add_u32_e32 v2, s38, v44
	v_add_u32_e32 v4, s38, v39
	v_add_u32_e32 v6, s38, v46
	v_add_u32_e32 v174, s38, v48
	v_add_u32_e32 v176, s38, v43
	v_ashrrev_i32_e32 v3, 31, v2
	v_ashrrev_i32_e32 v5, 31, v4
	v_ashrrev_i32_e32 v7, 31, v6
	v_add_u32_e32 v172, s38, v41
	v_ashrrev_i32_e32 v175, 31, v174
	v_ashrrev_i32_e32 v177, 31, v176
	v_add_u32_e32 v178, s38, v50
	v_add_u32_e32 v180, s38, v45
	v_lshlrev_b64 v[2:3], 13, v[2:3]
	v_lshlrev_b64 v[4:5], 13, v[4:5]
	v_lshlrev_b64 v[6:7], 13, v[6:7]
	v_ashrrev_i32_e32 v173, 31, v172
	v_lshlrev_b64 v[174:175], 13, v[174:175]
	v_lshlrev_b64 v[176:177], 13, v[176:177]
	v_ashrrev_i32_e32 v179, 31, v178
	v_ashrrev_i32_e32 v181, 31, v180
	v_lshl_add_u64 v[2:3], v[0:1], 0, v[2:3]
	v_lshl_add_u64 v[4:5], v[0:1], 0, v[4:5]
	v_lshl_add_u64 v[6:7], v[0:1], 0, v[6:7]
	v_lshlrev_b64 v[172:173], 13, v[172:173]
	v_lshl_add_u64 v[174:175], v[0:1], 0, v[174:175]
	v_lshl_add_u64 v[176:177], v[0:1], 0, v[176:177]
	v_lshlrev_b64 v[178:179], 13, v[178:179]
	v_lshlrev_b64 v[180:181], 13, v[180:181]
	v_lshl_add_u64 v[172:173], v[0:1], 0, v[172:173]
	v_lshl_add_u64 v[178:179], v[0:1], 0, v[178:179]
	v_lshl_add_u64 v[180:181], v[0:1], 0, v[180:181]
	global_load_dword v189, v[2:3], off nt
	global_load_dword v190, v[4:5], off nt
	global_load_dword v191, v[6:7], off nt
	global_load_dword v192, v[172:173], off nt
	s_nop 0
	global_load_dword v174, v[174:175], off nt
	s_nop 0
	global_load_dword v175, v[176:177], off nt
	s_nop 0
	global_load_dword v176, v[178:179], off nt
	global_load_dword v177, v[180:181], off nt
	v_add_u32_e32 v2, s38, v52
	v_add_u32_e32 v4, s38, v47
	v_add_u32_e32 v6, s38, v54
	v_ashrrev_i32_e32 v3, 31, v2
	v_ashrrev_i32_e32 v5, 31, v4
	v_ashrrev_i32_e32 v7, 31, v6
	v_lshlrev_b64 v[2:3], 13, v[2:3]
	v_lshlrev_b64 v[4:5], 13, v[4:5]
	v_lshlrev_b64 v[6:7], 13, v[6:7]
	v_lshl_add_u64 v[2:3], v[0:1], 0, v[2:3]
	v_lshl_add_u64 v[4:5], v[0:1], 0, v[4:5]
	v_lshl_add_u64 v[6:7], v[0:1], 0, v[6:7]
	global_load_dword v178, v[2:3], off nt
	global_load_dword v179, v[4:5], off nt
	global_load_dword v180, v[6:7], off nt
	v_add_u32_e32 v2, s38, v49
	v_add_u32_e32 v4, s38, v56
	v_add_u32_e32 v6, s38, v51
	v_ashrrev_i32_e32 v3, 31, v2
	v_ashrrev_i32_e32 v5, 31, v4
	v_ashrrev_i32_e32 v7, 31, v6
	v_add_u32_e32 v172, s38, v58
	v_lshlrev_b64 v[2:3], 13, v[2:3]
	v_lshlrev_b64 v[4:5], 13, v[4:5]
	v_lshlrev_b64 v[6:7], 13, v[6:7]
	v_ashrrev_i32_e32 v173, 31, v172
	v_lshl_add_u64 v[2:3], v[0:1], 0, v[2:3]
	v_lshl_add_u64 v[4:5], v[0:1], 0, v[4:5]
	v_lshl_add_u64 v[6:7], v[0:1], 0, v[6:7]
	v_lshlrev_b64 v[172:173], 13, v[172:173]
	v_lshl_add_u64 v[172:173], v[0:1], 0, v[172:173]
	global_load_dword v181, v[2:3], off nt
	s_nop 0
	global_load_dword v4, v[4:5], off nt
	s_nop 0
	global_load_dword v5, v[6:7], off nt
	s_nop 0
	global_load_dword v6, v[172:173], off nt
	v_add_u32_e32 v2, s38, v53
	v_ashrrev_i32_e32 v3, 31, v2
	v_lshlrev_b64 v[2:3], 13, v[2:3]
	v_lshl_add_u64 v[2:3], v[0:1], 0, v[2:3]
	global_load_dword v2, v[2:3], off nt
	v_add_u32_e32 v3, v97, v108
	v_add_u32_e32 v172, s38, v57
	v_ashrrev_i32_e32 v173, 31, v172
	v_lshlrev_b64 v[172:173], 13, v[172:173]
	s_waitcnt vmcnt(23)
;     ...
;     for (int i = 0; i < 64; ++i) { const int kk = 2 * i + (lane >> 5); scr[kk * 33 + (lane & 31)] = W[(size_t)(k0 + kk) * N + n0 + (lane & 31)]; }
	ds_write_b32 v3, v14
	v_add_u32_e32 v3, v97, v109
	s_waitcnt vmcnt(22)
	ds_write_b32 v3, v182
	v_add_u32_e32 v3, v97, v110
	s_waitcnt vmcnt(21)
	ds_write_b32 v3, v183
	v_add_u32_e32 v3, v97, v111
	s_waitcnt vmcnt(20)
	ds_write_b32 v3, v184
	v_add_u32_e32 v3, v97, v112
	s_waitcnt vmcnt(19)
	ds_write_b32 v3, v185
	v_add_u32_e32 v3, v97, v113
	s_waitcnt vmcnt(18)
	ds_write_b32 v3, v186
	v_add_u32_e32 v3, v97, v114
	s_waitcnt vmcnt(17)
	ds_write_b32 v3, v187
	v_add_u32_e32 v3, v97, v115
	s_waitcnt vmcnt(16)
	ds_write_b32 v3, v188
	v_add_u32_e32 v3, v97, v116
	v_lshl_add_u64 v[172:173], v[0:1], 0, v[172:173]
	s_lshl_b64 s[24:25], s[24:25], 1
	s_add_u32 s3, s8, s24
	s_addc_u32 s10, s9, s25
	s_ashr_i32 s39, s38, 31
	s_lshl_b64 s[24:25], s[38:39], 1
	s_add_u32 s24, s3, s24
	s_addc_u32 s25, s10, s25
	s_waitcnt vmcnt(15)
	ds_write_b32 v3, v189
	v_add_u32_e32 v3, v97, v117
	s_waitcnt vmcnt(14)
	ds_write_b32 v3, v190
	v_add_u32_e32 v3, v97, v118
	s_waitcnt vmcnt(13)
	ds_write_b32 v3, v191
	v_add_u32_e32 v3, v97, v119
	s_waitcnt vmcnt(12)
	ds_write_b32 v3, v192
	v_add_u32_e32 v3, v97, v120
	s_waitcnt vmcnt(11)
	ds_write_b32 v3, v174
	v_add_u32_e32 v3, v97, v121
	s_waitcnt vmcnt(10)
	ds_write_b32 v3, v175
	v_add_u32_e32 v3, v97, v122
	s_waitcnt vmcnt(9)
	ds_write_b32 v3, v176
	v_add_u32_e32 v3, v97, v123
	s_waitcnt vmcnt(8)
	ds_write_b32 v3, v177
	v_add_u32_e32 v3, v97, v124
	v_add_u32_e32 v174, s38, v64
	v_add_u32_e32 v176, s38, v59
	s_waitcnt vmcnt(7)
	ds_write_b32 v3, v178
	v_add_u32_e32 v3, v97, v125
	s_waitcnt vmcnt(6)
	ds_write_b32 v3, v179
	v_add_u32_e32 v3, v97, v126
	s_waitcnt vmcnt(5)
	ds_write_b32 v3, v180
	v_add_u32_e32 v3, v97, v127
	v_add_u32_e32 v178, s38, v66
	v_add_u32_e32 v180, s38, v61
	v_ashrrev_i32_e32 v175, 31, v174
	v_ashrrev_i32_e32 v177, 31, v176
	v_ashrrev_i32_e32 v179, 31, v178
	v_lshlrev_b64 v[174:175], 13, v[174:175]
	v_lshlrev_b64 v[176:177], 13, v[176:177]
	v_lshlrev_b64 v[178:179], 13, v[178:179]
	v_lshl_add_u64 v[174:175], v[0:1], 0, v[174:175]
	v_lshl_add_u64 v[176:177], v[0:1], 0, v[176:177]
	s_waitcnt vmcnt(4)
	ds_write_b32 v3, v181
	v_add_u32_e32 v3, v97, v128
	s_waitcnt vmcnt(3)
	ds_write_b32 v3, v4
	v_add_u32_e32 v3, v97, v129
	s_waitcnt vmcnt(2)
	ds_write_b32 v3, v5
	v_add_u32_e32 v3, v97, v130
	s_waitcnt vmcnt(1)
	ds_write_b32 v3, v6
	v_add_u32_e32 v3, v97, v131
	s_waitcnt vmcnt(0)
	ds_write_b32 v3, v2
	v_add_u32_e32 v2, s38, v60
	v_ashrrev_i32_e32 v3, 31, v2
	v_add_u32_e32 v4, s38, v55
	v_add_u32_e32 v6, s38, v62
	v_lshlrev_b64 v[2:3], 13, v[2:3]
	v_ashrrev_i32_e32 v5, 31, v4
	v_ashrrev_i32_e32 v7, 31, v6
	v_ashrrev_i32_e32 v181, 31, v180
	v_lshl_add_u64 v[2:3], v[0:1], 0, v[2:3]
	v_lshlrev_b64 v[4:5], 13, v[4:5]
	v_lshlrev_b64 v[6:7], 13, v[6:7]
	v_lshlrev_b64 v[180:181], 13, v[180:181]
	v_lshl_add_u64 v[4:5], v[0:1], 0, v[4:5]
	v_lshl_add_u64 v[6:7], v[0:1], 0, v[6:7]
	v_lshl_add_u64 v[178:179], v[0:1], 0, v[178:179]
	v_lshl_add_u64 v[180:181], v[0:1], 0, v[180:181]
	global_load_dword v14, v[2:3], off nt
	global_load_dword v182, v[4:5], off nt
	global_load_dword v183, v[6:7], off nt
	global_load_dword v184, v[172:173], off nt
	global_load_dword v185, v[174:175], off nt
	global_load_dword v186, v[176:177], off nt
	global_load_dword v187, v[178:179], off nt
	global_load_dword v188, v[180:181], off nt
	v_add_u32_e32 v2, s38, v68
	v_ashrrev_i32_e32 v3, 31, v2
	v_add_u32_e32 v4, s38, v63
	v_add_u32_e32 v6, s38, v70
	v_add_u32_e32 v172, s38, v65
	v_add_u32_e32 v174, s38, v72
	v_add_u32_e32 v176, s38, v67
	v_add_u32_e32 v178, s38, v74
	v_add_u32_e32 v180, s38, v69
	v_lshlrev_b64 v[2:3], 13, v[2:3]
	v_ashrrev_i32_e32 v5, 31, v4
	v_ashrrev_i32_e32 v7, 31, v6
	v_ashrrev_i32_e32 v173, 31, v172
	v_ashrrev_i32_e32 v175, 31, v174
	v_ashrrev_i32_e32 v177, 31, v176
	v_ashrrev_i32_e32 v179, 31, v178
	v_ashrrev_i32_e32 v181, 31, v180
	v_lshl_add_u64 v[2:3], v[0:1], 0, v[2:3]
	v_lshlrev_b64 v[4:5], 13, v[4:5]
	v_lshlrev_b64 v[6:7], 13, v[6:7]
	v_lshlrev_b64 v[172:173], 13, v[172:173]
	v_lshlrev_b64 v[174:175], 13, v[174:175]
	v_lshlrev_b64 v[176:177], 13, v[176:177]
	v_lshlrev_b64 v[178:179], 13, v[178:179]
	v_lshlrev_b64 v[180:181], 13, v[180:181]
	v_lshl_add_u64 v[4:5], v[0:1], 0, v[4:5]
	v_lshl_add_u64 v[6:7], v[0:1], 0, v[6:7]
	v_lshl_add_u64 v[172:173], v[0:1], 0, v[172:173]
	v_lshl_add_u64 v[174:175], v[0:1], 0, v[174:175]
	v_lshl_add_u64 v[176:177], v[0:1], 0, v[176:177]
	v_lshl_add_u64 v[178:179], v[0:1], 0, v[178:179]
	v_lshl_add_u64 v[180:181], v[0:1], 0, v[180:181]
	global_load_dword v189, v[2:3], off nt
	global_load_dword v190, v[4:5], off nt
	global_load_dword v191, v[6:7], off nt
	global_load_dword v192, v[172:173], off nt
	global_load_dword v193, v[174:175], off nt
	global_load_dword v194, v[176:177], off nt
	global_load_dword v195, v[178:179], off nt
	global_load_dword v196, v[180:181], off nt
	v_add_u32_e32 v2, s38, v76
	v_add_u32_e32 v176, s38, v75
	v_add_u32_e32 v178, s38, v82
	v_ashrrev_i32_e32 v3, 31, v2
	v_add_u32_e32 v4, s38, v71
	v_add_u32_e32 v6, s38, v78
	v_add_u32_e32 v172, s38, v73
	v_add_u32_e32 v174, s38, v80
	v_ashrrev_i32_e32 v177, 31, v176
	v_ashrrev_i32_e32 v179, 31, v178
	v_add_u32_e32 v180, s38, v77
	v_lshlrev_b64 v[2:3], 13, v[2:3]
	v_ashrrev_i32_e32 v5, 31, v4
	v_ashrrev_i32_e32 v7, 31, v6
	v_ashrrev_i32_e32 v173, 31, v172
	v_ashrrev_i32_e32 v175, 31, v174
	v_lshlrev_b64 v[176:177], 13, v[176:177]
	v_lshlrev_b64 v[178:179], 13, v[178:179]
	v_ashrrev_i32_e32 v181, 31, v180
	v_lshl_add_u64 v[2:3], v[0:1], 0, v[2:3]
	v_lshlrev_b64 v[4:5], 13, v[4:5]
	v_lshlrev_b64 v[6:7], 13, v[6:7]
	v_lshlrev_b64 v[172:173], 13, v[172:173]
	v_lshlrev_b64 v[174:175], 13, v[174:175]
;     ...
;     for (int i = 0; i < 64; ++i) { const int kk = 2 * i + (lane >> 5); scr[kk * 33 + (lane & 31)] = W[(size_t)(k0 + kk) * N + n0 + (lane & 31)]; }
	v_lshl_add_u64 v[176:177], v[0:1], 0, v[176:177]
	v_lshl_add_u64 v[178:179], v[0:1], 0, v[178:179]
	v_lshlrev_b64 v[180:181], 13, v[180:181]
	v_lshl_add_u64 v[4:5], v[0:1], 0, v[4:5]
	v_lshl_add_u64 v[6:7], v[0:1], 0, v[6:7]
	v_lshl_add_u64 v[172:173], v[0:1], 0, v[172:173]
	v_lshl_add_u64 v[174:175], v[0:1], 0, v[174:175]
	v_lshl_add_u64 v[180:181], v[0:1], 0, v[180:181]
	global_load_dword v197, v[2:3], off nt
	global_load_dword v198, v[4:5], off nt
	global_load_dword v199, v[6:7], off nt
	global_load_dword v200, v[172:173], off nt
	global_load_dword v201, v[174:175], off nt
	global_load_dword v202, v[176:177], off nt
	global_load_dword v203, v[178:179], off nt
	global_load_dword v204, v[180:181], off nt
	v_add_u32_e32 v2, s38, v84
	v_add_u32_e32 v176, s38, v83
	v_add_u32_e32 v178, s38, v90
	v_ashrrev_i32_e32 v3, 31, v2
	v_add_u32_e32 v4, s38, v79
	v_add_u32_e32 v6, s38, v86
	v_add_u32_e32 v172, s38, v81
	v_add_u32_e32 v174, s38, v88
	v_ashrrev_i32_e32 v177, 31, v176
	v_ashrrev_i32_e32 v179, 31, v178
	v_add_u32_e32 v180, s38, v85
	v_lshlrev_b64 v[2:3], 13, v[2:3]
	v_ashrrev_i32_e32 v5, 31, v4
	v_ashrrev_i32_e32 v7, 31, v6
	v_ashrrev_i32_e32 v173, 31, v172
	v_ashrrev_i32_e32 v175, 31, v174
	v_lshlrev_b64 v[176:177], 13, v[176:177]
	v_lshlrev_b64 v[178:179], 13, v[178:179]
	v_ashrrev_i32_e32 v181, 31, v180
	v_lshl_add_u64 v[2:3], v[0:1], 0, v[2:3]
	v_lshlrev_b64 v[4:5], 13, v[4:5]
	v_lshlrev_b64 v[6:7], 13, v[6:7]
	v_lshlrev_b64 v[172:173], 13, v[172:173]
	v_lshlrev_b64 v[174:175], 13, v[174:175]
	v_lshl_add_u64 v[176:177], v[0:1], 0, v[176:177]
	v_lshl_add_u64 v[178:179], v[0:1], 0, v[178:179]
	v_lshlrev_b64 v[180:181], 13, v[180:181]
	v_lshl_add_u64 v[4:5], v[0:1], 0, v[4:5]
	v_lshl_add_u64 v[6:7], v[0:1], 0, v[6:7]
	v_lshl_add_u64 v[172:173], v[0:1], 0, v[172:173]
	v_lshl_add_u64 v[174:175], v[0:1], 0, v[174:175]
	v_lshl_add_u64 v[180:181], v[0:1], 0, v[180:181]
	global_load_dword v205, v[2:3], off nt
	global_load_dword v206, v[4:5], off nt
	global_load_dword v207, v[6:7], off nt
	global_load_dword v208, v[172:173], off nt
	global_load_dword v209, v[174:175], off nt
	s_nop 0
	global_load_dword v176, v[176:177], off nt
	s_nop 0
	global_load_dword v177, v[178:179], off nt
	s_nop 0
	global_load_dword v178, v[180:181], off nt
	v_add_u32_e32 v2, s38, v92
	v_ashrrev_i32_e32 v3, 31, v2
	v_add_u32_e32 v4, s38, v87
	v_ashrrev_i32_e32 v5, 31, v4
	v_lshlrev_b64 v[2:3], 13, v[2:3]
	v_lshlrev_b64 v[4:5], 13, v[4:5]
	v_lshl_add_u64 v[2:3], v[0:1], 0, v[2:3]
	v_add_u32_e32 v6, s38, v94
	v_add_u32_e32 v172, s38, v89
	v_lshl_add_u64 v[4:5], v[0:1], 0, v[4:5]
	v_ashrrev_i32_e32 v7, 31, v6
	v_ashrrev_i32_e32 v173, 31, v172
	v_add_u32_e32 v174, s38, v96
	global_load_dword v179, v[2:3], off nt
	global_load_dword v180, v[4:5], off nt
	v_add_u32_e32 v2, s38, v91
	v_lshlrev_b64 v[172:173], 13, v[172:173]
	v_lshlrev_b64 v[6:7], 13, v[6:7]
	v_ashrrev_i32_e32 v175, 31, v174
	v_ashrrev_i32_e32 v3, 31, v2
	v_lshl_add_u64 v[6:7], v[0:1], 0, v[6:7]
	v_lshl_add_u64 v[172:173], v[0:1], 0, v[172:173]
	v_lshlrev_b64 v[2:3], 13, v[2:3]
	v_lshlrev_b64 v[4:5], 13, v[174:175]
	v_lshl_add_u64 v[4:5], v[0:1], 0, v[4:5]
	v_lshl_add_u64 v[2:3], v[0:1], 0, v[2:3]
	global_load_dword v174, v[6:7], off nt
	s_nop 0
	global_load_dword v172, v[172:173], off nt
	v_add_u32_e32 v6, s38, v98
	v_ashrrev_i32_e32 v7, 31, v6
	global_load_dword v173, v[4:5], off nt
	global_load_dword v175, v[2:3], off nt
	v_add_u32_e32 v2, s38, v93
	v_ashrrev_i32_e32 v3, 31, v2
	v_lshlrev_b64 v[4:5], 13, v[6:7]
	v_lshlrev_b64 v[2:3], 13, v[2:3]
	v_lshl_add_u64 v[4:5], v[0:1], 0, v[4:5]
	global_load_dword v4, v[4:5], off nt
	v_lshl_add_u64 v[0:1], v[0:1], 0, v[2:3]
	global_load_dword v0, v[0:1], off nt
	v_add_u32_e32 v1, v97, v132
	s_waitcnt vmcnt(39)
	ds_write_b32 v1, v14
	v_add_u32_e32 v1, v97, v133
	s_waitcnt vmcnt(38)
	ds_write_b32 v1, v182
	v_add_u32_e32 v1, v97, v134
	s_waitcnt vmcnt(37)
	ds_write_b32 v1, v183
	v_add_u32_e32 v1, v97, v135
	s_waitcnt vmcnt(36)
	ds_write_b32 v1, v184
	v_add_u32_e32 v1, v97, v136
	s_waitcnt vmcnt(35)
	ds_write_b32 v1, v185
	v_add_u32_e32 v1, v97, v137
	s_waitcnt vmcnt(34)
	ds_write_b32 v1, v186
	v_add_u32_e32 v1, v97, v138
	s_waitcnt vmcnt(33)
	ds_write_b32 v1, v187
	v_add_u32_e32 v1, v97, v139
	s_waitcnt vmcnt(32)
	ds_write_b32 v1, v188
	v_add_u32_e32 v1, v97, v140
	s_waitcnt vmcnt(31)
	ds_write_b32 v1, v189
	v_add_u32_e32 v1, v97, v141
	s_waitcnt vmcnt(30)
	ds_write_b32 v1, v190
	v_add_u32_e32 v1, v97, v142
	s_waitcnt vmcnt(29)
	ds_write_b32 v1, v191
	v_add_u32_e32 v1, v97, v143
	s_waitcnt vmcnt(28)
	ds_write_b32 v1, v192
	v_add_u32_e32 v1, v97, v144
	s_waitcnt vmcnt(27)
	ds_write_b32 v1, v193
	v_add_u32_e32 v1, v97, v145
	s_waitcnt vmcnt(26)
	ds_write_b32 v1, v194
	v_add_u32_e32 v1, v97, v146
	s_waitcnt vmcnt(25)
	ds_write_b32 v1, v195
	v_add_u32_e32 v1, v97, v147
	s_waitcnt vmcnt(24)
	ds_write_b32 v1, v196
	v_add_u32_e32 v1, v97, v148
	s_waitcnt vmcnt(23)
	ds_write_b32 v1, v197
	v_add_u32_e32 v1, v97, v149
	s_waitcnt vmcnt(22)
	ds_write_b32 v1, v198
	v_add_u32_e32 v1, v97, v150
	s_waitcnt vmcnt(21)
	ds_write_b32 v1, v199
	v_add_u32_e32 v1, v97, v151
	s_waitcnt vmcnt(20)
	ds_write_b32 v1, v200
	v_add_u32_e32 v1, v97, v152
	s_waitcnt vmcnt(19)
	ds_write_b32 v1, v201
	v_add_u32_e32 v1, v97, v153
	s_waitcnt vmcnt(18)
	ds_write_b32 v1, v202
	v_add_u32_e32 v1, v97, v154
	s_waitcnt vmcnt(17)
	ds_write_b32 v1, v203
	v_add_u32_e32 v1, v97, v155
	s_waitcnt vmcnt(16)
	ds_write_b32 v1, v204
	v_add_u32_e32 v1, v97, v156
	s_waitcnt vmcnt(15)
; __device__ __forceinline__ unsigned cvt_pk_bf16(float lo, float hi) { unsigned r; asm volatile("v_cvt_pk_bf16_f32 %0, %1, %2" : "=v"(r) : "v"(lo), "v"(hi)); return r; }
; #define GAS __attribute__((address_space(1)))
; #define LAS __attribute__((address_space(3)))
; #define LDS_WAIT() asm volatile("s_waitcnt lgkmcnt(0)" ::: "memory")
;     ...
;     LDS_WAIT(); asm volatile("" ::: "memory");
;     const int c = lane & 15;
;     float gk[8];
;     if (gain) load8f(gain + k0 + 8 * c, gk); else {
; #pragma unroll
;         for (int e = 0; e < 8; ++e) gk[e] = 1.0f; }
; #pragma unroll
;     for (int j = 0; j < 8; ++j) { const int n = (lane >> 4) + 4 * j; const LAS float* s = scr + (8 * c) * 33 + n;
;         v4u o; o.x = cvt_pk_bf16(s[0 * 33] * gk[0], s[1 * 33] * gk[1]); o.y = cvt_pk_bf16(s[2 * 33] * gk[2], s[3 * 33] * gk[3]); o.z = cvt_pk_bf16(s[4 * 33] * gk[4], s[5 * 33] * gk[5]); o.w = cvt_pk_bf16(s[6 * 33] * gk[6], s[7 * 33] * gk[7]);
;         *(GAS v4u*)(WT + (size_t)(nd0 + n) * K + k0 + 8 * c) = o; }
;     LDS_WAIT(); asm volatile("" ::: "memory");
	ds_write_b32 v1, v205
	v_add_u32_e32 v1, v97, v157
	s_waitcnt vmcnt(14)
	ds_write_b32 v1, v206
	v_add_u32_e32 v1, v97, v158
	s_waitcnt vmcnt(13)
	ds_write_b32 v1, v207
	v_add_u32_e32 v1, v97, v159
	s_waitcnt vmcnt(12)
	ds_write_b32 v1, v208
	v_add_u32_e32 v1, v97, v160
	s_waitcnt vmcnt(11)
	ds_write_b32 v1, v209
	v_add_u32_e32 v1, v97, v161
	s_waitcnt vmcnt(10)
	ds_write_b32 v1, v176
	v_add_u32_e32 v1, v97, v162
	s_waitcnt vmcnt(9)
	ds_write_b32 v1, v177
	v_add_u32_e32 v1, v97, v163
	s_waitcnt vmcnt(8)
	ds_write_b32 v1, v178
	v_add_u32_e32 v1, v97, v164
	s_waitcnt vmcnt(7)
	ds_write_b32 v1, v179
	v_add_u32_e32 v1, v97, v165
	s_waitcnt vmcnt(6)
	ds_write_b32 v1, v180
	v_add_u32_e32 v1, v97, v166
	s_waitcnt vmcnt(5)
	ds_write_b32 v1, v174
	v_add_u32_e32 v1, v97, v167
	s_waitcnt vmcnt(4)
	ds_write_b32 v1, v172
	v_add_u32_e32 v1, v97, v168
	s_waitcnt vmcnt(3)
	ds_write_b32 v1, v173
	v_add_u32_e32 v1, v97, v169
	s_waitcnt vmcnt(2)
	ds_write_b32 v1, v175
	v_add_u32_e32 v1, v97, v170
	s_waitcnt vmcnt(1)
	ds_write_b32 v1, v4
	v_add_u32_e32 v1, v97, v171
	s_waitcnt vmcnt(0)
	ds_write_b32 v1, v0
	s_waitcnt lgkmcnt(0)
	ds_read2_b32 v[0:1], v100 offset1:33
	s_waitcnt lgkmcnt(0)
	v_cvt_pk_bf16_f32 v0, v0, v1
	ds_read2_b32 v[2:3], v100 offset0:66 offset1:99
	v_lshlrev_b32_e32 v14, 1, v16
	s_waitcnt lgkmcnt(0)
	v_cvt_pk_bf16_f32 v1, v2, v3
	ds_read2_b32 v[2:3], v100 offset0:132 offset1:165
	v_add_u32_e32 v172, s2, v99
	v_lshl_add_u64 v[6:7], s[24:25], 0, v[14:15]
	s_waitcnt lgkmcnt(0)
	v_cvt_pk_bf16_f32 v2, v2, v3
	ds_read2_b32 v[4:5], v100 offset0:198 offset1:231
	s_waitcnt lgkmcnt(0)
	v_cvt_pk_bf16_f32 v3, v4, v5
	v_mad_i64_i32 v[172:173], s[24:25], v172, s51, v[6:7]
	ds_read2_b32 v[4:5], v100 offset0:4 offset1:37
	global_store_dwordx4 v[172:173], v[0:3], off
	v_add_u32_e32 v14, s2, v101
	v_mad_i64_i32 v[172:173], s[24:25], v14, s51, v[6:7]
	s_waitcnt lgkmcnt(0)
	v_cvt_pk_bf16_f32 v0, v4, v5
	ds_read2_b32 v[2:3], v100 offset0:70 offset1:103
	s_waitcnt lgkmcnt(0)
	v_cvt_pk_bf16_f32 v1, v2, v3
	ds_read2_b32 v[2:3], v100 offset0:136 offset1:169
	s_waitcnt lgkmcnt(0)
	v_cvt_pk_bf16_f32 v2, v2, v3
	ds_read2_b32 v[4:5], v100 offset0:202 offset1:235
	s_waitcnt lgkmcnt(0)
	v_cvt_pk_bf16_f32 v3, v4, v5
	ds_read2_b32 v[4:5], v100 offset0:8 offset1:41
	global_store_dwordx4 v[172:173], v[0:3], off
	v_add_u32_e32 v14, s2, v102
	v_mad_i64_i32 v[172:173], s[24:25], v14, s51, v[6:7]
	s_waitcnt lgkmcnt(0)
	v_cvt_pk_bf16_f32 v0, v4, v5
	ds_read2_b32 v[2:3], v100 offset0:74 offset1:107
	s_waitcnt lgkmcnt(0)
	v_cvt_pk_bf16_f32 v1, v2, v3
	ds_read2_b32 v[2:3], v100 offset0:140 offset1:173
	s_waitcnt lgkmcnt(0)
	v_cvt_pk_bf16_f32 v2, v2, v3
	ds_read2_b32 v[4:5], v100 offset0:206 offset1:239
	s_waitcnt lgkmcnt(0)
	v_cvt_pk_bf16_f32 v3, v4, v5
	ds_read2_b32 v[4:5], v100 offset0:12 offset1:45
	global_store_dwordx4 v[172:173], v[0:3], off
	v_add_u32_e32 v14, s2, v103
	v_mad_i64_i32 v[172:173], s[24:25], v14, s51, v[6:7]
	s_waitcnt lgkmcnt(0)
	v_cvt_pk_bf16_f32 v0, v4, v5
	ds_read2_b32 v[2:3], v100 offset0:78 offset1:111
	s_waitcnt lgkmcnt(0)
	v_cvt_pk_bf16_f32 v1, v2, v3
	ds_read2_b32 v[2:3], v100 offset0:144 offset1:177
	s_waitcnt lgkmcnt(0)
	v_cvt_pk_bf16_f32 v2, v2, v3
	ds_read2_b32 v[4:5], v100 offset0:210 offset1:243
	s_waitcnt lgkmcnt(0)
	v_cvt_pk_bf16_f32 v3, v4, v5
	ds_read2_b32 v[4:5], v100 offset0:16 offset1:49
	global_store_dwordx4 v[172:173], v[0:3], off
	v_add_u32_e32 v14, s2, v104
	v_mad_i64_i32 v[172:173], s[24:25], v14, s51, v[6:7]
	s_waitcnt lgkmcnt(0)
	v_cvt_pk_bf16_f32 v0, v4, v5
	ds_read2_b32 v[2:3], v100 offset0:82 offset1:115
	s_waitcnt lgkmcnt(0)
	v_cvt_pk_bf16_f32 v1, v2, v3
	ds_read2_b32 v[2:3], v100 offset0:148 offset1:181
	s_waitcnt lgkmcnt(0)
	v_cvt_pk_bf16_f32 v2, v2, v3
	ds_read2_b32 v[4:5], v100 offset0:214 offset1:247
	s_waitcnt lgkmcnt(0)
	v_cvt_pk_bf16_f32 v3, v4, v5
	ds_read2_b32 v[4:5], v100 offset0:20 offset1:53
	global_store_dwordx4 v[172:173], v[0:3], off
	v_add_u32_e32 v14, s2, v105
	v_mad_i64_i32 v[172:173], s[24:25], v14, s51, v[6:7]
	s_waitcnt lgkmcnt(0)
	v_cvt_pk_bf16_f32 v0, v4, v5
	ds_read2_b32 v[2:3], v100 offset0:86 offset1:119
	s_waitcnt lgkmcnt(0)
	v_cvt_pk_bf16_f32 v1, v2, v3
	ds_read2_b32 v[2:3], v100 offset0:152 offset1:185
	s_waitcnt lgkmcnt(0)
	v_cvt_pk_bf16_f32 v2, v2, v3
	ds_read2_b32 v[4:5], v100 offset0:218 offset1:251
	s_waitcnt lgkmcnt(0)
	v_cvt_pk_bf16_f32 v3, v4, v5
	ds_read2_b32 v[4:5], v100 offset0:24 offset1:57
	global_store_dwordx4 v[172:173], v[0:3], off
	v_add_u32_e32 v14, s2, v106
	v_mad_i64_i32 v[172:173], s[24:25], v14, s51, v[6:7]
	s_waitcnt lgkmcnt(0)
	v_cvt_pk_bf16_f32 v0, v4, v5
	ds_read2_b32 v[2:3], v100 offset0:90 offset1:123
	s_waitcnt lgkmcnt(0)
	v_cvt_pk_bf16_f32 v1, v2, v3
	ds_read2_b32 v[2:3], v100 offset0:156 offset1:189
	s_waitcnt lgkmcnt(0)
	v_cvt_pk_bf16_f32 v2, v2, v3
	ds_read2_b32 v[4:5], v100 offset0:222 offset1:255
	s_waitcnt lgkmcnt(0)
	v_cvt_pk_bf16_f32 v3, v4, v5
	ds_read2_b32 v[4:5], v100 offset0:28 offset1:61
	global_store_dwordx4 v[172:173], v[0:3], off
	s_waitcnt lgkmcnt(0)
	s_nop 0
	v_cvt_pk_bf16_f32 v0, v4, v5
	ds_read2_b32 v[2:3], v100 offset0:94 offset1:127
	s_waitcnt lgkmcnt(0)
	v_cvt_pk_bf16_f32 v1, v2, v3
	ds_read2_b32 v[2:3], v100 offset0:160 offset1:193
	s_waitcnt lgkmcnt(0)
	v_cvt_pk_bf16_f32 v2, v2, v3
	v_add_u32_e32 v3, 0x200, v100
	ds_read2_b32 v[4:5], v3 offset0:98 offset1:131
	s_waitcnt lgkmcnt(0)
	v_cvt_pk_bf16_f32 v3, v4, v5
	v_add_u32_e32 v4, s2, v107
	v_mad_i64_i32 v[4:5], s[2:3], v4, s51, v[6:7]
	global_store_dwordx4 v[4:5], v[0:3], off
	s_waitcnt lgkmcnt(0)
	s_branch .LBB0_10
